# gMLP and fnet tile epilogues: gate loads batched and prefetched one trip ahead; ctx outproj epilogue batched; inproj 16B stores; all flat ops to global
# speedup vs baseline: 1.0519x; 1.0238x over previous
; DI int otid() { int t = threadIdx.x; asm volatile("" : "+v"(t)); return t; }
; DI void phase_mix(KP p, int l, char* lds) {
;   unsigned char* ws = p->ws; asm volatile("" : "+s"(ws));
;   const bf16_t* P = (const bf16_t*)(ws + WS_P);
;   bf16_t* Y = (bf16_t*)(ws + WS_R1);
;   bf16_t* YD = (bf16_t*)(ws + WS_YD);
;   const bf16_t* QA = (const bf16_t*)(ws + WS_QA); const bf16_t* KA = (const bf16_t*)(ws + WS_KA); const bf16_t* VAT = (const bf16_t*)(ws + WS_VAT);
;   const bf16_t* QB = (const bf16_t*)(ws + WS_QB); const bf16_t* KB = (const bf16_t*)(ws + WS_KB); const bf16_t* VBT = (const bf16_t*)(ws + WS_VBT);
;   const bf16_t* FTF = (const bf16_t*)(ws + WS_FTF); const bf16_t* FTC = (const bf16_t*)(ws + WS_FTC);
;   const bf16_t* DL = (const bf16_t*)(ws + WS_DLAT); const bf16_t* DC = (const bf16_t*)(ws + WS_DCTX);
;   const bf16_t* vnT = (const bf16_t*)(ws + WS_VNT);
;   const bf16_t* wsb = (const bf16_t*)(ws + WS_WS) + (size_t)l * 4 * 128 * 128;
;   const bool upd = (l == 0);
;   const float sbA = ((const float*)(ws + WS_SBND))[l * 2], sbB = ((const float*)(ws + WS_SBND))[l * 2 + 1];
;   const int xcd = blockIdx.x & 7, lb = 2 * (blockIdx.x >> 3) + __builtin_amdgcn_readfirstlane(otid() >> 8), nlb = 2 * (gridDim.x >> 3);
;   const int nDL = 64, nA = 0, nB = 0, nDC = upd ? 8 : 0, nAc = 0, nBc = 0, nCM = 72, nFN = upd ? 72 : 64;
;   const int e0 = nDL, e1 = e0 + nA, e2 = e1 + nB, e3 = e2 + nDC, e4 = e3 + nAc, e5 = e4 + nBc, e6 = e5 + nCM, e7 = e6 + nFN;
;   unsigned* cnt = (unsigned*)(ws + WS_CNT) + l * 288;
;   const bf16_t* wf = (const bf16_t*)(ws + WS_WF) + (size_t)l * 256 * 256;
;   {
;     const int lbw = blockIdx.x >> 3, nlbw = gridDim.x >> 3;
;     const int nW = upd ? 144 : 128;
;     for (int it = lbw; it < nW; it += nlbw) {
; __global__ void __launch_bounds__(NTHR, 2) fwd_megakernel(Params p_byval) {
;     ...
;   for (int ph = p->ph_lo; ph < p->ph_hi; ++ph) {
;     asm volatile("" : "+s"(p));
;     if (ph == 0) phase0(p, lds);
;     else {
;       const int l = (ph - 1) / 7, s = (ph - 1) % 7;
;       switch (s) {
;         case 0: phase_norm(p, l); break;
;         case 1: phase_inproj(p, l, lds); break;
;         case 2: phase_feat_a(p, l, lds); break;
;         case 3: phase_feat_b(p, l, lds); break;
;         case 4: phase_feat_c(p, l); break;
;         case 5: phase_mix(p, l, lds); break;
;         default: phase_outproj(p, l, lds); break;
.LBB0_22:
	v_readlane_b32 s4, v253, 2
	v_readlane_b32 s5, v253, 3
	s_cmp_lg_u32 s4, 0
	s_mov_b64 s[4:5], -1
	s_cbranch_scc0 .LBB0_284
	v_readlane_b32 s4, v253, 2
	s_add_i32 s2, s4, -1
	s_mul_hi_i32 s4, s2, 0x92492493
	v_readlane_b32 s5, v253, 3
	s_add_i32 s4, s4, s2
	s_lshr_b32 s5, s4, 31
	s_ashr_i32 s4, s4, 2
	s_add_i32 s4, s4, s5
	s_mov_b32 s14, s4
	s_mul_i32 s4, s4, 7
	s_sub_i32 s2, s2, s4
	s_load_dwordx2 s[4:5], s[0:1], 0xb8
	v_writelane_b32 v255, s14, 26
	s_cmp_lt_i32 s2, 3
	s_mov_b64 s[44:45], 0
	v_writelane_b32 v255, s15, 27
	s_waitcnt lgkmcnt(0)
	v_writelane_b32 v255, s4, 28
	s_nop 1
	v_writelane_b32 v255, s5, 29
	s_mov_b64 s[4:5], -1
	v_writelane_b32 v255, s2, 30
	s_cbranch_scc1 .LBB0_256
	v_readlane_b32 s2, v255, 30
	s_cmp_gt_i32 s2, 3
	s_cbranch_scc0 .LBB0_215
	s_cmp_gt_i32 s2, 4
	s_cbranch_scc0 .LBB0_182
	s_cmp_eq_u32 s2, 5
	s_mov_b64 s[44:45], -1
	s_cbranch_scc0 .LBB0_181
	s_load_dwordx2 s[18:19], s[0:1], 0xb8
	s_waitcnt lgkmcnt(0)
	s_add_u32 s42, s18, 0x60b5100
	s_addc_u32 s43, s19, 0
	s_add_u32 s2, s18, 0x18b5100
	v_writelane_b32 v255, s2, 31
	s_addc_u32 s2, s19, 0
	v_readlane_b32 s4, v253, 2
	v_writelane_b32 v255, s2, 32
	v_readlane_b32 s5, v253, 3
	s_add_i32 s2, s4, -8
	v_readlane_b32 s4, v255, 26
	v_readlane_b32 s5, v255, 27
	s_lshl_b32 s4, s4, 1
	s_ashr_i32 s5, s4, 31
	s_lshl_b64 s[4:5], s[4:5], 2
	s_add_u32 s4, s18, s4
	v_writelane_b32 v255, s18, 33
	s_addc_u32 s5, s19, s5
	v_mov_b32_e32 v0, s4
	v_add_co_u32_e32 v2, vcc, 0x69000, v0
	v_mov_b32_e32 v0, s5
	s_nop 0
	v_addc_co_u32_e32 v3, vcc, 0, v0, vcc
	s_waitcnt vmcnt(0)
	global_load_dwordx2 v[18:19], v[2:3], off
	s_cmp_lt_u32 s2, -13
	v_writelane_b32 v255, s19, 34
	s_cselect_b64 s[4:5], -1, 0
	v_writelane_b32 v255, s4, 35
	s_movk_i32 s2, 0x90
	v_mov_b32_e32 v0, v196
	v_writelane_b32 v255, s5, 36
	s_and_b64 s[4:5], s[4:5], exec
	s_cselect_b32 s75, 0x80, s2
	v_readlane_b32 s2, v254, 42
	s_cmp_ge_u32 s2, s75
	v_readfirstlane_b32 s2, v0
	s_nop 1
	v_writelane_b32 v255, s2, 37
	s_cbranch_scc1 .LBB0_123
	v_readlane_b32 s4, v255, 33
	v_readlane_b32 s5, v255, 34
	s_add_u32 s2, s4, 0x16175100
	v_writelane_b32 v255, s2, 38
	s_addc_u32 s2, s5, 0
	v_writelane_b32 v255, s2, 39
	s_add_u32 s2, s4, 0x17c75100
	v_writelane_b32 v255, s2, 40
	s_addc_u32 s2, s5, 0
	v_writelane_b32 v255, s2, 41
	s_add_u32 s2, s4, 0x19775100
	v_writelane_b32 v255, s2, 42
	s_addc_u32 s2, s5, 0
	v_writelane_b32 v255, s2, 43
	s_add_u32 s2, s4, 0x1a975100
	v_writelane_b32 v255, s2, 44
	s_addc_u32 s2, s5, 0
	v_writelane_b32 v255, s2, 45
	s_add_u32 s2, s4, 0x1bb75100
	v_writelane_b32 v255, s2, 47
	s_addc_u32 s2, s5, 0
	v_writelane_b32 v255, s2, 48
	s_add_u32 s2, s4, 0x1c475100
	v_writelane_b32 v255, s2, 49
	s_addc_u32 s2, s5, 0
	v_writelane_b32 v255, s2, 50
	s_mov_b32 s2, 0x41f00000
	s_waitcnt vmcnt(0) lgkmcnt(0)
	v_cmp_ge_f32_e64 s[4:5], s2, v19
	v_xor_b32_e32 v2, 0x80000000, v19
	v_mov_b32_e32 v3, v2
	v_writelane_b32 v255, s4, 51
	v_mov_b32_e32 v4, v2
	v_mov_b32_e32 v5, v2
	v_writelane_b32 v255, s5, 52
	v_cmp_ge_f32_e64 s[4:5], s2, v18
	v_xor_b32_e32 v18, 0x80000000, v18
	v_mov_b32_e32 v6, v2
	v_writelane_b32 v255, s4, 53
	v_mov_b32_e32 v7, v2
	v_mov_b32_e32 v8, v2
	v_writelane_b32 v255, s5, 54
	v_mov_b32_e32 v9, v2
	v_mov_b32_e32 v10, v2
	v_mov_b32_e32 v11, v2
	v_mov_b32_e32 v12, v2
	v_mov_b32_e32 v13, v2
	v_mov_b32_e32 v14, v2
	v_mov_b32_e32 v15, v2
	v_mov_b32_e32 v16, v2
	v_mov_b32_e32 v17, v2
	v_mov_b32_e32 v19, v18
	v_mov_b32_e32 v20, v18
	v_mov_b32_e32 v21, v18
	v_mov_b32_e32 v22, v18
	v_mov_b32_e32 v23, v18
	v_mov_b32_e32 v24, v18
	v_mov_b32_e32 v25, v18
	v_mov_b32_e32 v26, v18
	v_mov_b32_e32 v27, v18
	v_mov_b32_e32 v28, v18
	v_mov_b32_e32 v29, v18
	v_mov_b32_e32 v30, v18
	v_mov_b32_e32 v31, v18
	v_mov_b32_e32 v32, v18
	v_mov_b32_e32 v33, v18
	v_readlane_b32 s64, v254, 42
	v_writelane_b32 v255, s75, 55
	s_branch .LBB0_32

; DI void phase_mix(KP p, int l, char* lds) {
;     ...
;       if (tid0 == 0) {
;         unsigned sp = 0;
;         while (__hip_atomic_load(&cnt[mt], __ATOMIC_RELAXED, __HIP_MEMORY_SCOPE_AGENT) < 2u) { __builtin_amdgcn_s_sleep(2); if (++sp > (1u << 24)) break; }
;         __builtin_amdgcn_fence(__ATOMIC_ACQUIRE, "agent");
;         asm volatile("s_waitcnt vmcnt(0)" ::: "memory");
;       }
;       __syncthreads();
.LBB0_139:
	v_mov_b64_e32 v[2:3], s[18:19]
	global_load_dword v0, v[2:3], off sc1
	s_or_b64 s[36:37], s[36:37], exec
	s_waitcnt vmcnt(0) lgkmcnt(0)
	v_cmp_gt_u32_e32 vcc, 2, v0
	s_and_saveexec_b64 s[40:41], vcc
	s_cbranch_execz .LBB0_138
	s_cmp_lg_u32 s69, 0
	s_sleep 2
	s_cbranch_scc0 .LBB0_149
	v_mov_b64_e32 v[2:3], s[18:19]
	global_load_dword v0, v[2:3], off sc1
	s_mov_b64 s[52:53], -1
	s_waitcnt vmcnt(0) lgkmcnt(0)
	v_cmp_gt_u32_e32 vcc, 2, v0
	s_and_saveexec_b64 s[50:51], vcc
	s_cbranch_execz .LBB0_136
	v_mov_b64_e32 v[2:3], s[18:19]
	s_sleep 2
	global_load_dword v0, v[2:3], off sc1
	s_mov_b64 s[34:35], -1
	s_waitcnt vmcnt(0) lgkmcnt(0)
	v_cmp_gt_u32_e32 vcc, 2, v0
	s_and_saveexec_b64 s[52:53], vcc
	s_cbranch_execz .LBB0_135
	v_mov_b64_e32 v[2:3], s[18:19]
	s_sleep 2
	global_load_dword v0, v[2:3], off sc1
	s_waitcnt vmcnt(0) lgkmcnt(0)
	v_cmp_gt_u32_e32 vcc, 2, v0
	s_and_saveexec_b64 s[54:55], vcc
	s_cbranch_execz .LBB0_134
	v_mov_b64_e32 v[2:3], s[18:19]
	s_sleep 2
	global_load_dword v0, v[2:3], off sc1
	s_mov_b64 s[48:49], s[64:65]
	s_waitcnt vmcnt(0) lgkmcnt(0)
	v_cmp_gt_u32_e32 vcc, 2, v0
	s_and_saveexec_b64 s[56:57], vcc
	s_cbranch_execz .LBB0_133
	v_mov_b64_e32 v[2:3], s[18:19]
	s_sleep 2
	global_load_dword v0, v[2:3], off sc1
	s_waitcnt vmcnt(0) lgkmcnt(0)
	v_cmp_gt_u32_e32 vcc, 2, v0
	s_and_saveexec_b64 s[64:65], vcc
	s_cbranch_execz .LBB0_132
	v_mov_b64_e32 v[2:3], s[18:19]
	s_sleep 2
	global_load_dword v0, v[2:3], off sc1
	s_waitcnt vmcnt(0) lgkmcnt(0)
	v_cmp_gt_u32_e32 vcc, 2, v0
	s_and_saveexec_b64 s[74:75], vcc
	s_cbranch_execz .LBB0_131
	v_mov_b64_e32 v[2:3], s[18:19]
	s_sleep 2
	global_load_dword v0, v[2:3], off sc1
	s_waitcnt vmcnt(0) lgkmcnt(0)
	v_cmp_gt_u32_e32 vcc, 2, v0
	s_and_saveexec_b64 s[76:77], vcc
	s_cbranch_execz .LBB0_130
	s_add_i32 s69, s69, -8
	s_xor_b64 s[34:35], exec, -1
	s_sleep 2
	s_branch .LBB0_130

; DI int otid() { int t = threadIdx.x; asm volatile("" : "+v"(t)); return t; }
; #define G_WAIT() { asm volatile("s_waitcnt vmcnt(0)" ::: "memory"); __syncthreads(); }
;   const int tid_full = otid(); const int tid = tid_full & 255; lds += (tid_full >> 8) * HALF_LDS;
;   const int lane = tid & 63, w = tid >> 6, l31 = lane & 31, h = lane >> 5;
;   const int wr = w >> 1, wc = w & 1;
;   const int lrow = tid >> 3, lch = (tid & 7) ^ ((tid >> 4) & 7);
;   const bf16_t* ag = A + (size_t)lrow * lda + lch * 8;
;   const bf16_t* bg = Bt + (size_t)lrow * ldb + lch * 8;
;   const size_t a32 = (size_t)32 * lda, b32 = (size_t)32 * ldb;
;   f32x16 acc[2][2];
; #pragma unroll
;   for (int i = 0; i < 2; ++i)
; #pragma unroll
;     for (int j = 0; j < 2; ++j)
; #pragma unroll
;       for (int e = 0; e < 16; ++e) acc[i][j][e] = 0.f;
;   const int nk = K >> 6;
;   const int rsw = (l31 >> 1) & 7;
;   const int aoff = (wr * 64 + l31) * 128, boff = 16384 + (wc * 64 + l31) * 128;
;   char* ldst = lds + tid * 16;
;     ...
;   G_DMA(0, 0);
;   G_WAIT();
;   for (int kt = 0; kt < nk; kt += 2) {
;     if (kt + 1 < nk) G_DMA(1, kt + 1);
;     G_COMPUTE(0);
;     G_WAIT();
;     if (kt + 1 < nk) {
;       if (kt + 2 < nk) G_DMA(0, kt + 2);
;       G_COMPUTE(1);
;       G_WAIT();
;     }
;   }
; DI void phase_mix(KP p, int l, char* lds) {
;     ...
;       const int m0 = mt * 128, n0 = nt * 128;
;       gemm_tile(YD + (size_t)m0 * 256, 256, wf + (size_t)n0 * 256, 256, 256, lds, [&](int m, int n, f32x4 v) {
.LBB0_151:
	s_or_b64 exec, exec, s[4:5]
	s_lshl_b32 s2, s2, 7
	s_lshl_b32 s4, s46, 7
	s_and_b32 s5, s4, 0x80
	s_lshl_b64 s[18:19], s[2:3], 9
	v_readlane_b32 s4, v255, 38
	s_add_u32 s18, s4, s18
	v_readlane_b32 s4, v255, 39
	v_mov_b32_e32 v71, v196
	s_barrier
	s_addc_u32 s19, s4, s19
	s_lshl_b32 s4, s5, 9
	v_readlane_b32 s20, v255, 40
	s_add_u32 s20, s20, s4
	v_lshrrev_b32_e32 v0, 4, v71
	v_readlane_b32 s4, v255, 41
	v_xor_b32_e32 v8, v0, v71
	v_lshlrev_b32_e32 v0, 6, v71
	s_addc_u32 s21, s4, 0
	v_and_b32_e32 v0, 0x3e00, v0
	v_lshrrev_b32_e32 v70, 8, v71
	s_mov_b32 s55, 0x11000
	v_lshl_add_u64 v[2:3], s[20:21], 0, v[0:1]
	v_lshl_add_u64 v[4:5], s[18:19], 0, v[0:1]
	v_lshlrev_b32_e32 v0, 4, v8
	v_and_b32_e32 v6, 0xff, v71
	v_mad_i32_i24 v73, v70, s55, 0
	v_and_b32_e32 v0, 0x70, v0
	v_lshl_add_u64 v[66:67], v[2:3], 0, v[0:1]
	v_lshlrev_b32_e32 v2, 7, v71
	v_lshl_add_u32 v94, v6, 4, v73
	v_lshl_add_u64 v[68:69], v[4:5], 0, v[0:1]
	v_and_b32_e32 v4, 0x2f80, v2
	v_add_u32_e32 v2, 0x4000, v94
	v_readfirstlane_b32 s36, v94
	s_mov_b32 m0, s36
	v_readfirstlane_b32 s20, v2
	v_add_u32_e32 v5, 0x1000, v94
	global_load_lds_dwordx4 v[68:69], off
	s_mov_b32 m0, s20
	s_mov_b64 s[18:19], 0x4000
	v_readfirstlane_b32 s4, v5
	global_load_lds_dwordx4 v[66:67], off
	v_lshl_add_u64 v[2:3], v[68:69], 0, s[18:19]
	s_mov_b32 m0, s4
	v_add_u32_e32 v5, 0x5000, v94
	global_load_lds_dwordx4 v[2:3], off
	v_lshl_add_u64 v[2:3], v[66:67], 0, s[18:19]
	v_readfirstlane_b32 s19, v5
	v_add_u32_e32 v5, 0x2000, v94
	s_mov_b32 m0, s19
	s_mov_b64 s[34:35], 0x8000
	v_readfirstlane_b32 s18, v5
	global_load_lds_dwordx4 v[2:3], off
	v_lshl_add_u64 v[2:3], v[68:69], 0, s[34:35]
	s_mov_b32 m0, s18
	v_add_u32_e32 v5, 0x6000, v94
	global_load_lds_dwordx4 v[2:3], off
	v_lshl_add_u64 v[2:3], v[66:67], 0, s[34:35]
	v_readfirstlane_b32 s34, v5
	v_add_u32_e32 v5, 0x3000, v94
	s_mov_b32 m0, s34
	s_mov_b64 s[40:41], 0xc000
	v_readfirstlane_b32 s21, v5
	v_add_u32_e32 v5, 0x7000, v94
	global_load_lds_dwordx4 v[2:3], off
	v_lshl_add_u64 v[2:3], v[68:69], 0, s[40:41]
	s_mov_b32 m0, s21
	v_readfirstlane_b32 s35, v5
	v_lshrrev_b32_e32 v7, 5, v71
	global_load_lds_dwordx4 v[2:3], off
	v_lshl_add_u64 v[2:3], v[66:67], 0, s[40:41]
	s_mov_b32 m0, s35
	v_bfe_u32 v95, v71, 1, 3
	global_load_lds_dwordx4 v[2:3], off
	v_bitop3_b32 v2, v7, v95, 1 bitop3:0x6c
	v_lshlrev_b32_e32 v6, 4, v2
	v_add_u32_e32 v96, v73, v4
	v_add_u32_e32 v97, v96, v6
	s_waitcnt vmcnt(0)
	s_waitcnt vmcnt(0) lgkmcnt(0)
	s_barrier
	ds_read_b128 v[2:5], v97 offset:16384
	v_and_b32_e32 v72, 31, v71
	v_lshrrev_b32_e32 v0, 1, v71
	v_and_or_b32 v0, v0, 64, v72
	v_lshl_add_u32 v98, v0, 7, v73
	v_add_u32_e32 v99, v98, v6
	ds_read_b128 v[6:9], v99
	ds_read_b128 v[10:13], v99 offset:4096
	ds_read_b128 v[14:17], v97 offset:20480
	v_bfe_u32 v100, v71, 5, 1
	s_waitcnt lgkmcnt(2)
	v_mfma_f32_32x32x16_bf16 v[50:65], v[2:5], v[6:9], 0
	v_add_u32_e32 v103, 0x8000, v94
	v_add_u32_e32 v104, 0xc000, v94
	v_readfirstlane_b32 s37, v103
	v_lshl_add_u64 v[90:91], v[68:69], 0, s[28:29]
	s_mov_b32 m0, s37
	s_mov_b64 s[50:51], 0x4080
	v_readfirstlane_b32 s41, v104
	s_waitcnt lgkmcnt(1)
	v_mfma_f32_32x32x16_bf16 v[18:33], v[2:5], v[10:13], 0
	v_bitop3_b32 v2, v100, v95, 2 bitop3:0x36
	v_lshlrev_b32_e32 v78, 4, v2
	v_add_u32_e32 v101, v96, v78
	ds_read_b128 v[74:77], v101 offset:16384
	v_add_u32_e32 v102, v98, v78
	ds_read_b128 v[78:81], v102
	ds_read_b128 v[82:85], v102 offset:4096
	ds_read_b128 v[86:89], v101 offset:20480
	v_lshl_add_u64 v[92:93], v[66:67], 0, s[28:29]
	s_waitcnt lgkmcnt(4)
	v_mfma_f32_32x32x16_bf16 v[34:49], v[14:17], v[6:9], 0
	s_mov_b64 s[52:53], 0x8080
	s_mov_b64 s[56:57], 0xc080
	v_mul_u32_u24_e32 v0, 0x210, v0
	v_mfma_f32_32x32x16_bf16 v[2:17], v[14:17], v[10:13], 0
	s_waitcnt lgkmcnt(2)
	v_mfma_f32_32x32x16_bf16 v[50:65], v[74:77], v[78:81], v[50:65]
	s_waitcnt lgkmcnt(1)
	v_mfma_f32_32x32x16_bf16 v[18:33], v[74:77], v[82:85], v[18:33]
	v_bitop3_b32 v74, v100, v95, 4 bitop3:0x36
	s_waitcnt lgkmcnt(0)
	v_mfma_f32_32x32x16_bf16 v[34:49], v[86:89], v[78:81], v[34:49]
	v_lshlrev_b32_e32 v78, 4, v74
	v_add_u32_e32 v105, v96, v78
	ds_read_b128 v[74:77], v105 offset:16384
	v_add_u32_e32 v106, v98, v78
	ds_read_b128 v[78:81], v106
	v_mfma_f32_32x32x16_bf16 v[2:17], v[86:89], v[82:85], v[2:17]
	ds_read_b128 v[82:85], v106 offset:4096
	ds_read_b128 v[86:89], v105 offset:20480
	global_load_lds_dwordx4 v[90:91], off
	v_lshl_add_u64 v[90:91], v[66:67], 0, s[50:51]
	s_mov_b32 m0, s41
	s_nop 0
	global_load_lds_dwordx4 v[92:93], off
	s_waitcnt lgkmcnt(0)
	v_mfma_f32_32x32x16_bf16 v[50:65], v[74:77], v[78:81], v[50:65]
	v_mfma_f32_32x32x16_bf16 v[18:33], v[74:77], v[82:85], v[18:33]
	v_add_u32_e32 v74, 0xd000, v94
	v_mfma_f32_32x32x16_bf16 v[34:49], v[86:89], v[78:81], v[34:49]
	v_lshl_add_u64 v[78:79], v[68:69], 0, s[50:51]
	v_readfirstlane_b32 s50, v74
	v_bitop3_b32 v74, v100, v95, 6 bitop3:0x36
	v_lshlrev_b32_e32 v74, 4, v74
	v_add_u32_e32 v80, 0x9000, v94
	v_add_u32_e32 v93, v96, v74
	v_readfirstlane_b32 s40, v80
	v_add_u32_e32 v92, v98, v74
	ds_read_b128 v[74:77], v93 offset:16384
	s_mov_b32 m0, s40
	v_mfma_f32_32x32x16_bf16 v[2:17], v[86:89], v[82:85], v[2:17]
	global_load_lds_dwordx4 v[78:79], off
	s_mov_b32 m0, s50
	ds_read_b128 v[78:81], v92
	global_load_lds_dwordx4 v[90:91], off
	ds_read_b128 v[82:85], v92 offset:4096
	ds_read_b128 v[86:89], v93 offset:20480
	v_add_u32_e32 v95, 0xa000, v94
	v_lshl_add_u64 v[90:91], v[68:69], 0, s[52:53]
	v_readfirstlane_b32 s51, v95
	s_mov_b32 m0, s51
	v_add_u32_e32 v95, 0xe000, v94
	s_waitcnt lgkmcnt(0)
	v_mfma_f32_32x32x16_bf16 v[50:65], v[74:77], v[78:81], v[50:65]
	global_load_lds_dwordx4 v[90:91], off
	v_lshl_add_u64 v[90:91], v[66:67], 0, s[52:53]
	v_readfirstlane_b32 s53, v95
	s_mov_b32 m0, s53
	s_nop 0
	global_load_lds_dwordx4 v[90:91], off
	v_mfma_f32_32x32x16_bf16 v[34:49], v[86:89], v[78:81], v[34:49]
	v_add_u32_e32 v80, 0xb000, v94
	v_lshl_add_u64 v[78:79], v[68:69], 0, s[56:57]
	v_readfirstlane_b32 s52, v80
	s_mov_b32 m0, s52
	v_lshl_add_u64 v[90:91], v[66:67], 0, s[22:23]
	global_load_lds_dwordx4 v[78:79], off
	v_mfma_f32_32x32x16_bf16 v[18:33], v[74:77], v[82:85], v[18:33]
	v_add_u32_e32 v76, 0xf000, v94
	v_lshl_add_u64 v[74:75], v[66:67], 0, s[56:57]
	v_readfirstlane_b32 s54, v76
	s_mov_b32 m0, s54
	s_mov_b64 s[56:57], 0x4100
	global_load_lds_dwordx4 v[74:75], off
	v_mfma_f32_32x32x16_bf16 v[2:17], v[86:89], v[82:85], v[2:17]
	s_waitcnt vmcnt(0)
	s_waitcnt vmcnt(0) lgkmcnt(0)
	s_barrier
; #define G_WAIT() { asm volatile("s_waitcnt vmcnt(0)" ::: "memory"); __syncthreads(); }
;     ...
;   G_DMA(0, 0);
;   G_WAIT();
;   for (int kt = 0; kt < nk; kt += 2) {
;     if (kt + 1 < nk) G_DMA(1, kt + 1);
;     G_COMPUTE(0);
;     G_WAIT();
;     if (kt + 1 < nk) {
;       if (kt + 2 < nk) G_DMA(0, kt + 2);
;       G_COMPUTE(1);
;       G_WAIT();
;     }
;   }
	ds_read_b128 v[74:77], v97 offset:49152
	ds_read_b128 v[78:81], v99 offset:32768
	ds_read_b128 v[82:85], v99 offset:36864
	ds_read_b128 v[86:89], v97 offset:53248
	s_mov_b32 m0, s36
	s_waitcnt lgkmcnt(2)
	v_mfma_f32_32x32x16_bf16 v[50:65], v[74:77], v[78:81], v[50:65]
	s_waitcnt lgkmcnt(1)
	v_mfma_f32_32x32x16_bf16 v[18:33], v[74:77], v[82:85], v[18:33]
	s_waitcnt lgkmcnt(0)
	v_mfma_f32_32x32x16_bf16 v[34:49], v[86:89], v[78:81], v[34:49]
	v_mfma_f32_32x32x16_bf16 v[2:17], v[86:89], v[82:85], v[2:17]
	ds_read_b128 v[74:77], v101 offset:49152
	ds_read_b128 v[78:81], v102 offset:32768
	ds_read_b128 v[82:85], v102 offset:36864
	ds_read_b128 v[86:89], v101 offset:53248
	s_waitcnt lgkmcnt(2)
	v_mfma_f32_32x32x16_bf16 v[50:65], v[74:77], v[78:81], v[50:65]
	s_waitcnt lgkmcnt(1)
	v_mfma_f32_32x32x16_bf16 v[18:33], v[74:77], v[82:85], v[18:33]
	s_waitcnt lgkmcnt(0)
	v_mfma_f32_32x32x16_bf16 v[34:49], v[86:89], v[78:81], v[34:49]
	v_mfma_f32_32x32x16_bf16 v[2:17], v[86:89], v[82:85], v[2:17]
	ds_read_b128 v[74:77], v105 offset:49152
	ds_read_b128 v[78:81], v106 offset:32768
	ds_read_b128 v[82:85], v106 offset:36864
	ds_read_b128 v[86:89], v105 offset:53248
	s_waitcnt lgkmcnt(2)
	v_mfma_f32_32x32x16_bf16 v[50:65], v[74:77], v[78:81], v[50:65]
	s_waitcnt lgkmcnt(1)
	v_mfma_f32_32x32x16_bf16 v[18:33], v[74:77], v[82:85], v[18:33]
	v_lshl_add_u64 v[74:75], v[68:69], 0, s[22:23]
	global_load_lds_dwordx4 v[74:75], off
	ds_read_b128 v[74:77], v93 offset:49152
	s_mov_b32 m0, s20
	s_nop 0
	global_load_lds_dwordx4 v[90:91], off
	s_waitcnt lgkmcnt(0)
	v_mfma_f32_32x32x16_bf16 v[34:49], v[86:89], v[78:81], v[34:49]
	ds_read_b128 v[78:81], v92 offset:32768
	v_lshl_add_u64 v[90:91], v[68:69], 0, s[56:57]
	s_mov_b32 m0, s4
	s_lshl_b32 s4, s5, 1
	v_mfma_f32_32x32x16_bf16 v[2:17], v[86:89], v[82:85], v[2:17]
	ds_read_b128 v[82:85], v92 offset:36864
	ds_read_b128 v[86:89], v93 offset:53248
	global_load_lds_dwordx4 v[90:91], off
	v_lshl_add_u64 v[90:91], v[66:67], 0, s[56:57]
	s_mov_b32 m0, s19
	s_mov_b64 s[56:57], 0x8100
	global_load_lds_dwordx4 v[90:91], off
	v_lshl_add_u64 v[90:91], v[68:69], 0, s[56:57]
	s_mov_b32 m0, s18
	s_waitcnt lgkmcnt(0)
	v_mfma_f32_32x32x16_bf16 v[50:65], v[74:77], v[78:81], v[50:65]
	global_load_lds_dwordx4 v[90:91], off
	s_mov_b32 m0, s34
	s_mov_b64 s[18:19], 0xc100
	v_mfma_f32_32x32x16_bf16 v[34:49], v[86:89], v[78:81], v[34:49]
	v_lshl_add_u64 v[78:79], v[66:67], 0, s[56:57]
	global_load_lds_dwordx4 v[78:79], off
	v_lshl_add_u64 v[78:79], v[68:69], 0, s[18:19]
	s_mov_b32 m0, s21
	s_nop 0
	global_load_lds_dwordx4 v[78:79], off
	v_mfma_f32_32x32x16_bf16 v[18:33], v[74:77], v[82:85], v[18:33]
	v_lshl_add_u64 v[74:75], v[66:67], 0, s[18:19]
	s_mov_b32 m0, s35
	s_mov_b64 s[18:19], 0x180
	global_load_lds_dwordx4 v[74:75], off
	s_waitcnt vmcnt(0)
	s_waitcnt vmcnt(0) lgkmcnt(0)
	v_mfma_f32_32x32x16_bf16 v[2:17], v[86:89], v[82:85], v[2:17]
	s_barrier
	ds_read_b128 v[74:77], v97 offset:16384
	ds_read_b128 v[78:81], v99
	ds_read_b128 v[82:85], v99 offset:4096
	ds_read_b128 v[86:89], v97 offset:20480
	s_mov_b32 m0, s37
	v_lshl_add_u64 v[90:91], v[66:67], 0, s[18:19]
	s_waitcnt lgkmcnt(2)
	v_mfma_f32_32x32x16_bf16 v[50:65], v[74:77], v[78:81], v[50:65]
	s_waitcnt lgkmcnt(1)
	v_mfma_f32_32x32x16_bf16 v[18:33], v[74:77], v[82:85], v[18:33]
	s_waitcnt lgkmcnt(0)
	v_mfma_f32_32x32x16_bf16 v[34:49], v[86:89], v[78:81], v[34:49]
	v_mfma_f32_32x32x16_bf16 v[2:17], v[86:89], v[82:85], v[2:17]
	ds_read_b128 v[74:77], v101 offset:16384
	ds_read_b128 v[78:81], v102
	ds_read_b128 v[82:85], v102 offset:4096
	ds_read_b128 v[86:89], v101 offset:20480
	s_waitcnt lgkmcnt(2)
	v_mfma_f32_32x32x16_bf16 v[50:65], v[74:77], v[78:81], v[50:65]
	s_waitcnt lgkmcnt(1)
	v_mfma_f32_32x32x16_bf16 v[18:33], v[74:77], v[82:85], v[18:33]
	s_waitcnt lgkmcnt(0)
	v_mfma_f32_32x32x16_bf16 v[34:49], v[86:89], v[78:81], v[34:49]
	v_mfma_f32_32x32x16_bf16 v[2:17], v[86:89], v[82:85], v[2:17]
	ds_read_b128 v[74:77], v105 offset:16384
	ds_read_b128 v[78:81], v106
	ds_read_b128 v[82:85], v106 offset:4096
	ds_read_b128 v[86:89], v105 offset:20480
	s_waitcnt lgkmcnt(2)
	v_mfma_f32_32x32x16_bf16 v[50:65], v[74:77], v[78:81], v[50:65]
	s_waitcnt lgkmcnt(1)
	v_mfma_f32_32x32x16_bf16 v[18:33], v[74:77], v[82:85], v[18:33]
	v_lshl_add_u64 v[74:75], v[68:69], 0, s[18:19]
	global_load_lds_dwordx4 v[74:75], off
	ds_read_b128 v[74:77], v93 offset:16384
	s_mov_b32 m0, s41
	s_mov_b64 s[18:19], 0x4180
	global_load_lds_dwordx4 v[90:91], off
	s_waitcnt lgkmcnt(0)
	v_mfma_f32_32x32x16_bf16 v[34:49], v[86:89], v[78:81], v[34:49]
	ds_read_b128 v[78:81], v92
	v_lshl_add_u64 v[90:91], v[68:69], 0, s[18:19]
	s_mov_b32 m0, s40
	v_mfma_f32_32x32x16_bf16 v[2:17], v[86:89], v[82:85], v[2:17]
	ds_read_b128 v[82:85], v92 offset:4096
	ds_read_b128 v[86:89], v93 offset:20480
	global_load_lds_dwordx4 v[90:91], off
	v_lshl_add_u64 v[90:91], v[66:67], 0, s[18:19]
	s_mov_b32 m0, s50
	s_mov_b64 s[18:19], 0x8180
	global_load_lds_dwordx4 v[90:91], off
	v_lshl_add_u64 v[90:91], v[68:69], 0, s[18:19]
	s_mov_b32 m0, s51
	s_waitcnt lgkmcnt(0)
	v_mfma_f32_32x32x16_bf16 v[50:65], v[74:77], v[78:81], v[50:65]
	global_load_lds_dwordx4 v[90:91], off
	s_mov_b32 m0, s53
	v_mfma_f32_32x32x16_bf16 v[34:49], v[86:89], v[78:81], v[34:49]
	v_lshl_add_u64 v[78:79], v[66:67], 0, s[18:19]
	s_mov_b64 s[18:19], 0xc180
	global_load_lds_dwordx4 v[78:79], off
	v_lshl_add_u64 v[68:69], v[68:69], 0, s[18:19]
	s_mov_b32 m0, s52
	v_lshl_add_u64 v[66:67], v[66:67], 0, s[18:19]
	global_load_lds_dwordx4 v[68:69], off
	s_mov_b32 m0, s54
	v_mfma_f32_32x32x16_bf16 v[2:17], v[86:89], v[82:85], v[2:17]
	global_load_lds_dwordx4 v[66:67], off
	s_waitcnt vmcnt(0)
	s_waitcnt vmcnt(0) lgkmcnt(0)
	s_barrier
; DI float silu(float x) { return x / (1.f + __expf(-x)); }
; DI f32x4 unpack4(u32x2 v) { f32x4 r = {bflo(v.x), bfhi(v.x), bflo(v.y), bfhi(v.y)}; return r; }
; DI u32x2 pack4(f32x4 v) { u32x2 r = {cvtpk(v[0], v[1]), cvtpk(v[2], v[3])}; return r; }
;     ...
;   float* ct = (float*)lds;
; #pragma unroll
;   for (int i = 0; i < 2; ++i)
; #pragma unroll
;     for (int j = 0; j < 2; ++j)
; #pragma unroll
;       for (int q = 0; q < 4; ++q) {
;         f32x4 v = {acc[i][j][4 * q], acc[i][j][4 * q + 1], acc[i][j][4 * q + 2], acc[i][j][4 * q + 3]};
;         *(f32x4*)(ct + (wr * 64 + i * 32 + l31) * 132 + wc * 64 + j * 32 + 8 * q + 4 * h) = v;
;       }
;   __syncthreads();
; #pragma unroll 4
;   for (int it = 0; it < 16; ++it) {
;     const int idx = it * 256 + tid; const int row = idx >> 5, c4 = (idx & 31) * 4;
;     f32x4 v = *(const f32x4*)(ct + row * 132 + c4);
;     epi(row, c4, v);
;   }
; DI void phase_mix(KP p, int l, char* lds) {
;     ...
;       gemm_tile(YD + (size_t)m0 * 256, 256, wf + (size_t)n0 * 256, 256, 256, lds, [&](int m, int n, f32x4 v) {
;         const size_t r = (size_t)m0 + m;
;         f32x4 gd = unpack4(*(const u32x2*)(P + r * NIN + O_GD + n0 + n));
;         f32x4 o = {v[0] * silu(gd[0]), v[1] * silu(gd[1]), v[2] * silu(gd[2]), v[3] * silu(gd[3])};
;         *(u32x2*)(Y + r * 1024 + 768 + n0 + n) = pack4(o); });
	v_and_b32_e32 v86, 64, v71
	v_mfma_f32_32x32x16_bf16 v[18:33], v[74:77], v[82:85], v[18:33]
	ds_read_b128 v[66:69], v97 offset:49152
	ds_read_b128 v[74:77], v99 offset:32768
	ds_read_b128 v[78:81], v99 offset:36864
	ds_read_b128 v[82:85], v97 offset:53248
	v_lshl_add_u32 v73, v86, 2, v73
	v_lshlrev_b32_e32 v86, 4, v100
	v_add3_u32 v0, v73, v86, v0
	v_readlane_b32 s18, v255, 31
	s_add_u32 s18, s18, s4
	v_readlane_b32 s4, v255, 32
	s_waitcnt lgkmcnt(2)
	v_mfma_f32_32x32x16_bf16 v[50:65], v[66:69], v[74:77], v[50:65]
	s_addc_u32 s19, s4, 0
	s_mov_b32 s4, 0
	s_waitcnt lgkmcnt(0)
	v_mfma_f32_32x32x16_bf16 v[34:49], v[82:85], v[74:77], v[34:49]
	v_mfma_f32_32x32x16_bf16 v[2:17], v[82:85], v[78:81], v[2:17]
	v_mfma_f32_32x32x16_bf16 v[18:33], v[66:69], v[78:81], v[18:33]
	ds_read_b128 v[66:69], v101 offset:49152
	ds_read_b128 v[74:77], v102 offset:32768
	ds_read_b128 v[78:81], v102 offset:36864
	ds_read_b128 v[82:85], v101 offset:53248
	s_waitcnt lgkmcnt(2)
	v_mfma_f32_32x32x16_bf16 v[50:65], v[66:69], v[74:77], v[50:65]
	s_waitcnt lgkmcnt(0)
	v_mfma_f32_32x32x16_bf16 v[34:49], v[82:85], v[74:77], v[34:49]
	v_mfma_f32_32x32x16_bf16 v[2:17], v[82:85], v[78:81], v[2:17]
	v_mfma_f32_32x32x16_bf16 v[18:33], v[66:69], v[78:81], v[18:33]
	ds_read_b128 v[66:69], v105 offset:49152
	ds_read_b128 v[74:77], v106 offset:32768
	ds_read_b128 v[78:81], v106 offset:36864
	ds_read_b128 v[82:85], v105 offset:53248
	s_waitcnt lgkmcnt(2)
	v_mfma_f32_32x32x16_bf16 v[50:65], v[66:69], v[74:77], v[50:65]
	s_waitcnt lgkmcnt(0)
	v_mfma_f32_32x32x16_bf16 v[34:49], v[82:85], v[74:77], v[34:49]
	v_mfma_f32_32x32x16_bf16 v[2:17], v[82:85], v[78:81], v[2:17]
	v_mfma_f32_32x32x16_bf16 v[18:33], v[66:69], v[78:81], v[18:33]
	ds_read_b128 v[66:69], v93 offset:49152
	ds_read_b128 v[74:77], v92 offset:32768
	ds_read_b128 v[78:81], v92 offset:36864
	ds_read_b128 v[82:85], v93 offset:53248
	s_waitcnt vmcnt(0)
	s_waitcnt lgkmcnt(0)
	s_barrier
	v_mfma_f32_32x32x16_bf16 v[50:65], v[66:69], v[74:77], v[50:65]
	v_mfma_f32_32x32x16_bf16 v[34:49], v[82:85], v[74:77], v[34:49]
	s_nop 10
	ds_write_b128 v0, v[50:53]
	ds_write_b128 v0, v[54:57] offset:32
	ds_write_b128 v0, v[58:61] offset:64
	ds_write_b128 v0, v[62:65] offset:96
	ds_write_b128 v0, v[34:37] offset:128
	v_mfma_f32_32x32x16_bf16 v[2:17], v[82:85], v[78:81], v[2:17]
	v_mfma_f32_32x32x16_bf16 v[18:33], v[66:69], v[78:81], v[18:33]
	ds_write_b128 v0, v[38:41] offset:160
	ds_write_b128 v0, v[42:45] offset:192
	ds_write_b128 v0, v[46:49] offset:224
	s_nop 8
	ds_write_b128 v0, v[18:21] offset:16896
	ds_write_b128 v0, v[22:25] offset:16928
	ds_write_b128 v0, v[26:29] offset:16960
	ds_write_b128 v0, v[30:33] offset:16992
	ds_write_b128 v0, v[2:5] offset:17024
	ds_write_b128 v0, v[6:9] offset:17056
	ds_write_b128 v0, v[10:13] offset:17088
	ds_write_b128 v0, v[14:17] offset:17120
	v_lshlrev_b32_e32 v0, 2, v71
	v_and_b32_e32 v2, 0x7c, v0
	v_lshlrev_b32_e32 v0, 1, v2
	v_lshl_add_u64 v[6:7], s[18:19], 0, v[0:1]
	v_bfe_u32 v0, v71, 5, 3
	v_or_b32_e32 v14, s2, v0
	v_mul_u32_u24_e32 v0, 0x210, v0
	v_mad_i32_i24 v0, v70, s55, v0
	v_lshlrev_b32_e32 v3, 4, v72
	v_add3_u32 v15, v0, v3, 0
	s_lshl_b32 s2, s5, 1
	v_lshlrev_b32_e32 v8, 1, v2
	s_waitcnt lgkmcnt(0)
	s_barrier
	s_add_u32 s48, s42, s2
	s_addc_u32 s49, s43, 0
	s_add_u32 s48, s48, 0x1000
	s_addc_u32 s49, s49, 0
	v_add_u32_e32 v120, s4, v14
	v_mad_u32_u24 v121, v120, s11, v8
	global_load_dwordx2 v[112:113], v121, s[48:49] offset:704
	v_add_u32_e32 v121, 8, v120
	v_mad_u32_u24 v121, v121, s11, v8
	global_load_dwordx2 v[114:115], v121, s[48:49] offset:704
	v_add_u32_e32 v121, 16, v120
	v_mad_u32_u24 v121, v121, s11, v8
	global_load_dwordx2 v[116:117], v121, s[48:49] offset:704
	v_add_u32_e32 v121, 24, v120
	v_mad_u32_u24 v121, v121, s11, v8
	global_load_dwordx2 v[118:119], v121, s[48:49] offset:704
.LBB0_152:
	v_add_u32_e32 v0, s4, v14
	v_mov_b64_e32 v[10:11], s[42:43]
	v_mad_u64_u32 v[12:13], s[18:19], v0, s11, v[10:11]
	v_lshl_add_u64 v[12:13], v[12:13], 0, s[2:3]
	v_mov_b32_e32 v9, v1
	v_lshl_add_u64 v[12:13], v[12:13], 0, v[8:9]
	v_add_co_u32_e32 v12, vcc, 0x1000, v12
	ds_read_b128 v[2:5], v15
	s_nop 0
	v_addc_co_u32_e32 v13, vcc, 0, v13, vcc
	s_add_i32 s4, s4, 32
	s_cmpk_lg_i32 s4, 0x80
	s_waitcnt vmcnt(3) lgkmcnt(0)
	v_mov_b32_e32 v12, v112
	v_mov_b32_e32 v13, v113
	v_lshlrev_b32_e32 v18, 16, v12
	v_and_b32_e32 v12, 0xffff0000, v12
	v_mul_f32_e32 v16, 0xbfb8aa3b, v18
	v_mul_f32_e32 v17, 0xbfb8aa3b, v12
	v_exp_f32_e32 v16, v16
	v_exp_f32_e32 v17, v17
	s_nop 0
	v_pk_add_f32 v[16:17], v[16:17], 1.0 op_sel_hi:[1,0]
	s_nop 0
	v_div_scale_f32 v19, s[18:19], v17, v17, v12
	v_rcp_f32_e32 v20, v19
	s_nop 0
	v_fma_f32 v21, -v19, v20, 1.0
	v_fmac_f32_e32 v20, v21, v20
	v_div_scale_f32 v21, vcc, v12, v17, v12
	v_mul_f32_e32 v22, v21, v20
	v_fma_f32 v23, -v19, v22, v21
	v_fmac_f32_e32 v22, v23, v20
	v_fma_f32 v19, -v19, v22, v21
	v_div_fmas_f32 v19, v19, v20, v22
	v_div_fixup_f32 v17, v19, v17, v12
	v_div_scale_f32 v12, s[18:19], v16, v16, v18
	v_rcp_f32_e32 v19, v12
	s_nop 0
	v_fma_f32 v20, -v12, v19, 1.0
	v_fmac_f32_e32 v19, v20, v19
	v_div_scale_f32 v20, vcc, v18, v16, v18
	v_mul_f32_e32 v21, v20, v19
	v_fma_f32 v22, -v12, v21, v20
	v_fmac_f32_e32 v21, v22, v19
	v_fma_f32 v12, -v12, v21, v20
	v_div_fmas_f32 v12, v12, v19, v21
	v_div_fixup_f32 v16, v12, v16, v18
	v_pk_mul_f32 v[2:3], v[2:3], v[16:17]
	v_lshlrev_b32_e32 v16, 16, v13
	v_and_b32_e32 v17, 0xffff0000, v13
	v_mul_f32_e32 v12, 0xbfb8aa3b, v16
	v_mul_f32_e32 v13, 0xbfb8aa3b, v17
	v_exp_f32_e32 v12, v12
	v_exp_f32_e32 v13, v13
	v_cvt_pk_bf16_f32 v2, v2, v3
	v_pk_add_f32 v[12:13], v[12:13], 1.0 op_sel_hi:[1,0]
	s_nop 0
	v_div_scale_f32 v18, s[18:19], v13, v13, v17
	v_rcp_f32_e32 v19, v18
	s_nop 0
	v_fma_f32 v20, -v18, v19, 1.0
	v_fmac_f32_e32 v19, v20, v19
	v_div_scale_f32 v20, vcc, v17, v13, v17
	v_mul_f32_e32 v21, v20, v19
	v_fma_f32 v22, -v18, v21, v20
	v_fmac_f32_e32 v21, v22, v19
	v_fma_f32 v18, -v18, v21, v20
	v_div_fmas_f32 v18, v18, v19, v21
	v_div_fixup_f32 v13, v18, v13, v17
	v_div_scale_f32 v17, s[18:19], v12, v12, v16
	v_rcp_f32_e32 v18, v17
	s_nop 0
	v_fma_f32 v19, -v17, v18, 1.0
	v_fmac_f32_e32 v18, v19, v18
	v_div_scale_f32 v19, vcc, v16, v12, v16
	v_mul_f32_e32 v20, v19, v18
	v_fma_f32 v21, -v17, v20, v19
	v_fmac_f32_e32 v20, v21, v18
	v_fma_f32 v17, -v17, v20, v19
	v_div_fmas_f32 v17, v17, v18, v20
	v_div_fixup_f32 v12, v17, v12, v16
	v_pk_mul_f32 v[4:5], v[4:5], v[12:13]
	v_add_u32_e32 v12, 8, v0
	v_mad_u64_u32 v[16:17], s[18:19], v12, s11, v[10:11]
	v_lshl_add_u64 v[16:17], v[16:17], 0, s[2:3]
	v_cvt_pk_bf16_f32 v3, v4, v5
	v_lshlrev_b64 v[4:5], 11, v[0:1]
	v_lshl_add_u64 v[16:17], v[16:17], 0, v[8:9]
	v_lshl_add_u64 v[4:5], v[6:7], 0, v[4:5]
	v_add_co_u32_e32 v16, vcc, s6, v16
	global_store_dwordx2 v[4:5], v[2:3], off offset:1536
	s_nop 0
	v_addc_co_u32_e32 v17, vcc, 0, v17, vcc
	ds_read_b128 v[2:5], v15 offset:4224
	v_mov_b32_e32 v13, v1
	s_waitcnt vmcnt(3) lgkmcnt(0)
; DI float silu(float x) { return x / (1.f + __expf(-x)); }
; DI f32x4 unpack4(u32x2 v) { f32x4 r = {bflo(v.x), bfhi(v.x), bflo(v.y), bfhi(v.y)}; return r; }
; DI u32x2 pack4(f32x4 v) { u32x2 r = {cvtpk(v[0], v[1]), cvtpk(v[2], v[3])}; return r; }
;     ...
; #pragma unroll 4
;   for (int it = 0; it < 16; ++it) {
;     const int idx = it * 256 + tid; const int row = idx >> 5, c4 = (idx & 31) * 4;
;     f32x4 v = *(const f32x4*)(ct + row * 132 + c4);
;     epi(row, c4, v);
;   }
; DI void phase_mix(KP p, int l, char* lds) {
;     ...
;       gemm_tile(YD + (size_t)m0 * 256, 256, wf + (size_t)n0 * 256, 256, 256, lds, [&](int m, int n, f32x4 v) {
;         const size_t r = (size_t)m0 + m;
;         f32x4 gd = unpack4(*(const u32x2*)(P + r * NIN + O_GD + n0 + n));
;         f32x4 o = {v[0] * silu(gd[0]), v[1] * silu(gd[1]), v[2] * silu(gd[2]), v[3] * silu(gd[3])};
;         *(u32x2*)(Y + r * 1024 + 768 + n0 + n) = pack4(o); });
	v_mov_b32_e32 v16, v114
	v_mov_b32_e32 v17, v115
	v_lshlrev_b32_e32 v20, 16, v16
	v_and_b32_e32 v16, 0xffff0000, v16
	v_mul_f32_e32 v18, 0xbfb8aa3b, v20
	v_mul_f32_e32 v19, 0xbfb8aa3b, v16
	v_exp_f32_e32 v18, v18
	v_exp_f32_e32 v19, v19
	s_nop 0
	v_pk_add_f32 v[18:19], v[18:19], 1.0 op_sel_hi:[1,0]
	s_nop 0
	v_div_scale_f32 v21, s[18:19], v19, v19, v16
	v_rcp_f32_e32 v22, v21
	s_nop 0
	v_fma_f32 v23, -v21, v22, 1.0
	v_fmac_f32_e32 v22, v23, v22
	v_div_scale_f32 v23, vcc, v16, v19, v16
	v_mul_f32_e32 v24, v23, v22
	v_fma_f32 v25, -v21, v24, v23
	v_fmac_f32_e32 v24, v25, v22
	v_fma_f32 v21, -v21, v24, v23
	v_div_fmas_f32 v21, v21, v22, v24
	v_div_fixup_f32 v19, v21, v19, v16
	v_div_scale_f32 v16, s[18:19], v18, v18, v20
	v_rcp_f32_e32 v21, v16
	s_nop 0
	v_fma_f32 v22, -v16, v21, 1.0
	v_fmac_f32_e32 v21, v22, v21
	v_div_scale_f32 v22, vcc, v20, v18, v20
	v_mul_f32_e32 v23, v22, v21
	v_fma_f32 v24, -v16, v23, v22
	v_fmac_f32_e32 v23, v24, v21
	v_fma_f32 v16, -v16, v23, v22
	v_div_fmas_f32 v16, v16, v21, v23
	v_div_fixup_f32 v18, v16, v18, v20
	v_pk_mul_f32 v[2:3], v[2:3], v[18:19]
	v_lshlrev_b32_e32 v18, 16, v17
	v_and_b32_e32 v19, 0xffff0000, v17
	v_mul_f32_e32 v16, 0xbfb8aa3b, v18
	v_mul_f32_e32 v17, 0xbfb8aa3b, v19
	v_exp_f32_e32 v16, v16
	v_exp_f32_e32 v17, v17
	v_cvt_pk_bf16_f32 v2, v2, v3
	v_pk_add_f32 v[16:17], v[16:17], 1.0 op_sel_hi:[1,0]
	s_nop 0
	v_div_scale_f32 v20, s[18:19], v17, v17, v19
	v_rcp_f32_e32 v21, v20
	s_nop 0
	v_fma_f32 v22, -v20, v21, 1.0
	v_fmac_f32_e32 v21, v22, v21
	v_div_scale_f32 v22, vcc, v19, v17, v19
	v_mul_f32_e32 v23, v22, v21
	v_fma_f32 v24, -v20, v23, v22
	v_fmac_f32_e32 v23, v24, v21
	v_fma_f32 v20, -v20, v23, v22
	v_div_fmas_f32 v20, v20, v21, v23
	v_div_fixup_f32 v17, v20, v17, v19
	v_div_scale_f32 v19, s[18:19], v16, v16, v18
	v_rcp_f32_e32 v20, v19
	s_nop 0
	v_fma_f32 v21, -v19, v20, 1.0
	v_fmac_f32_e32 v20, v21, v20
	v_div_scale_f32 v21, vcc, v18, v16, v18
	v_mul_f32_e32 v22, v21, v20
	v_fma_f32 v23, -v19, v22, v21
	v_fmac_f32_e32 v22, v23, v20
	v_fma_f32 v19, -v19, v22, v21
	v_div_fmas_f32 v19, v19, v20, v22
	v_div_fixup_f32 v16, v19, v16, v18
	v_pk_mul_f32 v[4:5], v[4:5], v[16:17]
	s_nop 0
	v_cvt_pk_bf16_f32 v3, v4, v5
	v_lshlrev_b64 v[4:5], 11, v[12:13]
	v_add_u32_e32 v12, 16, v0
	v_mad_u64_u32 v[16:17], s[18:19], v12, s11, v[10:11]
	v_lshl_add_u64 v[16:17], v[16:17], 0, s[2:3]
	v_lshl_add_u64 v[16:17], v[16:17], 0, v[8:9]
	v_lshl_add_u64 v[4:5], v[6:7], 0, v[4:5]
	v_add_co_u32_e32 v16, vcc, s6, v16
	global_store_dwordx2 v[4:5], v[2:3], off offset:1536
	s_nop 0
	v_addc_co_u32_e32 v17, vcc, 0, v17, vcc
	ds_read_b128 v[2:5], v15 offset:8448
	v_add_u32_e32 v0, 24, v0
	v_mad_u64_u32 v[10:11], s[18:19], v0, s11, v[10:11]
	v_lshl_add_u64 v[10:11], v[10:11], 0, s[2:3]
	v_lshl_add_u64 v[10:11], v[10:11], 0, v[8:9]
	s_waitcnt vmcnt(3) lgkmcnt(0)
	v_mov_b32_e32 v16, v116
	v_mov_b32_e32 v17, v117
	v_lshlrev_b32_e32 v20, 16, v16
	v_and_b32_e32 v16, 0xffff0000, v16
	v_mul_f32_e32 v18, 0xbfb8aa3b, v20
	v_mul_f32_e32 v19, 0xbfb8aa3b, v16
	v_exp_f32_e32 v18, v18
	v_exp_f32_e32 v19, v19
	s_nop 0
	v_pk_add_f32 v[18:19], v[18:19], 1.0 op_sel_hi:[1,0]
	s_nop 0
	v_div_scale_f32 v21, s[18:19], v19, v19, v16
	v_rcp_f32_e32 v22, v21
	s_nop 0
	v_fma_f32 v23, -v21, v22, 1.0
	v_fmac_f32_e32 v22, v23, v22
	v_div_scale_f32 v23, vcc, v16, v19, v16
	v_mul_f32_e32 v24, v23, v22
	v_fma_f32 v25, -v21, v24, v23
	v_fmac_f32_e32 v24, v25, v22
	v_fma_f32 v21, -v21, v24, v23
	v_div_fmas_f32 v21, v21, v22, v24
	v_div_fixup_f32 v19, v21, v19, v16
	v_div_scale_f32 v16, s[18:19], v18, v18, v20
	v_rcp_f32_e32 v21, v16
	s_nop 0
	v_fma_f32 v22, -v16, v21, 1.0
	v_fmac_f32_e32 v21, v22, v21
	v_div_scale_f32 v22, vcc, v20, v18, v20
	v_mul_f32_e32 v23, v22, v21
	v_fma_f32 v24, -v16, v23, v22
	v_fmac_f32_e32 v23, v24, v21
	v_fma_f32 v16, -v16, v23, v22
	v_div_fmas_f32 v16, v16, v21, v23
	v_div_fixup_f32 v18, v16, v18, v20
	v_pk_mul_f32 v[2:3], v[2:3], v[18:19]
	v_lshlrev_b32_e32 v18, 16, v17
	v_and_b32_e32 v19, 0xffff0000, v17
	v_mul_f32_e32 v16, 0xbfb8aa3b, v18
	v_mul_f32_e32 v17, 0xbfb8aa3b, v19
	v_exp_f32_e32 v16, v16
	v_exp_f32_e32 v17, v17
	v_cvt_pk_bf16_f32 v2, v2, v3
	v_pk_add_f32 v[16:17], v[16:17], 1.0 op_sel_hi:[1,0]
	s_nop 0
	v_div_scale_f32 v20, s[18:19], v17, v17, v19
	v_rcp_f32_e32 v21, v20
	s_nop 0
	v_fma_f32 v22, -v20, v21, 1.0
	v_fmac_f32_e32 v21, v22, v21
	v_div_scale_f32 v22, vcc, v19, v17, v19
	v_mul_f32_e32 v23, v22, v21
	v_fma_f32 v24, -v20, v23, v22
	v_fmac_f32_e32 v23, v24, v21
	v_fma_f32 v20, -v20, v23, v22
	v_div_fmas_f32 v20, v20, v21, v23
	v_div_fixup_f32 v17, v20, v17, v19
	v_div_scale_f32 v19, s[18:19], v16, v16, v18
	v_rcp_f32_e32 v20, v19
	s_nop 0
	v_fma_f32 v21, -v19, v20, 1.0
	v_fmac_f32_e32 v20, v21, v20
	v_div_scale_f32 v21, vcc, v18, v16, v18
	v_mul_f32_e32 v22, v21, v20
	v_fma_f32 v23, -v19, v22, v21
	v_fmac_f32_e32 v22, v23, v20
	v_fma_f32 v19, -v19, v22, v21
	v_div_fmas_f32 v19, v19, v20, v22
	v_div_fixup_f32 v16, v19, v16, v18
	v_pk_mul_f32 v[4:5], v[4:5], v[16:17]
	v_add_co_u32_e32 v10, vcc, s6, v10
	v_cvt_pk_bf16_f32 v3, v4, v5
	v_lshlrev_b64 v[4:5], 11, v[12:13]
	v_lshl_add_u64 v[4:5], v[6:7], 0, v[4:5]
	global_store_dwordx2 v[4:5], v[2:3], off offset:1536
	v_addc_co_u32_e32 v11, vcc, 0, v11, vcc
	ds_read_b128 v[2:5], v15 offset:12672
	v_add_u32_e32 v15, 0x4200, v15
	s_waitcnt vmcnt(3) lgkmcnt(0)
	v_mov_b32_e32 v10, v118
	v_mov_b32_e32 v11, v119
	s_cbranch_scc0 .Lfn_nopf
	v_add_u32_e32 v120, s4, v14
	v_mad_u32_u24 v121, v120, s11, v8
	global_load_dwordx2 v[112:113], v121, s[48:49] offset:704
	v_add_u32_e32 v121, 8, v120
	v_mad_u32_u24 v121, v121, s11, v8
	global_load_dwordx2 v[114:115], v121, s[48:49] offset:704
	v_add_u32_e32 v121, 16, v120
	v_mad_u32_u24 v121, v121, s11, v8
	global_load_dwordx2 v[116:117], v121, s[48:49] offset:704
	v_add_u32_e32 v121, 24, v120
	v_mad_u32_u24 v121, v121, s11, v8
	global_load_dwordx2 v[118:119], v121, s[48:49] offset:704
; DI float silu(float x) { return x / (1.f + __expf(-x)); }
; DI f32x4 unpack4(u32x2 v) { f32x4 r = {bflo(v.x), bfhi(v.x), bflo(v.y), bfhi(v.y)}; return r; }
; DI u32x2 pack4(f32x4 v) { u32x2 r = {cvtpk(v[0], v[1]), cvtpk(v[2], v[3])}; return r; }
; DI void phase_mix(KP p, int l, char* lds) {
;     ...
;       gemm_tile(YD + (size_t)m0 * 256, 256, wf + (size_t)n0 * 256, 256, 256, lds, [&](int m, int n, f32x4 v) {
;         const size_t r = (size_t)m0 + m;
;         f32x4 gd = unpack4(*(const u32x2*)(P + r * NIN + O_GD + n0 + n));
;         f32x4 o = {v[0] * silu(gd[0]), v[1] * silu(gd[1]), v[2] * silu(gd[2]), v[3] * silu(gd[3])};
;         *(u32x2*)(Y + r * 1024 + 768 + n0 + n) = pack4(o); });
;     ...
;       const int i2 = it - e5; const int bl = i2 / 36, rem = i2 % 36; const int cpl = rem >> 2, g = rem & 3;
;       const int ch = (2 * xcd + bl) * 18 + 2 * cpl;
;       if (!upd && cpl >= 8) continue;
;       const float* bs = p->cm_b_s + ((size_t)l * 4 + g) * 128;
;       const bf16_t* Pr = P + (size_t)ch * 128 * NIN + 64 * g; bf16_t* Yr = Y + (size_t)ch * 128 * 1024 + 512 + 64 * g;
;       gemm_tile(wsb + (size_t)g * 128 * 128, 128, vnT + ((size_t)ch * 256 + 64 * g) * 128, 128, 128, lds, [&](int m, int n, f32x4 v) {
.Lfn_nopf:
	v_lshlrev_b32_e32 v9, 16, v10
	v_and_b32_e32 v10, 0xffff0000, v10
	v_mul_f32_e32 v12, 0xbfb8aa3b, v9
	v_mul_f32_e32 v13, 0xbfb8aa3b, v10
	v_exp_f32_e32 v12, v12
	v_exp_f32_e32 v13, v13
	s_nop 0
	v_pk_add_f32 v[12:13], v[12:13], 1.0 op_sel_hi:[1,0]
	s_nop 0
	v_div_scale_f32 v16, s[18:19], v13, v13, v10
	v_rcp_f32_e32 v17, v16
	s_nop 0
	v_fma_f32 v18, -v16, v17, 1.0
	v_fmac_f32_e32 v17, v18, v17
	v_div_scale_f32 v18, vcc, v10, v13, v10
	v_mul_f32_e32 v19, v18, v17
	v_fma_f32 v20, -v16, v19, v18
	v_fmac_f32_e32 v19, v20, v17
	v_fma_f32 v16, -v16, v19, v18
	v_div_fmas_f32 v16, v16, v17, v19
	v_div_fixup_f32 v13, v16, v13, v10
	v_div_scale_f32 v10, s[18:19], v12, v12, v9
	v_rcp_f32_e32 v16, v10
	s_nop 0
	v_fma_f32 v17, -v10, v16, 1.0
	v_fmac_f32_e32 v16, v17, v16
	v_div_scale_f32 v17, vcc, v9, v12, v9
	v_mul_f32_e32 v18, v17, v16
	v_fma_f32 v19, -v10, v18, v17
	v_fmac_f32_e32 v18, v19, v16
	v_fma_f32 v10, -v10, v18, v17
	v_div_fmas_f32 v10, v10, v16, v18
	v_div_fixup_f32 v12, v10, v12, v9
	v_pk_mul_f32 v[2:3], v[2:3], v[12:13]
	v_lshlrev_b32_e32 v9, 16, v11
	v_and_b32_e32 v12, 0xffff0000, v11
	v_mul_f32_e32 v10, 0xbfb8aa3b, v9
	v_mul_f32_e32 v11, 0xbfb8aa3b, v12
	v_exp_f32_e32 v10, v10
	v_exp_f32_e32 v11, v11
	v_cvt_pk_bf16_f32 v2, v2, v3
	v_pk_add_f32 v[10:11], v[10:11], 1.0 op_sel_hi:[1,0]
	s_nop 0
	v_div_scale_f32 v13, s[18:19], v11, v11, v12
	v_rcp_f32_e32 v16, v13
	s_nop 0
	v_fma_f32 v17, -v13, v16, 1.0
	v_fmac_f32_e32 v16, v17, v16
	v_div_scale_f32 v17, vcc, v12, v11, v12
	v_mul_f32_e32 v18, v17, v16
	v_fma_f32 v19, -v13, v18, v17
	v_fmac_f32_e32 v18, v19, v16
	v_fma_f32 v13, -v13, v18, v17
	v_div_fmas_f32 v13, v13, v16, v18
	v_div_fixup_f32 v11, v13, v11, v12
	v_div_scale_f32 v12, s[18:19], v10, v10, v9
	v_rcp_f32_e32 v13, v12
	s_nop 0
	v_fma_f32 v16, -v12, v13, 1.0
	v_fmac_f32_e32 v13, v16, v13
	v_div_scale_f32 v16, vcc, v9, v10, v9
	v_mul_f32_e32 v17, v16, v13
	v_fma_f32 v18, -v12, v17, v16
	v_fmac_f32_e32 v17, v18, v13
	v_fma_f32 v12, -v12, v17, v16
	v_div_fmas_f32 v12, v12, v13, v17
	v_div_fixup_f32 v10, v12, v10, v9
	v_pk_mul_f32 v[4:5], v[4:5], v[10:11]
	s_nop 0
	v_cvt_pk_bf16_f32 v3, v4, v5
	v_lshlrev_b64 v[4:5], 11, v[0:1]
	v_lshl_add_u64 v[4:5], v[6:7], 0, v[4:5]
	global_store_dwordx2 v[4:5], v[2:3], off offset:1536
	s_cbranch_scc1 .LBB0_152
	s_mov_b64 s[4:5], 0
	s_waitcnt lgkmcnt(0)
	s_barrier
.LBB0_154:
	s_and_b64 vcc, exec, s[4:5]
	s_cbranch_vccz .LBB0_126
	s_cmp_lt_i32 s46, 64
	s_cselect_b64 s[36:37], -1, 0
	s_cmp_gt_i32 s46, 63
	s_cselect_b64 s[40:41], -1, 0
	s_cmp_ge_i32 s46, s47
	s_cselect_b64 s[4:5], -1, 0
	s_and_b64 s[18:19], s[40:41], s[4:5]
	s_mov_b64 s[4:5], -1
	s_and_b64 vcc, exec, s[18:19]
	s_cbranch_vccz .LBB0_161
	s_sub_i32 s4, s46, s47
	s_mul_hi_u32 s2, s4, 0x38e38e39
	s_lshr_b32 s2, s2, 3
	s_mul_i32 s5, s2, 36
	s_sub_i32 s4, s4, s5
	s_cmp_gt_u32 s4, 31
	v_readlane_b32 s20, v255, 35
	s_cselect_b64 s[18:19], -1, 0
	v_readlane_b32 s21, v255, 36
	s_and_b64 s[18:19], s[20:21], s[18:19]
	s_and_b64 vcc, exec, s[18:19]
	s_cbranch_vccnz .LBB0_160
	v_readlane_b32 s5, v253, 5
	s_add_i32 s2, s2, s5
	s_lshr_b32 s5, s4, 1
	s_mul_i32 s2, s2, 18
	s_and_b32 s5, s5, 30
	s_add_i32 s2, s2, s5
	s_and_b32 s19, s4, 3
	s_lshl_b32 s18, s19, 9
	s_lshl_b64 s[50:51], s[2:3], 18
	s_lshl_b32 s20, s19, 15
	v_readlane_b32 s21, v255, 55
	s_add_u32 s20, s21, s20
	v_readlane_b32 s21, v255, 56
	s_addc_u32 s21, s21, 0
	s_lshl_b64 s[34:35], s[2:3], 16
	v_readlane_b32 s52, v255, 51
	s_add_u32 s34, s52, s34
	v_readlane_b32 s52, v255, 53
	v_mov_b32_e32 v66, v196
	s_load_dwordx2 s[4:5], s[0:1], 0x98
	s_addc_u32 s35, s52, s35
	s_lshl_b32 s52, s19, 14
	s_add_u32 s34, s34, s52
	v_lshrrev_b32_e32 v0, 4, v66
	v_xor_b32_e32 v8, v0, v66
	v_lshlrev_b32_e32 v0, 5, v66
	s_addc_u32 s35, s35, 0
	v_and_b32_e32 v0, 0x1f00, v0
	v_lshrrev_b32_e32 v67, 8, v66
	s_mov_b32 s53, 0x11000
	v_lshl_add_u64 v[2:3], s[34:35], 0, v[0:1]
	v_lshl_add_u64 v[4:5], s[20:21], 0, v[0:1]
	v_lshlrev_b32_e32 v0, 4, v8
	v_and_b32_e32 v6, 0xff, v66
	v_mad_i32_i24 v90, v67, s53, 0
	v_and_b32_e32 v0, 0x70, v0
	v_lshl_add_u64 v[86:87], v[2:3], 0, v[0:1]
	v_lshlrev_b32_e32 v2, 7, v66
	v_lshl_add_u32 v92, v6, 4, v90
	v_lshl_add_u64 v[84:85], v[4:5], 0, v[0:1]
	v_and_b32_e32 v4, 0x2f80, v2
	v_add_u32_e32 v2, 0x4000, v92
	v_readfirstlane_b32 s20, v92
	s_mov_b32 m0, s20
	v_readfirstlane_b32 s20, v2
	v_add_u32_e32 v5, 0x1000, v92
	global_load_lds_dwordx4 v[84:85], off
	s_mov_b32 m0, s20
	s_mov_b64 s[34:35], 0x2000
	v_readfirstlane_b32 s20, v5
	v_add_u32_e32 v5, 0x5000, v92
	global_load_lds_dwordx4 v[86:87], off
	v_lshl_add_u64 v[2:3], v[84:85], 0, s[34:35]
	s_mov_b32 m0, s20
	v_readfirstlane_b32 s20, v5
	global_load_lds_dwordx4 v[2:3], off
	v_lshl_add_u64 v[2:3], v[86:87], 0, s[34:35]
	s_mov_b32 m0, s20
	s_mov_b64 s[20:21], 0x4000
	v_add_u32_e32 v5, 0x2000, v92
	global_load_lds_dwordx4 v[2:3], off
	v_lshl_add_u64 v[2:3], v[84:85], 0, s[20:21]
	v_readfirstlane_b32 s20, v5
	v_add_u32_e32 v5, 0x6000, v92
	s_mov_b32 m0, s20
	s_mov_b64 s[54:55], 0x10000
	v_readfirstlane_b32 s20, v5
	global_load_lds_dwordx4 v[2:3], off
	v_lshl_add_u64 v[2:3], v[86:87], 0, s[54:55]
	s_mov_b32 m0, s20
	s_mov_b64 s[20:21], 0x6000
	v_add_u32_e32 v5, 0x3000, v92
	global_load_lds_dwordx4 v[2:3], off
	v_lshl_add_u64 v[2:3], v[84:85], 0, s[20:21]
	v_readfirstlane_b32 s20, v5
	s_mov_b32 m0, s20
	s_mov_b64 s[20:21], 0x12000
	v_add_u32_e32 v5, 0x7000, v92
	global_load_lds_dwordx4 v[2:3], off
	v_lshl_add_u64 v[2:3], v[86:87], 0, s[20:21]
	v_readfirstlane_b32 s20, v5
	v_lshrrev_b32_e32 v7, 5, v66
	s_mov_b32 m0, s20
	v_bfe_u32 v93, v66, 1, 3
	global_load_lds_dwordx4 v[2:3], off
	v_bitop3_b32 v2, v7, v93, 1 bitop3:0x6c
	v_add_u32_e32 v94, v90, v4
	v_lshlrev_b32_e32 v6, 4, v2
	v_add_u32_e32 v95, v94, v6
	s_waitcnt vmcnt(0)
	s_waitcnt vmcnt(0) lgkmcnt(0)
	s_barrier
; #define G_WAIT() { asm volatile("s_waitcnt vmcnt(0)" ::: "memory"); __syncthreads(); }
;     ...
;   G_DMA(0, 0);
;   G_WAIT();
;   for (int kt = 0; kt < nk; kt += 2) {
;     if (kt + 1 < nk) G_DMA(1, kt + 1);
;     G_COMPUTE(0);
;     G_WAIT();
;     if (kt + 1 < nk) {
;       if (kt + 2 < nk) G_DMA(0, kt + 2);
;       G_COMPUTE(1);
;       G_WAIT();
;     }
;   }
; DI void phase_mix(KP p, int l, char* lds) {
;     ...
;       gemm_tile(wsb + (size_t)g * 128 * 128, 128, vnT + ((size_t)ch * 256 + 64 * g) * 128, 128, 128, lds, [&](int m, int n, f32x4 v) {
	ds_read_b128 v[2:5], v95 offset:16384
	v_and_b32_e32 v91, 31, v66
	v_lshrrev_b32_e32 v0, 1, v66
	v_and_or_b32 v0, v0, 64, v91
	v_lshl_add_u32 v96, v0, 7, v90
	v_add_u32_e32 v97, v96, v6
	ds_read_b128 v[6:9], v97
	ds_read_b128 v[10:13], v97 offset:4096
	ds_read_b128 v[14:17], v95 offset:20480
	v_bfe_u32 v98, v66, 5, 1
	s_waitcnt lgkmcnt(2)
	v_mfma_f32_32x32x16_bf16 v[50:65], v[2:5], v[6:9], 0
	v_add_u32_e32 v101, 0x8000, v92
	v_add_u32_e32 v103, 0xc000, v92
	v_readfirstlane_b32 s20, v101
	v_lshl_add_u64 v[88:89], v[84:85], 0, s[28:29]
	s_mov_b32 m0, s20
	v_readfirstlane_b32 s20, v103
	s_mov_b64 s[34:35], 0x2080
	s_waitcnt lgkmcnt(1)
	v_mfma_f32_32x32x16_bf16 v[18:33], v[2:5], v[10:13], 0
	v_bitop3_b32 v2, v98, v93, 2 bitop3:0x36
	v_lshlrev_b32_e32 v72, 4, v2
	v_add_u32_e32 v99, v94, v72
	ds_read_b128 v[68:71], v99 offset:16384
	v_add_u32_e32 v100, v96, v72
	ds_read_b128 v[72:75], v100
	ds_read_b128 v[76:79], v100 offset:4096
	ds_read_b128 v[80:83], v99 offset:20480
	v_mul_u32_u24_e32 v0, 0x210, v0
	s_waitcnt lgkmcnt(4)
	v_mfma_f32_32x32x16_bf16 v[34:49], v[14:17], v[6:9], 0
	s_lshl_b32 s19, s19, 7
	v_readlane_b32 s48, v255, 62
	s_mul_hi_u32 s52, s2, 0xa6000
	s_mul_i32 s2, s2, 0xa6000
	v_readlane_b32 s49, v255, 63
	v_readlane_b32 s56, v255, 33
	v_readlane_b32 s57, v255, 34
	v_mfma_f32_32x32x16_bf16 v[2:17], v[14:17], v[10:13], 0
	s_waitcnt lgkmcnt(2)
	v_mfma_f32_32x32x16_bf16 v[50:65], v[68:71], v[72:75], v[50:65]
	s_waitcnt lgkmcnt(1)
	v_mfma_f32_32x32x16_bf16 v[18:33], v[68:71], v[76:79], v[18:33]
	v_bitop3_b32 v68, v98, v93, 4 bitop3:0x36
	s_waitcnt lgkmcnt(0)
	v_mfma_f32_32x32x16_bf16 v[34:49], v[80:83], v[72:75], v[34:49]
	v_lshlrev_b32_e32 v72, 4, v68
	v_add_u32_e32 v102, v94, v72
	ds_read_b128 v[68:71], v102 offset:16384
	v_add_u32_e32 v104, v96, v72
	ds_read_b128 v[72:75], v104
	v_mfma_f32_32x32x16_bf16 v[2:17], v[80:83], v[76:79], v[2:17]
	ds_read_b128 v[76:79], v104 offset:4096
	ds_read_b128 v[80:83], v102 offset:20480
	global_load_lds_dwordx4 v[88:89], off
	v_lshl_add_u64 v[88:89], v[86:87], 0, s[28:29]
	s_mov_b32 m0, s20
	s_nop 0
	global_load_lds_dwordx4 v[88:89], off
	s_waitcnt lgkmcnt(0)
	v_mfma_f32_32x32x16_bf16 v[50:65], v[68:71], v[72:75], v[50:65]
	v_lshl_add_u64 v[88:89], v[86:87], 0, s[34:35]
	v_mfma_f32_32x32x16_bf16 v[34:49], v[80:83], v[72:75], v[34:49]
	v_add_u32_e32 v74, 0x9000, v92
	v_lshl_add_u64 v[72:73], v[84:85], 0, s[34:35]
	v_readfirstlane_b32 s20, v74
	s_mov_b32 m0, s20
	s_nop 0
	global_load_lds_dwordx4 v[72:73], off
	v_mfma_f32_32x32x16_bf16 v[18:33], v[68:71], v[76:79], v[18:33]
	v_add_u32_e32 v68, 0xd000, v92
	s_nop 0
	v_readfirstlane_b32 s20, v68
	v_bitop3_b32 v68, v98, v93, 6 bitop3:0x36
	v_lshlrev_b32_e32 v68, 4, v68
	v_add_u32_e32 v94, v94, v68
	v_add_u32_e32 v93, v96, v68
	ds_read_b128 v[68:71], v94 offset:16384
	ds_read_b128 v[72:75], v93
	s_mov_b32 m0, s20
	v_mfma_f32_32x32x16_bf16 v[2:17], v[80:83], v[76:79], v[2:17]
	global_load_lds_dwordx4 v[88:89], off
	ds_read_b128 v[76:79], v93 offset:4096
	ds_read_b128 v[80:83], v94 offset:20480
	s_mov_b64 s[20:21], 0x4080
	v_add_u32_e32 v96, 0xa000, v92
	v_lshl_add_u64 v[88:89], v[84:85], 0, s[20:21]
	v_readfirstlane_b32 s20, v96
	s_mov_b32 m0, s20
	s_mov_b64 s[20:21], 0x10080
	v_add_u32_e32 v96, 0xe000, v92
	global_load_lds_dwordx4 v[88:89], off
	v_lshl_add_u64 v[88:89], v[86:87], 0, s[20:21]
	v_readfirstlane_b32 s20, v96
	s_waitcnt lgkmcnt(0)
	v_mfma_f32_32x32x16_bf16 v[50:65], v[68:71], v[72:75], v[50:65]
	s_mov_b32 m0, s20
	s_mov_b64 s[20:21], 0x6080
	global_load_lds_dwordx4 v[88:89], off
	v_mfma_f32_32x32x16_bf16 v[34:49], v[80:83], v[72:75], v[34:49]
	v_add_u32_e32 v74, 0xb000, v92
	v_lshl_add_u64 v[72:73], v[84:85], 0, s[20:21]
	v_readfirstlane_b32 s20, v74
	s_mov_b32 m0, s20
	s_mov_b64 s[20:21], 0x12080
	global_load_lds_dwordx4 v[72:73], off
	v_mfma_f32_32x32x16_bf16 v[18:33], v[68:71], v[76:79], v[18:33]
	v_add_u32_e32 v70, 0xf000, v92
	v_lshl_add_u64 v[68:69], v[86:87], 0, s[20:21]
	v_readfirstlane_b32 s20, v70
	s_mov_b32 m0, s20
	v_and_b32_e32 v84, 64, v66
	global_load_lds_dwordx4 v[68:69], off
	v_mfma_f32_32x32x16_bf16 v[2:17], v[80:83], v[76:79], v[2:17]
	s_waitcnt vmcnt(0)
	s_waitcnt vmcnt(0) lgkmcnt(0)
	s_barrier
	ds_read_b128 v[68:71], v95 offset:49152
	ds_read_b128 v[72:75], v97 offset:32768
	ds_read_b128 v[76:79], v97 offset:36864
	ds_read_b128 v[80:83], v95 offset:53248
	v_lshl_add_u32 v84, v84, 2, v90
	v_lshlrev_b32_e32 v85, 4, v98
	s_waitcnt lgkmcnt(2)
	v_mfma_f32_32x32x16_bf16 v[50:65], v[68:71], v[72:75], v[50:65]
	v_add3_u32 v0, v84, v85, v0
	s_or_b32 s20, s50, s19
	s_movk_i32 s21, 0x80
	s_add_u32 s20, s48, s20
	s_waitcnt lgkmcnt(0)
	v_mfma_f32_32x32x16_bf16 v[34:49], v[80:83], v[72:75], v[34:49]
	v_mfma_f32_32x32x16_bf16 v[2:17], v[80:83], v[76:79], v[2:17]
	v_mfma_f32_32x32x16_bf16 v[18:33], v[68:71], v[76:79], v[18:33]
	ds_read_b128 v[68:71], v99 offset:49152
	ds_read_b128 v[72:75], v100 offset:32768
	ds_read_b128 v[76:79], v100 offset:36864
	ds_read_b128 v[80:83], v99 offset:53248
	s_waitcnt lgkmcnt(2)
	v_mfma_f32_32x32x16_bf16 v[50:65], v[68:71], v[72:75], v[50:65]
	s_waitcnt lgkmcnt(0)
	v_mfma_f32_32x32x16_bf16 v[34:49], v[80:83], v[72:75], v[34:49]
	v_mfma_f32_32x32x16_bf16 v[2:17], v[80:83], v[76:79], v[2:17]
	v_mfma_f32_32x32x16_bf16 v[18:33], v[68:71], v[76:79], v[18:33]
	ds_read_b128 v[68:71], v102 offset:49152
	ds_read_b128 v[72:75], v104 offset:32768
	ds_read_b128 v[76:79], v104 offset:36864
	ds_read_b128 v[80:83], v102 offset:53248
	s_waitcnt lgkmcnt(2)
	v_mfma_f32_32x32x16_bf16 v[50:65], v[68:71], v[72:75], v[50:65]
	s_waitcnt lgkmcnt(0)
	v_mfma_f32_32x32x16_bf16 v[34:49], v[80:83], v[72:75], v[34:49]
	v_mfma_f32_32x32x16_bf16 v[2:17], v[80:83], v[76:79], v[2:17]
	v_mfma_f32_32x32x16_bf16 v[18:33], v[68:71], v[76:79], v[18:33]
	ds_read_b128 v[68:71], v94 offset:49152
	ds_read_b128 v[72:75], v93 offset:32768
	ds_read_b128 v[76:79], v93 offset:36864
	ds_read_b128 v[80:83], v94 offset:53248
	s_waitcnt vmcnt(0)
	s_waitcnt lgkmcnt(0)
	s_barrier
; DI float silu(float x) { return x / (1.f + __expf(-x)); }
; DI f32x4 unpack4(u32x2 v) { f32x4 r = {bflo(v.x), bfhi(v.x), bflo(v.y), bfhi(v.y)}; return r; }
; DI u32x2 pack4(f32x4 v) { u32x2 r = {cvtpk(v[0], v[1]), cvtpk(v[2], v[3])}; return r; }
;     ...
; #pragma unroll
;   for (int i = 0; i < 2; ++i)
; #pragma unroll
;     for (int j = 0; j < 2; ++j)
; #pragma unroll
;       for (int q = 0; q < 4; ++q) {
;         f32x4 v = {acc[i][j][4 * q], acc[i][j][4 * q + 1], acc[i][j][4 * q + 2], acc[i][j][4 * q + 3]};
;         *(f32x4*)(ct + (wr * 64 + i * 32 + l31) * 132 + wc * 64 + j * 32 + 8 * q + 4 * h) = v;
;       }
;   __syncthreads();
; #pragma unroll 4
;   for (int it = 0; it < 16; ++it) {
;     const int idx = it * 256 + tid; const int row = idx >> 5, c4 = (idx & 31) * 4;
;     f32x4 v = *(const f32x4*)(ct + row * 132 + c4);
;     epi(row, c4, v);
; DI void phase_mix(KP p, int l, char* lds) {
;     ...
;       gemm_tile(wsb + (size_t)g * 128 * 128, 128, vnT + ((size_t)ch * 256 + 64 * g) * 128, 128, 128, lds, [&](int m, int n, f32x4 v) {
;         const int c2 = n >> 6, nn = n & 63;
;         const size_t rr = (size_t)c2 * 128 + m;
;         const float bias = bs[m];
;         f32x4 uu = unpack4(*(const u32x2*)(Pr + rr * NIN + O_U + nn)), gc = unpack4(*(const u32x2*)(Pr + rr * NIN + O_GC + nn));
;         f32x4 o;
; #pragma unroll
;         for (int e = 0; e < 4; ++e) o[e] = uu[e] * (v[e] + bias) * silu(gc[e]);
;         *(u32x2*)(Yr + rr * 1024 + nn) = pack4(o);
	v_mfma_f32_32x32x16_bf16 v[50:65], v[68:71], v[72:75], v[50:65]
	v_mfma_f32_32x32x16_bf16 v[34:49], v[80:83], v[72:75], v[34:49]
	s_nop 10
	ds_write_b128 v0, v[50:53]
	ds_write_b128 v0, v[54:57] offset:32
	ds_write_b128 v0, v[58:61] offset:64
	ds_write_b128 v0, v[62:65] offset:96
	ds_write_b128 v0, v[34:37] offset:128
	v_mfma_f32_32x32x16_bf16 v[2:17], v[80:83], v[76:79], v[2:17]
	v_mfma_f32_32x32x16_bf16 v[18:33], v[68:71], v[76:79], v[18:33]
	ds_write_b128 v0, v[38:41] offset:160
	ds_write_b128 v0, v[42:45] offset:192
	ds_write_b128 v0, v[46:49] offset:224
	s_nop 8
	ds_write_b128 v0, v[18:21] offset:16896
	ds_write_b128 v0, v[22:25] offset:16928
	ds_write_b128 v0, v[26:29] offset:16960
	ds_write_b128 v0, v[30:33] offset:16992
	ds_write_b128 v0, v[2:5] offset:17024
	ds_write_b128 v0, v[6:9] offset:17056
	ds_write_b128 v0, v[10:13] offset:17088
	ds_write_b128 v0, v[14:17] offset:17120
	v_lshlrev_b32_e32 v2, 3, v66
	v_bfe_u32 v18, v66, 5, 3
	v_and_or_b32 v19, v2, s21, v18
	s_addc_u32 s21, s49, s51
	s_or_b32 s34, s2, s19
	v_or_b32_e32 v4, 24, v19
	s_add_u32 s34, s56, s34
	v_or_b32_e32 v8, 16, v19
	v_or_b32_e32 v12, 8, v19
	v_lshlrev_b32_e32 v2, 11, v4
	v_mov_b32_e32 v3, v1
	s_addc_u32 s35, s57, s52
	v_lshlrev_b32_e32 v6, 11, v8
	v_mov_b32_e32 v7, v1
	v_lshlrev_b32_e32 v10, 11, v12
	v_mov_b32_e32 v11, v1
	v_lshl_add_u64 v[2:3], s[20:21], 0, v[2:3]
	v_lshl_add_u64 v[6:7], s[20:21], 0, v[6:7]
	v_lshl_add_u64 v[10:11], s[20:21], 0, v[10:11]
	s_add_u32 s20, s48, s19
	s_addc_u32 s21, s49, 0
	s_add_u32 s20, s20, s50
	s_addc_u32 s21, s21, s51
	v_lshlrev_b32_e32 v14, 11, v19
	v_mov_b32_e32 v15, v1
	s_add_u32 s19, s56, s19
	v_lshl_add_u64 v[14:15], s[20:21], 0, v[14:15]
	s_addc_u32 s21, s57, 0
	s_add_u32 s20, s19, s2
	s_addc_u32 s21, s21, s52
	v_mov_b64_e32 v[16:17], s[20:21]
	v_mad_u64_u32 v[16:17], s[20:21], v19, s11, v[16:17]
	v_readlane_b32 s20, v255, 57
	v_mul_u32_u24_e32 v18, 0x210, v18
	v_readlane_b32 s21, v255, 58
	s_add_u32 s2, s4, s20
	v_mad_i32_i24 v18, v67, s53, v18
	v_lshlrev_b32_e32 v19, 4, v91
	s_addc_u32 s5, s5, s21
	v_add3_u32 v22, v18, v19, 0
	v_lshrrev_b32_e32 v18, 3, v66
	s_add_u32 s4, s2, s18
	v_and_b32_e32 v18, 28, v18
	v_mov_b32_e32 v19, v1
	s_addc_u32 s5, s5, 0
	v_and_b32_e32 v0, 15, v66
	v_mul_u32_u24_e32 v4, 0x14c0, v4
	v_mov_b32_e32 v5, v1
	v_mul_u32_u24_e32 v8, 0x14c0, v8
	v_mov_b32_e32 v9, v1
	v_mul_u32_u24_e32 v12, 0x14c0, v12
	v_mov_b32_e32 v13, v1
	v_lshl_add_u64 v[18:19], s[4:5], 0, v[18:19]
	v_lshlrev_b32_e32 v0, 3, v0
	v_lshl_add_u64 v[4:5], s[34:35], 0, v[4:5]
	v_lshl_add_u64 v[8:9], s[34:35], 0, v[8:9]
	v_lshl_add_u64 v[12:13], s[34:35], 0, v[12:13]
	v_lshl_add_u64 v[18:19], v[18:19], 0, 64
	s_mov_b32 s2, 0
	s_mov_b32 s18, 0x60b5000
	s_mov_b64 s[20:21], 0x29800
	s_waitcnt lgkmcnt(0)
	s_barrier
	s_mov_b32 s48, 0x60b5000
	s_mov_b32 s49, 0
	v_lshl_add_u64 v[132:133], v[16:17], 0, v[0:1]
	v_lshl_add_u64 v[132:133], v[132:133], 0, s[48:49]
	global_load_dword v112, v[18:19], off offset:-64
	global_load_dwordx2 v[116:117], v[132:133], off offset:3008
	global_load_dwordx2 v[118:119], v[132:133], off offset:4032
	v_lshl_add_u64 v[132:133], v[12:13], 0, v[0:1]
	v_lshl_add_u64 v[132:133], v[132:133], 0, s[48:49]
	global_load_dword v113, v[18:19], off offset:-32
	global_load_dwordx2 v[120:121], v[132:133], off offset:3008
	global_load_dwordx2 v[122:123], v[132:133], off offset:4032
	v_lshl_add_u64 v[132:133], v[8:9], 0, v[0:1]
	v_lshl_add_u64 v[132:133], v[132:133], 0, s[48:49]
	global_load_dword v114, v[18:19], off
	global_load_dwordx2 v[124:125], v[132:133], off offset:3008
	global_load_dwordx2 v[126:127], v[132:133], off offset:4032
	v_lshl_add_u64 v[132:133], v[4:5], 0, v[0:1]
	v_lshl_add_u64 v[132:133], v[132:133], 0, s[48:49]
	global_load_dword v115, v[18:19], off offset:32
	global_load_dwordx2 v[128:129], v[132:133], off offset:3008
	global_load_dwordx2 v[130:131], v[132:133], off offset:4032
.LBB0_158:
	v_lshl_add_u64 v[28:29], v[16:17], 0, v[0:1]
	v_add_co_u32_e32 v28, vcc, 0x60b5000, v28
	v_add_u32_e32 v23, s2, v22
	s_nop 0
	v_addc_co_u32_e32 v29, vcc, 0, v29, vcc
	ds_read_b128 v[24:27], v23
	s_nop 0
	s_addk_i32 s2, 0x4200
	v_lshl_add_u64 v[16:17], v[16:17], 0, s[20:21]
	s_cmp_lg_u32 s2, 0x10800
	s_waitcnt vmcnt(9) lgkmcnt(0)
	v_mov_b32_e32 v20, v112
	v_mov_b32_e32 v30, v116
	v_mov_b32_e32 v31, v117
	v_mov_b32_e32 v28, v118
	v_mov_b32_e32 v29, v119
	v_lshlrev_b32_e32 v32, 16, v30
	v_lshlrev_b32_e32 v21, 16, v28
	v_and_b32_e32 v33, 0xffff0000, v30
	v_and_b32_e32 v28, 0xffff0000, v28
	v_mul_f32_e32 v30, 0xbfb8aa3b, v21
	v_exp_f32_e32 v34, v30
	v_mul_f32_e32 v30, 0xbfb8aa3b, v28
	v_exp_f32_e32 v35, v30
	v_pk_add_f32 v[24:25], v[24:25], v[20:21] op_sel_hi:[1,0]
	s_nop 0
	v_pk_mul_f32 v[24:25], v[24:25], v[32:33]
	v_pk_add_f32 v[32:33], v[34:35], 1.0 op_sel_hi:[1,0]
	s_nop 0
	v_div_scale_f32 v30, s[4:5], v33, v33, v28
	v_rcp_f32_e32 v34, v30
	s_nop 0
	v_fma_f32 v35, -v30, v34, 1.0
	v_fmac_f32_e32 v34, v35, v34
	v_div_scale_f32 v35, vcc, v28, v33, v28
	v_mul_f32_e32 v36, v35, v34
	v_fma_f32 v37, -v30, v36, v35
	v_fmac_f32_e32 v36, v37, v34
	v_fma_f32 v30, -v30, v36, v35
	v_div_fmas_f32 v30, v30, v34, v36
	v_div_fixup_f32 v33, v30, v33, v28
	v_div_scale_f32 v28, s[4:5], v32, v32, v21
	v_rcp_f32_e32 v30, v28
	s_nop 0
	v_fma_f32 v34, -v28, v30, 1.0
	v_fmac_f32_e32 v30, v34, v30
	v_div_scale_f32 v34, vcc, v21, v32, v21
	v_mul_f32_e32 v35, v34, v30
	v_fma_f32 v36, -v28, v35, v34
	v_fmac_f32_e32 v35, v36, v30
	v_fma_f32 v28, -v28, v35, v34
	v_div_fmas_f32 v28, v28, v30, v35
	v_div_fixup_f32 v32, v28, v32, v21
	v_pk_mul_f32 v[24:25], v[24:25], v[32:33]
	v_lshlrev_b32_e32 v32, 16, v29
	v_and_b32_e32 v33, 0xffff0000, v29
; DI float silu(float x) { return x / (1.f + __expf(-x)); }
; DI f32x4 unpack4(u32x2 v) { f32x4 r = {bflo(v.x), bfhi(v.x), bflo(v.y), bfhi(v.y)}; return r; }
; DI u32x2 pack4(f32x4 v) { u32x2 r = {cvtpk(v[0], v[1]), cvtpk(v[2], v[3])}; return r; }
; DI void phase_mix(KP p, int l, char* lds) {
;     ...
;       gemm_tile(wsb + (size_t)g * 128 * 128, 128, vnT + ((size_t)ch * 256 + 64 * g) * 128, 128, 128, lds, [&](int m, int n, f32x4 v) {
;         const int c2 = n >> 6, nn = n & 63;
;         const size_t rr = (size_t)c2 * 128 + m;
;         const float bias = bs[m];
;         f32x4 uu = unpack4(*(const u32x2*)(Pr + rr * NIN + O_U + nn)), gc = unpack4(*(const u32x2*)(Pr + rr * NIN + O_GC + nn));
;         f32x4 o;
; #pragma unroll
;         for (int e = 0; e < 4; ++e) o[e] = uu[e] * (v[e] + bias) * silu(gc[e]);
;         *(u32x2*)(Yr + rr * 1024 + nn) = pack4(o);
	v_mul_f32_e32 v21, 0xbfb8aa3b, v32
	v_exp_f32_e32 v28, v21
	v_pk_add_f32 v[20:21], v[26:27], v[20:21] op_sel_hi:[1,0]
	v_mul_f32_e32 v26, 0xbfb8aa3b, v33
	v_exp_f32_e32 v29, v26
	v_lshlrev_b32_e32 v30, 16, v31
	v_and_b32_e32 v31, 0xffff0000, v31
	v_pk_mul_f32 v[20:21], v[20:21], v[30:31]
	v_pk_add_f32 v[26:27], v[28:29], 1.0 op_sel_hi:[1,0]
	s_nop 0
	v_div_scale_f32 v28, s[4:5], v27, v27, v33
	v_rcp_f32_e32 v29, v28
	s_nop 0
	v_fma_f32 v30, -v28, v29, 1.0
	v_fmac_f32_e32 v29, v30, v29
	v_div_scale_f32 v30, vcc, v33, v27, v33
	v_mul_f32_e32 v31, v30, v29
	v_fma_f32 v34, -v28, v31, v30
	v_fmac_f32_e32 v31, v34, v29
	v_fma_f32 v28, -v28, v31, v30
	v_div_fmas_f32 v28, v28, v29, v31
	v_div_fixup_f32 v27, v28, v27, v33
	v_div_scale_f32 v28, s[4:5], v26, v26, v32
	v_rcp_f32_e32 v29, v28
	s_nop 0
	v_fma_f32 v30, -v28, v29, 1.0
	v_fmac_f32_e32 v29, v30, v29
	v_div_scale_f32 v30, vcc, v32, v26, v32
	v_mul_f32_e32 v31, v30, v29
	v_fma_f32 v33, -v28, v31, v30
	v_fmac_f32_e32 v31, v33, v29
	v_fma_f32 v28, -v28, v31, v30
	v_div_fmas_f32 v28, v28, v29, v31
	v_div_fixup_f32 v26, v28, v26, v32
	v_pk_mul_f32 v[26:27], v[20:21], v[26:27]
	v_lshl_add_u64 v[28:29], v[12:13], 0, v[0:1]
	v_cvt_pk_bf16_f32 v20, v24, v25
	v_cvt_pk_bf16_f32 v21, v26, v27
	v_lshl_add_u64 v[24:25], v[14:15], 0, v[0:1]
	v_add_co_u32_e32 v28, vcc, s18, v28
	global_store_dwordx2 v[24:25], v[20:21], off
	s_nop 0
	v_addc_co_u32_e32 v29, vcc, 0, v29, vcc
	ds_read_b128 v[24:27], v23 offset:4224
	s_nop 0
	v_lshl_add_u64 v[12:13], v[12:13], 0, s[20:21]
	v_lshl_add_u64 v[14:15], v[14:15], 0, s[54:55]
	s_waitcnt vmcnt(7) lgkmcnt(0)
	v_mov_b32_e32 v20, v113
	v_mov_b32_e32 v30, v120
	v_mov_b32_e32 v31, v121
	v_mov_b32_e32 v28, v122
	v_mov_b32_e32 v29, v123
	v_lshlrev_b32_e32 v32, 16, v30
	v_lshlrev_b32_e32 v21, 16, v28
	v_and_b32_e32 v33, 0xffff0000, v30
	v_and_b32_e32 v28, 0xffff0000, v28
	v_mul_f32_e32 v30, 0xbfb8aa3b, v21
	v_exp_f32_e32 v34, v30
	v_mul_f32_e32 v30, 0xbfb8aa3b, v28
	v_exp_f32_e32 v35, v30
	v_pk_add_f32 v[24:25], v[24:25], v[20:21] op_sel_hi:[1,0]
	s_nop 0
	v_pk_mul_f32 v[24:25], v[24:25], v[32:33]
	v_pk_add_f32 v[32:33], v[34:35], 1.0 op_sel_hi:[1,0]
	s_nop 0
	v_div_scale_f32 v30, s[4:5], v33, v33, v28
	v_rcp_f32_e32 v34, v30
	s_nop 0
	v_fma_f32 v35, -v30, v34, 1.0
	v_fmac_f32_e32 v34, v35, v34
	v_div_scale_f32 v35, vcc, v28, v33, v28
	v_mul_f32_e32 v36, v35, v34
	v_fma_f32 v37, -v30, v36, v35
	v_fmac_f32_e32 v36, v37, v34
	v_fma_f32 v30, -v30, v36, v35
	v_div_fmas_f32 v30, v30, v34, v36
	v_div_fixup_f32 v33, v30, v33, v28
	v_div_scale_f32 v28, s[4:5], v32, v32, v21
	v_rcp_f32_e32 v30, v28
	s_nop 0
	v_fma_f32 v34, -v28, v30, 1.0
	v_fmac_f32_e32 v30, v34, v30
	v_div_scale_f32 v34, vcc, v21, v32, v21
	v_mul_f32_e32 v35, v34, v30
	v_fma_f32 v36, -v28, v35, v34
	v_fmac_f32_e32 v35, v36, v30
	v_fma_f32 v28, -v28, v35, v34
	v_div_fmas_f32 v28, v28, v30, v35
	v_div_fixup_f32 v32, v28, v32, v21
	v_pk_mul_f32 v[24:25], v[24:25], v[32:33]
	v_lshlrev_b32_e32 v32, 16, v29
	v_and_b32_e32 v33, 0xffff0000, v29
	v_mul_f32_e32 v21, 0xbfb8aa3b, v32
	v_exp_f32_e32 v28, v21
	v_pk_add_f32 v[20:21], v[26:27], v[20:21] op_sel_hi:[1,0]
	v_mul_f32_e32 v26, 0xbfb8aa3b, v33
	v_exp_f32_e32 v29, v26
	v_lshlrev_b32_e32 v30, 16, v31
	v_and_b32_e32 v31, 0xffff0000, v31
	v_pk_mul_f32 v[20:21], v[20:21], v[30:31]
	v_pk_add_f32 v[26:27], v[28:29], 1.0 op_sel_hi:[1,0]
	s_nop 0
	v_div_scale_f32 v28, s[4:5], v27, v27, v33
	v_rcp_f32_e32 v29, v28
	s_nop 0
	v_fma_f32 v30, -v28, v29, 1.0
	v_fmac_f32_e32 v29, v30, v29
	v_div_scale_f32 v30, vcc, v33, v27, v33
	v_mul_f32_e32 v31, v30, v29
	v_fma_f32 v34, -v28, v31, v30
	v_fmac_f32_e32 v31, v34, v29
	v_fma_f32 v28, -v28, v31, v30
	v_div_fmas_f32 v28, v28, v29, v31
	v_div_fixup_f32 v27, v28, v27, v33
	v_div_scale_f32 v28, s[4:5], v26, v26, v32
	v_rcp_f32_e32 v29, v28
	s_nop 0
	v_fma_f32 v30, -v28, v29, 1.0
	v_fmac_f32_e32 v29, v30, v29
	v_div_scale_f32 v30, vcc, v32, v26, v32
	v_mul_f32_e32 v31, v30, v29
	v_fma_f32 v33, -v28, v31, v30
	v_fmac_f32_e32 v31, v33, v29
	v_fma_f32 v28, -v28, v31, v30
	v_div_fmas_f32 v28, v28, v29, v31
	v_div_fixup_f32 v26, v28, v26, v32
	v_pk_mul_f32 v[26:27], v[20:21], v[26:27]
	v_lshl_add_u64 v[28:29], v[8:9], 0, v[0:1]
	v_cvt_pk_bf16_f32 v20, v24, v25
	v_cvt_pk_bf16_f32 v21, v26, v27
	v_lshl_add_u64 v[24:25], v[10:11], 0, v[0:1]
	v_add_co_u32_e32 v28, vcc, s18, v28
	global_store_dwordx2 v[24:25], v[20:21], off
	s_nop 0
	v_addc_co_u32_e32 v29, vcc, 0, v29, vcc
	ds_read_b128 v[24:27], v23 offset:8448
	s_nop 0
	v_lshl_add_u64 v[8:9], v[8:9], 0, s[20:21]
	v_lshl_add_u64 v[10:11], v[10:11], 0, s[54:55]
	s_waitcnt vmcnt(5) lgkmcnt(0)
; DI float silu(float x) { return x / (1.f + __expf(-x)); }
; DI f32x4 unpack4(u32x2 v) { f32x4 r = {bflo(v.x), bfhi(v.x), bflo(v.y), bfhi(v.y)}; return r; }
; DI u32x2 pack4(f32x4 v) { u32x2 r = {cvtpk(v[0], v[1]), cvtpk(v[2], v[3])}; return r; }
; DI void phase_mix(KP p, int l, char* lds) {
;     ...
;       gemm_tile(wsb + (size_t)g * 128 * 128, 128, vnT + ((size_t)ch * 256 + 64 * g) * 128, 128, 128, lds, [&](int m, int n, f32x4 v) {
;         const int c2 = n >> 6, nn = n & 63;
;         const size_t rr = (size_t)c2 * 128 + m;
;         const float bias = bs[m];
;         f32x4 uu = unpack4(*(const u32x2*)(Pr + rr * NIN + O_U + nn)), gc = unpack4(*(const u32x2*)(Pr + rr * NIN + O_GC + nn));
;         f32x4 o;
; #pragma unroll
;         for (int e = 0; e < 4; ++e) o[e] = uu[e] * (v[e] + bias) * silu(gc[e]);
;         *(u32x2*)(Yr + rr * 1024 + nn) = pack4(o);
	v_mov_b32_e32 v20, v114
	v_mov_b32_e32 v30, v124
	v_mov_b32_e32 v31, v125
	v_mov_b32_e32 v28, v126
	v_mov_b32_e32 v29, v127
	v_lshlrev_b32_e32 v32, 16, v30
	v_lshlrev_b32_e32 v21, 16, v28
	v_and_b32_e32 v33, 0xffff0000, v30
	v_and_b32_e32 v28, 0xffff0000, v28
	v_mul_f32_e32 v30, 0xbfb8aa3b, v21
	v_exp_f32_e32 v34, v30
	v_mul_f32_e32 v30, 0xbfb8aa3b, v28
	v_exp_f32_e32 v35, v30
	v_pk_add_f32 v[24:25], v[24:25], v[20:21] op_sel_hi:[1,0]
	s_nop 0
	v_pk_mul_f32 v[24:25], v[24:25], v[32:33]
	v_pk_add_f32 v[32:33], v[34:35], 1.0 op_sel_hi:[1,0]
	s_nop 0
	v_div_scale_f32 v30, s[4:5], v33, v33, v28
	v_rcp_f32_e32 v34, v30
	s_nop 0
	v_fma_f32 v35, -v30, v34, 1.0
	v_fmac_f32_e32 v34, v35, v34
	v_div_scale_f32 v35, vcc, v28, v33, v28
	v_mul_f32_e32 v36, v35, v34
	v_fma_f32 v37, -v30, v36, v35
	v_fmac_f32_e32 v36, v37, v34
	v_fma_f32 v30, -v30, v36, v35
	v_div_fmas_f32 v30, v30, v34, v36
	v_div_fixup_f32 v33, v30, v33, v28
	v_div_scale_f32 v28, s[4:5], v32, v32, v21
	v_rcp_f32_e32 v30, v28
	s_nop 0
	v_fma_f32 v34, -v28, v30, 1.0
	v_fmac_f32_e32 v30, v34, v30
	v_div_scale_f32 v34, vcc, v21, v32, v21
	v_mul_f32_e32 v35, v34, v30
	v_fma_f32 v36, -v28, v35, v34
	v_fmac_f32_e32 v35, v36, v30
	v_fma_f32 v28, -v28, v35, v34
	v_div_fmas_f32 v28, v28, v30, v35
	v_div_fixup_f32 v32, v28, v32, v21
	v_pk_mul_f32 v[24:25], v[24:25], v[32:33]
	v_lshlrev_b32_e32 v32, 16, v29
	v_and_b32_e32 v33, 0xffff0000, v29
	v_mul_f32_e32 v21, 0xbfb8aa3b, v32
	v_exp_f32_e32 v28, v21
	v_pk_add_f32 v[20:21], v[26:27], v[20:21] op_sel_hi:[1,0]
	v_mul_f32_e32 v26, 0xbfb8aa3b, v33
	v_exp_f32_e32 v29, v26
	v_lshlrev_b32_e32 v30, 16, v31
	v_and_b32_e32 v31, 0xffff0000, v31
	v_pk_mul_f32 v[20:21], v[20:21], v[30:31]
	v_pk_add_f32 v[26:27], v[28:29], 1.0 op_sel_hi:[1,0]
	s_nop 0
	v_div_scale_f32 v28, s[4:5], v27, v27, v33
	v_rcp_f32_e32 v29, v28
	s_nop 0
	v_fma_f32 v30, -v28, v29, 1.0
	v_fmac_f32_e32 v29, v30, v29
	v_div_scale_f32 v30, vcc, v33, v27, v33
	v_mul_f32_e32 v31, v30, v29
	v_fma_f32 v34, -v28, v31, v30
	v_fmac_f32_e32 v31, v34, v29
	v_fma_f32 v28, -v28, v31, v30
	v_div_fmas_f32 v28, v28, v29, v31
	v_div_fixup_f32 v27, v28, v27, v33
	v_div_scale_f32 v28, s[4:5], v26, v26, v32
	v_rcp_f32_e32 v29, v28
	s_nop 0
	v_fma_f32 v30, -v28, v29, 1.0
	v_fmac_f32_e32 v29, v30, v29
	v_div_scale_f32 v30, vcc, v32, v26, v32
	v_mul_f32_e32 v31, v30, v29
	v_fma_f32 v33, -v28, v31, v30
	v_fmac_f32_e32 v31, v33, v29
	v_fma_f32 v28, -v28, v31, v30
	v_div_fmas_f32 v28, v28, v29, v31
	v_div_fixup_f32 v26, v28, v26, v32
	v_pk_mul_f32 v[26:27], v[20:21], v[26:27]
	v_lshl_add_u64 v[28:29], v[4:5], 0, v[0:1]
	v_cvt_pk_bf16_f32 v20, v24, v25
	v_cvt_pk_bf16_f32 v21, v26, v27
	v_lshl_add_u64 v[24:25], v[6:7], 0, v[0:1]
	v_add_co_u32_e32 v28, vcc, s18, v28
	global_store_dwordx2 v[24:25], v[20:21], off
	s_nop 0
	v_addc_co_u32_e32 v29, vcc, 0, v29, vcc
	ds_read_b128 v[24:27], v23 offset:12672
	s_nop 0
	v_lshl_add_u64 v[4:5], v[4:5], 0, s[20:21]
	v_lshl_add_u64 v[6:7], v[6:7], 0, s[54:55]
	v_lshl_add_u64 v[18:19], v[18:19], 0, s[28:29]
	s_waitcnt vmcnt(3) lgkmcnt(0)
	v_mov_b32_e32 v20, v115
	v_mov_b32_e32 v30, v128
	v_mov_b32_e32 v31, v129
	v_mov_b32_e32 v28, v130
	v_mov_b32_e32 v29, v131
	s_cbranch_scc0 .Lcm_nopf
	v_lshl_add_u64 v[132:133], v[16:17], 0, v[0:1]
	v_lshl_add_u64 v[132:133], v[132:133], 0, s[48:49]
	global_load_dword v112, v[18:19], off offset:-64
	global_load_dwordx2 v[116:117], v[132:133], off offset:3008
	global_load_dwordx2 v[118:119], v[132:133], off offset:4032
	v_lshl_add_u64 v[132:133], v[12:13], 0, v[0:1]
	v_lshl_add_u64 v[132:133], v[132:133], 0, s[48:49]
	global_load_dword v113, v[18:19], off offset:-32
	global_load_dwordx2 v[120:121], v[132:133], off offset:3008
	global_load_dwordx2 v[122:123], v[132:133], off offset:4032
	v_lshl_add_u64 v[132:133], v[8:9], 0, v[0:1]
	v_lshl_add_u64 v[132:133], v[132:133], 0, s[48:49]
	global_load_dword v114, v[18:19], off
	global_load_dwordx2 v[124:125], v[132:133], off offset:3008
	global_load_dwordx2 v[126:127], v[132:133], off offset:4032
	v_lshl_add_u64 v[132:133], v[4:5], 0, v[0:1]
	v_lshl_add_u64 v[132:133], v[132:133], 0, s[48:49]
	global_load_dword v115, v[18:19], off offset:32
	global_load_dwordx2 v[128:129], v[132:133], off offset:3008
	global_load_dwordx2 v[130:131], v[132:133], off offset:4032
.Lcm_nopf:
	v_lshlrev_b32_e32 v32, 16, v30
	v_lshlrev_b32_e32 v21, 16, v28
	v_and_b32_e32 v23, 0xffff0000, v28
	v_mul_f32_e32 v28, 0xbfb8aa3b, v21
	v_exp_f32_e32 v34, v28
	v_mul_f32_e32 v28, 0xbfb8aa3b, v23
	v_exp_f32_e32 v35, v28
	v_and_b32_e32 v33, 0xffff0000, v30
	v_pk_add_f32 v[24:25], v[24:25], v[20:21] op_sel_hi:[1,0]
	s_nop 0
	v_pk_mul_f32 v[24:25], v[24:25], v[32:33]
	v_pk_add_f32 v[32:33], v[34:35], 1.0 op_sel_hi:[1,0]
	s_nop 0
	v_div_scale_f32 v28, s[4:5], v33, v33, v23
	v_rcp_f32_e32 v30, v28
	s_nop 0
	v_fma_f32 v34, -v28, v30, 1.0
	v_fmac_f32_e32 v30, v34, v30
	v_div_scale_f32 v34, vcc, v23, v33, v23
	v_mul_f32_e32 v35, v34, v30
	v_fma_f32 v36, -v28, v35, v34
	v_fmac_f32_e32 v35, v36, v30
	v_fma_f32 v28, -v28, v35, v34
	v_div_fmas_f32 v28, v28, v30, v35
	v_div_fixup_f32 v33, v28, v33, v23
	v_div_scale_f32 v23, s[4:5], v32, v32, v21
	v_rcp_f32_e32 v28, v23
	s_nop 0
	v_fma_f32 v30, -v23, v28, 1.0
	v_fmac_f32_e32 v28, v30, v28
	v_div_scale_f32 v30, vcc, v21, v32, v21
	v_mul_f32_e32 v34, v30, v28
	v_fma_f32 v35, -v23, v34, v30
	v_fmac_f32_e32 v34, v35, v28
	v_fma_f32 v23, -v23, v34, v30
	v_div_fmas_f32 v23, v23, v28, v34
	v_div_fixup_f32 v32, v23, v32, v21
	v_lshlrev_b32_e32 v23, 16, v29
	v_pk_mul_f32 v[24:25], v[24:25], v[32:33]
	v_and_b32_e32 v32, 0xffff0000, v29
	v_mul_f32_e32 v21, 0xbfb8aa3b, v23
	v_exp_f32_e32 v28, v21
	v_pk_add_f32 v[20:21], v[26:27], v[20:21] op_sel_hi:[1,0]
	v_mul_f32_e32 v26, 0xbfb8aa3b, v32
	v_exp_f32_e32 v29, v26
	v_lshlrev_b32_e32 v30, 16, v31
	v_and_b32_e32 v31, 0xffff0000, v31
	v_pk_mul_f32 v[20:21], v[20:21], v[30:31]
	v_pk_add_f32 v[26:27], v[28:29], 1.0 op_sel_hi:[1,0]
	s_nop 0
	v_div_scale_f32 v28, s[4:5], v27, v27, v32
	v_rcp_f32_e32 v29, v28
	s_nop 0
	v_fma_f32 v30, -v28, v29, 1.0
	v_fmac_f32_e32 v29, v30, v29
	v_div_scale_f32 v30, vcc, v32, v27, v32
	v_mul_f32_e32 v31, v30, v29
	v_fma_f32 v33, -v28, v31, v30
	v_fmac_f32_e32 v31, v33, v29
	v_fma_f32 v28, -v28, v31, v30
	v_div_fmas_f32 v28, v28, v29, v31
	v_div_fixup_f32 v27, v28, v27, v32
	v_div_scale_f32 v28, s[4:5], v26, v26, v23
	v_rcp_f32_e32 v29, v28
	s_nop 0
	v_fma_f32 v30, -v28, v29, 1.0
	v_fmac_f32_e32 v29, v30, v29
	v_div_scale_f32 v30, vcc, v23, v26, v23
	v_mul_f32_e32 v31, v30, v29
	v_fma_f32 v32, -v28, v31, v30
	v_fmac_f32_e32 v31, v32, v29
	v_fma_f32 v28, -v28, v31, v30
	v_div_fmas_f32 v28, v28, v29, v31
	v_div_fixup_f32 v26, v28, v26, v23
	v_pk_mul_f32 v[26:27], v[20:21], v[26:27]
	v_cvt_pk_bf16_f32 v20, v24, v25
	v_cvt_pk_bf16_f32 v21, v26, v27
	v_lshl_add_u64 v[24:25], v[2:3], 0, v[0:1]
	v_lshl_add_u64 v[2:3], v[2:3], 0, s[54:55]
	global_store_dwordx2 v[24:25], v[20:21], off
	s_cbranch_scc1 .LBB0_158
	s_waitcnt lgkmcnt(0)
	s_barrier

; DI u32x2 pack4(f32x4 v) { u32x2 r = {cvtpk(v[0], v[1]), cvtpk(v[2], v[3])}; return r; }
; DI void phase_mix(KP p, int l, char* lds) {
;     ...
;       bf16_t* yo = YD + rbase * 256 + nt * 128;
;       gemm_tile(Ap, K, Bp, K, K, lds, [&](int m, int n, f32x4 v) {
;         f32x4 o = {v[0] * sc, v[1] * sc, v[2] * sc, v[3] * sc};
;         *(u32x2*)(yo + (size_t)m * 256 + n) = pack4(o); });
;       asm volatile("s_waitcnt vmcnt(0)" ::: "memory");
;       __syncthreads();
;       if (tid0 == 0) {
;         __builtin_amdgcn_fence(__ATOMIC_RELEASE, "agent");
;         asm volatile("s_waitcnt vmcnt(0)" ::: "memory");
;         __hip_atomic_fetch_add(&cnt[b * 18 + (isl ? mt : 16 + mt)], 1u, __ATOMIC_RELAXED, __HIP_MEMORY_SCOPE_AGENT);
;       }
.LBB0_177:
	ds_read_b128 v[4:7], v0
	v_lshl_add_u64 v[8:9], v[2:3], 0, s[50:51]
	s_mov_b32 s2, 0x14f76000
	s_add_u32 s50, s50, 0x4000
	s_addc_u32 s51, s51, 0
	s_waitcnt lgkmcnt(0)
	v_pk_mul_f32 v[4:5], s[40:41], v[4:5]
	v_pk_mul_f32 v[6:7], s[40:41], v[6:7]
	v_cvt_pk_bf16_f32 v4, v4, v5
	v_cvt_pk_bf16_f32 v5, v6, v7
	v_add_co_u32_e32 v6, vcc, 0x14f75000, v8
	s_cmp_lg_u32 s50, 0x10000
	s_nop 0
	v_addc_co_u32_e32 v7, vcc, 0, v9, vcc
	global_store_dwordx2 v[6:7], v[4:5], off offset:256
	ds_read_b128 v[4:7], v0 offset:4224
	s_waitcnt lgkmcnt(0)
	v_pk_mul_f32 v[4:5], s[40:41], v[4:5]
	v_pk_mul_f32 v[6:7], s[40:41], v[6:7]
	v_cvt_pk_bf16_f32 v4, v4, v5
	v_cvt_pk_bf16_f32 v5, v6, v7
	v_add_co_u32_e32 v6, vcc, s2, v8
	s_mov_b32 s2, 0x14f77000
	s_nop 0
	v_addc_co_u32_e32 v7, vcc, 0, v9, vcc
	global_store_dwordx2 v[6:7], v[4:5], off offset:256
	ds_read_b128 v[4:7], v0 offset:8448
	s_waitcnt lgkmcnt(0)
	v_pk_mul_f32 v[4:5], s[40:41], v[4:5]
	v_pk_mul_f32 v[6:7], s[40:41], v[6:7]
	v_cvt_pk_bf16_f32 v4, v4, v5
	v_cvt_pk_bf16_f32 v5, v6, v7
	v_add_co_u32_e32 v6, vcc, s2, v8
	s_mov_b32 s2, 0x14f78000
	s_nop 0
	v_addc_co_u32_e32 v7, vcc, 0, v9, vcc
	global_store_dwordx2 v[6:7], v[4:5], off offset:256
	ds_read_b128 v[4:7], v0 offset:12672
	v_add_u32_e32 v0, 0x4200, v0
	s_waitcnt lgkmcnt(0)
	v_pk_mul_f32 v[4:5], s[40:41], v[4:5]
	v_pk_mul_f32 v[6:7], s[40:41], v[6:7]
	v_cvt_pk_bf16_f32 v4, v4, v5
	v_cvt_pk_bf16_f32 v5, v6, v7
	v_add_co_u32_e32 v6, vcc, s2, v8
	s_nop 1
	v_addc_co_u32_e32 v7, vcc, 0, v9, vcc
	global_store_dwordx2 v[6:7], v[4:5], off offset:256
	s_cbranch_scc1 .LBB0_177
	s_waitcnt lgkmcnt(0)
	s_barrier
	s_waitcnt vmcnt(0)
	s_barrier
	s_and_saveexec_b64 s[18:19], s[64:65]
	s_cbranch_execz .LBB0_125
	s_or_b32 s20, s34, 16
	s_mul_i32 s2, s4, 18
	s_and_b64 s[4:5], s[36:37], exec
	s_cselect_b32 s4, s34, s20
	s_add_i32 s4, s2, s4
	s_ashr_i32 s5, s4, 31
	s_lshl_b64 s[4:5], s[4:5], 2
	v_readlane_b32 s2, v255, 43
	s_add_u32 s4, s2, s4
	v_readlane_b32 s2, v255, 44
	s_addc_u32 s5, s2, s5
	buffer_wbl2 sc1
	s_waitcnt vmcnt(0)
	s_waitcnt vmcnt(0)
	v_mov_b64_e32 v[2:3], s[4:5]
	global_atomic_add v[2:3], v197, off
	s_branch .LBB0_125

; DI unsigned cvtpk(float lo, float hi) { f32x2 v = {lo, hi}; bf16x2_t b = __builtin_convertvector(v, bf16x2_t); return __builtin_bit_cast(unsigned, b); }
; DI float bflo(unsigned u) { return __uint_as_float(u << 16); }
; DI float bfhi(unsigned u) { return __uint_as_float(u & 0xffff0000u); }
; DI void phase_feat_c(KP p, int l) {
;     ...
;     for (int task = gw; task < NB * 256 * 4; task += nw) {
;       const int row = task >> 2, k8 = (task & 3) * 512 + lane * 8;
;       const bf16_t* fr = FT + (size_t)row * 4096;
;       const bool cosp = k8 < 1024;
;       const int f0 = cosp ? k8 : 2048 + (k8 - 1024);
;       const int mi = cosp ? 2048 - k8 : 4096 - (k8 - 1024);
;       const u32x4 fw = *(const u32x4*)(fr + f0), ml = *(const u32x4*)(fr + mi - 8);
;       const float m0v = bflo((unsigned)fr[(mi < 4096) ? mi : 4095]);
;       const float f[8] = {bflo(fw.x), bfhi(fw.x), bflo(fw.y), bfhi(fw.y), bflo(fw.z), bfhi(fw.z), bflo(fw.w), bfhi(fw.w)};
;       const float mr[8] = {m0v, bfhi(ml.w), bflo(ml.w), bfhi(ml.z), bflo(ml.z), bfhi(ml.y), bflo(ml.y), bfhi(ml.x)};
;       float v[8];
; #pragma unroll
;       for (int e = 0; e < 8; ++e) {
;         const int k = k8 + e;
;         if (k < 1024) v[e] = f[e] + ((k == 0) ? 0.f : mr[e]);
;         else if (k == 1024) v[e] = bflo((unsigned)fr[1024]);
;         else v[e] = f[e] - mr[e];
;       }
;       u32x4 o = {cvtpk(v[0], v[1]), cvtpk(v[2], v[3]), cvtpk(v[4], v[5]), cvtpk(v[6], v[7])};
;       *(u32x4*)(FTF + (size_t)row * 2048 + k8) = o;
;     }
.LBB0_185:
	s_or_b64 exec, exec, s[34:35]
	v_and_b32_e32 v21, 0xffff0000, v5
	v_lshlrev_b32_e32 v5, 16, v5
	v_lshlrev_b32_e32 v12, 16, v7
	v_and_b32_e32 v22, 0xffff0000, v4
	v_cndmask_b32_e64 v5, -v5, v5, vcc
	v_and_b32_e32 v6, 0xffff0000, v6
	v_and_b32_e32 v7, 0xffff0000, v7
	v_and_b32_e32 v23, 0xffff0000, v3
	v_lshlrev_b32_e32 v3, 16, v3
	v_and_b32_e32 v2, 0xffff0000, v2
	v_cndmask_b32_e64 v21, -v21, v21, vcc
	v_add_f32_e32 v5, v5, v12
	v_cndmask_b32_e64 v12, -v22, v22, vcc
	v_lshlrev_b32_e32 v13, 16, v8
	v_and_b32_e32 v8, 0xffff0000, v8
	v_lshlrev_b32_e32 v20, 16, v9
	v_and_b32_e32 v9, 0xffff0000, v9
	v_lshlrev_b32_e32 v4, 16, v4
	v_add_f32_e32 v6, v21, v6
	v_add_f32_e32 v7, v12, v7
	v_cndmask_b32_e64 v12, -v23, v23, vcc
	v_cndmask_b32_e64 v3, -v3, v3, vcc
	v_cndmask_b32_e64 v2, -v2, v2, vcc
	v_readlane_b32 s2, v254, 37
	v_cndmask_b32_e64 v4, -v4, v4, vcc
	v_add_f32_e32 v8, v12, v8
	v_add_f32_e32 v12, v3, v20
	v_add_f32_e32 v9, v2, v9
	v_cvt_pk_bf16_f32 v2, v0, v6
	v_cvt_pk_bf16_f32 v3, v5, v7
	v_lshlrev_b64 v[6:7], 12, v[10:11]
	v_add_u32_e32 v18, s2, v18
	s_movk_i32 s2, 0x3fff
	v_add_f32_e32 v4, v4, v13
	v_lshl_add_u64 v[6:7], s[36:37], 0, v[6:7]
	v_lshlrev_b32_e32 v0, 1, v19
	v_cmp_lt_i32_e32 vcc, s2, v18
	v_readlane_b32 s2, v254, 48
	v_cvt_pk_bf16_f32 v4, v4, v8
	v_cvt_pk_bf16_f32 v5, v12, v9
	v_lshl_add_u64 v[6:7], v[6:7], 0, v[0:1]
	s_or_b64 s[42:43], vcc, s[42:43]
	v_add_u32_e32 v17, s2, v17
	global_store_dwordx4 v[6:7], v[2:5], off
	s_andn2_b64 exec, exec, s[42:43]
	s_cbranch_execz .LBB0_194
.LBB0_186:
	v_ashrrev_i32_e32 v10, 2, v18
	v_ashrrev_i32_e32 v11, 31, v10
	v_and_b32_e32 v20, 0x600, v17
	v_lshlrev_b64 v[2:3], 13, v[10:11]
	v_lshl_add_u64 v[12:13], s[20:21], 0, v[2:3]
	v_cmp_gt_u32_e32 vcc, s15, v20
	v_mov_b32_e32 v2, 0x1400
	v_mov_b32_e32 v3, 0x800
	v_or_b32_e32 v19, v20, v16
	v_and_b32_e32 v0, 0x400, v17
	v_cndmask_b32_e32 v2, v2, v3, vcc
	v_sub_u32_e32 v6, v2, v19
	v_add_lshl_u32 v0, v19, v0, 1
	v_lshl_add_u64 v[2:3], v[12:13], 0, v[0:1]
	v_lshlrev_b32_e32 v0, 1, v6
	v_lshl_add_u64 v[4:5], v[12:13], 0, v[0:1]
	v_min_u32_e32 v0, 0xfff, v6
	v_add_co_u32_e64 v4, s[40:41], -16, v4
	v_lshlrev_b32_e32 v0, 1, v0
	s_nop 0
	v_addc_co_u32_e64 v5, s[40:41], -1, v5, s[40:41]
	v_lshl_add_u64 v[6:7], v[12:13], 0, v[0:1]
	global_load_ushort v0, v[6:7], off
	s_nop 0
	global_load_dwordx4 v[6:9], v[2:3], off
	s_nop 0
	global_load_dwordx4 v[2:5], v[4:5], off
	s_movk_i32 s2, 0x3ff
	v_cmp_lt_u32_e64 s[40:41], s2, v20
	s_waitcnt vmcnt(0) lgkmcnt(0)
	v_lshlrev_b32_e32 v20, 16, v0
	v_lshlrev_b32_e32 v21, 16, v6
	s_and_saveexec_b64 s[34:35], s[40:41]
	s_xor_b64 s[46:47], exec, s[34:35]
	s_cbranch_execz .LBB0_192
	v_cmp_ne_u32_e64 s[40:41], s15, v19
	s_and_saveexec_b64 s[34:35], s[40:41]
	s_xor_b64 s[34:35], exec, s[34:35]
	v_sub_f32_e32 v0, v21, v20
	s_andn2_saveexec_b64 s[34:35], s[34:35]
	s_cbranch_execz .LBB0_191
	global_load_ushort v0, v[12:13], off offset:2048
	s_waitcnt vmcnt(0) lgkmcnt(0)
	v_lshlrev_b32_e32 v0, 16, v0

; DI unsigned cvtpk(float lo, float hi) { f32x2 v = {lo, hi}; bf16x2_t b = __builtin_convertvector(v, bf16x2_t); return __builtin_bit_cast(unsigned, b); }
; DI float bflo(unsigned u) { return __uint_as_float(u << 16); }
; DI float bfhi(unsigned u) { return __uint_as_float(u & 0xffff0000u); }
; DI f32x4 unpack4(u32x2 v) { f32x4 r = {bflo(v.x), bfhi(v.x), bflo(v.y), bfhi(v.y)}; return r; }
; DI void phase_feat_c(KP p, int l) {
;     ...
;   for (int task = gw; task < M / 4; task += nw) {
;     const int r = task * 4 + sub; const int b = r / T, t = r % T;
;     const unsigned krp = *(const unsigned*)(P + (size_t)r * NIN + O_KR + 2 * u);
;     const int posm = (u & 8) ? (t & 63) : (t >> 6); const float sgm = (u & 4) ? 1.f : -1.f;
;     const f32x4 csm = *(const f32x4*)(rm + (posm * 8 + 2 * (u & 3)) * 2);
;     const f32x4 gq4 = *(const f32x4*)(p->mla_qn + l * 96 + 4 * u), gk4 = *(const f32x4*)(p->mla_kn + l * 96 + 4 * u);
;     const f32x2 gq2 = *(const f32x2*)(p->mla_qn + l * 96 + 64 + 2 * u), gk2 = *(const f32x2*)(p->mla_kn + l * 96 + 64 + 2 * u);
; #pragma unroll
;     for (int hh = 0; hh < 8; ++hh) {
;       const bool isq = hh < 4; const int hd = hh & 3;
;       f32x4 v; float ra, rb;
;       if (isq) {
;         v = unpack4(*(const u32x2*)(q1r + (size_t)r * 384 + 96 * hd + 4 * u));
;         const unsigned rr = *(const unsigned*)(q1r + (size_t)r * 384 + 96 * hd + 64 + 2 * u); ra = bflo(rr); rb = bfhi(rr);
;       } else {
;         v = unpack4(*(const u32x2*)(krw + (size_t)r * 256 + 64 * hd + 4 * u));
;         ra = bflo(krp); rb = bfhi(krp);
;       }
;       float ss = red16(v[0] * v[0] + v[1] * v[1] + v[2] * v[2] + v[3] * v[3] + ra * ra + rb * rb);
;       const float rs = rsqrtf(ss * (1.f / 96.f) + 1e-6f);
;       const f32x4 g = isq ? gq4 : gk4; const f32x2 g2 = isq ? gq2 : gk2;
; #pragma unroll
;       for (int e = 0; e < 4; ++e) v[e] = v[e] * rs * g[e];
;       ra = ra * rs * g2[0]; rb = rb * rs * g2[1];
;       if (t < SEQ) rope2(ra, rb, sgm, csm);
;       if (isq) {
;         const float cq = 1.4426950408889634f / __builtin_sqrtf(96.f);
; #pragma unroll
;         for (int e = 0; e < 4; ++e) v[e] *= cq;
;         ra *= cq; rb *= cq;
;       }
;       bf16_t* dst = (isq ? QA : KA) + (((size_t)b * 4 + hd) * T + t) * 96;
;       *(u32x2*)(dst + 4 * u) = pack4(v);
;       *(unsigned*)(dst + 64 + 2 * u) = cvtpk(ra, rb);
.LBB0_196:
	s_or_b64 exec, exec, s[18:19]
	s_movk_i32 s2, 0xc0
	v_mov_b32_e32 v35, v34
	v_mad_u64_u32 v[6:7], s[18:19], v10, s2, 0
	v_pk_mul_f32 v[8:9], v[34:35], v[32:33]
	v_add_u32_e32 v7, v7, v11
	v_pk_mul_f32 v[2:3], v[2:3], v[8:9]
	v_pk_mul_f32 v[8:9], v[34:35], v[12:13]
	v_readlane_b32 s2, v254, 37
	v_pk_mul_f32 v[4:5], v[4:5], v[8:9]
	v_lshl_add_u64 v[6:7], s[50:51], 0, v[6:7]
	v_mov_b32_e32 v29, v1
	v_add_u32_e32 v50, s2, v50
	s_movk_i32 s2, 0x23ff
	v_cvt_pk_bf16_f32 v2, v2, v3
	v_cvt_pk_bf16_f32 v3, v4, v5
	v_lshl_add_u64 v[4:5], v[6:7], 0, v[28:29]
	v_cmp_lt_i32_e32 vcc, s2, v50
	v_readlane_b32 s2, v254, 50
	global_store_dwordx2 v[4:5], v[2:3], off
	v_cvt_pk_bf16_f32 v4, v30, v31
	v_lshl_add_u64 v[2:3], v[6:7], 0, v[0:1]
	s_or_b64 s[56:57], vcc, s[56:57]
	v_add_u32_e32 v26, s2, v26
	global_store_dword v[2:3], v4, off offset:128
	s_andn2_b64 exec, exec, s[56:57]
	s_cbranch_execz .LBB0_213
.LBB0_197:
	v_mov_b64_e32 v[2:3], s[46:47]
	v_mad_i64_i32 v[2:3], s[18:19], v26, s58, v[2:3]
	v_mov_b32_e32 v29, v1
	v_lshl_add_u64 v[38:39], v[2:3], 0, v[0:1]
	v_lshl_add_u64 v[40:41], v[2:3], 0, v[28:29]
	global_load_dword v33, v[38:39], off offset:128
	global_load_dwordx2 v[44:45], v[40:41], off
	s_mov_b32 s2, 0x38e38e39
	v_mul_hi_i32 v2, v26, s2
	v_lshrrev_b32_e32 v3, 31, v2
	v_ashrrev_i32_e32 v2, 9, v2
	v_add_u32_e32 v27, v2, v3
	v_mul_i32_i24_e32 v2, 0x900, v27
	v_sub_u32_e32 v32, v26, v2
	v_and_b32_e32 v2, 63, v32
	v_ashrrev_i32_e32 v3, 6, v32
	v_cndmask_b32_e64 v2, v2, v3, s[40:41]
	v_lshl_or_b32 v2, v2, 4, v51
	v_ashrrev_i32_e32 v3, 31, v2
	v_lshl_add_u64 v[6:7], v[2:3], 2, s[48:49]
	v_mov_b64_e32 v[2:3], s[4:5]
	v_mad_i64_i32 v[2:3], s[18:19], v26, s11, v[2:3]
	v_lshl_add_u64 v[2:3], v[2:3], 0, v[0:1]
	v_add_co_u32_e32 v34, vcc, 0x60b5000, v2
	s_mov_b32 s2, 0x800000
	s_nop 0
	v_addc_co_u32_e32 v35, vcc, 0, v3, vcc
	global_load_dwordx4 v[10:13], v[16:17], off
	global_load_dwordx4 v[2:5], v[18:19], off
	global_load_dwordx2 v[42:43], v[20:21], off offset:256
	global_load_dwordx2 v[30:31], v[22:23], off offset:256
	s_nop 0
	global_load_dwordx4 v[6:9], v[6:7], off
	s_nop 0
	global_load_dword v52, v[34:35], off offset:896
	s_waitcnt vmcnt(0) lgkmcnt(0)
	v_and_b32_e32 v49, 0xffff0000, v33
	v_lshlrev_b32_e32 v36, 16, v44
	v_and_b32_e32 v37, 0xffff0000, v44
	v_lshlrev_b32_e32 v34, 16, v45
	v_and_b32_e32 v35, 0xffff0000, v45
	v_pk_mul_f32 v[54:55], v[36:37], v[36:37]
	v_lshlrev_b32_e32 v48, 16, v33
	v_pk_mul_f32 v[46:47], v[34:35], v[34:35]
	v_add_f32_e32 v33, v54, v55
	v_add_f32_e32 v33, v46, v33
	v_pk_mul_f32 v[44:45], v[48:49], v[48:49]
	v_add_f32_e32 v33, v47, v33
	v_add_f32_e32 v33, v44, v33
	v_add_f32_e32 v33, v45, v33
	s_nop 1
	v_add_f32_dpp v33, v33, v33 quad_perm:[1,0,3,2] row_mask:0xf bank_mask:0xf bound_ctrl:1
	s_nop 1
	v_add_f32_dpp v33, v33, v33 quad_perm:[2,3,0,1] row_mask:0xf bank_mask:0xf bound_ctrl:1
	s_nop 1
	v_add_f32_dpp v33, v33, v33 row_ror:4 row_mask:0xf bank_mask:0xf bound_ctrl:1
	s_nop 1
	v_add_f32_dpp v33, v33, v33 row_ror:8 row_mask:0xf bank_mask:0xf bound_ctrl:1
	v_fmamk_f32 v33, v33, 0x3c2aaaab, v198
	v_mul_f32_e32 v44, 0x4b800000, v33
	v_cmp_gt_f32_e64 s[42:43], s2, v33
	s_movk_i32 s2, 0x800
	v_cmp_gt_i32_e32 vcc, s2, v32
	v_cndmask_b32_e64 v33, v33, v44, s[42:43]
	v_rsq_f32_e32 v33, v33
	s_nop 0
	v_mul_f32_e32 v44, 0x45800000, v33
	v_cndmask_b32_e64 v46, v33, v44, s[42:43]
	v_pk_mul_f32 v[44:45], v[46:47], v[48:49] op_sel_hi:[0,1]
	v_pk_mul_f32 v[44:45], v[42:43], v[44:45]
	s_and_saveexec_b64 s[18:19], vcc
	s_cbranch_execz .LBB0_199
	v_and_b32_e32 v47, 64, v204
	v_xor_b32_e32 v33, 4, v204
	v_add_u32_e32 v47, 64, v47
	v_cmp_lt_i32_e64 s[42:43], v33, v47
	v_mov_b32_e32 v56, v7
	v_mov_b32_e32 v57, v9
	v_cndmask_b32_e64 v33, v204, v33, s[42:43]
	v_lshlrev_b32_e32 v33, 2, v33
	ds_bpermute_b32 v48, v33, v44
	ds_bpermute_b32 v49, v33, v45
	v_mov_b32_e32 v54, v6
	v_mov_b32_e32 v55, v8
	s_waitcnt lgkmcnt(0)
	v_pk_mul_f32 v[48:49], v[14:15], v[48:49]
	s_nop 0
	v_pk_mul_f32 v[48:49], v[56:57], v[48:49]
	s_nop 0
	v_pk_fma_f32 v[44:45], v[54:55], v[44:45], v[48:49]
.LBB0_199:
	s_or_b64 exec, exec, s[18:19]
	v_mov_b32_e32 v47, v46
	v_pk_mul_f32 v[36:37], v[46:47], v[36:37]
	v_pk_mul_f32 v[34:35], v[46:47], v[34:35]
	v_ashrrev_i32_e32 v33, 31, v32
	v_pk_mul_f32 v[36:37], v[10:11], v[36:37]
	v_pk_mul_f32 v[34:35], v[12:13], v[34:35]
	s_mov_b32 s2, 0x3e16c73f
	v_mul_hi_i32_i24_e32 v47, 0x2400, v27
	v_mul_i32_i24_e32 v46, 0x2400, v27
	v_pk_mul_f32 v[44:45], v[44:45], s[2:3] op_sel_hi:[1,0]
	v_pk_mul_f32 v[34:35], v[34:35], s[2:3] op_sel_hi:[1,0]
	v_pk_mul_f32 v[36:37], v[36:37], s[2:3] op_sel_hi:[1,0]
	v_lshl_add_u64 v[32:33], v[46:47], 0, v[32:33]
	s_movk_i32 s2, 0xc0
	v_mov_b64_e32 v[46:47], s[54:55]
	v_mul_lo_u32 v53, v33, s2
	v_mad_u64_u32 v[46:47], s[18:19], v32, s2, v[46:47]
	v_add_u32_e32 v47, v53, v47
	v_cvt_pk_bf16_f32 v36, v36, v37
	v_cvt_pk_bf16_f32 v37, v34, v35
	v_lshl_add_u64 v[34:35], v[46:47], 0, v[28:29]
	global_store_dwordx2 v[34:35], v[36:37], off
	v_cvt_pk_bf16_f32 v27, v44, v45
	v_lshl_add_u64 v[34:35], v[46:47], 0, v[0:1]
	global_store_dword v[34:35], v27, off offset:128
	global_load_dword v29, v[38:39], off offset:320
	global_load_dwordx2 v[44:45], v[40:41], off offset:192
	s_mov_b32 s2, 0x800000
	s_waitcnt vmcnt(0) lgkmcnt(0)
	v_and_b32_e32 v49, 0xffff0000, v29
	v_lshlrev_b32_e32 v36, 16, v44
	v_and_b32_e32 v37, 0xffff0000, v44
	v_lshlrev_b32_e32 v34, 16, v45
	v_and_b32_e32 v35, 0xffff0000, v45
	v_pk_mul_f32 v[54:55], v[36:37], v[36:37]
	v_pk_mul_f32 v[46:47], v[34:35], v[34:35]
	v_add_f32_e32 v27, v54, v55
	v_lshlrev_b32_e32 v48, 16, v29
	v_add_f32_e32 v27, v46, v27
	v_pk_mul_f32 v[44:45], v[48:49], v[48:49]
	v_add_f32_e32 v27, v47, v27
	v_add_f32_e32 v27, v44, v27
	v_add_f32_e32 v27, v45, v27
	s_nop 1
	v_add_f32_dpp v27, v27, v27 quad_perm:[1,0,3,2] row_mask:0xf bank_mask:0xf bound_ctrl:1
	s_nop 1
	v_add_f32_dpp v27, v27, v27 quad_perm:[2,3,0,1] row_mask:0xf bank_mask:0xf bound_ctrl:1
	s_nop 1
	v_add_f32_dpp v27, v27, v27 row_ror:4 row_mask:0xf bank_mask:0xf bound_ctrl:1
	s_nop 1
	v_add_f32_dpp v27, v27, v27 row_ror:8 row_mask:0xf bank_mask:0xf bound_ctrl:1
	v_fmamk_f32 v27, v27, 0x3c2aaaab, v198
	v_mul_f32_e32 v29, 0x4b800000, v27
	v_cmp_gt_f32_e64 s[42:43], s2, v27
	s_nop 1
	v_cndmask_b32_e64 v27, v27, v29, s[42:43]
	v_rsq_f32_e32 v27, v27
	s_nop 0
	v_mul_f32_e32 v29, 0x45800000, v27
	v_cndmask_b32_e64 v46, v27, v29, s[42:43]
	v_pk_mul_f32 v[44:45], v[46:47], v[48:49] op_sel_hi:[0,1]
	v_pk_mul_f32 v[44:45], v[42:43], v[44:45]
	s_and_saveexec_b64 s[18:19], vcc
	s_cbranch_execz .LBB0_201
; DI unsigned cvtpk(float lo, float hi) { f32x2 v = {lo, hi}; bf16x2_t b = __builtin_convertvector(v, bf16x2_t); return __builtin_bit_cast(unsigned, b); }
; DI float bflo(unsigned u) { return __uint_as_float(u << 16); }
; DI float bfhi(unsigned u) { return __uint_as_float(u & 0xffff0000u); }
; DI f32x4 unpack4(u32x2 v) { f32x4 r = {bflo(v.x), bfhi(v.x), bflo(v.y), bfhi(v.y)}; return r; }
; DI u32x2 pack4(f32x4 v) { u32x2 r = {cvtpk(v[0], v[1]), cvtpk(v[2], v[3])}; return r; }
; DI float red16(float v) { v += dpp_f(v, 0); v += dpp_f(v, 1); v += dpp_f(v, 2); v += dpp_f(v, 3); return v; }
; DI void phase_feat_c(KP p, int l) {
;     ...
; #pragma unroll
;     for (int hh = 0; hh < 8; ++hh) {
;       const bool isq = hh < 4; const int hd = hh & 3;
;       f32x4 v; float ra, rb;
;       if (isq) {
;         v = unpack4(*(const u32x2*)(q1r + (size_t)r * 384 + 96 * hd + 4 * u));
;         const unsigned rr = *(const unsigned*)(q1r + (size_t)r * 384 + 96 * hd + 64 + 2 * u); ra = bflo(rr); rb = bfhi(rr);
;       } else {
;         v = unpack4(*(const u32x2*)(krw + (size_t)r * 256 + 64 * hd + 4 * u));
;         ra = bflo(krp); rb = bfhi(krp);
;       }
;       float ss = red16(v[0] * v[0] + v[1] * v[1] + v[2] * v[2] + v[3] * v[3] + ra * ra + rb * rb);
;       const float rs = rsqrtf(ss * (1.f / 96.f) + 1e-6f);
;       const f32x4 g = isq ? gq4 : gk4; const f32x2 g2 = isq ? gq2 : gk2;
; #pragma unroll
;       for (int e = 0; e < 4; ++e) v[e] = v[e] * rs * g[e];
;       ra = ra * rs * g2[0]; rb = rb * rs * g2[1];
;       if (t < SEQ) rope2(ra, rb, sgm, csm);
;       if (isq) {
;         const float cq = 1.4426950408889634f / __builtin_sqrtf(96.f);
; #pragma unroll
;         for (int e = 0; e < 4; ++e) v[e] *= cq;
;         ra *= cq; rb *= cq;
;       }
;       bf16_t* dst = (isq ? QA : KA) + (((size_t)b * 4 + hd) * T + t) * 96;
;       *(u32x2*)(dst + 4 * u) = pack4(v);
;       *(unsigned*)(dst + 64 + 2 * u) = cvtpk(ra, rb);
	v_and_b32_e32 v29, 64, v204
	v_xor_b32_e32 v27, 4, v204
	v_add_u32_e32 v29, 64, v29
	v_cmp_lt_i32_e64 s[42:43], v27, v29
	v_mov_b32_e32 v56, v7
	v_mov_b32_e32 v57, v9
	v_cndmask_b32_e64 v27, v204, v27, s[42:43]
	v_lshlrev_b32_e32 v27, 2, v27
	ds_bpermute_b32 v48, v27, v44
	ds_bpermute_b32 v49, v27, v45
	v_mov_b32_e32 v54, v6
	v_mov_b32_e32 v55, v8
	s_waitcnt lgkmcnt(0)
	v_pk_mul_f32 v[48:49], v[14:15], v[48:49]
	s_nop 0
	v_pk_mul_f32 v[48:49], v[56:57], v[48:49]
	s_nop 0
	v_pk_fma_f32 v[44:45], v[54:55], v[44:45], v[48:49]
.LBB0_201:
	s_or_b64 exec, exec, s[18:19]
	v_mov_b32_e32 v47, v46
	v_pk_mul_f32 v[36:37], v[46:47], v[36:37]
	v_pk_mul_f32 v[34:35], v[46:47], v[34:35]
	v_pk_mul_f32 v[36:37], v[10:11], v[36:37]
	v_pk_mul_f32 v[34:35], v[12:13], v[34:35]
	s_mov_b32 s2, 0x3e16c73f
	s_mov_b64 s[18:19], 0x900
	v_pk_mul_f32 v[44:45], v[44:45], s[2:3] op_sel_hi:[1,0]
	v_pk_mul_f32 v[46:47], v[34:35], s[2:3] op_sel_hi:[1,0]
	v_pk_mul_f32 v[36:37], v[36:37], s[2:3] op_sel_hi:[1,0]
	v_lshl_add_u64 v[34:35], v[32:33], 0, s[18:19]
	s_movk_i32 s2, 0xc0
	v_mov_b64_e32 v[48:49], s[54:55]
	v_mul_lo_u32 v35, v35, s2
	v_mad_u64_u32 v[48:49], s[18:19], v34, s2, v[48:49]
	v_add_u32_e32 v49, v35, v49
	v_mov_b32_e32 v29, v1
	v_cvt_pk_bf16_f32 v36, v36, v37
	v_cvt_pk_bf16_f32 v37, v46, v47
	v_lshl_add_u64 v[46:47], v[48:49], 0, v[28:29]
	global_store_dwordx2 v[46:47], v[36:37], off
	v_cvt_pk_bf16_f32 v27, v44, v45
	v_lshl_add_u64 v[36:37], v[48:49], 0, v[0:1]
	global_store_dword v[36:37], v27, off offset:128
	global_load_dword v27, v[38:39], off offset:512
	s_nop 0
	global_load_dwordx2 v[46:47], v[40:41], off offset:384
	s_mov_b32 s2, 0x800000
	s_waitcnt vmcnt(0) lgkmcnt(0)
	v_and_b32_e32 v55, 0xffff0000, v27
	v_lshlrev_b32_e32 v44, 16, v46
	v_and_b32_e32 v45, 0xffff0000, v46
	v_lshlrev_b32_e32 v36, 16, v47
	v_and_b32_e32 v37, 0xffff0000, v47
	v_pk_mul_f32 v[56:57], v[44:45], v[44:45]
	v_lshlrev_b32_e32 v54, 16, v27
	v_pk_mul_f32 v[48:49], v[36:37], v[36:37]
	v_add_f32_e32 v27, v56, v57
	v_add_f32_e32 v27, v48, v27
	v_pk_mul_f32 v[46:47], v[54:55], v[54:55]
	v_add_f32_e32 v27, v49, v27
	v_add_f32_e32 v27, v46, v27
	v_add_f32_e32 v27, v47, v27
	s_nop 1
	v_add_f32_dpp v27, v27, v27 quad_perm:[1,0,3,2] row_mask:0xf bank_mask:0xf bound_ctrl:1
	s_nop 1
	v_add_f32_dpp v27, v27, v27 quad_perm:[2,3,0,1] row_mask:0xf bank_mask:0xf bound_ctrl:1
	s_nop 1
	v_add_f32_dpp v27, v27, v27 row_ror:4 row_mask:0xf bank_mask:0xf bound_ctrl:1
	s_nop 1
	v_add_f32_dpp v27, v27, v27 row_ror:8 row_mask:0xf bank_mask:0xf bound_ctrl:1
	v_fmamk_f32 v27, v27, 0x3c2aaaab, v198
	v_mul_f32_e32 v46, 0x4b800000, v27
	v_cmp_gt_f32_e64 s[42:43], s2, v27
	s_nop 1
	v_cndmask_b32_e64 v27, v27, v46, s[42:43]
	v_rsq_f32_e32 v27, v27
	s_nop 0
	v_mul_f32_e32 v46, 0x45800000, v27
	v_cndmask_b32_e64 v48, v27, v46, s[42:43]
	v_pk_mul_f32 v[46:47], v[48:49], v[54:55] op_sel_hi:[0,1]
	v_pk_mul_f32 v[46:47], v[42:43], v[46:47]
	s_and_saveexec_b64 s[18:19], vcc
	s_cbranch_execz .LBB0_203
	v_and_b32_e32 v49, 64, v204
	v_xor_b32_e32 v27, 4, v204
	v_add_u32_e32 v49, 64, v49
	v_cmp_lt_i32_e64 s[42:43], v27, v49
	v_mov_b32_e32 v58, v7
	v_mov_b32_e32 v59, v9
	v_cndmask_b32_e64 v27, v204, v27, s[42:43]
	v_lshlrev_b32_e32 v27, 2, v27
	ds_bpermute_b32 v54, v27, v46
	ds_bpermute_b32 v55, v27, v47
	v_mov_b32_e32 v56, v6
	v_mov_b32_e32 v57, v8
	s_waitcnt lgkmcnt(0)
	v_pk_mul_f32 v[54:55], v[14:15], v[54:55]
	s_nop 0
	v_pk_mul_f32 v[54:55], v[58:59], v[54:55]
	s_nop 0
	v_pk_fma_f32 v[46:47], v[56:57], v[46:47], v[54:55]
.LBB0_203:
	s_or_b64 exec, exec, s[18:19]
	v_mov_b32_e32 v49, v48
	v_pk_mul_f32 v[44:45], v[48:49], v[44:45]
	v_pk_mul_f32 v[36:37], v[48:49], v[36:37]
	v_pk_mul_f32 v[44:45], v[10:11], v[44:45]
	v_pk_mul_f32 v[36:37], v[12:13], v[36:37]
	s_mov_b32 s2, 0x3e16c73f
	s_mov_b64 s[18:19], 0x1200
	v_pk_mul_f32 v[46:47], v[46:47], s[2:3] op_sel_hi:[1,0]
	v_pk_mul_f32 v[48:49], v[36:37], s[2:3] op_sel_hi:[1,0]
	v_pk_mul_f32 v[44:45], v[44:45], s[2:3] op_sel_hi:[1,0]
	v_lshl_add_u64 v[36:37], v[32:33], 0, s[18:19]
	s_movk_i32 s2, 0xc0
	v_mov_b64_e32 v[54:55], s[54:55]
	v_mul_lo_u32 v37, v37, s2
	v_mad_u64_u32 v[54:55], s[18:19], v36, s2, v[54:55]
	v_add_u32_e32 v55, v37, v55
	v_cvt_pk_bf16_f32 v44, v44, v45
	v_cvt_pk_bf16_f32 v45, v48, v49
	v_lshl_add_u64 v[48:49], v[54:55], 0, v[28:29]
	global_store_dwordx2 v[48:49], v[44:45], off
	v_cvt_pk_bf16_f32 v27, v46, v47
	v_lshl_add_u64 v[44:45], v[54:55], 0, v[0:1]
	global_store_dword v[44:45], v27, off offset:128
	global_load_dword v27, v[38:39], off offset:704
	s_nop 0
	global_load_dwordx2 v[44:45], v[40:41], off offset:576
	s_mov_b32 s2, 0x800000
	s_waitcnt vmcnt(0) lgkmcnt(0)
	v_and_b32_e32 v47, 0xffff0000, v27
	v_lshlrev_b32_e32 v40, 16, v44
	v_and_b32_e32 v41, 0xffff0000, v44
	v_lshlrev_b32_e32 v38, 16, v45
	v_and_b32_e32 v39, 0xffff0000, v45
	v_pk_mul_f32 v[54:55], v[40:41], v[40:41]
	v_lshlrev_b32_e32 v46, 16, v27
	v_pk_mul_f32 v[48:49], v[38:39], v[38:39]
	v_add_f32_e32 v27, v54, v55
	v_add_f32_e32 v27, v48, v27
	v_pk_mul_f32 v[44:45], v[46:47], v[46:47]
	v_add_f32_e32 v27, v49, v27
	v_add_f32_e32 v27, v44, v27
	v_add_f32_e32 v27, v45, v27
	s_nop 1
	v_add_f32_dpp v27, v27, v27 quad_perm:[1,0,3,2] row_mask:0xf bank_mask:0xf bound_ctrl:1
	s_nop 1
	v_add_f32_dpp v27, v27, v27 quad_perm:[2,3,0,1] row_mask:0xf bank_mask:0xf bound_ctrl:1
	s_nop 1
	v_add_f32_dpp v27, v27, v27 row_ror:4 row_mask:0xf bank_mask:0xf bound_ctrl:1
	s_nop 1
	v_add_f32_dpp v27, v27, v27 row_ror:8 row_mask:0xf bank_mask:0xf bound_ctrl:1
	v_fmamk_f32 v27, v27, 0x3c2aaaab, v198
	v_mul_f32_e32 v29, 0x4b800000, v27
	v_cmp_gt_f32_e64 s[42:43], s2, v27
	s_nop 1
	v_cndmask_b32_e64 v27, v27, v29, s[42:43]
	v_rsq_f32_e32 v27, v27
	s_nop 0
	v_mul_f32_e32 v29, 0x45800000, v27
	v_cndmask_b32_e64 v44, v27, v29, s[42:43]
	v_pk_mul_f32 v[46:47], v[44:45], v[46:47] op_sel_hi:[0,1]
	v_pk_mul_f32 v[42:43], v[42:43], v[46:47]
	s_and_saveexec_b64 s[18:19], vcc
	s_cbranch_execz .LBB0_205
	v_and_b32_e32 v29, 64, v204
	v_xor_b32_e32 v27, 4, v204
	v_add_u32_e32 v29, 64, v29
	v_cmp_lt_i32_e64 s[42:43], v27, v29
	v_mov_b32_e32 v54, v7
	v_mov_b32_e32 v55, v9
	v_cndmask_b32_e64 v27, v204, v27, s[42:43]
	v_lshlrev_b32_e32 v27, 2, v27
	ds_bpermute_b32 v46, v27, v42
	ds_bpermute_b32 v47, v27, v43
	v_mov_b32_e32 v48, v6
	v_mov_b32_e32 v49, v8
	s_waitcnt lgkmcnt(0)
	v_pk_mul_f32 v[46:47], v[14:15], v[46:47]
	s_nop 0
	v_pk_mul_f32 v[46:47], v[54:55], v[46:47]
	s_nop 0
	v_pk_fma_f32 v[42:43], v[48:49], v[42:43], v[46:47]
; DI unsigned cvtpk(float lo, float hi) { f32x2 v = {lo, hi}; bf16x2_t b = __builtin_convertvector(v, bf16x2_t); return __builtin_bit_cast(unsigned, b); }
; DI float bflo(unsigned u) { return __uint_as_float(u << 16); }
; DI float bfhi(unsigned u) { return __uint_as_float(u & 0xffff0000u); }
; DI f32x4 unpack4(u32x2 v) { f32x4 r = {bflo(v.x), bfhi(v.x), bflo(v.y), bfhi(v.y)}; return r; }
; DI u32x2 pack4(f32x4 v) { u32x2 r = {cvtpk(v[0], v[1]), cvtpk(v[2], v[3])}; return r; }
; DI float red16(float v) { v += dpp_f(v, 0); v += dpp_f(v, 1); v += dpp_f(v, 2); v += dpp_f(v, 3); return v; }
; DI void phase_feat_c(KP p, int l) {
;     ...
; #pragma unroll
;     for (int hh = 0; hh < 8; ++hh) {
;       const bool isq = hh < 4; const int hd = hh & 3;
;       f32x4 v; float ra, rb;
;       if (isq) {
;         v = unpack4(*(const u32x2*)(q1r + (size_t)r * 384 + 96 * hd + 4 * u));
;         const unsigned rr = *(const unsigned*)(q1r + (size_t)r * 384 + 96 * hd + 64 + 2 * u); ra = bflo(rr); rb = bfhi(rr);
;       } else {
;         v = unpack4(*(const u32x2*)(krw + (size_t)r * 256 + 64 * hd + 4 * u));
;         ra = bflo(krp); rb = bfhi(krp);
;       }
;       float ss = red16(v[0] * v[0] + v[1] * v[1] + v[2] * v[2] + v[3] * v[3] + ra * ra + rb * rb);
;       const float rs = rsqrtf(ss * (1.f / 96.f) + 1e-6f);
;       const f32x4 g = isq ? gq4 : gk4; const f32x2 g2 = isq ? gq2 : gk2;
; #pragma unroll
;       for (int e = 0; e < 4; ++e) v[e] = v[e] * rs * g[e];
;       ra = ra * rs * g2[0]; rb = rb * rs * g2[1];
;       if (t < SEQ) rope2(ra, rb, sgm, csm);
;       if (isq) {
;         const float cq = 1.4426950408889634f / __builtin_sqrtf(96.f);
; #pragma unroll
;         for (int e = 0; e < 4; ++e) v[e] *= cq;
;         ra *= cq; rb *= cq;
;       }
;       bf16_t* dst = (isq ? QA : KA) + (((size_t)b * 4 + hd) * T + t) * 96;
;       *(u32x2*)(dst + 4 * u) = pack4(v);
;       *(unsigned*)(dst + 64 + 2 * u) = cvtpk(ra, rb);
.LBB0_205:
	s_or_b64 exec, exec, s[18:19]
	v_mov_b32_e32 v45, v44
	v_pk_mul_f32 v[40:41], v[44:45], v[40:41]
	v_pk_mul_f32 v[38:39], v[44:45], v[38:39]
	v_pk_mul_f32 v[10:11], v[10:11], v[40:41]
	v_pk_mul_f32 v[38:39], v[12:13], v[38:39]
	s_mov_b32 s2, 0x3e16c73f
	s_mov_b64 s[18:19], 0x1b00
	v_pk_mul_f32 v[40:41], v[42:43], s[2:3] op_sel_hi:[1,0]
	v_pk_mul_f32 v[38:39], v[38:39], s[2:3] op_sel_hi:[1,0]
	v_pk_mul_f32 v[42:43], v[10:11], s[2:3] op_sel_hi:[1,0]
	v_lshl_add_u64 v[10:11], v[32:33], 0, s[18:19]
	s_movk_i32 s2, 0xc0
	v_mov_b64_e32 v[44:45], s[54:55]
	v_mul_lo_u32 v11, v11, s2
	v_mad_u64_u32 v[44:45], s[18:19], v10, s2, v[44:45]
	v_add_u32_e32 v45, v11, v45
	v_mov_b32_e32 v29, v1
	v_ashrrev_i32_e32 v27, 31, v26
	v_cvt_pk_bf16_f32 v42, v42, v43
	v_cvt_pk_bf16_f32 v43, v38, v39
	v_lshl_add_u64 v[38:39], v[44:45], 0, v[28:29]
	v_lshlrev_b64 v[12:13], 9, v[26:27]
	global_store_dwordx2 v[38:39], v[42:43], off
	v_cvt_pk_bf16_f32 v27, v40, v41
	v_lshl_add_u64 v[38:39], v[44:45], 0, v[0:1]
	v_lshl_add_u64 v[12:13], v[24:25], 0, v[12:13]
	global_store_dword v[38:39], v27, off offset:128
	global_load_dwordx2 v[46:47], v[12:13], off
	v_and_b32_e32 v39, 0xffff0000, v52
	v_lshlrev_b32_e32 v38, 16, v52
	v_pk_mul_f32 v[40:41], v[38:39], v[38:39]
	s_mov_b32 s2, 0x800000
	s_waitcnt vmcnt(0) lgkmcnt(0)
	v_lshlrev_b32_e32 v44, 16, v46
	v_and_b32_e32 v45, 0xffff0000, v46
	v_lshlrev_b32_e32 v42, 16, v47
	v_and_b32_e32 v43, 0xffff0000, v47
	v_pk_mul_f32 v[48:49], v[44:45], v[44:45]
	v_pk_mul_f32 v[46:47], v[42:43], v[42:43]
	v_add_f32_e32 v27, v48, v49
	v_add_f32_e32 v27, v46, v27
	v_add_f32_e32 v27, v47, v27
	v_add_f32_e32 v27, v40, v27
	v_add_f32_e32 v27, v41, v27
	s_nop 1
	v_add_f32_dpp v27, v27, v27 quad_perm:[1,0,3,2] row_mask:0xf bank_mask:0xf bound_ctrl:1
	s_nop 1
	v_add_f32_dpp v27, v27, v27 quad_perm:[2,3,0,1] row_mask:0xf bank_mask:0xf bound_ctrl:1
	s_nop 1
	v_add_f32_dpp v27, v27, v27 row_ror:4 row_mask:0xf bank_mask:0xf bound_ctrl:1
	s_nop 1
	v_add_f32_dpp v27, v27, v27 row_ror:8 row_mask:0xf bank_mask:0xf bound_ctrl:1
	v_fmamk_f32 v27, v27, 0x3c2aaaab, v198
	v_mul_f32_e32 v33, 0x4b800000, v27
	v_cmp_gt_f32_e64 s[42:43], s2, v27
	s_nop 1
	v_cndmask_b32_e64 v27, v27, v33, s[42:43]
	v_rsq_f32_e32 v27, v27
	s_nop 0
	v_mul_f32_e32 v33, 0x45800000, v27
	v_cndmask_b32_e64 v48, v27, v33, s[42:43]
	v_pk_mul_f32 v[46:47], v[48:49], v[38:39] op_sel_hi:[0,1]
	v_pk_mul_f32 v[46:47], v[30:31], v[46:47]
	s_and_saveexec_b64 s[18:19], vcc
	s_cbranch_execz .LBB0_207
	v_and_b32_e32 v33, 64, v204
	v_xor_b32_e32 v27, 4, v204
	v_add_u32_e32 v33, 64, v33
	v_cmp_lt_i32_e64 s[42:43], v27, v33
	v_mov_b32_e32 v58, v7
	v_mov_b32_e32 v59, v9
	v_cndmask_b32_e64 v27, v204, v27, s[42:43]
	v_lshlrev_b32_e32 v27, 2, v27
	ds_bpermute_b32 v54, v27, v46
	ds_bpermute_b32 v55, v27, v47
	v_mov_b32_e32 v56, v6
	v_mov_b32_e32 v57, v8
	s_waitcnt lgkmcnt(0)
	v_pk_mul_f32 v[54:55], v[14:15], v[54:55]
	s_nop 0
	v_pk_mul_f32 v[54:55], v[58:59], v[54:55]
	s_nop 0
	v_pk_fma_f32 v[46:47], v[56:57], v[46:47], v[54:55]
.LBB0_207:
	s_or_b64 exec, exec, s[18:19]
	s_movk_i32 s2, 0xc0
	v_mad_u64_u32 v[32:33], s[18:19], v32, s2, 0
	v_mov_b32_e32 v49, v48
	v_add_u32_e32 v33, v33, v53
	v_pk_mul_f32 v[44:45], v[48:49], v[44:45]
	v_pk_mul_f32 v[42:43], v[48:49], v[42:43]
	v_pk_mul_f32 v[44:45], v[2:3], v[44:45]
	v_pk_mul_f32 v[42:43], v[4:5], v[42:43]
	v_lshl_add_u64 v[32:33], s[50:51], 0, v[32:33]
	v_cvt_pk_bf16_f32 v44, v44, v45
	v_cvt_pk_bf16_f32 v45, v42, v43
	v_lshl_add_u64 v[42:43], v[32:33], 0, v[28:29]
	v_cvt_pk_bf16_f32 v27, v46, v47
	v_lshl_add_u64 v[32:33], v[32:33], 0, v[0:1]
	global_store_dwordx2 v[42:43], v[44:45], off
	global_store_dword v[32:33], v27, off offset:128
	global_load_dwordx2 v[44:45], v[12:13], off offset:128
	s_mov_b32 s2, 0x800000
	s_waitcnt vmcnt(0) lgkmcnt(0)
	v_lshlrev_b32_e32 v42, 16, v44
	v_and_b32_e32 v43, 0xffff0000, v44
	v_lshlrev_b32_e32 v32, 16, v45
	v_and_b32_e32 v33, 0xffff0000, v45
	v_pk_mul_f32 v[46:47], v[42:43], v[42:43]
	v_pk_mul_f32 v[44:45], v[32:33], v[32:33]
	v_add_f32_e32 v27, v46, v47
	v_add_f32_e32 v27, v44, v27
	v_add_f32_e32 v27, v45, v27
	v_add_f32_e32 v27, v40, v27
	v_add_f32_e32 v27, v41, v27
	s_nop 1
	v_add_f32_dpp v27, v27, v27 quad_perm:[1,0,3,2] row_mask:0xf bank_mask:0xf bound_ctrl:1
	s_nop 1
	v_add_f32_dpp v27, v27, v27 quad_perm:[2,3,0,1] row_mask:0xf bank_mask:0xf bound_ctrl:1
	s_nop 1
	v_add_f32_dpp v27, v27, v27 row_ror:4 row_mask:0xf bank_mask:0xf bound_ctrl:1
	s_nop 1
	v_add_f32_dpp v27, v27, v27 row_ror:8 row_mask:0xf bank_mask:0xf bound_ctrl:1
	v_fmamk_f32 v27, v27, 0x3c2aaaab, v198
	v_mul_f32_e32 v29, 0x4b800000, v27
	v_cmp_gt_f32_e64 s[42:43], s2, v27
	s_nop 1
	v_cndmask_b32_e64 v27, v27, v29, s[42:43]
	v_rsq_f32_e32 v27, v27
	s_nop 0
	v_mul_f32_e32 v29, 0x45800000, v27
	v_cndmask_b32_e64 v46, v27, v29, s[42:43]
	v_pk_mul_f32 v[44:45], v[46:47], v[38:39] op_sel_hi:[0,1]
	v_pk_mul_f32 v[44:45], v[30:31], v[44:45]
	s_and_saveexec_b64 s[18:19], vcc
	s_cbranch_execz .LBB0_209
	v_and_b32_e32 v29, 64, v204
	v_xor_b32_e32 v27, 4, v204
	v_add_u32_e32 v29, 64, v29
	v_cmp_lt_i32_e64 s[42:43], v27, v29
	v_mov_b32_e32 v54, v7
	v_mov_b32_e32 v55, v9
	v_cndmask_b32_e64 v27, v204, v27, s[42:43]
	v_lshlrev_b32_e32 v27, 2, v27
	ds_bpermute_b32 v48, v27, v44
	ds_bpermute_b32 v49, v27, v45
	v_mov_b32_e32 v52, v6
	v_mov_b32_e32 v53, v8
	s_waitcnt lgkmcnt(0)
	v_pk_mul_f32 v[48:49], v[14:15], v[48:49]
	s_nop 0
	v_pk_mul_f32 v[48:49], v[54:55], v[48:49]
	s_nop 0
	v_pk_fma_f32 v[44:45], v[52:53], v[44:45], v[48:49]
; DI unsigned cvtpk(float lo, float hi) { f32x2 v = {lo, hi}; bf16x2_t b = __builtin_convertvector(v, bf16x2_t); return __builtin_bit_cast(unsigned, b); }
; DI float bflo(unsigned u) { return __uint_as_float(u << 16); }
; DI float bfhi(unsigned u) { return __uint_as_float(u & 0xffff0000u); }
; DI f32x4 unpack4(u32x2 v) { f32x4 r = {bflo(v.x), bfhi(v.x), bflo(v.y), bfhi(v.y)}; return r; }
; DI u32x2 pack4(f32x4 v) { u32x2 r = {cvtpk(v[0], v[1]), cvtpk(v[2], v[3])}; return r; }
; DI float red16(float v) { v += dpp_f(v, 0); v += dpp_f(v, 1); v += dpp_f(v, 2); v += dpp_f(v, 3); return v; }
; DI void phase_feat_c(KP p, int l) {
;     ...
; #pragma unroll
;     for (int hh = 0; hh < 8; ++hh) {
;       const bool isq = hh < 4; const int hd = hh & 3;
;       f32x4 v; float ra, rb;
;       if (isq) {
;         v = unpack4(*(const u32x2*)(q1r + (size_t)r * 384 + 96 * hd + 4 * u));
;         const unsigned rr = *(const unsigned*)(q1r + (size_t)r * 384 + 96 * hd + 64 + 2 * u); ra = bflo(rr); rb = bfhi(rr);
;       } else {
;         v = unpack4(*(const u32x2*)(krw + (size_t)r * 256 + 64 * hd + 4 * u));
;         ra = bflo(krp); rb = bfhi(krp);
;       }
;       float ss = red16(v[0] * v[0] + v[1] * v[1] + v[2] * v[2] + v[3] * v[3] + ra * ra + rb * rb);
;       const float rs = rsqrtf(ss * (1.f / 96.f) + 1e-6f);
;       const f32x4 g = isq ? gq4 : gk4; const f32x2 g2 = isq ? gq2 : gk2;
; #pragma unroll
;       for (int e = 0; e < 4; ++e) v[e] = v[e] * rs * g[e];
;       ra = ra * rs * g2[0]; rb = rb * rs * g2[1];
;       if (t < SEQ) rope2(ra, rb, sgm, csm);
;       if (isq) {
;         const float cq = 1.4426950408889634f / __builtin_sqrtf(96.f);
; #pragma unroll
;         for (int e = 0; e < 4; ++e) v[e] *= cq;
;         ra *= cq; rb *= cq;
;       }
;       bf16_t* dst = (isq ? QA : KA) + (((size_t)b * 4 + hd) * T + t) * 96;
;       *(u32x2*)(dst + 4 * u) = pack4(v);
;       *(unsigned*)(dst + 64 + 2 * u) = cvtpk(ra, rb);
.LBB0_209:
	s_or_b64 exec, exec, s[18:19]
	s_movk_i32 s2, 0xc0
	v_mad_u64_u32 v[48:49], s[18:19], v34, s2, 0
	v_mov_b32_e32 v47, v46
	v_add_u32_e32 v49, v49, v35
	v_pk_mul_f32 v[34:35], v[46:47], v[42:43]
	v_pk_mul_f32 v[32:33], v[46:47], v[32:33]
	v_pk_mul_f32 v[34:35], v[2:3], v[34:35]
	v_pk_mul_f32 v[32:33], v[4:5], v[32:33]
	v_lshl_add_u64 v[42:43], s[50:51], 0, v[48:49]
	v_mov_b32_e32 v29, v1
	v_cvt_pk_bf16_f32 v34, v34, v35
	v_cvt_pk_bf16_f32 v35, v32, v33
	v_lshl_add_u64 v[32:33], v[42:43], 0, v[28:29]
	global_store_dwordx2 v[32:33], v[34:35], off
	v_cvt_pk_bf16_f32 v27, v44, v45
	v_lshl_add_u64 v[32:33], v[42:43], 0, v[0:1]
	global_store_dword v[32:33], v27, off offset:128
	global_load_dwordx2 v[42:43], v[12:13], off offset:256
	s_mov_b32 s2, 0x800000
	s_waitcnt vmcnt(0) lgkmcnt(0)
	v_lshlrev_b32_e32 v34, 16, v42
	v_and_b32_e32 v35, 0xffff0000, v42
	v_lshlrev_b32_e32 v32, 16, v43
	v_and_b32_e32 v33, 0xffff0000, v43
	v_pk_mul_f32 v[44:45], v[34:35], v[34:35]
	v_pk_mul_f32 v[42:43], v[32:33], v[32:33]
	v_add_f32_e32 v27, v44, v45
	v_add_f32_e32 v27, v42, v27
	v_add_f32_e32 v27, v43, v27
	v_add_f32_e32 v27, v40, v27
	v_add_f32_e32 v27, v41, v27
	s_nop 1
	v_add_f32_dpp v27, v27, v27 quad_perm:[1,0,3,2] row_mask:0xf bank_mask:0xf bound_ctrl:1
	s_nop 1
	v_add_f32_dpp v27, v27, v27 quad_perm:[2,3,0,1] row_mask:0xf bank_mask:0xf bound_ctrl:1
	s_nop 1
	v_add_f32_dpp v27, v27, v27 row_ror:4 row_mask:0xf bank_mask:0xf bound_ctrl:1
	s_nop 1
	v_add_f32_dpp v27, v27, v27 row_ror:8 row_mask:0xf bank_mask:0xf bound_ctrl:1
	v_fmamk_f32 v27, v27, 0x3c2aaaab, v198
	v_mul_f32_e32 v42, 0x4b800000, v27
	v_cmp_gt_f32_e64 s[42:43], s2, v27
	s_nop 1
	v_cndmask_b32_e64 v27, v27, v42, s[42:43]
	v_rsq_f32_e32 v27, v27
	s_nop 0
	v_mul_f32_e32 v42, 0x45800000, v27
	v_cndmask_b32_e64 v44, v27, v42, s[42:43]
	v_pk_mul_f32 v[42:43], v[44:45], v[38:39] op_sel_hi:[0,1]
	v_pk_mul_f32 v[42:43], v[30:31], v[42:43]
	s_and_saveexec_b64 s[18:19], vcc
	s_cbranch_execz .LBB0_211
	v_and_b32_e32 v45, 64, v204
	v_xor_b32_e32 v27, 4, v204
	v_add_u32_e32 v45, 64, v45
	v_cmp_lt_i32_e64 s[42:43], v27, v45
	v_mov_b32_e32 v52, v7
	v_mov_b32_e32 v53, v9
	v_cndmask_b32_e64 v27, v204, v27, s[42:43]
	v_lshlrev_b32_e32 v27, 2, v27
	ds_bpermute_b32 v46, v27, v42
	ds_bpermute_b32 v47, v27, v43
	v_mov_b32_e32 v48, v6
	v_mov_b32_e32 v49, v8
	s_waitcnt lgkmcnt(0)
	v_pk_mul_f32 v[46:47], v[14:15], v[46:47]
	s_nop 0
	v_pk_mul_f32 v[46:47], v[52:53], v[46:47]
	s_nop 0
	v_pk_fma_f32 v[42:43], v[48:49], v[42:43], v[46:47]
.LBB0_211:
	s_or_b64 exec, exec, s[18:19]
	s_movk_i32 s2, 0xc0
	v_mad_u64_u32 v[46:47], s[18:19], v36, s2, 0
	v_mov_b32_e32 v45, v44
	v_add_u32_e32 v47, v47, v37
	v_pk_mul_f32 v[34:35], v[44:45], v[34:35]
	v_pk_mul_f32 v[32:33], v[44:45], v[32:33]
	v_pk_mul_f32 v[34:35], v[2:3], v[34:35]
	v_pk_mul_f32 v[32:33], v[4:5], v[32:33]
	v_lshl_add_u64 v[36:37], s[50:51], 0, v[46:47]
	v_cvt_pk_bf16_f32 v34, v34, v35
	v_cvt_pk_bf16_f32 v35, v32, v33
	v_lshl_add_u64 v[32:33], v[36:37], 0, v[28:29]
	global_store_dwordx2 v[32:33], v[34:35], off
	v_cvt_pk_bf16_f32 v27, v42, v43
	v_lshl_add_u64 v[32:33], v[36:37], 0, v[0:1]
	global_store_dword v[32:33], v27, off offset:128
	global_load_dwordx2 v[34:35], v[12:13], off offset:384
	s_mov_b32 s2, 0x800000
	s_waitcnt vmcnt(0) lgkmcnt(0)
	v_lshlrev_b32_e32 v32, 16, v34
	v_and_b32_e32 v33, 0xffff0000, v34
	v_lshlrev_b32_e32 v12, 16, v35
	v_and_b32_e32 v13, 0xffff0000, v35
	v_pk_mul_f32 v[36:37], v[32:33], v[32:33]
	v_pk_mul_f32 v[34:35], v[12:13], v[12:13]
	v_add_f32_e32 v27, v36, v37
	v_add_f32_e32 v27, v34, v27
	v_add_f32_e32 v27, v35, v27
	v_add_f32_e32 v27, v40, v27
	v_add_f32_e32 v27, v41, v27
	s_nop 1
	v_add_f32_dpp v27, v27, v27 quad_perm:[1,0,3,2] row_mask:0xf bank_mask:0xf bound_ctrl:1
	s_nop 1
	v_add_f32_dpp v27, v27, v27 quad_perm:[2,3,0,1] row_mask:0xf bank_mask:0xf bound_ctrl:1
	s_nop 1
	v_add_f32_dpp v27, v27, v27 row_ror:4 row_mask:0xf bank_mask:0xf bound_ctrl:1
	s_nop 1
	v_add_f32_dpp v27, v27, v27 row_ror:8 row_mask:0xf bank_mask:0xf bound_ctrl:1
	v_fmamk_f32 v27, v27, 0x3c2aaaab, v198
	v_mul_f32_e32 v29, 0x4b800000, v27
	v_cmp_gt_f32_e64 s[42:43], s2, v27
	s_nop 1
	v_cndmask_b32_e64 v27, v27, v29, s[42:43]
	v_rsq_f32_e32 v27, v27
	s_nop 0
	v_mul_f32_e32 v29, 0x45800000, v27
	v_cndmask_b32_e64 v34, v27, v29, s[42:43]
	v_pk_mul_f32 v[36:37], v[34:35], v[38:39] op_sel_hi:[0,1]
	v_pk_mul_f32 v[30:31], v[30:31], v[36:37]
	s_and_saveexec_b64 s[18:19], vcc
	s_cbranch_execz .LBB0_196
	v_and_b32_e32 v29, 64, v204
	v_xor_b32_e32 v27, 4, v204
	v_add_u32_e32 v29, 64, v29
	v_cmp_lt_i32_e32 vcc, v27, v29
	v_mov_b32_e32 v39, v8
	v_mov_b32_e32 v8, v7
	v_cndmask_b32_e32 v27, v204, v27, vcc
	v_lshlrev_b32_e32 v27, 2, v27
	ds_bpermute_b32 v36, v27, v30
	ds_bpermute_b32 v37, v27, v31
	v_mov_b32_e32 v38, v6
	s_waitcnt lgkmcnt(0)
	v_pk_mul_f32 v[36:37], v[14:15], v[36:37]
	s_nop 0
	v_pk_mul_f32 v[6:7], v[8:9], v[36:37]
	s_nop 0
	v_pk_fma_f32 v[30:31], v[38:39], v[30:31], v[6:7]
	s_branch .LBB0_196

; DI u32x2 pack4(f32x4 v) { u32x2 r = {cvtpk(v[0], v[1]), cvtpk(v[2], v[3])}; return r; }
; DI void phase_feat_b(KP p, int l, char* lds) {
;     ...
;       gemm_tile(cm, 64, P + (size_t)tt * 128 * NIN + O_F + 64 * g, NIN, 64, lds, [&](int m, int n, f32x4 v) {
;         const int col = 64 * g + (m & 63), part = m >> 6; const int r = tt * 128 + n; const int b = r / T, t = r % T;
;         if (t < SEQ) *(u32x2*)(FT + ((size_t)b * 256 + col) * 4096 + part * 2048 + t) = pack4(v);
;         else *(u32x2*)(FTC + ((size_t)b * 256 + col) * 512 + part * 256 + (t - SEQ)) = pack4(v); });
.LBB0_224:
	ds_read_b128 v[10:13], v8
	v_and_or_b32 v0, v3, 39, s69
	s_lshr_b32 s73, s72, 3
	v_lshlrev_b32_e32 v4, 1, v2
	s_waitcnt lgkmcnt(0)
	v_cvt_pk_bf16_f32 v6, v10, v11
	v_cvt_pk_bf16_f32 v7, v12, v13
	s_and_saveexec_b64 s[18:19], s[40:41]
	s_xor_b64 s[18:19], exec, s[18:19]
	s_cbranch_execz .LBB0_226
	v_lshlrev_b32_e32 v0, 10, v0
	v_lshl_add_u64 v[10:11], s[4:5], 0, v[0:1]
	s_lshl_b32 s2, s73, 9
	v_lshl_add_u64 v[10:11], v[10:11], 0, s[2:3]
	v_mov_b32_e32 v5, v1
	v_lshl_add_u64 v[10:11], v[10:11], 0, v[4:5]
	v_add_co_u32_e32 v10, vcc, 0x14b74000, v10
	s_nop 1
	v_addc_co_u32_e32 v11, vcc, 0, v11, vcc
	global_store_dwordx2 v[10:11], v[6:7], off offset:256
.LBB0_226:
	s_andn2_saveexec_b64 s[18:19], s[18:19]
	s_cbranch_execz .LBB0_228
	v_lshlrev_b32_e32 v0, 13, v0
	v_lshl_add_u64 v[10:11], s[50:51], 0, v[0:1]
	s_lshl_b32 s2, s73, 12
	v_lshl_add_u64 v[10:11], v[10:11], 0, s[2:3]
	v_mov_b32_e32 v5, v1
	v_lshl_add_u64 v[10:11], v[10:11], 0, v[4:5]
	global_store_dwordx2 v[10:11], v[6:7], off
.LBB0_228:
	s_or_b64 exec, exec, s[18:19]
	ds_read_b128 v[10:13], v8 offset:4224
	v_add_u32_e32 v0, 8, v3
	v_and_or_b32 v0, v0, 47, s69
	s_waitcnt lgkmcnt(0)
	v_cvt_pk_bf16_f32 v6, v10, v11
	v_cvt_pk_bf16_f32 v7, v12, v13
	s_and_saveexec_b64 s[18:19], s[40:41]
	s_xor_b64 s[18:19], exec, s[18:19]
	s_cbranch_execz .LBB0_230
	v_lshlrev_b32_e32 v0, 10, v0
	v_lshl_add_u64 v[10:11], s[4:5], 0, v[0:1]
	s_lshl_b32 s2, s73, 9
	v_lshl_add_u64 v[10:11], v[10:11], 0, s[2:3]
	v_mov_b32_e32 v5, v1
	v_lshl_add_u64 v[10:11], v[10:11], 0, v[4:5]
	v_add_co_u32_e32 v10, vcc, 0x14b74000, v10
	s_nop 1
	v_addc_co_u32_e32 v11, vcc, 0, v11, vcc
	global_store_dwordx2 v[10:11], v[6:7], off offset:256

; DI u32x2 pack4(f32x4 v) { u32x2 r = {cvtpk(v[0], v[1]), cvtpk(v[2], v[3])}; return r; }
; DI void phase_feat_b(KP p, int l, char* lds) {
;     ...
;       gemm_tile(cm, 64, P + (size_t)tt * 128 * NIN + O_F + 64 * g, NIN, 64, lds, [&](int m, int n, f32x4 v) {
;         const int col = 64 * g + (m & 63), part = m >> 6; const int r = tt * 128 + n; const int b = r / T, t = r % T;
;         if (t < SEQ) *(u32x2*)(FT + ((size_t)b * 256 + col) * 4096 + part * 2048 + t) = pack4(v);
;         else *(u32x2*)(FTC + ((size_t)b * 256 + col) * 512 + part * 256 + (t - SEQ)) = pack4(v); });
.LBB0_232:
	s_or_b64 exec, exec, s[18:19]
	ds_read_b128 v[10:13], v8 offset:8448
	v_add_u32_e32 v0, 16, v3
	v_and_or_b32 v0, v0, 55, s69
	s_waitcnt lgkmcnt(0)
	v_cvt_pk_bf16_f32 v6, v10, v11
	v_cvt_pk_bf16_f32 v7, v12, v13
	s_and_saveexec_b64 s[18:19], s[40:41]
	s_xor_b64 s[18:19], exec, s[18:19]
	s_cbranch_execz .LBB0_234
	v_lshlrev_b32_e32 v0, 10, v0
	v_lshl_add_u64 v[10:11], s[4:5], 0, v[0:1]
	s_lshl_b32 s2, s73, 9
	v_lshl_add_u64 v[10:11], v[10:11], 0, s[2:3]
	v_mov_b32_e32 v5, v1
	v_lshl_add_u64 v[10:11], v[10:11], 0, v[4:5]
	v_add_co_u32_e32 v10, vcc, 0x14b74000, v10
	s_nop 1
	v_addc_co_u32_e32 v11, vcc, 0, v11, vcc
	global_store_dwordx2 v[10:11], v[6:7], off offset:256

; DI u32x2 pack4(f32x4 v) { u32x2 r = {cvtpk(v[0], v[1]), cvtpk(v[2], v[3])}; return r; }
; DI void phase_feat_b(KP p, int l, char* lds) {
;     ...
;       gemm_tile(cm, 64, P + (size_t)tt * 128 * NIN + O_F + 64 * g, NIN, 64, lds, [&](int m, int n, f32x4 v) {
;         const int col = 64 * g + (m & 63), part = m >> 6; const int r = tt * 128 + n; const int b = r / T, t = r % T;
;         if (t < SEQ) *(u32x2*)(FT + ((size_t)b * 256 + col) * 4096 + part * 2048 + t) = pack4(v);
;         else *(u32x2*)(FTC + ((size_t)b * 256 + col) * 512 + part * 256 + (t - SEQ)) = pack4(v); });
.LBB0_236:
	s_or_b64 exec, exec, s[18:19]
	ds_read_b128 v[10:13], v8 offset:12672
	v_add_u32_e32 v0, 24, v3
	v_and_or_b32 v0, v0, 63, s69
	s_waitcnt lgkmcnt(0)
	v_cvt_pk_bf16_f32 v6, v10, v11
	v_cvt_pk_bf16_f32 v7, v12, v13
	s_and_saveexec_b64 s[18:19], s[40:41]
	s_xor_b64 s[18:19], exec, s[18:19]
	s_cbranch_execz .LBB0_238
	v_lshlrev_b32_e32 v0, 10, v0
	v_lshl_add_u64 v[10:11], s[4:5], 0, v[0:1]
	s_lshl_b32 s2, s73, 9
	v_lshl_add_u64 v[10:11], v[10:11], 0, s[2:3]
	v_mov_b32_e32 v5, v1
	v_lshl_add_u64 v[4:5], v[10:11], 0, v[4:5]
	v_add_co_u32_e32 v4, vcc, 0x14b74000, v4
	s_nop 1
	v_addc_co_u32_e32 v5, vcc, 0, v5, vcc
	global_store_dwordx2 v[4:5], v[6:7], off offset:256
.LBB0_238:
	s_andn2_saveexec_b64 s[18:19], s[18:19]
	s_cbranch_execz .LBB0_223
	v_lshlrev_b32_e32 v0, 13, v0
	v_lshl_add_u64 v[10:11], s[50:51], 0, v[0:1]
	s_lshl_b32 s2, s73, 12
	v_lshl_add_u64 v[10:11], v[10:11], 0, s[2:3]
	v_mov_b32_e32 v5, v1
	v_lshl_add_u64 v[4:5], v[10:11], 0, v[4:5]
	global_store_dwordx2 v[4:5], v[6:7], off
	s_branch .LBB0_223

; DI u32x2 pack4(f32x4 v) { u32x2 r = {cvtpk(v[0], v[1]), cvtpk(v[2], v[3])}; return r; }
; DI void phase_feat_b(KP p, int l, char* lds) {
;     ...
;       gemm_tile(wukv + (size_t)(256 + 128 * mt2) * 128, 128, ckvn + (size_t)tt * 128 * 128, 128, 128, lds, [&](int m, int n, f32x4 v) {
;         const int mm = 128 * mt2 + m, head = mm >> 6, dv = mm & 63; const int r = tt * 128 + n; const int b = r / T, t = r % T;
;         *(u32x2*)(VAT + (((size_t)b * 4 + head) * 64 + dv) * T + t) = pack4(v); });
.LBB0_243:
	ds_read_b128 v[6:9], v5
	v_add_u32_e32 v11, s4, v4
	v_and_b32_e32 v11, 0x7ffffc0, v11
	v_add_u32_e32 v10, s4, v0
	v_add_u32_e32 v11, s2, v11
	s_waitcnt lgkmcnt(0)
	v_cvt_pk_bf16_f32 v6, v6, v7
	v_cvt_pk_bf16_f32 v7, v8, v9
	v_and_or_b32 v8, v10, 39, v11
	v_mad_u64_u32 v[8:9], s[18:19], v8, s5, v[2:3]
	global_store_dwordx2 v[8:9], v[6:7], off
	ds_read_b128 v[6:9], v5 offset:4224
	v_add_u32_e32 v12, 8, v10
	s_add_i32 s4, s4, 32
	s_cmpk_lg_i32 s4, 0x80
	s_waitcnt lgkmcnt(0)
	v_cvt_pk_bf16_f32 v6, v6, v7
	v_cvt_pk_bf16_f32 v7, v8, v9
	v_and_or_b32 v8, v12, 47, v11
	v_mad_u64_u32 v[8:9], s[18:19], v8, s5, v[2:3]
	global_store_dwordx2 v[8:9], v[6:7], off
	ds_read_b128 v[6:9], v5 offset:8448
	v_add_u32_e32 v12, 16, v10
	v_add_u32_e32 v10, 24, v10
	s_waitcnt lgkmcnt(0)
	v_cvt_pk_bf16_f32 v6, v6, v7
	v_cvt_pk_bf16_f32 v7, v8, v9
	v_and_or_b32 v8, v12, 55, v11
	v_mad_u64_u32 v[8:9], s[18:19], v8, s5, v[2:3]
	global_store_dwordx2 v[8:9], v[6:7], off
	ds_read_b128 v[6:9], v5 offset:12672
	v_add_u32_e32 v5, 0x4200, v5
	s_waitcnt lgkmcnt(0)
	v_cvt_pk_bf16_f32 v6, v6, v7
	v_cvt_pk_bf16_f32 v7, v8, v9
	v_and_or_b32 v8, v10, 63, v11
	v_mad_u64_u32 v[8:9], s[18:19], v8, s5, v[2:3]
	global_store_dwordx2 v[8:9], v[6:7], off
	s_cbranch_scc1 .LBB0_243
	s_waitcnt lgkmcnt(0)
	s_barrier

; DI u32x2 pack4(f32x4 v) { u32x2 r = {cvtpk(v[0], v[1]), cvtpk(v[2], v[3])}; return r; }
; DI void phase_feat_b(KP p, int l, char* lds) {
;     ...
;       gemm_tile(ckvn + (size_t)m0 * 128, 128, wukv + (size_t)n0 * 128, 128, 128, lds, [&](int m, int n, f32x4 v) {
;         *(u32x2*)(kr + (size_t)(m0 + m) * 256 + n0 + n) = pack4(v); });
.LBB0_248:
	ds_read_b128 v[6:9], v5
	v_add_u32_e32 v10, s2, v4
	v_add_u32_e32 v0, 0xffff2800, v10
	s_add_i32 s2, s2, 32
	s_cmpk_lg_i32 s2, 0x80
	s_waitcnt lgkmcnt(0)
	v_cvt_pk_bf16_f32 v6, v6, v7
	v_cvt_pk_bf16_f32 v7, v8, v9
	v_lshlrev_b64 v[8:9], 9, v[0:1]
	v_lshl_add_u64 v[8:9], v[2:3], 0, v[8:9]
	global_store_dwordx2 v[8:9], v[6:7], off
	ds_read_b128 v[6:9], v5 offset:4224
	v_add_u32_e32 v0, 0xffff2808, v10
	s_waitcnt lgkmcnt(0)
	v_cvt_pk_bf16_f32 v6, v6, v7
	v_cvt_pk_bf16_f32 v7, v8, v9
	v_lshlrev_b64 v[8:9], 9, v[0:1]
	v_lshl_add_u64 v[8:9], v[2:3], 0, v[8:9]
	global_store_dwordx2 v[8:9], v[6:7], off
	ds_read_b128 v[6:9], v5 offset:8448
	v_add_u32_e32 v0, 0xffff2810, v10
	s_waitcnt lgkmcnt(0)
	v_cvt_pk_bf16_f32 v6, v6, v7
	v_cvt_pk_bf16_f32 v7, v8, v9
	v_lshlrev_b64 v[8:9], 9, v[0:1]
	v_lshl_add_u64 v[8:9], v[2:3], 0, v[8:9]
	global_store_dwordx2 v[8:9], v[6:7], off
	ds_read_b128 v[6:9], v5 offset:12672
	v_add_u32_e32 v0, 0xffff2818, v10
	v_add_u32_e32 v5, 0x4200, v5
	s_waitcnt lgkmcnt(0)
	v_cvt_pk_bf16_f32 v6, v6, v7
	v_cvt_pk_bf16_f32 v7, v8, v9
	v_lshlrev_b64 v[8:9], 9, v[0:1]
	v_lshl_add_u64 v[8:9], v[2:3], 0, v[8:9]
	global_store_dwordx2 v[8:9], v[6:7], off
	s_cbranch_scc1 .LBB0_248
	s_waitcnt lgkmcnt(0)
	s_barrier

; DI u32x2 pack4(f32x4 v) { u32x2 r = {cvtpk(v[0], v[1]), cvtpk(v[2], v[3])}; return r; }
; DI void phase_feat_b(KP p, int l, char* lds) {
;     ...
;       gemm_tile(cqn + (size_t)m0 * 192, 192, wuq + (size_t)n0 * 192, 192, 192, lds, [&](int m, int n, f32x4 v) {
;         *(u32x2*)(q1r + (size_t)(m0 + m) * 384 + n0 + n) = pack4(v); });
.LBB0_253:
	ds_read_b128 v[6:9], v4
	v_add_u32_e32 v5, s2, v0
	s_add_i32 s2, s2, 32
	s_cmpk_lg_i32 s2, 0x80
	s_waitcnt lgkmcnt(0)
	v_cvt_pk_bf16_f32 v6, v6, v7
	v_cvt_pk_bf16_f32 v7, v8, v9
	v_mad_i64_i32 v[8:9], s[4:5], v5, s58, v[2:3]
	global_store_dwordx2 v[8:9], v[6:7], off
	ds_read_b128 v[6:9], v4 offset:4224
	s_waitcnt lgkmcnt(0)
	v_cvt_pk_bf16_f32 v6, v6, v7
	v_cvt_pk_bf16_f32 v7, v8, v9
	v_add_u32_e32 v8, 8, v5
	v_mad_i64_i32 v[8:9], s[4:5], v8, s58, v[2:3]
	global_store_dwordx2 v[8:9], v[6:7], off
	ds_read_b128 v[6:9], v4 offset:8448
	s_waitcnt lgkmcnt(0)
	v_cvt_pk_bf16_f32 v6, v6, v7
	v_cvt_pk_bf16_f32 v7, v8, v9
	v_add_u32_e32 v8, 16, v5
	v_mad_i64_i32 v[8:9], s[4:5], v8, s58, v[2:3]
	global_store_dwordx2 v[8:9], v[6:7], off
	ds_read_b128 v[6:9], v4 offset:12672
	v_add_u32_e32 v5, 24, v5
	v_add_u32_e32 v4, 0x4200, v4
	s_waitcnt lgkmcnt(0)
	v_cvt_pk_bf16_f32 v6, v6, v7
	v_cvt_pk_bf16_f32 v7, v8, v9
	v_mad_i64_i32 v[8:9], s[4:5], v5, s58, v[2:3]
	global_store_dwordx2 v[8:9], v[6:7], off
	s_cbranch_scc1 .LBB0_253
	v_readlane_b32 s69, v255, 25
	s_mov_b64 s[72:73], 0x1000
	s_waitcnt lgkmcnt(0)
	s_barrier
	s_branch .LBB0_218

; DI void phase_feat_a(KP p, int l, char* lds) {
;     ...
;         const int c = tq & 31, rb = 2 * (tq >> 5);
;         f32x4 g0 = *(const f32x4*)(lg + 8 * c), g1 = *(const f32x4*)(lg + 8 * c + 4), b0 = *(const f32x4*)(lbp + 8 * c), b1 = *(const f32x4*)(lbp + 8 * c + 4);
;         const float gg[8] = {g0[0], g0[1], g0[2], g0[3], g1[0], g1[1], g1[2], g1[3]};
;         const float bb[8] = {b0[0], b0[1], b0[2], b0[3], b1[0], b1[1], b1[2], b1[3]};
; #pragma unroll
;         for (int i = 0; i < 4; ++i) {
;           float vn[2][8];
; #pragma unroll
;           for (int rr = 0; rr < 2; ++rr) {
;             const int row = rb + 16 * i + rr;
;             u32x4 q = *(const u32x4*)(P + (size_t)(r0 + row) * NIN + O_V + 8 * c);
;     ...
;         const int c = tq & 15, rb = 2 * (tq >> 4);
; #pragma unroll
;         for (int i = 0; i < 2; ++i) {
;           u32x4 q0 = *(const u32x4*)(P + (size_t)(r0 + rb + 32 * i) * NIN + O_V2 + 8 * c);
;           u32x4 q1 = *(const u32x4*)(P + (size_t)(r0 + rb + 32 * i + 1) * NIN + O_V2 + 8 * c);
;           const unsigned a[4] = {q0.x, q0.y, q0.z, q0.w}, d[4] = {q1.x, q1.y, q1.z, q1.w};
; #pragma unroll
;           for (int e = 0; e < 4; ++e) {
;             *(unsigned*)(ldh + (8 * c + 2 * e) * STR + (rb + 32 * i) * 2) = (a[e] & 0xffffu) | (d[e] << 16);
;             *(unsigned*)(ldh + (8 * c + 2 * e + 1) * STR + (rb + 32 * i) * 2) = (a[e] >> 16) | (d[e] & 0xffff0000u);
;           }
;         }
;         __syncthreads();
;         bf16_t* vb = VBT + (size_t)b * 2 * 64 * T + t0;
; #pragma unroll
;         for (int i = 0; i < 4; ++i) {
;           const int ch = (tq >> 3) + 32 * i, part = tq & 7;
;           *(u32x4*)(vb + (size_t)ch * T + part * 8) = *(const u32x4*)(ldh + ch * STR + part * 16);
;         }
.LBB0_262:
	v_lshlrev_b32_e32 v46, 1, v18
	s_and_saveexec_b64 s[18:19], s[40:41]
	s_xor_b64 s[42:43], exec, s[18:19]
	s_cbranch_execz .LBB0_264
	v_and_b32_e32 v0, 0xffffffc0, v56
	s_mov_b32 s2, 0x38e38e39
	v_mul_hi_i32 v2, v0, s2
	v_lshrrev_b32_e32 v3, 31, v2
	v_ashrrev_i32_e32 v2, 9, v2
	v_add_u32_e32 v3, v2, v3
	v_mul_i32_i24_e32 v2, 0x900, v3
	v_sub_u32_e32 v2, v0, v2
	v_or_b32_e32 v0, v0, v54
	v_mad_i64_i32 v[4:5], s[18:19], v0, s11, v[24:25]
	v_or_b32_e32 v8, 1, v0
	global_load_dwordx4 v[4:7], v[4:5], off offset:1984
	v_mad_i64_i32 v[8:9], s[18:19], v8, s11, v[24:25]
	global_load_dwordx4 v[8:11], v[8:9], off offset:1984
	s_mov_b32 s2, 0xffff0000
	v_mov_b32_e32 v47, v1
	v_mov_b32_e32 v29, v1
	s_waitcnt vmcnt(0) lgkmcnt(0)
	v_and_b32_e32 v12, 0xffff, v4
	v_lshrrev_b32_e32 v4, 16, v4
	v_and_or_b32 v4, v8, s2, v4
	ds_write_b32 v57, v4 offset:144
	v_and_b32_e32 v4, 0xffff, v5
	v_lshl_or_b32 v4, v9, 16, v4
	ds_write_b32 v57, v4 offset:288
	v_lshrrev_b32_e32 v4, 16, v5
	v_and_or_b32 v4, v9, s2, v4
	ds_write_b32 v57, v4 offset:432
	v_and_b32_e32 v4, 0xffff, v6
	v_lshl_or_b32 v4, v10, 16, v4
	ds_write_b32 v57, v4 offset:576
	v_lshrrev_b32_e32 v4, 16, v6
	v_and_or_b32 v4, v10, s2, v4
	ds_write_b32 v57, v4 offset:720
	v_and_b32_e32 v4, 0xffff, v7
	v_lshl_or_b32 v4, v11, 16, v4
	ds_write_b32 v57, v4 offset:864
	v_lshrrev_b32_e32 v4, 16, v7
	v_and_or_b32 v4, v11, s2, v4
	v_lshl_or_b32 v12, v8, 16, v12
	ds_write_b32 v57, v4 offset:1008
	v_or_b32_e32 v4, 32, v0
	ds_write_b32 v57, v12
	v_mad_i64_i32 v[4:5], s[18:19], v4, s11, v[24:25]
	v_or_b32_e32 v0, 33, v0
	global_load_dwordx4 v[4:7], v[4:5], off offset:1984
	v_mad_i64_i32 v[8:9], s[18:19], v0, s11, v[24:25]
	global_load_dwordx4 v[8:11], v[8:9], off offset:1984
	s_waitcnt vmcnt(0) lgkmcnt(0)
	v_and_b32_e32 v0, 0xffff, v4
	v_lshl_or_b32 v0, v8, 16, v0
	ds_write_b32 v57, v0 offset:64
	v_lshrrev_b32_e32 v0, 16, v4
	v_and_or_b32 v0, v8, s2, v0
	ds_write_b32 v57, v0 offset:208
	v_and_b32_e32 v0, 0xffff, v5
	v_lshl_or_b32 v0, v9, 16, v0
	ds_write_b32 v57, v0 offset:352
	v_lshrrev_b32_e32 v0, 16, v5
	v_and_or_b32 v0, v9, s2, v0
	ds_write_b32 v57, v0 offset:496
	v_and_b32_e32 v0, 0xffff, v6
	v_lshl_or_b32 v0, v10, 16, v0
	ds_write_b32 v57, v0 offset:640
	v_lshrrev_b32_e32 v0, 16, v6
	v_and_or_b32 v0, v10, s2, v0
	ds_write_b32 v57, v0 offset:784
	v_and_b32_e32 v0, 0xffff, v7
	v_lshl_or_b32 v0, v11, 16, v0
	v_mul_hi_i32_i24_e32 v5, 0x90000, v3
	v_mul_i32_i24_e32 v4, 0x90000, v3
	ds_write_b32 v57, v0 offset:928
	v_lshrrev_b32_e32 v0, 16, v7
	v_lshl_add_u64 v[4:5], s[56:57], 0, v[4:5]
	v_ashrrev_i32_e32 v3, 31, v2
	v_and_or_b32 v0, v11, s2, v0
	v_lshl_add_u64 v[2:3], v[2:3], 1, v[4:5]
	ds_write_b32 v57, v0 offset:1072
	s_waitcnt lgkmcnt(0)
	s_barrier
	v_lshl_add_u64 v[6:7], v[2:3], 0, v[46:47]
	ds_read_b128 v[2:5], v60
	v_lshl_add_u64 v[6:7], v[6:7], 0, v[28:29]
	v_add_co_u32_e32 v8, vcc, 0x24000, v6
	s_waitcnt lgkmcnt(0)
	global_store_dwordx4 v[6:7], v[2:5], off
	ds_read_b128 v[2:5], v60 offset:4608
	v_addc_co_u32_e32 v9, vcc, 0, v7, vcc
	s_waitcnt lgkmcnt(0)
	global_store_dwordx4 v[8:9], v[2:5], off
	ds_read_b128 v[2:5], v60 offset:9216
	v_add_co_u32_e32 v8, vcc, 0x48000, v6
	s_nop 1
	v_addc_co_u32_e32 v9, vcc, 0, v7, vcc
	s_waitcnt lgkmcnt(0)
	global_store_dwordx4 v[8:9], v[2:5], off
	ds_read_b128 v[2:5], v60 offset:13824
	v_add_co_u32_e32 v6, vcc, 0x6c000, v6
	s_nop 1
	v_addc_co_u32_e32 v7, vcc, 0, v7, vcc
	s_waitcnt lgkmcnt(0)
	global_store_dwordx4 v[6:7], v[2:5], off
.LBB0_264:
	s_andn2_saveexec_b64 s[54:55], s[42:43]
	s_cbranch_execz .LBB0_261
	v_add_u32_e32 v35, v55, v56
	v_mad_i64_i32 v[2:3], s[18:19], v35, s11, v[26:27]
	global_load_dwordx4 v[62:65], v[2:3], off offset:3264
	v_add_u32_e32 v0, 1, v35
	v_mad_i64_i32 v[2:3], s[18:19], v0, s11, v[26:27]
	global_load_dwordx4 v[66:69], v[2:3], off offset:3264
	s_nop 0
	global_load_dwordx4 v[2:5], v[20:21], off offset:16
	global_load_dwordx4 v[10:13], v[20:21], off
	global_load_dwordx4 v[6:9], v[22:23], off offset:16
	global_load_dwordx4 v[14:17], v[22:23], off
	v_and_b32_e32 v0, 64, v204
	v_xor_b32_e32 v29, 1, v204
	v_add_u32_e32 v0, 64, v0
	v_xor_b32_e32 v31, 2, v204
	v_cmp_lt_i32_e32 vcc, v29, v0
	v_xor_b32_e32 v33, 4, v204
	v_xor_b32_e32 v37, 8, v204
	v_cndmask_b32_e32 v29, v204, v29, vcc
	v_cmp_lt_i32_e32 vcc, v31, v0
	v_xor_b32_e32 v39, 16, v204
	s_mov_b32 s34, 0x3b800000
	v_cndmask_b32_e32 v31, v204, v31, vcc
	v_cmp_lt_i32_e32 vcc, v33, v0
	v_lshlrev_b32_e32 v31, 2, v31
	s_mov_b32 s50, 0x358637bd
	v_cndmask_b32_e32 v41, v204, v33, vcc
	v_cmp_lt_i32_e32 vcc, v37, v0
	v_lshlrev_b32_e32 v33, 2, v29
	v_lshlrev_b32_e32 v29, 2, v41
	v_cndmask_b32_e32 v37, v204, v37, vcc
	v_cmp_lt_i32_e32 vcc, v39, v0
	v_lshlrev_b32_e32 v37, 2, v37
	s_mov_b32 s2, 0x800000
	v_cndmask_b32_e32 v0, v204, v39, vcc
	s_mov_b32 s20, 0x45800000
	s_waitcnt vmcnt(0) lgkmcnt(0)
; DI unsigned cvtpk(float lo, float hi) { f32x2 v = {lo, hi}; bf16x2_t b = __builtin_convertvector(v, bf16x2_t); return __builtin_bit_cast(unsigned, b); }
; DI float bflo(unsigned u) { return __uint_as_float(u << 16); }
; DI float bfhi(unsigned u) { return __uint_as_float(u & 0xffff0000u); }
; DI void phase_feat_a(KP p, int l, char* lds) {
;     ...
;         for (int i = 0; i < 4; ++i) {
;           float vn[2][8];
; #pragma unroll
;           for (int rr = 0; rr < 2; ++rr) {
;             const int row = rb + 16 * i + rr;
;             u32x4 q = *(const u32x4*)(P + (size_t)(r0 + row) * NIN + O_V + 8 * c);
;             float f[8] = {bflo(q.x), bfhi(q.x), bflo(q.y), bfhi(q.y), bflo(q.z), bfhi(q.z), bflo(q.w), bfhi(q.w)};
;             float s1 = 0.f, s2 = 0.f;
; #pragma unroll
;             for (int e = 0; e < 8; ++e) { s1 += f[e]; s2 += f[e] * f[e]; }
; #pragma unroll
;             for (int m = 1; m < 32; m <<= 1) { s1 += __shfl_xor(s1, m); s2 += __shfl_xor(s2, m); }
;             const float mu = s1 * (1.f / 256.f); const float var = fmaxf(s2 * (1.f / 256.f) - mu * mu, 0.f); const float rs = rsqrtf(var + 1e-6f);
; #pragma unroll
;             for (int e = 0; e < 8; ++e) vn[rr][e] = (f[e] - mu) * rs * gg[e] + bb[e];
;           }
; #pragma unroll
;           for (int e = 0; e < 8; ++e) *(unsigned*)(ldh + (8 * c + e) * STR + (rb + 16 * i) * 2) = cvtpk(vn[0][e], vn[1][e]);
	v_lshlrev_b32_e32 v73, 16, v66
	v_lshlrev_b32_e32 v72, 16, v62
	v_and_b32_e32 v62, 0xffff0000, v62
	v_lshlrev_b32_e32 v74, 16, v63
	v_and_b32_e32 v76, 0xffff0000, v63
	v_and_b32_e32 v63, 0xffff0000, v66
	v_lshlrev_b32_e32 v75, 16, v67
	v_and_b32_e32 v77, 0xffff0000, v67
	v_mov_b32_e32 v66, v76
	v_mov_b32_e32 v67, v74
	v_pk_mul_f32 v[84:85], v[62:63], v[62:63]
	v_lshlrev_b32_e32 v78, 16, v64
	v_and_b32_e32 v64, 0xffff0000, v64
	v_pk_mul_f32 v[66:67], v[66:67], v[66:67]
	v_pk_fma_f32 v[84:85], v[72:73], v[72:73], v[84:85]
	v_mov_b32_e32 v82, v64
	v_mov_b32_e32 v83, v78
	v_add_f32_e32 v39, v67, v84
	v_and_b32_e32 v70, 0xffff0000, v65
	v_lshlrev_b32_e32 v80, 16, v65
	v_pk_mul_f32 v[82:83], v[82:83], v[82:83]
	v_pk_add_f32 v[92:93], v[72:73], 0 op_sel_hi:[1,0]
	v_add_f32_e32 v39, v66, v39
	v_and_b32_e32 v71, 0xffff0000, v69
	v_lshlrev_b32_e32 v79, 16, v68
	v_and_b32_e32 v65, 0xffff0000, v68
	v_lshlrev_b32_e32 v81, 16, v69
	v_mov_b32_e32 v68, v70
	v_mov_b32_e32 v69, v80
	v_pk_add_f32 v[92:93], v[92:93], v[62:63]
	v_add_f32_e32 v39, v83, v39
	v_pk_mul_f32 v[68:69], v[68:69], v[68:69]
	v_pk_add_f32 v[92:93], v[92:93], v[74:75]
	v_add_f32_e32 v39, v82, v39
	v_mov_b32_e32 v86, v77
	v_mov_b32_e32 v87, v75
	v_pk_add_f32 v[66:67], v[92:93], v[76:77]
	v_add_f32_e32 v39, v69, v39
	v_pk_mul_f32 v[86:87], v[86:87], v[86:87]
	v_pk_add_f32 v[66:67], v[66:67], v[78:79]
	v_add_f32_e32 v39, v68, v39
	v_mov_b32_e32 v88, v65
	v_mov_b32_e32 v89, v79
	v_add_f32_e32 v41, v87, v85
	v_pk_add_f32 v[66:67], v[66:67], v[64:65]
	ds_bpermute_b32 v43, v33, v39
	v_pk_mul_f32 v[88:89], v[88:89], v[88:89]
	v_pk_add_f32 v[66:67], v[66:67], v[80:81]
	v_add_f32_e32 v41, v86, v41
	v_mov_b32_e32 v90, v71
	v_mov_b32_e32 v91, v81
	v_pk_add_f32 v[66:67], v[66:67], v[70:71]
	v_add_f32_e32 v41, v89, v41
	v_pk_mul_f32 v[90:91], v[90:91], v[90:91]
	ds_bpermute_b32 v68, v33, v66
	ds_bpermute_b32 v69, v33, v67
	v_add_f32_e32 v41, v88, v41
	v_add_f32_e32 v41, v91, v41
	s_waitcnt lgkmcnt(2)
	v_add_f32_e32 v39, v39, v43
	v_add_f32_e32 v41, v90, v41
	ds_bpermute_b32 v43, v31, v39
	ds_bpermute_b32 v45, v33, v41
	s_waitcnt lgkmcnt(2)
	v_pk_add_f32 v[66:67], v[66:67], v[68:69]
	ds_bpermute_b32 v68, v31, v66
	ds_bpermute_b32 v69, v31, v67
	s_waitcnt lgkmcnt(3)
	v_add_f32_e32 v39, v39, v43
	s_waitcnt lgkmcnt(2)
	v_add_f32_e32 v41, v41, v45
	ds_bpermute_b32 v43, v29, v39
	ds_bpermute_b32 v45, v31, v41
	s_waitcnt lgkmcnt(2)
	v_pk_add_f32 v[66:67], v[66:67], v[68:69]
	ds_bpermute_b32 v68, v29, v66
	ds_bpermute_b32 v69, v29, v67
	s_waitcnt lgkmcnt(3)
	v_add_f32_e32 v43, v39, v43
	v_lshlrev_b32_e32 v39, 2, v0
	s_waitcnt lgkmcnt(2)
	v_add_f32_e32 v0, v41, v45
	ds_bpermute_b32 v41, v29, v0
	s_waitcnt lgkmcnt(1)
	v_pk_add_f32 v[66:67], v[66:67], v[68:69]
	ds_bpermute_b32 v68, v37, v66
	ds_bpermute_b32 v69, v37, v67
	ds_bpermute_b32 v47, v37, v43
	s_waitcnt lgkmcnt(3)
	v_add_f32_e32 v0, v0, v41
	ds_bpermute_b32 v41, v37, v0
	v_mov_b32_e32 v50, v5
	s_waitcnt lgkmcnt(2)
	v_pk_add_f32 v[66:67], v[66:67], v[68:69]
	ds_bpermute_b32 v68, v39, v66
	ds_bpermute_b32 v69, v39, v67
	s_waitcnt lgkmcnt(3)
	v_add_f32_e32 v43, v43, v47
	ds_bpermute_b32 v45, v39, v43
	s_waitcnt lgkmcnt(3)
	v_add_f32_e32 v0, v0, v41
	ds_bpermute_b32 v41, v39, v0
	s_waitcnt lgkmcnt(2)
	v_pk_add_f32 v[66:67], v[66:67], v[68:69]
	v_mov_b32_e32 v48, v17
	v_pk_mul_f32 v[68:69], v[66:67], s[34:35] op_sel_hi:[1,0]
	s_waitcnt lgkmcnt(1)
	v_add_f32_e32 v82, v43, v45
	v_mov_b32_e32 v83, v68
	v_mov_b32_e32 v45, v187
	v_mov_b32_e32 v187, v68
	v_pk_mul_f32 v[82:83], v[82:83], v[186:187]
	s_waitcnt lgkmcnt(0)
	v_add_f32_e32 v68, v0, v41
	v_mov_b32_e32 v187, v69
	v_pk_mul_f32 v[68:69], v[68:69], v[186:187]
	v_sub_f32_e32 v43, v82, v83
	v_sub_f32_e32 v0, v68, v69
	v_max_f32_e32 v82, 0, v43
	v_max_f32_e32 v83, 0, v0
	v_pk_add_f32 v[68:69], v[82:83], s[50:51] op_sel_hi:[1,0]
	v_pk_fma_f32 v[72:73], v[66:67], s[34:35], v[72:73] op_sel_hi:[1,0,1] neg_lo:[1,0,0] neg_hi:[1,0,0]
	v_mul_f32_e32 v0, 0x4b800000, v68
	v_cmp_gt_f32_e32 vcc, s2, v68
	v_cmp_gt_f32_e64 s[42:43], s2, v69
	v_pk_fma_f32 v[62:63], v[66:67], s[34:35], v[62:63] op_sel_hi:[1,0,1] neg_lo:[1,0,0] neg_hi:[1,0,0]
	v_cndmask_b32_e32 v0, v68, v0, vcc
	v_rsq_f32_e32 v68, v0
	v_mul_f32_e32 v0, 0x4b800000, v69
	v_cndmask_b32_e64 v0, v69, v0, s[42:43]
	v_rsq_f32_e32 v69, v0
	v_pk_fma_f32 v[80:81], v[66:67], s[34:35], v[80:81] op_sel_hi:[1,0,1] neg_lo:[1,0,0] neg_hi:[1,0,0]
	v_pk_fma_f32 v[74:75], v[66:67], s[34:35], v[74:75] op_sel_hi:[1,0,1] neg_lo:[1,0,0] neg_hi:[1,0,0]
	v_pk_fma_f32 v[76:77], v[66:67], s[34:35], v[76:77] op_sel_hi:[1,0,1] neg_lo:[1,0,0] neg_hi:[1,0,0]
	v_pk_mul_f32 v[82:83], v[68:69], s[20:21] op_sel_hi:[1,0]
	v_mov_b32_e32 v0, v13
	v_cndmask_b32_e64 v69, v69, v83, s[42:43]
	v_cndmask_b32_e32 v68, v68, v82, vcc
	v_pk_mul_f32 v[72:73], v[72:73], v[68:69]
	v_pk_mul_f32 v[62:63], v[62:63], v[68:69]
	v_pk_fma_f32 v[72:73], v[10:11], v[72:73], v[14:15] op_sel_hi:[0,1,0]
	v_pk_mul_f32 v[80:81], v[80:81], v[68:69]
	v_pk_fma_f32 v[62:63], v[10:11], v[62:63], v[14:15] op_sel:[1,0,1]
	v_pk_mul_f32 v[74:75], v[74:75], v[68:69]
	v_pk_fma_f32 v[80:81], v[4:5], v[80:81], v[8:9] op_sel_hi:[0,1,0]
	v_cvt_pk_bf16_f32 v5, v72, v73
	v_pk_fma_f32 v[74:75], v[12:13], v[74:75], v[16:17] op_sel_hi:[0,1,0]
	v_pk_mul_f32 v[76:77], v[76:77], v[68:69]
	v_pk_fma_f32 v[78:79], v[66:67], s[34:35], v[78:79] op_sel_hi:[1,0,1] neg_lo:[1,0,0] neg_hi:[1,0,0]
	ds_write_b32 v58, v5
	v_cvt_pk_bf16_f32 v5, v62, v63
	v_pk_fma_f32 v[76:77], v[0:1], v[76:77], v[48:49] op_sel_hi:[0,1,0]
	v_pk_mul_f32 v[78:79], v[78:79], v[68:69]
	v_pk_fma_f32 v[64:65], v[66:67], s[34:35], v[64:65] op_sel_hi:[1,0,1] neg_lo:[1,0,0] neg_hi:[1,0,0]
	ds_write_b32 v58, v5 offset:144
	v_cvt_pk_bf16_f32 v5, v74, v75
	v_pk_fma_f32 v[78:79], v[2:3], v[78:79], v[6:7] op_sel_hi:[0,1,0]
	v_pk_mul_f32 v[64:65], v[64:65], v[68:69]
	ds_write_b32 v58, v5 offset:288
	v_cvt_pk_bf16_f32 v5, v76, v77
	v_pk_fma_f32 v[64:65], v[2:3], v[64:65], v[6:7] op_sel:[1,0,1]
	v_pk_fma_f32 v[66:67], v[66:67], s[34:35], v[70:71] op_sel_hi:[1,0,1] neg_lo:[1,0,0] neg_hi:[1,0,0]
	ds_write_b32 v58, v5 offset:432
	v_cvt_pk_bf16_f32 v5, v78, v79
	v_pk_mul_f32 v[66:67], v[66:67], v[68:69]
	v_mov_b32_e32 v52, v9
	ds_write_b32 v58, v5 offset:576
	v_cvt_pk_bf16_f32 v5, v64, v65
	v_pk_fma_f32 v[66:67], v[50:51], v[66:67], v[52:53] op_sel_hi:[0,1,0]
	ds_write_b32 v58, v5 offset:720
	v_cvt_pk_bf16_f32 v5, v80, v81
	ds_write_b32 v58, v5 offset:864
	v_cvt_pk_bf16_f32 v5, v66, v67
	ds_write_b32 v58, v5 offset:1008
	v_add_u32_e32 v5, 16, v35
	v_mad_i64_i32 v[66:67], s[18:19], v5, s11, v[26:27]
	v_add_u32_e32 v5, 17, v35
	v_mad_i64_i32 v[62:63], s[18:19], v5, s11, v[26:27]
	global_load_dwordx4 v[62:65], v[62:63], off offset:3264
	s_nop 0
	global_load_dwordx4 v[66:69], v[66:67], off offset:3264
	v_mov_b32_e32 v47, v1
	v_mov_b32_e32 v41, v1
	v_mov_b32_e32 v43, v1
	s_waitcnt vmcnt(0) lgkmcnt(0)
; DI unsigned cvtpk(float lo, float hi) { f32x2 v = {lo, hi}; bf16x2_t b = __builtin_convertvector(v, bf16x2_t); return __builtin_bit_cast(unsigned, b); }
; DI float bflo(unsigned u) { return __uint_as_float(u << 16); }
; DI float bfhi(unsigned u) { return __uint_as_float(u & 0xffff0000u); }
; DI void phase_feat_a(KP p, int l, char* lds) {
;     ...
;         for (int i = 0; i < 4; ++i) {
;           float vn[2][8];
; #pragma unroll
;           for (int rr = 0; rr < 2; ++rr) {
;             const int row = rb + 16 * i + rr;
;             u32x4 q = *(const u32x4*)(P + (size_t)(r0 + row) * NIN + O_V + 8 * c);
;             float f[8] = {bflo(q.x), bfhi(q.x), bflo(q.y), bfhi(q.y), bflo(q.z), bfhi(q.z), bflo(q.w), bfhi(q.w)};
;             float s1 = 0.f, s2 = 0.f;
; #pragma unroll
;             for (int e = 0; e < 8; ++e) { s1 += f[e]; s2 += f[e] * f[e]; }
; #pragma unroll
;             for (int m = 1; m < 32; m <<= 1) { s1 += __shfl_xor(s1, m); s2 += __shfl_xor(s2, m); }
;             const float mu = s1 * (1.f / 256.f); const float var = fmaxf(s2 * (1.f / 256.f) - mu * mu, 0.f); const float rs = rsqrtf(var + 1e-6f);
; #pragma unroll
;             for (int e = 0; e < 8; ++e) vn[rr][e] = (f[e] - mu) * rs * gg[e] + bb[e];
;           }
; #pragma unroll
;           for (int e = 0; e < 8; ++e) *(unsigned*)(ldh + (8 * c + e) * STR + (rb + 16 * i) * 2) = cvtpk(vn[0][e], vn[1][e]);
	v_lshlrev_b32_e32 v73, 16, v62
	v_and_b32_e32 v75, 0xffff0000, v62
	v_and_b32_e32 v74, 0xffff0000, v66
	v_lshlrev_b32_e32 v76, 16, v67
	v_and_b32_e32 v62, 0xffff0000, v67
	v_and_b32_e32 v70, 0xffff0000, v69
	v_lshlrev_b32_e32 v72, 16, v66
	v_lshlrev_b32_e32 v67, 16, v64
	v_lshlrev_b32_e32 v66, 16, v68
	v_and_b32_e32 v79, 0xffff0000, v64
	v_and_b32_e32 v78, 0xffff0000, v68
	v_lshlrev_b32_e32 v64, 16, v69
	v_pk_mul_f32 v[68:69], v[74:75], v[74:75]
	v_mov_b32_e32 v80, v62
	v_mov_b32_e32 v81, v76
	v_pk_mul_f32 v[80:81], v[80:81], v[80:81]
	v_pk_fma_f32 v[68:69], v[72:73], v[72:73], v[68:69]
	v_mov_b32_e32 v82, v78
	v_mov_b32_e32 v83, v66
	v_add_f32_e32 v5, v81, v68
	v_pk_mul_f32 v[82:83], v[82:83], v[82:83]
	v_add_f32_e32 v5, v80, v5
	v_mov_b32_e32 v84, v70
	v_mov_b32_e32 v85, v64
	v_add_f32_e32 v5, v83, v5
	v_pk_mul_f32 v[84:85], v[84:85], v[84:85]
	v_add_f32_e32 v5, v82, v5
	v_add_f32_e32 v5, v85, v5
	v_add_f32_e32 v5, v84, v5
	ds_bpermute_b32 v9, v33, v5
	v_pk_add_f32 v[80:81], v[72:73], 0 op_sel_hi:[1,0]
	v_lshlrev_b32_e32 v77, 16, v63
	v_pk_add_f32 v[80:81], v[80:81], v[74:75]
	v_and_b32_e32 v63, 0xffff0000, v63
	s_waitcnt lgkmcnt(0)
	v_add_f32_e32 v5, v5, v9
	ds_bpermute_b32 v9, v31, v5
	v_pk_add_f32 v[80:81], v[80:81], v[76:77]
	v_mov_b32_e32 v86, v63
	v_mov_b32_e32 v87, v77
	v_pk_add_f32 v[80:81], v[80:81], v[62:63]
	s_waitcnt lgkmcnt(0)
	v_add_f32_e32 v5, v5, v9
	ds_bpermute_b32 v9, v29, v5
	v_pk_mul_f32 v[86:87], v[86:87], v[86:87]
	v_pk_add_f32 v[80:81], v[80:81], v[66:67]
	v_and_b32_e32 v71, 0xffff0000, v65
	v_lshlrev_b32_e32 v65, 16, v65
	v_mov_b32_e32 v88, v79
	v_mov_b32_e32 v89, v67
	v_pk_add_f32 v[80:81], v[80:81], v[78:79]
	s_waitcnt lgkmcnt(0)
	v_add_f32_e32 v5, v5, v9
	v_add_f32_e32 v9, v87, v69
	v_pk_add_f32 v[80:81], v[80:81], v[64:65]
	v_pk_mul_f32 v[84:85], v[88:89], v[88:89]
	v_add_f32_e32 v9, v86, v9
	v_pk_add_f32 v[80:81], v[80:81], v[70:71]
	v_mov_b32_e32 v88, v71
	v_mov_b32_e32 v89, v65
	v_add_f32_e32 v9, v85, v9
	ds_bpermute_b32 v82, v33, v80
	ds_bpermute_b32 v83, v33, v81
	v_pk_mul_f32 v[88:89], v[88:89], v[88:89]
	v_add_f32_e32 v9, v84, v9
	v_add_f32_e32 v9, v89, v9
	v_add_f32_e32 v9, v88, v9
	ds_bpermute_b32 v13, v33, v9
	s_waitcnt lgkmcnt(1)
	v_pk_add_f32 v[80:81], v[80:81], v[82:83]
	ds_bpermute_b32 v82, v31, v80
	ds_bpermute_b32 v83, v31, v81
	ds_bpermute_b32 v17, v37, v5
	s_waitcnt lgkmcnt(3)
	v_add_f32_e32 v9, v9, v13
	ds_bpermute_b32 v13, v31, v9
	s_waitcnt lgkmcnt(2)
	v_pk_add_f32 v[80:81], v[80:81], v[82:83]
	ds_bpermute_b32 v82, v29, v80
	ds_bpermute_b32 v83, v29, v81
	s_waitcnt lgkmcnt(2)
	v_add_f32_e32 v9, v9, v13
	ds_bpermute_b32 v13, v29, v9
	v_add_f32_e32 v5, v5, v17
	ds_bpermute_b32 v17, v39, v5
	s_waitcnt lgkmcnt(2)
	v_pk_add_f32 v[68:69], v[80:81], v[82:83]
	ds_bpermute_b32 v80, v37, v68
	ds_bpermute_b32 v81, v37, v69
	s_waitcnt lgkmcnt(3)
	v_add_f32_e32 v9, v9, v13
	ds_bpermute_b32 v13, v37, v9
	s_waitcnt lgkmcnt(3)
	v_add_f32_e32 v82, v5, v17
	s_waitcnt lgkmcnt(1)
	v_pk_add_f32 v[68:69], v[68:69], v[80:81]
	ds_bpermute_b32 v80, v39, v68
	ds_bpermute_b32 v81, v39, v69
	s_waitcnt lgkmcnt(2)
	v_add_f32_e32 v5, v9, v13
	ds_bpermute_b32 v9, v39, v5
	s_waitcnt lgkmcnt(1)
	v_pk_add_f32 v[68:69], v[68:69], v[80:81]
	s_nop 0
	v_pk_mul_f32 v[80:81], v[68:69], s[34:35] op_sel_hi:[1,0]
	v_pk_fma_f32 v[72:73], v[68:69], s[34:35], v[72:73] op_sel_hi:[1,0,1] neg_lo:[1,0,0] neg_hi:[1,0,0]
	v_mov_b32_e32 v83, v80
	v_mov_b32_e32 v187, v80
	v_pk_mul_f32 v[82:83], v[82:83], v[186:187]
	s_waitcnt lgkmcnt(0)
	v_add_f32_e32 v80, v5, v9
	v_mov_b32_e32 v187, v81
	v_pk_mul_f32 v[80:81], v[80:81], v[186:187]
	v_sub_f32_e32 v13, v82, v83
	v_sub_f32_e32 v5, v80, v81
	v_max_f32_e32 v82, 0, v13
	v_max_f32_e32 v83, 0, v5
	v_pk_add_f32 v[80:81], v[82:83], s[50:51] op_sel_hi:[1,0]
	v_pk_fma_f32 v[74:75], v[68:69], s[34:35], v[74:75] op_sel_hi:[1,0,1] neg_lo:[1,0,0] neg_hi:[1,0,0]
	v_mul_f32_e32 v5, 0x4b800000, v80
	v_cmp_gt_f32_e32 vcc, s2, v80
	v_cmp_gt_f32_e64 s[42:43], s2, v81
	v_pk_fma_f32 v[64:65], v[68:69], s[34:35], v[64:65] op_sel_hi:[1,0,1] neg_lo:[1,0,0] neg_hi:[1,0,0]
	v_cndmask_b32_e32 v5, v80, v5, vcc
	v_rsq_f32_e32 v80, v5
	v_mul_f32_e32 v5, 0x4b800000, v81
	v_cndmask_b32_e64 v5, v81, v5, s[42:43]
	v_rsq_f32_e32 v81, v5
	v_pk_fma_f32 v[76:77], v[68:69], s[34:35], v[76:77] op_sel_hi:[1,0,1] neg_lo:[1,0,0] neg_hi:[1,0,0]
	v_pk_fma_f32 v[62:63], v[68:69], s[34:35], v[62:63] op_sel_hi:[1,0,1] neg_lo:[1,0,0] neg_hi:[1,0,0]
	v_pk_fma_f32 v[66:67], v[68:69], s[34:35], v[66:67] op_sel_hi:[1,0,1] neg_lo:[1,0,0] neg_hi:[1,0,0]
	v_pk_mul_f32 v[82:83], v[80:81], s[20:21] op_sel_hi:[1,0]
	v_pk_fma_f32 v[78:79], v[68:69], s[34:35], v[78:79] op_sel_hi:[1,0,1] neg_lo:[1,0,0] neg_hi:[1,0,0]
	v_cndmask_b32_e64 v81, v81, v83, s[42:43]
	v_cndmask_b32_e32 v80, v80, v82, vcc
	v_pk_mul_f32 v[72:73], v[72:73], v[80:81]
	v_pk_mul_f32 v[74:75], v[74:75], v[80:81]
	v_pk_fma_f32 v[72:73], v[10:11], v[72:73], v[14:15] op_sel_hi:[0,1,0]
	v_pk_mul_f32 v[64:65], v[64:65], v[80:81]
	v_pk_fma_f32 v[74:75], v[10:11], v[74:75], v[14:15] op_sel:[1,0,1]
	v_pk_mul_f32 v[76:77], v[76:77], v[80:81]
	v_pk_fma_f32 v[64:65], v[4:5], v[64:65], v[8:9] op_sel_hi:[0,1,0]
	v_cvt_pk_bf16_f32 v5, v72, v73
	v_pk_fma_f32 v[76:77], v[12:13], v[76:77], v[16:17] op_sel_hi:[0,1,0]
	v_pk_mul_f32 v[62:63], v[62:63], v[80:81]
	ds_write_b32 v58, v5 offset:32
	v_cvt_pk_bf16_f32 v5, v74, v75
	v_pk_fma_f32 v[62:63], v[0:1], v[62:63], v[48:49] op_sel_hi:[0,1,0]
	v_pk_mul_f32 v[66:67], v[66:67], v[80:81]
	ds_write_b32 v58, v5 offset:176
	v_cvt_pk_bf16_f32 v5, v76, v77
	v_pk_fma_f32 v[66:67], v[2:3], v[66:67], v[6:7] op_sel_hi:[0,1,0]
	v_pk_mul_f32 v[78:79], v[78:79], v[80:81]
	ds_write_b32 v58, v5 offset:320
	v_cvt_pk_bf16_f32 v5, v62, v63
	v_pk_fma_f32 v[78:79], v[2:3], v[78:79], v[6:7] op_sel:[1,0,1]
	v_pk_fma_f32 v[68:69], v[68:69], s[34:35], v[70:71] op_sel_hi:[1,0,1] neg_lo:[1,0,0] neg_hi:[1,0,0]
	ds_write_b32 v58, v5 offset:464
	v_cvt_pk_bf16_f32 v5, v66, v67
	v_pk_mul_f32 v[68:69], v[68:69], v[80:81]
	ds_write_b32 v58, v5 offset:608
	v_cvt_pk_bf16_f32 v5, v78, v79
	v_pk_fma_f32 v[68:69], v[50:51], v[68:69], v[52:53] op_sel_hi:[0,1,0]
	ds_write_b32 v58, v5 offset:752
	v_cvt_pk_bf16_f32 v5, v64, v65
	ds_write_b32 v58, v5 offset:896
	v_cvt_pk_bf16_f32 v5, v68, v69
	ds_write_b32 v58, v5 offset:1040
	v_add_u32_e32 v5, 32, v35
	v_mad_i64_i32 v[66:67], s[18:19], v5, s11, v[26:27]
	v_add_u32_e32 v5, 33, v35
	v_mad_i64_i32 v[62:63], s[18:19], v5, s11, v[26:27]
	global_load_dwordx4 v[62:65], v[62:63], off offset:3264
	s_nop 0
	global_load_dwordx4 v[66:69], v[66:67], off offset:3264
	s_waitcnt vmcnt(0) lgkmcnt(0)
; DI unsigned cvtpk(float lo, float hi) { f32x2 v = {lo, hi}; bf16x2_t b = __builtin_convertvector(v, bf16x2_t); return __builtin_bit_cast(unsigned, b); }
; DI float bflo(unsigned u) { return __uint_as_float(u << 16); }
; DI float bfhi(unsigned u) { return __uint_as_float(u & 0xffff0000u); }
; DI void phase_feat_a(KP p, int l, char* lds) {
;     ...
;         for (int i = 0; i < 4; ++i) {
;           float vn[2][8];
; #pragma unroll
;           for (int rr = 0; rr < 2; ++rr) {
;             const int row = rb + 16 * i + rr;
;             u32x4 q = *(const u32x4*)(P + (size_t)(r0 + row) * NIN + O_V + 8 * c);
;             float f[8] = {bflo(q.x), bfhi(q.x), bflo(q.y), bfhi(q.y), bflo(q.z), bfhi(q.z), bflo(q.w), bfhi(q.w)};
;             float s1 = 0.f, s2 = 0.f;
; #pragma unroll
;             for (int e = 0; e < 8; ++e) { s1 += f[e]; s2 += f[e] * f[e]; }
; #pragma unroll
;             for (int m = 1; m < 32; m <<= 1) { s1 += __shfl_xor(s1, m); s2 += __shfl_xor(s2, m); }
;             const float mu = s1 * (1.f / 256.f); const float var = fmaxf(s2 * (1.f / 256.f) - mu * mu, 0.f); const float rs = rsqrtf(var + 1e-6f);
; #pragma unroll
;             for (int e = 0; e < 8; ++e) vn[rr][e] = (f[e] - mu) * rs * gg[e] + bb[e];
;           }
; #pragma unroll
;           for (int e = 0; e < 8; ++e) *(unsigned*)(ldh + (8 * c + e) * STR + (rb + 16 * i) * 2) = cvtpk(vn[0][e], vn[1][e]);
	v_lshlrev_b32_e32 v73, 16, v62
	v_and_b32_e32 v75, 0xffff0000, v62
	v_and_b32_e32 v74, 0xffff0000, v66
	v_lshlrev_b32_e32 v78, 16, v67
	v_and_b32_e32 v62, 0xffff0000, v67
	v_lshlrev_b32_e32 v72, 16, v66
	v_pk_mul_f32 v[76:77], v[74:75], v[74:75]
	v_mov_b32_e32 v66, v62
	v_mov_b32_e32 v67, v78
	v_pk_mul_f32 v[66:67], v[66:67], v[66:67]
	v_lshlrev_b32_e32 v80, 16, v68
	v_and_b32_e32 v82, 0xffff0000, v68
	v_pk_fma_f32 v[76:77], v[72:73], v[72:73], v[76:77]
	v_mov_b32_e32 v84, v82
	v_mov_b32_e32 v85, v80
	v_add_f32_e32 v5, v67, v76
	v_and_b32_e32 v70, 0xffff0000, v69
	v_lshlrev_b32_e32 v81, 16, v64
	v_and_b32_e32 v83, 0xffff0000, v64
	v_pk_mul_f32 v[84:85], v[84:85], v[84:85]
	v_lshlrev_b32_e32 v64, 16, v69
	v_add_f32_e32 v5, v66, v5
	v_mov_b32_e32 v68, v70
	v_mov_b32_e32 v69, v64
	v_add_f32_e32 v5, v85, v5
	v_pk_mul_f32 v[68:69], v[68:69], v[68:69]
	v_add_f32_e32 v5, v84, v5
	v_add_f32_e32 v5, v69, v5
	v_add_f32_e32 v5, v68, v5
	ds_bpermute_b32 v9, v33, v5
	v_pk_add_f32 v[66:67], v[72:73], 0 op_sel_hi:[1,0]
	v_lshlrev_b32_e32 v79, 16, v63
	v_pk_add_f32 v[66:67], v[66:67], v[74:75]
	v_and_b32_e32 v63, 0xffff0000, v63
	s_waitcnt lgkmcnt(0)
	v_add_f32_e32 v5, v5, v9
	ds_bpermute_b32 v9, v31, v5
	v_pk_add_f32 v[66:67], v[66:67], v[78:79]
	v_mov_b32_e32 v86, v63
	v_mov_b32_e32 v87, v79
	v_pk_add_f32 v[66:67], v[66:67], v[62:63]
	s_waitcnt lgkmcnt(0)
	v_add_f32_e32 v5, v5, v9
	ds_bpermute_b32 v9, v29, v5
	v_pk_mul_f32 v[86:87], v[86:87], v[86:87]
	v_pk_add_f32 v[66:67], v[66:67], v[80:81]
	v_and_b32_e32 v71, 0xffff0000, v65
	v_lshlrev_b32_e32 v65, 16, v65
	v_mov_b32_e32 v88, v83
	v_mov_b32_e32 v89, v81
	v_pk_add_f32 v[66:67], v[66:67], v[82:83]
	s_waitcnt lgkmcnt(0)
	v_add_f32_e32 v5, v5, v9
	v_add_f32_e32 v9, v87, v77
	v_pk_add_f32 v[66:67], v[66:67], v[64:65]
	v_pk_mul_f32 v[84:85], v[88:89], v[88:89]
	v_add_f32_e32 v9, v86, v9
	v_pk_add_f32 v[66:67], v[66:67], v[70:71]
	v_mov_b32_e32 v88, v71
	v_mov_b32_e32 v89, v65
	v_add_f32_e32 v9, v85, v9
	ds_bpermute_b32 v68, v33, v66
	ds_bpermute_b32 v69, v33, v67
	v_pk_mul_f32 v[88:89], v[88:89], v[88:89]
	v_add_f32_e32 v9, v84, v9
	v_add_f32_e32 v9, v89, v9
	v_add_f32_e32 v9, v88, v9
	ds_bpermute_b32 v13, v33, v9
	s_waitcnt lgkmcnt(1)
	v_pk_add_f32 v[66:67], v[66:67], v[68:69]
	ds_bpermute_b32 v68, v31, v66
	ds_bpermute_b32 v69, v31, v67
	ds_bpermute_b32 v17, v37, v5
	s_waitcnt lgkmcnt(3)
	v_add_f32_e32 v9, v9, v13
	ds_bpermute_b32 v13, v31, v9
	s_waitcnt lgkmcnt(2)
	v_pk_add_f32 v[66:67], v[66:67], v[68:69]
	ds_bpermute_b32 v68, v29, v66
	ds_bpermute_b32 v69, v29, v67
	s_waitcnt lgkmcnt(2)
	v_add_f32_e32 v9, v9, v13
	ds_bpermute_b32 v13, v29, v9
	v_add_f32_e32 v5, v5, v17
	ds_bpermute_b32 v17, v39, v5
	s_waitcnt lgkmcnt(2)
	v_pk_add_f32 v[66:67], v[66:67], v[68:69]
	ds_bpermute_b32 v68, v37, v66
	ds_bpermute_b32 v69, v37, v67
	s_waitcnt lgkmcnt(3)
	v_add_f32_e32 v9, v9, v13
	ds_bpermute_b32 v13, v37, v9
	s_waitcnt lgkmcnt(3)
	v_add_f32_e32 v76, v5, v17
	s_waitcnt lgkmcnt(1)
	v_pk_add_f32 v[66:67], v[66:67], v[68:69]
	ds_bpermute_b32 v68, v39, v66
	ds_bpermute_b32 v69, v39, v67
	s_waitcnt lgkmcnt(2)
	v_add_f32_e32 v5, v9, v13
	ds_bpermute_b32 v9, v39, v5
	s_waitcnt lgkmcnt(1)
	v_pk_add_f32 v[66:67], v[66:67], v[68:69]
	s_nop 0
	v_pk_mul_f32 v[68:69], v[66:67], s[34:35] op_sel_hi:[1,0]
	v_pk_fma_f32 v[72:73], v[66:67], s[34:35], v[72:73] op_sel_hi:[1,0,1] neg_lo:[1,0,0] neg_hi:[1,0,0]
	v_mov_b32_e32 v77, v68
	v_mov_b32_e32 v187, v68
	v_pk_mul_f32 v[76:77], v[76:77], v[186:187]
	s_waitcnt lgkmcnt(0)
	v_add_f32_e32 v68, v5, v9
	v_mov_b32_e32 v187, v69
	v_pk_mul_f32 v[68:69], v[68:69], v[186:187]
	v_sub_f32_e32 v13, v76, v77
	v_sub_f32_e32 v5, v68, v69
	v_max_f32_e32 v76, 0, v13
	v_max_f32_e32 v77, 0, v5
	v_pk_add_f32 v[68:69], v[76:77], s[50:51] op_sel_hi:[1,0]
	v_pk_fma_f32 v[74:75], v[66:67], s[34:35], v[74:75] op_sel_hi:[1,0,1] neg_lo:[1,0,0] neg_hi:[1,0,0]
	v_mul_f32_e32 v5, 0x4b800000, v68
	v_cmp_gt_f32_e32 vcc, s2, v68
	v_cmp_gt_f32_e64 s[42:43], s2, v69
	v_pk_fma_f32 v[64:65], v[66:67], s[34:35], v[64:65] op_sel_hi:[1,0,1] neg_lo:[1,0,0] neg_hi:[1,0,0]
	v_cndmask_b32_e32 v5, v68, v5, vcc
	v_rsq_f32_e32 v68, v5
	v_mul_f32_e32 v5, 0x4b800000, v69
	v_cndmask_b32_e64 v5, v69, v5, s[42:43]
	v_rsq_f32_e32 v69, v5
	v_pk_fma_f32 v[62:63], v[66:67], s[34:35], v[62:63] op_sel_hi:[1,0,1] neg_lo:[1,0,0] neg_hi:[1,0,0]
	v_pk_mul_f32 v[76:77], v[68:69], s[20:21] op_sel_hi:[1,0]
	s_nop 0
	v_cndmask_b32_e64 v69, v69, v77, s[42:43]
	v_cndmask_b32_e32 v68, v68, v76, vcc
	v_pk_mul_f32 v[72:73], v[72:73], v[68:69]
	v_pk_mul_f32 v[74:75], v[74:75], v[68:69]
	v_pk_fma_f32 v[72:73], v[10:11], v[72:73], v[14:15] op_sel_hi:[0,1,0]
	v_pk_fma_f32 v[76:77], v[66:67], s[34:35], v[78:79] op_sel_hi:[1,0,1] neg_lo:[1,0,0] neg_hi:[1,0,0]
	v_pk_mul_f32 v[64:65], v[64:65], v[68:69]
	v_pk_fma_f32 v[74:75], v[10:11], v[74:75], v[14:15] op_sel:[1,0,1]
	v_pk_mul_f32 v[76:77], v[76:77], v[68:69]
	v_pk_fma_f32 v[64:65], v[4:5], v[64:65], v[8:9] op_sel_hi:[0,1,0]
	v_cvt_pk_bf16_f32 v5, v72, v73
	v_pk_fma_f32 v[76:77], v[12:13], v[76:77], v[16:17] op_sel_hi:[0,1,0]
	v_pk_mul_f32 v[62:63], v[62:63], v[68:69]
	v_pk_fma_f32 v[78:79], v[66:67], s[34:35], v[80:81] op_sel_hi:[1,0,1] neg_lo:[1,0,0] neg_hi:[1,0,0]
	ds_write_b32 v58, v5 offset:64
	v_cvt_pk_bf16_f32 v5, v74, v75
	v_pk_fma_f32 v[62:63], v[0:1], v[62:63], v[48:49] op_sel_hi:[0,1,0]
	v_pk_mul_f32 v[78:79], v[78:79], v[68:69]
	v_pk_fma_f32 v[80:81], v[66:67], s[34:35], v[82:83] op_sel_hi:[1,0,1] neg_lo:[1,0,0] neg_hi:[1,0,0]
	ds_write_b32 v58, v5 offset:208
	v_cvt_pk_bf16_f32 v5, v76, v77
	v_pk_fma_f32 v[78:79], v[2:3], v[78:79], v[6:7] op_sel_hi:[0,1,0]
	v_pk_mul_f32 v[80:81], v[80:81], v[68:69]
	ds_write_b32 v58, v5 offset:352
	v_cvt_pk_bf16_f32 v5, v62, v63
	v_pk_fma_f32 v[80:81], v[2:3], v[80:81], v[6:7] op_sel:[1,0,1]
	v_pk_fma_f32 v[66:67], v[66:67], s[34:35], v[70:71] op_sel_hi:[1,0,1] neg_lo:[1,0,0] neg_hi:[1,0,0]
	ds_write_b32 v58, v5 offset:496
	v_cvt_pk_bf16_f32 v5, v78, v79
	v_pk_mul_f32 v[66:67], v[66:67], v[68:69]
	ds_write_b32 v58, v5 offset:640
	v_cvt_pk_bf16_f32 v5, v80, v81
	v_pk_fma_f32 v[66:67], v[50:51], v[66:67], v[52:53] op_sel_hi:[0,1,0]
	ds_write_b32 v58, v5 offset:784
	v_cvt_pk_bf16_f32 v5, v64, v65
	ds_write_b32 v58, v5 offset:928
	v_cvt_pk_bf16_f32 v5, v66, v67
	ds_write_b32 v58, v5 offset:1072
	v_add_u32_e32 v5, 48, v35
	v_mad_i64_i32 v[66:67], s[18:19], v5, s11, v[26:27]
	v_add_u32_e32 v5, 49, v35
	v_mad_i64_i32 v[62:63], s[18:19], v5, s11, v[26:27]
	global_load_dwordx4 v[62:65], v[62:63], off offset:3264
	s_nop 0
	global_load_dwordx4 v[66:69], v[66:67], off offset:3264
	v_mov_b32_e32 v35, v1
	s_waitcnt vmcnt(0) lgkmcnt(0)
; DI unsigned cvtpk(float lo, float hi) { f32x2 v = {lo, hi}; bf16x2_t b = __builtin_convertvector(v, bf16x2_t); return __builtin_bit_cast(unsigned, b); }
; DI float bflo(unsigned u) { return __uint_as_float(u << 16); }
; DI float bfhi(unsigned u) { return __uint_as_float(u & 0xffff0000u); }
; DI void phase_feat_a(KP p, int l, char* lds) {
;     ...
;         for (int i = 0; i < 4; ++i) {
;           float vn[2][8];
; #pragma unroll
;           for (int rr = 0; rr < 2; ++rr) {
;             const int row = rb + 16 * i + rr;
;             u32x4 q = *(const u32x4*)(P + (size_t)(r0 + row) * NIN + O_V + 8 * c);
;             float f[8] = {bflo(q.x), bfhi(q.x), bflo(q.y), bfhi(q.y), bflo(q.z), bfhi(q.z), bflo(q.w), bfhi(q.w)};
;             float s1 = 0.f, s2 = 0.f;
; #pragma unroll
;             for (int e = 0; e < 8; ++e) { s1 += f[e]; s2 += f[e] * f[e]; }
; #pragma unroll
;             for (int m = 1; m < 32; m <<= 1) { s1 += __shfl_xor(s1, m); s2 += __shfl_xor(s2, m); }
;             const float mu = s1 * (1.f / 256.f); const float var = fmaxf(s2 * (1.f / 256.f) - mu * mu, 0.f); const float rs = rsqrtf(var + 1e-6f);
; #pragma unroll
;             for (int e = 0; e < 8; ++e) vn[rr][e] = (f[e] - mu) * rs * gg[e] + bb[e];
;           }
; #pragma unroll
;           for (int e = 0; e < 8; ++e) *(unsigned*)(ldh + (8 * c + e) * STR + (rb + 16 * i) * 2) = cvtpk(vn[0][e], vn[1][e]);
;         }
;         __syncthreads();
	v_lshlrev_b32_e32 v73, 16, v62
	v_and_b32_e32 v75, 0xffff0000, v62
	v_and_b32_e32 v74, 0xffff0000, v66
	v_lshlrev_b32_e32 v78, 16, v67
	v_and_b32_e32 v62, 0xffff0000, v67
	v_lshlrev_b32_e32 v72, 16, v66
	v_pk_mul_f32 v[76:77], v[74:75], v[74:75]
	v_mov_b32_e32 v66, v62
	v_mov_b32_e32 v67, v78
	v_pk_mul_f32 v[66:67], v[66:67], v[66:67]
	v_lshlrev_b32_e32 v80, 16, v68
	v_and_b32_e32 v82, 0xffff0000, v68
	v_pk_fma_f32 v[76:77], v[72:73], v[72:73], v[76:77]
	v_mov_b32_e32 v84, v82
	v_mov_b32_e32 v85, v80
	v_add_f32_e32 v5, v67, v76
	v_and_b32_e32 v70, 0xffff0000, v69
	v_lshlrev_b32_e32 v81, 16, v64
	v_and_b32_e32 v83, 0xffff0000, v64
	v_pk_mul_f32 v[84:85], v[84:85], v[84:85]
	v_lshlrev_b32_e32 v64, 16, v69
	v_add_f32_e32 v5, v66, v5
	v_mov_b32_e32 v68, v70
	v_mov_b32_e32 v69, v64
	v_add_f32_e32 v5, v85, v5
	v_pk_mul_f32 v[68:69], v[68:69], v[68:69]
	v_add_f32_e32 v5, v84, v5
	v_add_f32_e32 v5, v69, v5
	v_add_f32_e32 v5, v68, v5
	ds_bpermute_b32 v9, v33, v5
	v_pk_add_f32 v[66:67], v[72:73], 0 op_sel_hi:[1,0]
	v_lshlrev_b32_e32 v79, 16, v63
	v_pk_add_f32 v[66:67], v[66:67], v[74:75]
	v_and_b32_e32 v63, 0xffff0000, v63
	s_waitcnt lgkmcnt(0)
	v_add_f32_e32 v5, v5, v9
	ds_bpermute_b32 v9, v31, v5
	v_pk_add_f32 v[66:67], v[66:67], v[78:79]
	v_mov_b32_e32 v86, v63
	v_mov_b32_e32 v87, v79
	v_pk_add_f32 v[66:67], v[66:67], v[62:63]
	s_waitcnt lgkmcnt(0)
	v_add_f32_e32 v5, v5, v9
	ds_bpermute_b32 v9, v29, v5
	v_pk_mul_f32 v[86:87], v[86:87], v[86:87]
	v_pk_add_f32 v[66:67], v[66:67], v[80:81]
	v_and_b32_e32 v71, 0xffff0000, v65
	v_lshlrev_b32_e32 v65, 16, v65
	v_mov_b32_e32 v88, v83
	v_mov_b32_e32 v89, v81
	v_pk_add_f32 v[66:67], v[66:67], v[82:83]
	s_waitcnt lgkmcnt(0)
	v_add_f32_e32 v5, v5, v9
	v_add_f32_e32 v9, v87, v77
	v_pk_add_f32 v[66:67], v[66:67], v[64:65]
	v_pk_mul_f32 v[84:85], v[88:89], v[88:89]
	v_add_f32_e32 v9, v86, v9
	v_pk_add_f32 v[66:67], v[66:67], v[70:71]
	v_mov_b32_e32 v88, v71
	v_mov_b32_e32 v89, v65
	v_add_f32_e32 v9, v85, v9
	ds_bpermute_b32 v68, v33, v66
	ds_bpermute_b32 v69, v33, v67
	v_pk_mul_f32 v[88:89], v[88:89], v[88:89]
	v_add_f32_e32 v9, v84, v9
	v_add_f32_e32 v9, v89, v9
	v_add_f32_e32 v9, v88, v9
	ds_bpermute_b32 v13, v33, v9
	s_waitcnt lgkmcnt(1)
	v_pk_add_f32 v[66:67], v[66:67], v[68:69]
	ds_bpermute_b32 v68, v31, v66
	ds_bpermute_b32 v69, v31, v67
	ds_bpermute_b32 v17, v37, v5
	s_waitcnt lgkmcnt(3)
	v_add_f32_e32 v9, v9, v13
	ds_bpermute_b32 v13, v31, v9
	v_mov_b32_e32 v31, v1
	s_waitcnt lgkmcnt(2)
	v_pk_add_f32 v[66:67], v[66:67], v[68:69]
	ds_bpermute_b32 v68, v29, v66
	ds_bpermute_b32 v69, v29, v67
	s_waitcnt lgkmcnt(2)
	v_add_f32_e32 v9, v9, v13
	ds_bpermute_b32 v13, v29, v9
	v_add_f32_e32 v5, v5, v17
	ds_bpermute_b32 v17, v39, v5
	s_waitcnt lgkmcnt(2)
	v_pk_add_f32 v[66:67], v[66:67], v[68:69]
	ds_bpermute_b32 v68, v37, v66
	ds_bpermute_b32 v69, v37, v67
	s_waitcnt lgkmcnt(3)
	v_add_f32_e32 v9, v9, v13
	ds_bpermute_b32 v13, v37, v9
	s_waitcnt lgkmcnt(3)
	v_add_f32_e32 v76, v5, v17
	v_mov_b32_e32 v33, v1
	s_waitcnt lgkmcnt(1)
	v_pk_add_f32 v[66:67], v[66:67], v[68:69]
	ds_bpermute_b32 v68, v39, v66
	ds_bpermute_b32 v69, v39, v67
	s_waitcnt lgkmcnt(2)
	v_add_f32_e32 v5, v9, v13
	ds_bpermute_b32 v9, v39, v5
	v_mov_b32_e32 v37, v1
	v_mov_b32_e32 v39, v1
	s_waitcnt lgkmcnt(1)
	v_pk_add_f32 v[66:67], v[66:67], v[68:69]
	s_nop 0
	v_pk_mul_f32 v[68:69], v[66:67], s[34:35] op_sel_hi:[1,0]
	v_pk_fma_f32 v[72:73], v[66:67], s[34:35], v[72:73] op_sel_hi:[1,0,1] neg_lo:[1,0,0] neg_hi:[1,0,0]
	v_mov_b32_e32 v77, v68
	v_mov_b32_e32 v187, v68
	v_pk_mul_f32 v[76:77], v[76:77], v[186:187]
	s_waitcnt lgkmcnt(0)
	v_add_f32_e32 v68, v5, v9
	v_mov_b32_e32 v187, v69
	v_pk_mul_f32 v[68:69], v[68:69], v[186:187]
	v_sub_f32_e32 v13, v76, v77
	v_sub_f32_e32 v5, v68, v69
	v_max_f32_e32 v76, 0, v13
	v_max_f32_e32 v77, 0, v5
	v_pk_add_f32 v[68:69], v[76:77], s[50:51] op_sel_hi:[1,0]
	v_pk_fma_f32 v[74:75], v[66:67], s[34:35], v[74:75] op_sel_hi:[1,0,1] neg_lo:[1,0,0] neg_hi:[1,0,0]
	v_mul_f32_e32 v5, 0x4b800000, v68
	v_cmp_gt_f32_e32 vcc, s2, v68
	v_cmp_gt_f32_e64 s[42:43], s2, v69
	v_mov_b32_e32 v187, v45
	v_cndmask_b32_e32 v5, v68, v5, vcc
	v_rsq_f32_e32 v68, v5
	v_mul_f32_e32 v5, 0x4b800000, v69
	v_cndmask_b32_e64 v5, v69, v5, s[42:43]
	v_rsq_f32_e32 v69, v5
	v_mov_b32_e32 v45, v1
	v_pk_mul_f32 v[76:77], v[68:69], s[20:21] op_sel_hi:[1,0]
	s_nop 0
	v_cndmask_b32_e64 v69, v69, v77, s[42:43]
	v_cndmask_b32_e32 v68, v68, v76, vcc
	v_pk_mul_f32 v[72:73], v[72:73], v[68:69]
	v_pk_mul_f32 v[74:75], v[74:75], v[68:69]
	v_pk_fma_f32 v[72:73], v[10:11], v[72:73], v[14:15] op_sel_hi:[0,1,0]
	v_pk_fma_f32 v[10:11], v[10:11], v[74:75], v[14:15] op_sel:[1,0,1]
	v_pk_fma_f32 v[14:15], v[66:67], s[34:35], v[78:79] op_sel_hi:[1,0,1] neg_lo:[1,0,0] neg_hi:[1,0,0]
	s_nop 0
	v_pk_mul_f32 v[14:15], v[14:15], v[68:69]
	s_nop 0
	v_pk_fma_f32 v[12:13], v[12:13], v[14:15], v[16:17] op_sel_hi:[0,1,0]
	v_pk_fma_f32 v[14:15], v[66:67], s[34:35], v[62:63] op_sel_hi:[1,0,1] neg_lo:[1,0,0] neg_hi:[1,0,0]
	v_pk_fma_f32 v[16:17], v[66:67], s[34:35], v[80:81] op_sel_hi:[1,0,1] neg_lo:[1,0,0] neg_hi:[1,0,0]
	v_pk_mul_f32 v[14:15], v[14:15], v[68:69]
	v_pk_fma_f32 v[62:63], v[66:67], s[34:35], v[82:83] op_sel_hi:[1,0,1] neg_lo:[1,0,0] neg_hi:[1,0,0]
	v_pk_fma_f32 v[14:15], v[0:1], v[14:15], v[48:49] op_sel_hi:[0,1,0]
	v_cvt_pk_bf16_f32 v0, v72, v73
	v_pk_mul_f32 v[16:17], v[16:17], v[68:69]
	v_pk_mul_f32 v[62:63], v[62:63], v[68:69]
	ds_write_b32 v58, v0 offset:96
	v_cvt_pk_bf16_f32 v0, v10, v11
	v_pk_fma_f32 v[16:17], v[2:3], v[16:17], v[6:7] op_sel_hi:[0,1,0]
	v_pk_fma_f32 v[2:3], v[2:3], v[62:63], v[6:7] op_sel:[1,0,1]
	v_pk_fma_f32 v[6:7], v[66:67], s[34:35], v[64:65] op_sel_hi:[1,0,1] neg_lo:[1,0,0] neg_hi:[1,0,0]
	ds_write_b32 v58, v0 offset:240
	v_cvt_pk_bf16_f32 v0, v12, v13
	v_pk_mul_f32 v[6:7], v[6:7], v[68:69]
	ds_write_b32 v58, v0 offset:384
	v_cvt_pk_bf16_f32 v0, v14, v15
	v_pk_fma_f32 v[4:5], v[4:5], v[6:7], v[8:9] op_sel_hi:[0,1,0]
	v_pk_fma_f32 v[6:7], v[66:67], s[34:35], v[70:71] op_sel_hi:[1,0,1] neg_lo:[1,0,0] neg_hi:[1,0,0]
	ds_write_b32 v58, v0 offset:528
	v_cvt_pk_bf16_f32 v0, v16, v17
	v_pk_mul_f32 v[6:7], v[6:7], v[68:69]
	ds_write_b32 v58, v0 offset:672
	v_cvt_pk_bf16_f32 v0, v2, v3
	v_pk_fma_f32 v[6:7], v[50:51], v[6:7], v[52:53] op_sel_hi:[0,1,0]
	ds_write_b32 v58, v0 offset:816
	v_cvt_pk_bf16_f32 v0, v4, v5
	v_ashrrev_i32_e32 v2, 2, v19
	ds_write_b32 v58, v0 offset:960
	v_cvt_pk_bf16_f32 v0, v6, v7
	v_ashrrev_i32_e32 v3, 31, v2
	ds_write_b32 v58, v0 offset:1104
	v_lshlrev_b64 v[2:3], 16, v[2:3]
	v_and_b32_e32 v0, 64, v56
	v_lshl_add_u64 v[2:3], s[48:49], 0, v[2:3]
	v_lshlrev_b32_e32 v0, 1, v0
	s_waitcnt lgkmcnt(0)
	s_barrier
; DI void phase_feat_a(KP p, int l, char* lds) {
;     ...
;         bf16_t* vo = vnT + (size_t)(r0 >> 7) * 256 * 128 + (r0 & 127);
; #pragma unroll
;         for (int i = 0; i < 8; ++i) {
;           const int ch = (tq >> 3) + 32 * i, part = tq & 7;
;           *(u32x4*)(vo + (size_t)ch * 128 + part * 8) = *(const u32x4*)(ldh + ch * STR + part * 16);
;         }
	v_lshl_add_u64 v[6:7], v[2:3], 0, v[0:1]
	ds_read_b128 v[2:5], v60
	v_lshl_add_u64 v[6:7], v[6:7], 0, v[46:47]
	v_lshl_add_u64 v[8:9], v[6:7], 0, v[30:31]
	s_waitcnt lgkmcnt(0)
	global_store_dwordx4 v[8:9], v[2:5], off
	ds_read_b128 v[2:5], v60 offset:4608
	v_lshl_add_u64 v[8:9], v[6:7], 0, v[32:33]
	s_waitcnt lgkmcnt(0)
	global_store_dwordx4 v[8:9], v[2:5], off
	ds_read_b128 v[2:5], v60 offset:9216
	v_lshl_add_u64 v[8:9], v[6:7], 0, v[34:35]
	s_waitcnt lgkmcnt(0)
	global_store_dwordx4 v[8:9], v[2:5], off
	ds_read_b128 v[2:5], v60 offset:13824
	v_lshl_add_u64 v[8:9], v[6:7], 0, v[36:37]
	s_waitcnt lgkmcnt(0)
	global_store_dwordx4 v[8:9], v[2:5], off
	ds_read_b128 v[2:5], v59
	v_lshl_add_u64 v[8:9], v[6:7], 0, v[38:39]
	s_waitcnt lgkmcnt(0)
	global_store_dwordx4 v[8:9], v[2:5], off
	ds_read_b128 v[2:5], v59 offset:4608
	v_lshl_add_u64 v[8:9], v[6:7], 0, v[40:41]
	s_waitcnt lgkmcnt(0)
	global_store_dwordx4 v[8:9], v[2:5], off
	ds_read_b128 v[2:5], v59 offset:9216
	v_lshl_add_u64 v[8:9], v[6:7], 0, v[42:43]
	v_lshl_add_u64 v[6:7], v[6:7], 0, v[44:45]
	s_waitcnt lgkmcnt(0)
	global_store_dwordx4 v[8:9], v[2:5], off
	ds_read_b128 v[2:5], v59 offset:13824
	s_waitcnt lgkmcnt(0)
	global_store_dwordx4 v[6:7], v[2:5], off
	s_branch .LBB0_261

; DI u32x2 pack4(f32x4 v) { u32x2 r = {cvtpk(v[0], v[1]), cvtpk(v[2], v[3])}; return r; }
; DI float red64(float v) { v = red16(v); v += __shfl_xor(v, 16); v += __shfl_xor(v, 32); return v; }
; DI void phase_norm(KP p, int l) {
;     ...
;   for (int r = gw * rpw; r < min(M, (gw + 1) * rpw); ++r) {
;     const int b = r / T, t = r % T;
;     const float* src = (t < SEQ) ? xl + ((size_t)b * SEQ + t) * 1024 : xc + ((size_t)b * CL + (t - SEQ)) * 1024;
;     const int mrow = (t < SEQ) ? b : 16;
;     if (mrow != cur_mod) {
;       cur_mod = mrow;
;       const float* mr = mod + (size_t)mrow * 3072;
; #pragma unroll
;       for (int i = 0; i < 4; ++i) {
;         const int k = i * 256 + lane * 4;
;         const f32x4 gg = *(const f32x4*)(g + k), sc = *(const f32x4*)(mr + 1024 + k);
;         SH[i] = *(const f32x4*)(mr + k);
; #pragma unroll
;         for (int e = 0; e < 4; ++e) G[i][e] = gg[e] * (1.f + sc[e]);
;       }
;     }
;     f32x4 v[4]; float ss = 0.f;
; #pragma unroll
;     for (int i = 0; i < 4; ++i) { v[i] = *(const f32x4*)(src + i * 256 + lane * 4); ss += v[i][0] * v[i][0] + v[i][1] * v[i][1] + v[i][2] * v[i][2] + v[i][3] * v[i][3]; }
;     ss = red64(ss);
;     const float rstd = rsqrtf(ss * (1.f / 1024.f) + 1e-6f);
; #pragma unroll
;     for (int i = 0; i < 4; ++i) {
;       const int k = i * 256 + lane * 4;
;       f32x4 o;
; #pragma unroll
;       for (int e = 0; e < 4; ++e) o[e] = v[i][e] * rstd * G[i][e] + SH[i][e];
;       *(u32x2*)(hx + (size_t)r * 1024 + k) = pack4(o);
;     }
.LBB0_274:
	s_or_b64 exec, exec, s[18:19]
	v_lshl_add_u64 v[52:53], v[48:49], 0, v[0:1]
	global_load_dwordx4 v[48:51], v[52:53], off
	global_load_dwordx4 v[56:59], v[52:53], off offset:1024
	global_load_dwordx4 v[60:63], v[52:53], off offset:2048
	global_load_dwordx4 v[64:67], v[52:53], off offset:3072
	s_mov_b32 s2, 0x800000
	s_waitcnt vmcnt(0) lgkmcnt(0)
	v_mov_b32_e32 v68, v49
	v_mov_b32_e32 v69, v57
	v_mov_b32_e32 v52, v48
	v_mov_b32_e32 v53, v56
	v_mov_b32_e32 v76, v61
	v_mov_b32_e32 v77, v65
	v_pk_mul_f32 v[68:69], v[68:69], v[68:69]
	v_mov_b32_e32 v70, v50
	v_mov_b32_e32 v71, v58
	v_mov_b32_e32 v74, v60
	v_mov_b32_e32 v75, v64
	v_pk_mul_f32 v[76:77], v[76:77], v[76:77]
	v_pk_fma_f32 v[52:53], v[52:53], v[52:53], v[68:69]
	v_mov_b32_e32 v72, v51
	v_mov_b32_e32 v73, v59
	v_mov_b32_e32 v78, v62
	v_mov_b32_e32 v79, v66
	v_pk_fma_f32 v[68:69], v[74:75], v[74:75], v[76:77]
	v_pk_fma_f32 v[52:53], v[70:71], v[70:71], v[52:53]
	v_mov_b32_e32 v80, v63
	v_mov_b32_e32 v81, v67
	v_pk_fma_f32 v[68:69], v[78:79], v[78:79], v[68:69]
	v_pk_fma_f32 v[52:53], v[72:73], v[72:73], v[52:53]
	v_pk_fma_f32 v[68:69], v[80:81], v[80:81], v[68:69]
	v_add_f32_e32 v0, v52, v53
	v_add_f32_e32 v0, v0, v68
	v_add_f32_e32 v0, v0, v69
	s_nop 1
	v_add_f32_dpp v0, v0, v0 quad_perm:[1,0,3,2] row_mask:0xf bank_mask:0xf bound_ctrl:1
	s_nop 1
	v_add_f32_dpp v0, v0, v0 quad_perm:[2,3,0,1] row_mask:0xf bank_mask:0xf bound_ctrl:1
	s_nop 1
	v_add_f32_dpp v0, v0, v0 row_ror:4 row_mask:0xf bank_mask:0xf bound_ctrl:1
	s_nop 1
	v_add_f32_dpp v0, v0, v0 row_ror:8 row_mask:0xf bank_mask:0xf bound_ctrl:1
	ds_bpermute_b32 v35, v54, v0
	s_waitcnt lgkmcnt(0)
	v_add_f32_e32 v0, v0, v35
	ds_bpermute_b32 v45, v55, v0
	v_ashrrev_i32_e32 v35, 31, v34
	v_lshlrev_b64 v[52:53], 11, v[34:35]
	v_add_u32_e32 v34, 1, v34
	v_cmp_ge_i32_e64 s[40:41], v34, v37
	s_waitcnt lgkmcnt(0)
	v_add_f32_e32 v0, v0, v45
	v_fmamk_f32 v0, v0, 0x3a800000, v198
	v_mul_f32_e32 v35, 0x4b800000, v0
	v_cmp_gt_f32_e32 vcc, s2, v0
	v_lshl_add_u64 v[52:53], v[40:41], 0, v[52:53]
	s_or_b64 s[46:47], s[40:41], s[46:47]
	v_cndmask_b32_e32 v0, v0, v35, vcc
	v_rsq_f32_e32 v0, v0
	s_nop 0
	v_mul_f32_e32 v35, 0x45800000, v0
	v_cndmask_b32_e32 v0, v0, v35, vcc
	v_pk_mul_f32 v[48:49], v[48:49], v[0:1] op_sel_hi:[1,0]
	v_pk_mul_f32 v[50:51], v[50:51], v[0:1] op_sel_hi:[1,0]
	v_pk_mul_f32 v[56:57], v[56:57], v[0:1] op_sel_hi:[1,0]
	v_pk_mul_f32 v[58:59], v[58:59], v[0:1] op_sel_hi:[1,0]
	v_pk_mul_f32 v[60:61], v[60:61], v[0:1] op_sel_hi:[1,0]
	v_pk_mul_f32 v[62:63], v[62:63], v[0:1] op_sel_hi:[1,0]
	v_pk_mul_f32 v[64:65], v[64:65], v[0:1] op_sel_hi:[1,0]
	v_pk_mul_f32 v[66:67], v[66:67], v[0:1] op_sel_hi:[1,0]
	v_pk_fma_f32 v[48:49], v[2:3], v[48:49], v[30:31]
	v_pk_fma_f32 v[50:51], v[4:5], v[50:51], v[32:33]
	v_pk_fma_f32 v[56:57], v[6:7], v[56:57], v[26:27]
	v_pk_fma_f32 v[58:59], v[8:9], v[58:59], v[28:29]
	v_pk_fma_f32 v[60:61], v[10:11], v[60:61], v[22:23]
	v_pk_fma_f32 v[62:63], v[12:13], v[62:63], v[24:25]
	v_pk_fma_f32 v[64:65], v[14:15], v[64:65], v[18:19]
	v_pk_fma_f32 v[66:67], v[16:17], v[66:67], v[20:21]
	v_cvt_pk_bf16_f32 v48, v48, v49
	v_cvt_pk_bf16_f32 v49, v50, v51
	v_cvt_pk_bf16_f32 v50, v56, v57
	v_cvt_pk_bf16_f32 v51, v58, v59
	v_cvt_pk_bf16_f32 v56, v60, v61
	v_cvt_pk_bf16_f32 v57, v62, v63
	v_cvt_pk_bf16_f32 v58, v64, v65
	v_cvt_pk_bf16_f32 v59, v66, v67
	global_store_dwordx2 v[52:53], v[48:49], off
	global_store_dwordx2 v[52:53], v[50:51], off offset:512
	global_store_dwordx2 v[52:53], v[56:57], off offset:1024
	global_store_dwordx2 v[52:53], v[58:59], off offset:1536
	s_andn2_b64 exec, exec, s[46:47]
	s_cbranch_execz .LBB0_283
.LBB0_275:
	s_mov_b32 s2, 0x38e38e39
	v_mul_hi_i32 v0, v34, s2
	v_lshrrev_b32_e32 v35, 31, v0
	v_ashrrev_i32_e32 v0, 9, v0
	v_add_u32_e32 v50, v0, v35
	v_mul_i32_i24_e32 v0, 0x900, v50
	v_sub_u32_e32 v52, v34, v0
	s_movk_i32 s2, 0x7ff
	v_cmp_lt_i32_e32 vcc, s2, v52
	v_ashrrev_i32_e32 v51, 31, v50
	s_and_saveexec_b64 s[18:19], vcc
	s_xor_b64 s[18:19], exec, s[18:19]
	v_add_u32_e32 v0, 0xfffff800, v52
	v_lshlrev_b64 v[48:49], 20, v[50:51]
	v_lshl_add_u64 v[48:49], s[4:5], 0, v[48:49]
	v_lshlrev_b64 v[50:51], 12, v[0:1]
	v_lshl_add_u64 v[48:49], v[48:49], 0, v[50:51]
	s_or_saveexec_b64 s[18:19], s[18:19]
	v_mov_b32_e32 v35, 16
	s_xor_b64 exec, exec, s[18:19]
	v_ashrrev_i32_e32 v53, 31, v52
	v_lshlrev_b64 v[48:49], 23, v[50:51]
	v_lshl_add_u64 v[48:49], s[36:37], 0, v[48:49]
	v_lshlrev_b64 v[52:53], 12, v[52:53]
	v_lshl_add_u64 v[48:49], v[48:49], 0, v[52:53]
	v_mov_b32_e32 v35, v50
	s_or_b64 exec, exec, s[18:19]
	v_cmp_ne_u32_e32 vcc, v35, v43
	v_lshlrev_b32_e32 v0, 2, v36
	s_and_saveexec_b64 s[18:19], vcc
	s_cbranch_execz .LBB0_274
	v_mul_hi_i32_i24_e32 v3, 0x3000, v35
	v_mul_i32_i24_e32 v2, 0x3000, v35
	v_lshl_add_u64 v[18:19], s[44:45], 0, v[2:3]
	v_lshl_add_u64 v[10:11], v[18:19], 0, s[72:73]
	v_mov_b32_e32 v43, v1
	v_mov_b32_e32 v45, v1
	v_mov_b32_e32 v47, v1
	v_lshl_add_u64 v[2:3], v[10:11], 0, v[0:1]
	v_lshl_add_u64 v[6:7], v[10:11], 0, v[42:43]
	v_lshl_add_u64 v[12:13], v[10:11], 0, v[44:45]
	v_lshl_add_u64 v[14:15], v[10:11], 0, v[46:47]
	v_lshl_add_u64 v[18:19], v[18:19], 0, v[0:1]
	global_load_dwordx4 v[2:5], v[2:3], off
	v_mov_b32_e32 v43, v35
	global_load_dwordx4 v[6:9], v[6:7], off
	s_nop 0
	global_load_dwordx4 v[10:13], v[12:13], off
	s_nop 0
	global_load_dwordx4 v[14:17], v[14:15], off
	s_nop 0
	global_load_dwordx4 v[50:53], v[38:39], off offset:3072
	global_load_dwordx4 v[56:59], v[38:39], off offset:2048
	global_load_dwordx4 v[60:63], v[38:39], off offset:1024
	global_load_dwordx4 v[64:67], v[38:39], off
	global_load_dwordx4 v[30:33], v[18:19], off
	global_load_dwordx4 v[26:29], v[18:19], off offset:1024
	global_load_dwordx4 v[22:25], v[18:19], off offset:2048
	s_nop 0
	global_load_dwordx4 v[18:21], v[18:19], off offset:3072
	s_waitcnt vmcnt(0) lgkmcnt(0)
	v_pk_add_f32 v[12:13], v[12:13], 1.0 op_sel_hi:[1,0]
	v_pk_add_f32 v[16:17], v[16:17], 1.0 op_sel_hi:[1,0]
	v_pk_add_f32 v[4:5], v[4:5], 1.0 op_sel_hi:[1,0]
	v_pk_add_f32 v[2:3], v[2:3], 1.0 op_sel_hi:[1,0]
	v_pk_add_f32 v[8:9], v[8:9], 1.0 op_sel_hi:[1,0]
	v_pk_add_f32 v[6:7], v[6:7], 1.0 op_sel_hi:[1,0]
	v_pk_add_f32 v[10:11], v[10:11], 1.0 op_sel_hi:[1,0]
	v_pk_add_f32 v[14:15], v[14:15], 1.0 op_sel_hi:[1,0]
	v_pk_mul_f32 v[16:17], v[52:53], v[16:17]
	v_pk_mul_f32 v[12:13], v[58:59], v[12:13]
	v_pk_mul_f32 v[8:9], v[62:63], v[8:9]
	v_pk_mul_f32 v[4:5], v[66:67], v[4:5]
	v_pk_mul_f32 v[14:15], v[50:51], v[14:15]
	v_pk_mul_f32 v[10:11], v[56:57], v[10:11]
	v_pk_mul_f32 v[6:7], v[60:61], v[6:7]
	v_pk_mul_f32 v[2:3], v[64:65], v[2:3]
	s_branch .LBB0_274

; DI f32x4 unpack4(u32x2 v) { f32x4 r = {bflo(v.x), bfhi(v.x), bflo(v.y), bfhi(v.y)}; return r; }
; DI u32x2 pack4(f32x4 v) { u32x2 r = {cvtpk(v[0], v[1]), cvtpk(v[2], v[3])}; return r; }
; DI void phase_feat_a(KP p, int l, char* lds) {
;     ...
;     {
;       const int r = task * 4 + sub; const int b = r / T, t = r % T;
;       const bf16_t* pr = P + (size_t)r * NIN;
;       {
;         f32x4 v[3]; float ss = 0.f;
; #pragma unroll
;         for (int e = 0; e < 3; ++e) { v[e] = unpack4(*(const u32x2*)(pr + O_CQ + 12 * u + 4 * e)); ss += v[e][0] * v[e][0] + v[e][1] * v[e][1] + v[e][2] * v[e][2] + v[e][3] * v[e][3]; }
;         ss = red16(ss); const float rs = rsqrtf(ss * (1.f / 192.f) + 1e-6f);
; #pragma unroll
;         for (int e = 0; e < 3; ++e) {
;           const f32x4 g = gcq[e];
;           f32x4 o = {v[e][0] * rs * g[0], v[e][1] * rs * g[1], v[e][2] * rs * g[2], v[e][3] * rs * g[3]};
;           *(u32x2*)(cqn + (size_t)r * 192 + 12 * u + 4 * e) = pack4(o);
;         }
;       }
;       {
;         f32x4 v[2]; float ss = 0.f;
; #pragma unroll
;         for (int e = 0; e < 2; ++e) { v[e] = unpack4(*(const u32x2*)(pr + O_CKV + 8 * u + 4 * e)); ss += v[e][0] * v[e][0] + v[e][1] * v[e][1] + v[e][2] * v[e][2] + v[e][3] * v[e][3]; }
;         ss = red16(ss); const float rs = rsqrtf(ss * (1.f / 128.f) + 1e-6f);
; #pragma unroll
;         for (int e = 0; e < 2; ++e) {
;           const f32x4 g = gckv[e];
;           f32x4 o = {v[e][0] * rs * g[0], v[e][1] * rs * g[1], v[e][2] * rs * g[2], v[e][3] * rs * g[3]};
;           *(u32x2*)(ckvn + (size_t)r * 128 + 8 * u + 4 * e) = pack4(o);
;         }
;       }
;       const int posg = (u & 8) ? (t & 63) : (t >> 6); const float sgg = (u & 4) ? 1.f : -1.f;
;       const f32x4 c01 = *(const f32x4*)(rg + (posg * 16 + 4 * (u & 3)) * 2), c23 = *(const f32x4*)(rg + (posg * 16 + 4 * (u & 3) + 2) * 2);
;       const float csg[8] = {c01[0], c01[1], c01[2], c01[3], c23[0], c23[1], c23[2], c23[3]};
;       const f32x4 gqv = *(const f32x4*)(p->gqa_qn + l * 64 + 4 * u), gkv = *(const f32x4*)(p->gqa_kn + l * 64 + 4 * u);
; #pragma unroll
;       for (int hh = 0; hh < 6; ++hh) {
;         const bool isq = hh < 4; const int hd = isq ? hh : hh - 4;
;         f32x4 v = unpack4(*(const u32x2*)(pr + (isq ? O_Q2 : O_K2) + 64 * hd + 4 * u));
;         float ss = red16(v[0] * v[0] + v[1] * v[1] + v[2] * v[2] + v[3] * v[3]);
.LBB0_287:
	s_or_b64 exec, exec, s[18:19]
	v_readlane_b32 s2, v254, 37
	v_lshl_add_u64 v[22:23], v[62:63], 0, v[34:35]
	v_lshlrev_b64 v[22:23], 7, v[22:23]
	v_add_u32_e32 v70, s2, v70
	s_movk_i32 s2, 0x23ff
	v_cmp_lt_i32_e32 vcc, s2, v70
	v_readlane_b32 s2, v254, 50
	v_lshl_add_u64 v[22:23], v[50:51], 0, v[22:23]
	v_cvt_pk_bf16_f32 v24, v30, v31
	v_cvt_pk_bf16_f32 v25, v32, v33
	s_or_b64 s[46:47], vcc, s[46:47]
	v_add_u32_e32 v52, s2, v52
	global_store_dwordx2 v[22:23], v[24:25], off
	s_andn2_b64 exec, exec, s[46:47]
	s_cbranch_execz .LBB0_300
.LBB0_288:
	v_mov_b64_e32 v[22:23], s[36:37]
	v_mad_i64_i32 v[26:27], s[18:19], v52, s11, v[22:23]
	v_lshl_add_u64 v[28:29], v[26:27], 0, v[0:1]
	global_load_dwordx4 v[22:25], v[28:29], off
	s_nop 0
	global_load_dwordx2 v[28:29], v[28:29], off offset:16
	s_mov_b32 s20, 0x800000
	v_mov_b32_e32 v55, v1
	v_mov_b32_e32 v57, v1
	s_mov_b32 s2, 0x38e38e39
	s_waitcnt vmcnt(0) lgkmcnt(0)
	v_and_b32_e32 v33, 0xffff0000, v22
	v_and_b32_e32 v37, 0xffff0000, v28
	v_lshlrev_b32_e32 v32, 16, v22
	v_lshlrev_b32_e32 v34, 16, v24
	v_and_b32_e32 v35, 0xffff0000, v24
	v_lshlrev_b32_e32 v36, 16, v28
	v_mov_b32_e32 v66, v33
	v_mov_b32_e32 v67, v37
	v_lshlrev_b32_e32 v30, 16, v23
	v_and_b32_e32 v31, 0xffff0000, v23
	v_lshlrev_b32_e32 v22, 16, v25
	v_and_b32_e32 v23, 0xffff0000, v25
	v_lshlrev_b32_e32 v24, 16, v29
	v_pk_mul_f32 v[58:59], v[34:35], v[34:35]
	v_mov_b32_e32 v64, v32
	v_mov_b32_e32 v65, v36
	v_pk_mul_f32 v[66:67], v[66:67], v[66:67]
	v_and_b32_e32 v25, 0xffff0000, v29
	v_pk_mul_f32 v[28:29], v[22:23], v[22:23]
	v_mov_b32_e32 v60, v30
	v_mov_b32_e32 v61, v24
	v_add_f32_e32 v53, v58, v59
	v_pk_fma_f32 v[58:59], v[64:65], v[64:65], v[66:67]
	v_mov_b32_e32 v62, v31
	v_mov_b32_e32 v63, v25
	v_add_f32_e32 v28, v28, v53
	v_pk_fma_f32 v[58:59], v[60:61], v[60:61], v[58:59]
	v_add_f32_e32 v53, v29, v28
	v_pk_fma_f32 v[28:29], v[62:63], v[62:63], v[58:59]
	v_lshl_add_u64 v[58:59], v[26:27], 0, v[54:55]
	v_add_f32_e32 v28, v28, v53
	v_add_f32_e32 v28, v28, v29
	s_nop 1
	v_add_f32_dpp v28, v28, v28 quad_perm:[1,0,3,2] row_mask:0xf bank_mask:0xf bound_ctrl:1
	s_nop 1
	v_add_f32_dpp v28, v28, v28 quad_perm:[2,3,0,1] row_mask:0xf bank_mask:0xf bound_ctrl:1
	s_nop 1
	v_add_f32_dpp v28, v28, v28 row_ror:4 row_mask:0xf bank_mask:0xf bound_ctrl:1
	s_nop 1
	v_add_f32_dpp v28, v28, v28 row_ror:8 row_mask:0xf bank_mask:0xf bound_ctrl:1
	v_fmamk_f32 v28, v28, 0x3baaaaab, v198
	v_mul_f32_e32 v29, 0x4b800000, v28
	v_cmp_gt_f32_e32 vcc, s20, v28
	s_nop 1
	v_cndmask_b32_e32 v28, v28, v29, vcc
	v_rsq_f32_e32 v53, v28
	v_mad_i64_i32 v[28:29], s[18:19], v52, s8, v[38:39]
	v_mul_f32_e32 v55, 0x45800000, v53
	v_cndmask_b32_e32 v60, v53, v55, vcc
	v_pk_mul_f32 v[32:33], v[60:61], v[32:33] op_sel_hi:[0,1]
	v_pk_mul_f32 v[30:31], v[60:61], v[30:31] op_sel_hi:[0,1]
	v_pk_mul_f32 v[34:35], v[60:61], v[34:35] op_sel_hi:[0,1]
	v_pk_mul_f32 v[22:23], v[60:61], v[22:23] op_sel_hi:[0,1]
	v_pk_mul_f32 v[36:37], v[60:61], v[36:37] op_sel_hi:[0,1]
	v_pk_mul_f32 v[24:25], v[60:61], v[24:25] op_sel_hi:[0,1]
	v_pk_mul_f32 v[32:33], v[18:19], v[32:33]
	v_pk_mul_f32 v[30:31], v[20:21], v[30:31]
	v_pk_mul_f32 v[34:35], v[14:15], v[34:35]
	v_pk_mul_f32 v[60:61], v[16:17], v[22:23]
	v_pk_mul_f32 v[36:37], v[10:11], v[36:37]
	v_pk_mul_f32 v[62:63], v[12:13], v[24:25]
	v_cvt_pk_bf16_f32 v22, v32, v33
	v_cvt_pk_bf16_f32 v23, v30, v31
	v_cvt_pk_bf16_f32 v24, v34, v35
	v_cvt_pk_bf16_f32 v25, v60, v61
	v_cvt_pk_bf16_f32 v30, v36, v37
	v_cvt_pk_bf16_f32 v31, v62, v63
	global_store_dwordx4 v[28:29], v[22:25], off
	global_store_dwordx2 v[28:29], v[30:31], off offset:16
	global_load_dwordx4 v[22:25], v[58:59], off offset:384
	v_ashrrev_i32_e32 v53, 31, v52
	s_waitcnt vmcnt(0) lgkmcnt(0)
	v_and_b32_e32 v31, 0xffff0000, v22
	v_and_b32_e32 v33, 0xffff0000, v24
	v_lshlrev_b32_e32 v30, 16, v22
	v_lshlrev_b32_e32 v32, 16, v24
	v_mov_b32_e32 v58, v31
	v_mov_b32_e32 v59, v33
	v_lshlrev_b32_e32 v28, 16, v23
	v_lshlrev_b32_e32 v22, 16, v25
	v_mov_b32_e32 v36, v30
	v_mov_b32_e32 v37, v32
	v_pk_mul_f32 v[58:59], v[58:59], v[58:59]
	v_and_b32_e32 v29, 0xffff0000, v23
	v_and_b32_e32 v23, 0xffff0000, v25
	v_mov_b32_e32 v24, v28
	v_mov_b32_e32 v25, v22
	v_pk_fma_f32 v[36:37], v[36:37], v[36:37], v[58:59]
	v_mov_b32_e32 v34, v29
	v_mov_b32_e32 v35, v23
	v_pk_fma_f32 v[24:25], v[24:25], v[24:25], v[36:37]
	v_lshl_add_u64 v[58:59], v[26:27], 0, v[56:57]
	v_pk_fma_f32 v[24:25], v[34:35], v[34:35], v[24:25]
	s_nop 0
	v_add_f32_e32 v24, v24, v25
	s_nop 1
	v_add_f32_dpp v24, v24, v24 quad_perm:[1,0,3,2] row_mask:0xf bank_mask:0xf bound_ctrl:1
	s_nop 1
	v_add_f32_dpp v24, v24, v24 quad_perm:[2,3,0,1] row_mask:0xf bank_mask:0xf bound_ctrl:1
	s_nop 1
	v_add_f32_dpp v24, v24, v24 row_ror:4 row_mask:0xf bank_mask:0xf bound_ctrl:1
	s_nop 1
	v_add_f32_dpp v24, v24, v24 row_ror:8 row_mask:0xf bank_mask:0xf bound_ctrl:1
	v_fmamk_f32 v24, v24, 0x3c000000, v198
	v_mul_f32_e32 v25, 0x4b800000, v24
	v_cmp_gt_f32_e32 vcc, s20, v24
	s_nop 1
	v_cndmask_b32_e32 v24, v24, v25, vcc
	v_rsq_f32_e32 v36, v24
	v_lshlrev_b64 v[24:25], 8, v[52:53]
	v_lshl_add_u64 v[34:35], v[40:41], 0, v[24:25]
	v_mul_f32_e32 v24, 0x45800000, v36
	v_cndmask_b32_e32 v24, v36, v24, vcc
	v_pk_mul_f32 v[26:27], v[24:25], v[30:31] op_sel_hi:[0,1]
	v_pk_mul_f32 v[28:29], v[24:25], v[28:29] op_sel_hi:[0,1]
	v_pk_mul_f32 v[30:31], v[24:25], v[32:33] op_sel_hi:[0,1]
	v_pk_mul_f32 v[22:23], v[24:25], v[22:23] op_sel_hi:[0,1]
	v_pk_mul_f32 v[24:25], v[6:7], v[26:27]
	v_pk_mul_f32 v[26:27], v[8:9], v[28:29]
	v_pk_mul_f32 v[28:29], v[2:3], v[30:31]
	v_pk_mul_f32 v[30:31], v[4:5], v[22:23]
	v_cvt_pk_bf16_f32 v22, v24, v25
	v_cvt_pk_bf16_f32 v23, v26, v27
	v_cvt_pk_bf16_f32 v24, v28, v29
	v_cvt_pk_bf16_f32 v25, v30, v31
	global_store_dwordx4 v[34:35], v[22:25], off
	global_load_dwordx2 v[62:63], v[58:59], off offset:1216
	s_waitcnt vmcnt(0) lgkmcnt(0)
; DI f32x4 unpack4(u32x2 v) { f32x4 r = {bflo(v.x), bfhi(v.x), bflo(v.y), bfhi(v.y)}; return r; }
; DI u32x2 pack4(f32x4 v) { u32x2 r = {cvtpk(v[0], v[1]), cvtpk(v[2], v[3])}; return r; }
; DI float red16(float v) { v += dpp_f(v, 0); v += dpp_f(v, 1); v += dpp_f(v, 2); v += dpp_f(v, 3); return v; }
; DI void phase_feat_a(KP p, int l, char* lds) {
;     ...
;       const int posg = (u & 8) ? (t & 63) : (t >> 6); const float sgg = (u & 4) ? 1.f : -1.f;
;       const f32x4 c01 = *(const f32x4*)(rg + (posg * 16 + 4 * (u & 3)) * 2), c23 = *(const f32x4*)(rg + (posg * 16 + 4 * (u & 3) + 2) * 2);
;       const float csg[8] = {c01[0], c01[1], c01[2], c01[3], c23[0], c23[1], c23[2], c23[3]};
;       const f32x4 gqv = *(const f32x4*)(p->gqa_qn + l * 64 + 4 * u), gkv = *(const f32x4*)(p->gqa_kn + l * 64 + 4 * u);
; #pragma unroll
;       for (int hh = 0; hh < 6; ++hh) {
;         const bool isq = hh < 4; const int hd = isq ? hh : hh - 4;
;         f32x4 v = unpack4(*(const u32x2*)(pr + (isq ? O_Q2 : O_K2) + 64 * hd + 4 * u));
;         float ss = red16(v[0] * v[0] + v[1] * v[1] + v[2] * v[2] + v[3] * v[3]);
;         const float rs = rsqrtf(ss * (1.f / 64.f) + 1e-6f);
;         const f32x4 g = isq ? gqv : gkv;
; #pragma unroll
;         for (int e = 0; e < 4; ++e) v[e] = v[e] * rs * g[e];
;         if (t < SEQ) rope4(v, u, sgg, csg);
;         if (isq) {
; #pragma unroll
;           for (int e = 0; e < 4; ++e) v[e] *= 0.18033688011112042f;
;         }
;         bf16_t* dst = isq ? QB + (((size_t)b * 4 + hd) * T + t) * 64 + 4 * u : KB + (((size_t)b * 2 + hd) * T + t) * 64 + 4 * u;
;         *(u32x2*)dst = pack4(v);
	v_lshlrev_b32_e32 v64, 16, v62
	v_mul_hi_i32 v22, v52, s2
	v_lshrrev_b32_e32 v23, 31, v22
	v_ashrrev_i32_e32 v22, 9, v22
	v_add_u32_e32 v53, v22, v23
	v_mul_i32_i24_e32 v22, 0x900, v53
	v_sub_u32_e32 v60, v52, v22
	v_and_b32_e32 v22, 63, v60
	v_ashrrev_i32_e32 v23, 6, v60
	v_cndmask_b32_e64 v22, v22, v23, s[40:41]
	v_lshl_or_b32 v22, v22, 5, v71
	v_ashrrev_i32_e32 v23, 31, v22
	v_lshl_add_u64 v[22:23], v[22:23], 2, s[48:49]
	global_load_dwordx4 v[26:29], v[22:23], off
	global_load_dwordx4 v[34:37], v[44:45], off
	s_nop 0
	global_load_dwordx4 v[22:25], v[22:23], off offset:16
	s_nop 0
	global_load_dwordx4 v[30:33], v[46:47], off
	v_and_b32_e32 v65, 0xffff0000, v62
	v_lshlrev_b32_e32 v62, 16, v63
	v_and_b32_e32 v63, 0xffff0000, v63
	v_pk_mul_f32 v[66:67], v[64:65], v[64:65]
	v_pk_mul_f32 v[68:69], v[62:63], v[62:63]
	v_add_f32_e32 v55, v66, v67
	v_add_f32_e32 v55, v68, v55
	v_add_f32_e32 v55, v69, v55
	s_movk_i32 s2, 0x800
	v_cmp_gt_i32_e64 s[42:43], s2, v60
	v_add_f32_dpp v55, v55, v55 quad_perm:[1,0,3,2] row_mask:0xf bank_mask:0xf bound_ctrl:1
	s_nop 1
	v_add_f32_dpp v55, v55, v55 quad_perm:[2,3,0,1] row_mask:0xf bank_mask:0xf bound_ctrl:1
	s_nop 1
	v_add_f32_dpp v55, v55, v55 row_ror:4 row_mask:0xf bank_mask:0xf bound_ctrl:1
	s_nop 1
	v_add_f32_dpp v55, v55, v55 row_ror:8 row_mask:0xf bank_mask:0xf bound_ctrl:1
	v_fmamk_f32 v55, v55, 0x3c800000, v198
	v_mul_f32_e32 v57, 0x4b800000, v55
	v_cmp_gt_f32_e32 vcc, s20, v55
	s_nop 1
	v_cndmask_b32_e32 v55, v55, v57, vcc
	v_rsq_f32_e32 v55, v55
	s_nop 0
	v_mul_f32_e32 v57, 0x45800000, v55
	v_cndmask_b32_e32 v66, v55, v57, vcc
	v_pk_mul_f32 v[64:65], v[66:67], v[64:65] op_sel_hi:[0,1]
	v_pk_mul_f32 v[66:67], v[66:67], v[62:63] op_sel_hi:[0,1]
	s_waitcnt vmcnt(0)
	v_pk_mul_f32 v[62:63], v[34:35], v[64:65]
	v_pk_mul_f32 v[64:65], v[36:37], v[66:67]
	s_and_saveexec_b64 s[18:19], s[42:43]
	s_cbranch_execz .LBB0_290
	v_and_b32_e32 v57, 64, v204
	v_xor_b32_e32 v55, 4, v204
	v_add_u32_e32 v57, 64, v57
	v_cmp_lt_i32_e32 vcc, v55, v57
	v_mov_b32_e32 v74, v65
	s_waitcnt lgkmcnt(0)
	v_mov_b32_e32 v72, v27
	v_cndmask_b32_e32 v55, v204, v55, vcc
	v_lshlrev_b32_e32 v55, 2, v55
	ds_bpermute_b32 v66, v55, v62
	ds_bpermute_b32 v67, v55, v63
	ds_bpermute_b32 v57, v55, v64
	ds_bpermute_b32 v55, v55, v65
	v_mov_b32_e32 v73, v29
	v_mov_b32_e32 v68, v26
	s_waitcnt lgkmcnt(2)
	v_pk_mul_f32 v[66:67], v[42:43], v[66:67]
	s_waitcnt lgkmcnt(1)
	v_mul_f32_e32 v57, v42, v57
	s_waitcnt lgkmcnt(0)
	v_mul_f32_e32 v75, v42, v55
	v_pk_mul_f32 v[74:75], v[24:25], v[74:75]
	v_mov_b32_e32 v69, v28
	v_pk_mul_f32 v[66:67], v[72:73], v[66:67]
	v_mul_f32_e32 v64, v22, v64
	v_mul_f32_e32 v72, v23, v57
	v_mov_b32_e32 v65, v74
	v_mov_b32_e32 v73, v75
	v_pk_fma_f32 v[62:63], v[68:69], v[62:63], v[66:67]
	v_pk_add_f32 v[64:65], v[64:65], v[72:73]
.LBB0_290:
	s_or_b64 exec, exec, s[18:19]
	v_ashrrev_i32_e32 v61, 31, v60
	v_mul_hi_i32_i24_e32 v67, 0x2400, v53
	v_mul_i32_i24_e32 v66, 0x2400, v53
	v_lshl_add_u64 v[60:61], v[66:67], 0, v[60:61]
	s_mov_b32 s2, 0x3e38aa3b
	v_lshlrev_b64 v[66:67], 7, v[60:61]
	v_pk_mul_f32 v[62:63], v[62:63], s[2:3] op_sel_hi:[1,0]
	v_pk_mul_f32 v[68:69], v[64:65], s[2:3] op_sel_hi:[1,0]
	v_lshl_add_u64 v[64:65], v[48:49], 0, v[66:67]
	v_cvt_pk_bf16_f32 v62, v62, v63
	v_cvt_pk_bf16_f32 v63, v68, v69
	global_store_dwordx2 v[64:65], v[62:63], off
	global_load_dwordx2 v[62:63], v[58:59], off offset:1344
	s_mov_b32 s2, 0x800000
	s_waitcnt vmcnt(0) lgkmcnt(0)
	v_lshlrev_b32_e32 v66, 16, v62
	v_and_b32_e32 v67, 0xffff0000, v62
	v_lshlrev_b32_e32 v62, 16, v63
	v_and_b32_e32 v63, 0xffff0000, v63
	v_pk_mul_f32 v[68:69], v[66:67], v[66:67]
	v_pk_mul_f32 v[72:73], v[62:63], v[62:63]
	v_add_f32_e32 v55, v68, v69
	v_add_f32_e32 v55, v72, v55
	v_add_f32_e32 v55, v73, v55
	s_nop 1
	v_add_f32_dpp v55, v55, v55 quad_perm:[1,0,3,2] row_mask:0xf bank_mask:0xf bound_ctrl:1
	s_nop 1
	v_add_f32_dpp v55, v55, v55 quad_perm:[2,3,0,1] row_mask:0xf bank_mask:0xf bound_ctrl:1
	s_nop 1
	v_add_f32_dpp v55, v55, v55 row_ror:4 row_mask:0xf bank_mask:0xf bound_ctrl:1
	s_nop 1
	v_add_f32_dpp v55, v55, v55 row_ror:8 row_mask:0xf bank_mask:0xf bound_ctrl:1
	v_fmamk_f32 v55, v55, 0x3c800000, v198
	v_mul_f32_e32 v57, 0x4b800000, v55
	v_cmp_gt_f32_e32 vcc, s2, v55
	s_nop 1
	v_cndmask_b32_e32 v55, v55, v57, vcc
	v_rsq_f32_e32 v55, v55
	s_nop 0
	v_mul_f32_e32 v57, 0x45800000, v55
	v_cndmask_b32_e32 v68, v55, v57, vcc
	v_pk_mul_f32 v[66:67], v[68:69], v[66:67] op_sel_hi:[0,1]
	v_pk_mul_f32 v[62:63], v[68:69], v[62:63] op_sel_hi:[0,1]
	v_pk_mul_f32 v[66:67], v[34:35], v[66:67]
	v_pk_mul_f32 v[68:69], v[36:37], v[62:63]
	s_and_saveexec_b64 s[18:19], s[42:43]
	s_cbranch_execz .LBB0_292
	v_and_b32_e32 v57, 64, v204
	v_xor_b32_e32 v55, 4, v204
	v_add_u32_e32 v57, 64, v57
	v_cmp_lt_i32_e32 vcc, v55, v57
	v_mov_b32_e32 v76, v69
	v_mov_b32_e32 v74, v27
	v_cndmask_b32_e32 v55, v204, v55, vcc
	v_lshlrev_b32_e32 v55, 2, v55
	ds_bpermute_b32 v62, v55, v66
	ds_bpermute_b32 v63, v55, v67
	ds_bpermute_b32 v57, v55, v68
	ds_bpermute_b32 v55, v55, v69
	v_mov_b32_e32 v75, v29
	v_mov_b32_e32 v72, v26
	s_waitcnt lgkmcnt(2)
	v_pk_mul_f32 v[62:63], v[42:43], v[62:63]
	s_waitcnt lgkmcnt(1)
	v_mul_f32_e32 v57, v42, v57
	s_waitcnt lgkmcnt(0)
	v_mul_f32_e32 v77, v42, v55
	v_pk_mul_f32 v[76:77], v[24:25], v[76:77]
	v_mov_b32_e32 v73, v28
	v_pk_mul_f32 v[62:63], v[74:75], v[62:63]
	v_mul_f32_e32 v68, v22, v68
	v_mul_f32_e32 v74, v23, v57
	v_mov_b32_e32 v69, v76
	v_mov_b32_e32 v75, v77
	v_pk_fma_f32 v[66:67], v[72:73], v[66:67], v[62:63]
	v_pk_add_f32 v[68:69], v[68:69], v[74:75]
; DI f32x4 unpack4(u32x2 v) { f32x4 r = {bflo(v.x), bfhi(v.x), bflo(v.y), bfhi(v.y)}; return r; }
; DI u32x2 pack4(f32x4 v) { u32x2 r = {cvtpk(v[0], v[1]), cvtpk(v[2], v[3])}; return r; }
; DI float red16(float v) { v += dpp_f(v, 0); v += dpp_f(v, 1); v += dpp_f(v, 2); v += dpp_f(v, 3); return v; }
; DI void phase_feat_a(KP p, int l, char* lds) {
;     ...
; #pragma unroll
;       for (int hh = 0; hh < 6; ++hh) {
;         const bool isq = hh < 4; const int hd = isq ? hh : hh - 4;
;         f32x4 v = unpack4(*(const u32x2*)(pr + (isq ? O_Q2 : O_K2) + 64 * hd + 4 * u));
;         float ss = red16(v[0] * v[0] + v[1] * v[1] + v[2] * v[2] + v[3] * v[3]);
;         const float rs = rsqrtf(ss * (1.f / 64.f) + 1e-6f);
;         const f32x4 g = isq ? gqv : gkv;
; #pragma unroll
;         for (int e = 0; e < 4; ++e) v[e] = v[e] * rs * g[e];
;         if (t < SEQ) rope4(v, u, sgg, csg);
;         if (isq) {
; #pragma unroll
;           for (int e = 0; e < 4; ++e) v[e] *= 0.18033688011112042f;
;         }
;         bf16_t* dst = isq ? QB + (((size_t)b * 4 + hd) * T + t) * 64 + 4 * u : KB + (((size_t)b * 2 + hd) * T + t) * 64 + 4 * u;
;         *(u32x2*)dst = pack4(v);
.LBB0_292:
	s_or_b64 exec, exec, s[18:19]
	s_mov_b64 s[18:19], 0x900
	v_lshl_add_u64 v[62:63], v[60:61], 0, s[18:19]
	s_mov_b32 s2, 0x3e38aa3b
	v_lshlrev_b64 v[72:73], 7, v[62:63]
	v_pk_mul_f32 v[66:67], v[66:67], s[2:3] op_sel_hi:[1,0]
	v_pk_mul_f32 v[68:69], v[68:69], s[2:3] op_sel_hi:[1,0]
	v_lshl_add_u64 v[72:73], v[48:49], 0, v[72:73]
	v_cvt_pk_bf16_f32 v66, v66, v67
	v_cvt_pk_bf16_f32 v67, v68, v69
	global_store_dwordx2 v[72:73], v[66:67], off
	global_load_dwordx2 v[66:67], v[58:59], off offset:1472
	s_mov_b32 s2, 0x800000
	s_waitcnt vmcnt(0) lgkmcnt(0)
	v_lshlrev_b32_e32 v68, 16, v66
	v_and_b32_e32 v69, 0xffff0000, v66
	v_lshlrev_b32_e32 v66, 16, v67
	v_and_b32_e32 v67, 0xffff0000, v67
	v_pk_mul_f32 v[72:73], v[68:69], v[68:69]
	v_pk_mul_f32 v[74:75], v[66:67], v[66:67]
	v_add_f32_e32 v55, v72, v73
	v_add_f32_e32 v55, v74, v55
	v_add_f32_e32 v55, v75, v55
	s_nop 1
	v_add_f32_dpp v55, v55, v55 quad_perm:[1,0,3,2] row_mask:0xf bank_mask:0xf bound_ctrl:1
	s_nop 1
	v_add_f32_dpp v55, v55, v55 quad_perm:[2,3,0,1] row_mask:0xf bank_mask:0xf bound_ctrl:1
	s_nop 1
	v_add_f32_dpp v55, v55, v55 row_ror:4 row_mask:0xf bank_mask:0xf bound_ctrl:1
	s_nop 1
	v_add_f32_dpp v55, v55, v55 row_ror:8 row_mask:0xf bank_mask:0xf bound_ctrl:1
	v_fmamk_f32 v55, v55, 0x3c800000, v198
	v_mul_f32_e32 v57, 0x4b800000, v55
	v_cmp_gt_f32_e32 vcc, s2, v55
	s_nop 1
	v_cndmask_b32_e32 v55, v55, v57, vcc
	v_rsq_f32_e32 v55, v55
	s_nop 0
	v_mul_f32_e32 v57, 0x45800000, v55
	v_cndmask_b32_e32 v72, v55, v57, vcc
	v_pk_mul_f32 v[68:69], v[72:73], v[68:69] op_sel_hi:[0,1]
	v_pk_mul_f32 v[72:73], v[72:73], v[66:67] op_sel_hi:[0,1]
	v_pk_mul_f32 v[66:67], v[34:35], v[68:69]
	v_pk_mul_f32 v[68:69], v[36:37], v[72:73]
	s_and_saveexec_b64 s[18:19], s[42:43]
	s_cbranch_execz .LBB0_294
	v_and_b32_e32 v57, 64, v204
	v_xor_b32_e32 v55, 4, v204
	v_add_u32_e32 v57, 64, v57
	v_cmp_lt_i32_e32 vcc, v55, v57
	v_mov_b32_e32 v78, v69
	v_mov_b32_e32 v76, v27
	v_cndmask_b32_e32 v55, v204, v55, vcc
	v_lshlrev_b32_e32 v55, 2, v55
	ds_bpermute_b32 v72, v55, v66
	ds_bpermute_b32 v73, v55, v67
	ds_bpermute_b32 v57, v55, v68
	ds_bpermute_b32 v55, v55, v69
	v_mov_b32_e32 v77, v29
	v_mov_b32_e32 v74, v26
	s_waitcnt lgkmcnt(2)
	v_pk_mul_f32 v[72:73], v[42:43], v[72:73]
	s_waitcnt lgkmcnt(1)
	v_mul_f32_e32 v57, v42, v57
	s_waitcnt lgkmcnt(0)
	v_mul_f32_e32 v79, v42, v55
	v_pk_mul_f32 v[78:79], v[24:25], v[78:79]
	v_mov_b32_e32 v75, v28
	v_pk_mul_f32 v[72:73], v[76:77], v[72:73]
	v_mul_f32_e32 v68, v22, v68
	v_mul_f32_e32 v76, v23, v57
	v_mov_b32_e32 v69, v78
	v_mov_b32_e32 v77, v79
	v_pk_fma_f32 v[66:67], v[74:75], v[66:67], v[72:73]
	v_pk_add_f32 v[68:69], v[68:69], v[76:77]
.LBB0_294:
	s_or_b64 exec, exec, s[18:19]
	s_mov_b32 s2, 0x3e38aa3b
	v_pk_mul_f32 v[66:67], v[66:67], s[2:3] op_sel_hi:[1,0]
	v_pk_mul_f32 v[68:69], v[68:69], s[2:3] op_sel_hi:[1,0]
	v_cvt_pk_bf16_f32 v66, v66, v67
	v_cvt_pk_bf16_f32 v67, v68, v69
	v_add_co_u32_e32 v68, vcc, 0x90000, v64
	s_mov_b32 s2, 0x800000
	s_nop 0
	v_addc_co_u32_e32 v69, vcc, 0, v65, vcc
	global_store_dwordx2 v[68:69], v[66:67], off
	global_load_dwordx2 v[66:67], v[58:59], off offset:1600
	s_waitcnt vmcnt(0) lgkmcnt(0)
	v_lshlrev_b32_e32 v68, 16, v66
	v_and_b32_e32 v69, 0xffff0000, v66
	v_lshlrev_b32_e32 v66, 16, v67
	v_and_b32_e32 v67, 0xffff0000, v67
	v_pk_mul_f32 v[72:73], v[68:69], v[68:69]
	v_pk_mul_f32 v[74:75], v[66:67], v[66:67]
	v_add_f32_e32 v55, v72, v73
	v_add_f32_e32 v55, v74, v55
	v_add_f32_e32 v55, v75, v55
	s_nop 1
	v_add_f32_dpp v55, v55, v55 quad_perm:[1,0,3,2] row_mask:0xf bank_mask:0xf bound_ctrl:1
	s_nop 1
	v_add_f32_dpp v55, v55, v55 quad_perm:[2,3,0,1] row_mask:0xf bank_mask:0xf bound_ctrl:1
	s_nop 1
	v_add_f32_dpp v55, v55, v55 row_ror:4 row_mask:0xf bank_mask:0xf bound_ctrl:1
	s_nop 1
	v_add_f32_dpp v55, v55, v55 row_ror:8 row_mask:0xf bank_mask:0xf bound_ctrl:1
	v_fmamk_f32 v55, v55, 0x3c800000, v198
	v_mul_f32_e32 v57, 0x4b800000, v55
	v_cmp_gt_f32_e32 vcc, s2, v55
	s_nop 1
	v_cndmask_b32_e32 v55, v55, v57, vcc
	v_rsq_f32_e32 v55, v55
	s_nop 0
	v_mul_f32_e32 v57, 0x45800000, v55
	v_cndmask_b32_e32 v72, v55, v57, vcc
	v_pk_mul_f32 v[68:69], v[72:73], v[68:69] op_sel_hi:[0,1]
	v_pk_mul_f32 v[66:67], v[72:73], v[66:67] op_sel_hi:[0,1]
	v_pk_mul_f32 v[34:35], v[34:35], v[68:69]
	v_pk_mul_f32 v[36:37], v[36:37], v[66:67]
	s_and_saveexec_b64 s[18:19], s[42:43]
	s_cbranch_execz .LBB0_296
	v_and_b32_e32 v57, 64, v204
	v_xor_b32_e32 v55, 4, v204
	v_add_u32_e32 v57, 64, v57
	v_cmp_lt_i32_e32 vcc, v55, v57
	v_mov_b32_e32 v74, v37
	v_mov_b32_e32 v72, v27
	v_cndmask_b32_e32 v55, v204, v55, vcc
	v_lshlrev_b32_e32 v55, 2, v55
	ds_bpermute_b32 v66, v55, v34
	ds_bpermute_b32 v67, v55, v35
	ds_bpermute_b32 v57, v55, v36
	ds_bpermute_b32 v55, v55, v37
	v_mov_b32_e32 v73, v29
	v_mov_b32_e32 v68, v26
	s_waitcnt lgkmcnt(2)
	v_pk_mul_f32 v[66:67], v[42:43], v[66:67]
	s_waitcnt lgkmcnt(1)
	v_mul_f32_e32 v57, v42, v57
	s_waitcnt lgkmcnt(0)
	v_mul_f32_e32 v75, v42, v55
	v_pk_mul_f32 v[74:75], v[24:25], v[74:75]
	v_mov_b32_e32 v69, v28
	v_pk_mul_f32 v[66:67], v[72:73], v[66:67]
	v_mul_f32_e32 v36, v22, v36
	v_mul_f32_e32 v72, v23, v57
	v_mov_b32_e32 v37, v74
	v_mov_b32_e32 v73, v75
	v_pk_fma_f32 v[34:35], v[68:69], v[34:35], v[66:67]
	v_pk_add_f32 v[36:37], v[36:37], v[72:73]
; DI f32x4 unpack4(u32x2 v) { f32x4 r = {bflo(v.x), bfhi(v.x), bflo(v.y), bfhi(v.y)}; return r; }
; DI u32x2 pack4(f32x4 v) { u32x2 r = {cvtpk(v[0], v[1]), cvtpk(v[2], v[3])}; return r; }
; DI float red16(float v) { v += dpp_f(v, 0); v += dpp_f(v, 1); v += dpp_f(v, 2); v += dpp_f(v, 3); return v; }
; DI void phase_feat_a(KP p, int l, char* lds) {
;     ...
; #pragma unroll
;       for (int hh = 0; hh < 6; ++hh) {
;         const bool isq = hh < 4; const int hd = isq ? hh : hh - 4;
;         f32x4 v = unpack4(*(const u32x2*)(pr + (isq ? O_Q2 : O_K2) + 64 * hd + 4 * u));
;         float ss = red16(v[0] * v[0] + v[1] * v[1] + v[2] * v[2] + v[3] * v[3]);
;         const float rs = rsqrtf(ss * (1.f / 64.f) + 1e-6f);
;         const f32x4 g = isq ? gqv : gkv;
; #pragma unroll
;         for (int e = 0; e < 4; ++e) v[e] = v[e] * rs * g[e];
;         if (t < SEQ) rope4(v, u, sgg, csg);
;         if (isq) {
; #pragma unroll
;           for (int e = 0; e < 4; ++e) v[e] *= 0.18033688011112042f;
;         }
;         bf16_t* dst = isq ? QB + (((size_t)b * 4 + hd) * T + t) * 64 + 4 * u : KB + (((size_t)b * 2 + hd) * T + t) * 64 + 4 * u;
;         *(u32x2*)dst = pack4(v);
.LBB0_296:
	s_or_b64 exec, exec, s[18:19]
	s_mov_b32 s2, 0x3e38aa3b
	v_pk_mul_f32 v[34:35], v[34:35], s[2:3] op_sel_hi:[1,0]
	v_pk_mul_f32 v[36:37], v[36:37], s[2:3] op_sel_hi:[1,0]
	v_cvt_pk_bf16_f32 v34, v34, v35
	v_cvt_pk_bf16_f32 v35, v36, v37
	v_add_co_u32_e32 v36, vcc, 0xd8000, v64
	s_mov_b32 s2, 0x800000
	s_nop 0
	v_addc_co_u32_e32 v37, vcc, 0, v65, vcc
	global_store_dwordx2 v[36:37], v[34:35], off
	global_load_dwordx2 v[34:35], v[58:59], off offset:1728
	s_waitcnt vmcnt(0) lgkmcnt(0)
	v_lshlrev_b32_e32 v36, 16, v34
	v_and_b32_e32 v37, 0xffff0000, v34
	v_lshlrev_b32_e32 v34, 16, v35
	v_and_b32_e32 v35, 0xffff0000, v35
	v_pk_mul_f32 v[64:65], v[36:37], v[36:37]
	v_pk_mul_f32 v[66:67], v[34:35], v[34:35]
	v_add_f32_e32 v55, v64, v65
	v_add_f32_e32 v55, v66, v55
	v_add_f32_e32 v55, v67, v55
	s_nop 1
	v_add_f32_dpp v55, v55, v55 quad_perm:[1,0,3,2] row_mask:0xf bank_mask:0xf bound_ctrl:1
	s_nop 1
	v_add_f32_dpp v55, v55, v55 quad_perm:[2,3,0,1] row_mask:0xf bank_mask:0xf bound_ctrl:1
	s_nop 1
	v_add_f32_dpp v55, v55, v55 row_ror:4 row_mask:0xf bank_mask:0xf bound_ctrl:1
	s_nop 1
	v_add_f32_dpp v55, v55, v55 row_ror:8 row_mask:0xf bank_mask:0xf bound_ctrl:1
	v_fmamk_f32 v55, v55, 0x3c800000, v198
	v_mul_f32_e32 v57, 0x4b800000, v55
	v_cmp_gt_f32_e32 vcc, s2, v55
	s_nop 1
	v_cndmask_b32_e32 v55, v55, v57, vcc
	v_rsq_f32_e32 v55, v55
	s_nop 0
	v_mul_f32_e32 v57, 0x45800000, v55
	v_cndmask_b32_e32 v64, v55, v57, vcc
	v_pk_mul_f32 v[36:37], v[64:65], v[36:37] op_sel_hi:[0,1]
	v_pk_mul_f32 v[34:35], v[64:65], v[34:35] op_sel_hi:[0,1]
	v_pk_mul_f32 v[36:37], v[30:31], v[36:37]
	v_pk_mul_f32 v[64:65], v[32:33], v[34:35]
	s_and_saveexec_b64 s[18:19], s[42:43]
	s_cbranch_execz .LBB0_298
	v_and_b32_e32 v35, 64, v204
	v_xor_b32_e32 v34, 4, v204
	v_add_u32_e32 v35, 64, v35
	v_cmp_lt_i32_e32 vcc, v34, v35
	v_mov_b32_e32 v72, v65
	v_mov_b32_e32 v68, v27
	v_cndmask_b32_e32 v34, v204, v34, vcc
	v_lshlrev_b32_e32 v55, 2, v34
	ds_bpermute_b32 v34, v55, v36
	ds_bpermute_b32 v35, v55, v37
	ds_bpermute_b32 v57, v55, v64
	ds_bpermute_b32 v55, v55, v65
	v_mov_b32_e32 v69, v29
	v_mov_b32_e32 v66, v26
	s_waitcnt lgkmcnt(2)
	v_pk_mul_f32 v[34:35], v[42:43], v[34:35]
	s_waitcnt lgkmcnt(1)
	v_mul_f32_e32 v57, v42, v57
	s_waitcnt lgkmcnt(0)
	v_mul_f32_e32 v73, v42, v55
	v_pk_mul_f32 v[72:73], v[24:25], v[72:73]
	v_mov_b32_e32 v67, v28
	v_pk_mul_f32 v[34:35], v[68:69], v[34:35]
	v_mul_f32_e32 v64, v22, v64
	v_mul_f32_e32 v68, v23, v57
	v_mov_b32_e32 v65, v72
	v_mov_b32_e32 v69, v73
	v_pk_fma_f32 v[36:37], v[66:67], v[36:37], v[34:35]
	v_pk_add_f32 v[64:65], v[64:65], v[68:69]
.LBB0_298:
	s_or_b64 exec, exec, s[18:19]
	v_mul_hi_i32_i24_e32 v35, 0xffffee00, v53
	v_mul_i32_i24_e32 v34, 0xffffee00, v53
	v_lshl_add_u64 v[60:61], v[60:61], 0, v[34:35]
	v_lshlrev_b64 v[60:61], 7, v[60:61]
	v_lshl_add_u64 v[60:61], v[50:51], 0, v[60:61]
	v_cvt_pk_bf16_f32 v36, v36, v37
	v_cvt_pk_bf16_f32 v37, v64, v65
	global_store_dwordx2 v[60:61], v[36:37], off
	global_load_dwordx2 v[36:37], v[58:59], off offset:1856
	s_waitcnt vmcnt(0) lgkmcnt(0)
	v_lshlrev_b32_e32 v58, 16, v36
	v_and_b32_e32 v59, 0xffff0000, v36
	v_lshlrev_b32_e32 v36, 16, v37
	v_and_b32_e32 v37, 0xffff0000, v37
	v_pk_mul_f32 v[60:61], v[58:59], v[58:59]
	v_pk_mul_f32 v[64:65], v[36:37], v[36:37]
	v_add_f32_e32 v53, v60, v61
	v_add_f32_e32 v53, v64, v53
	v_add_f32_e32 v53, v65, v53
	s_nop 1
	v_add_f32_dpp v53, v53, v53 quad_perm:[1,0,3,2] row_mask:0xf bank_mask:0xf bound_ctrl:1
	s_nop 1
	v_add_f32_dpp v53, v53, v53 quad_perm:[2,3,0,1] row_mask:0xf bank_mask:0xf bound_ctrl:1
	s_nop 1
	v_add_f32_dpp v53, v53, v53 row_ror:4 row_mask:0xf bank_mask:0xf bound_ctrl:1
	s_nop 1
	v_add_f32_dpp v53, v53, v53 row_ror:8 row_mask:0xf bank_mask:0xf bound_ctrl:1
	v_fmamk_f32 v53, v53, 0x3c800000, v198
	v_mul_f32_e32 v55, 0x4b800000, v53
	v_cmp_gt_f32_e32 vcc, s2, v53
	s_nop 1
	v_cndmask_b32_e32 v53, v53, v55, vcc
	v_rsq_f32_e32 v53, v53
	s_nop 0
	v_mul_f32_e32 v55, 0x45800000, v53
	v_cndmask_b32_e32 v60, v53, v55, vcc
	v_pk_mul_f32 v[58:59], v[60:61], v[58:59] op_sel_hi:[0,1]
	v_pk_mul_f32 v[36:37], v[60:61], v[36:37] op_sel_hi:[0,1]
	v_pk_mul_f32 v[30:31], v[30:31], v[58:59]
	v_pk_mul_f32 v[32:33], v[32:33], v[36:37]
	s_and_saveexec_b64 s[18:19], s[42:43]
	s_cbranch_execz .LBB0_287
	v_and_b32_e32 v37, 64, v204
	v_xor_b32_e32 v36, 4, v204
	v_add_u32_e32 v37, 64, v37
	v_cmp_lt_i32_e32 vcc, v36, v37
	v_mov_b32_e32 v59, v28
	v_mov_b32_e32 v28, v27
	v_cndmask_b32_e32 v36, v204, v36, vcc
	v_lshlrev_b32_e32 v53, 2, v36
	ds_bpermute_b32 v36, v53, v30
	ds_bpermute_b32 v37, v53, v31
	v_mov_b32_e32 v58, v26
	v_mul_f32_e32 v22, v22, v32
	s_waitcnt lgkmcnt(0)
	v_pk_mul_f32 v[36:37], v[42:43], v[36:37]
	s_nop 0
	v_pk_mul_f32 v[26:27], v[28:29], v[36:37]
	ds_bpermute_b32 v28, v53, v32
	v_mov_b32_e32 v36, v33
	v_pk_fma_f32 v[30:31], v[58:59], v[30:31], v[26:27]
	s_waitcnt lgkmcnt(0)
	v_mul_f32_e32 v28, v42, v28
	v_mul_f32_e32 v28, v23, v28
	ds_bpermute_b32 v23, v53, v33
	s_waitcnt lgkmcnt(0)
	v_mul_f32_e32 v37, v42, v23
	v_pk_mul_f32 v[24:25], v[24:25], v[36:37]
	s_nop 0
	v_mov_b32_e32 v23, v24
	v_mov_b32_e32 v29, v25
	v_pk_add_f32 v[32:33], v[22:23], v[28:29]
	s_branch .LBB0_287

; DI u32x2 pack4(f32x4 v) { u32x2 r = {cvtpk(v[0], v[1]), cvtpk(v[2], v[3])}; return r; }
; template <class Epi>
; DI void gemm256(const bf16_t* __restrict__ A, int lda, const bf16_t* __restrict__ Bt, int ldb, int K, char* lds, Epi epi) {
;     ...
;   float* ct = (float*)lds;
; #pragma unroll
;   for (int ai = 0; ai < 2; ++ai) {
;     __syncthreads();
; #pragma unroll
;     for (int bj = 0; bj < 2; ++bj)
; #pragma unroll
;       for (int m = 0; m < 4; ++m)
; #pragma unroll
;         for (int n = 0; n < 2; ++n)
; #pragma unroll
;           for (int j = 0; j < 4; ++j) ct[(wr * 64 + m * 16 + fq * 4 + j) * 260 + bj * 128 + wc * 32 + n * 16 + fr] = acc[ai][bj][m][n][j];
;     __syncthreads();
; #pragma unroll 2
;     for (int it = 0; it < 16; ++it) {
;       const int idx = it * NTHR + tid; const int row = idx >> 6, c4 = (idx & 63) * 4;
;       f32x4 v = *(const f32x4*)(ct + row * 260 + c4);
;       epi(ai * 128 + row, c4, v);
;     }
;   }
; DI void phase_inproj(KP p, int l, char* lds) {
;     ...
;       gemm256(hx + (size_t)m0 * 1024, 1024, wt + (size_t)n0 * 1024, 1024, 1024, lds, [&](int m, int n, f32x4 v) {
;         __builtin_nontemporal_store(pack4(v), (u32x2*)(P + (size_t)(m0 + m) * NIN + n0 + n));
;       });
.LBB0_321:
	s_or_b64 exec, exec, s[18:19]
	v_lshlrev_b32_e32 v0, 6, v141
	v_lshl_or_b32 v0, v144, 2, v0
	v_lshl_add_u32 v131, v142, 7, 0
	v_lshlrev_b32_e32 v132, 2, v145
	v_mul_lo_u32 v0, v0, s9
	v_add3_u32 v131, v131, v132, v0
	s_waitcnt vmcnt(0)
	s_barrier
	ds_write2_b32 v131, v114, v126 offset1:16
	v_add_u32_e32 v114, 0x400, v131
	ds_write2_b32 v114, v115, v127 offset0:4 offset1:20
	v_add_u32_e32 v115, 0x800, v131
	ds_write2_b32 v115, v116, v128 offset0:8 offset1:24
	v_add_u32_e32 v116, 0xc00, v131
	ds_write2_b32 v116, v117, v129 offset0:12 offset1:28
	v_add_u32_e32 v117, 0x4000, v131
	ds_write2_b32 v117, v82, v94 offset0:64 offset1:80
	v_add_u32_e32 v82, 0x4400, v131
	ds_write2_b32 v82, v83, v95 offset0:68 offset1:84
	v_add_u32_e32 v83, 0x4800, v131
	ds_write2_b32 v83, v84, v96 offset0:72 offset1:88
	v_add_u32_e32 v84, 0x4c00, v131
	ds_write2_b32 v84, v85, v97 offset0:76 offset1:92
	v_add_u32_e32 v85, 0x8000, v131
	ds_write2_b32 v85, v74, v78 offset0:128 offset1:144
	v_add_u32_e32 v74, 0x8400, v131
	ds_write2_b32 v74, v75, v79 offset0:132 offset1:148
	v_add_u32_e32 v75, 0x8800, v131
	ds_write2_b32 v75, v76, v80 offset0:136 offset1:152
	v_add_u32_e32 v76, 0x8c00, v131
	ds_write2_b32 v76, v77, v81 offset0:140 offset1:156
	v_add_u32_e32 v77, 0xc000, v131
	ds_write2_b32 v77, v66, v70 offset0:192 offset1:208
	v_add_u32_e32 v70, 0xc400, v131
	s_lshl_b64 s[18:19], s[2:3], 1
	v_and_b32_e32 v133, 0xfc, v143
	ds_write2_b32 v70, v67, v71 offset0:196 offset1:212
	v_add_u32_e32 v71, 0xc800, v131
	s_add_u32 s18, s42, s18
	ds_write2_b32 v71, v68, v72 offset0:200 offset1:216
	v_add_u32_e32 v68, 0xcc00, v131
	s_addc_u32 s19, s43, s19
	v_lshlrev_b32_e32 v0, 1, v133
	v_lshl_add_u32 v130, v133, 2, 0
	ds_write2_b32 v68, v69, v73 offset0:204 offset1:220
	ds_write2_b32 v131, v98, v118 offset0:128 offset1:144
	ds_write2_b32 v114, v99, v119 offset0:132 offset1:148
	ds_write2_b32 v115, v100, v120 offset0:136 offset1:152
	ds_write2_b32 v116, v101, v121 offset0:140 offset1:156
	ds_write2_b32 v117, v102, v122 offset0:192 offset1:208
	ds_write2_b32 v82, v103, v123 offset0:196 offset1:212
	ds_write2_b32 v83, v104, v124 offset0:200 offset1:216
	ds_write2_b32 v84, v105, v125 offset0:204 offset1:220
	ds_write2_b32 v74, v90, v110 offset1:16
	ds_write2_b32 v75, v91, v111 offset0:4 offset1:20
	ds_write2_b32 v76, v92, v112 offset0:8 offset1:24
	v_add_u32_e32 v69, 0x9000, v131
	v_add_u32_e32 v72, 0xd000, v131
	v_lshl_add_u64 v[66:67], s[18:19], 0, v[0:1]
	s_mov_b32 s2, 0
	ds_write2_b32 v69, v93, v113 offset0:12 offset1:28
	ds_write2_b32 v70, v86, v106 offset0:64 offset1:80
	ds_write2_b32 v71, v87, v107 offset0:68 offset1:84
	ds_write2_b32 v68, v88, v108 offset0:72 offset1:88
	ds_write2_b32 v72, v89, v109 offset0:76 offset1:92
	s_waitcnt lgkmcnt(0)
	s_barrier
	v_and_b32_e32 v141, 31, v140
	v_lshrrev_b32_e32 v142, 5, v140
	v_lshlrev_b32_e32 v143, 4, v141
	v_mad_u32_u24 v143, v142, s11, v143
	v_lshlrev_b32_e32 v141, 5, v141
	v_mad_u32_u24 v141, v142, s9, v141
	v_add_u32_e32 v142, 0x10400, v141
	s_mul_i32 s20, s4, s11
	s_add_u32 s20, s18, s20
	s_addc_u32 s21, s19, 0
	ds_read_b128 v[144:147], v141 offset:0
	ds_read_b128 v[148:151], v141 offset:16
	ds_read_b128 v[152:155], v141 offset:16640
	ds_read_b128 v[156:159], v141 offset:16656
	ds_read_b128 v[160:163], v141 offset:33280
	ds_read_b128 v[164:167], v141 offset:33296
	ds_read_b128 v[168:171], v141 offset:49920
	ds_read_b128 v[172:175], v141 offset:49936
	s_waitcnt lgkmcnt(6)
	v_cvt_pk_bf16_f32 v144, v144, v145
	v_cvt_pk_bf16_f32 v145, v146, v147
	v_cvt_pk_bf16_f32 v146, v148, v149
	v_cvt_pk_bf16_f32 v147, v150, v151
	s_add_u32 s46, s20, 0x0
	s_addc_u32 s47, s21, 0
	global_store_dwordx4 v143, v[144:147], s[46:47] nt
	s_waitcnt lgkmcnt(4)
	v_cvt_pk_bf16_f32 v152, v152, v153
	v_cvt_pk_bf16_f32 v153, v154, v155
	v_cvt_pk_bf16_f32 v154, v156, v157
	v_cvt_pk_bf16_f32 v155, v158, v159
	s_add_u32 s46, s20, 0x14c00
	s_addc_u32 s47, s21, 0
	global_store_dwordx4 v143, v[152:155], s[46:47] nt
	s_waitcnt lgkmcnt(2)
	v_cvt_pk_bf16_f32 v160, v160, v161
	v_cvt_pk_bf16_f32 v161, v162, v163
	v_cvt_pk_bf16_f32 v162, v164, v165
	v_cvt_pk_bf16_f32 v163, v166, v167
	s_add_u32 s46, s20, 0x29800
	s_addc_u32 s47, s21, 0
	global_store_dwordx4 v143, v[160:163], s[46:47] nt
	s_waitcnt lgkmcnt(0)
	v_cvt_pk_bf16_f32 v168, v168, v169
	v_cvt_pk_bf16_f32 v169, v170, v171
	v_cvt_pk_bf16_f32 v170, v172, v173
	v_cvt_pk_bf16_f32 v171, v174, v175
	s_add_u32 s46, s20, 0x3e400
	s_addc_u32 s47, s21, 0
	global_store_dwordx4 v143, v[168:171], s[46:47] nt
	ds_read_b128 v[144:147], v142 offset:0
	ds_read_b128 v[148:151], v142 offset:16
	ds_read_b128 v[152:155], v142 offset:16640
	ds_read_b128 v[156:159], v142 offset:16656
	ds_read_b128 v[160:163], v142 offset:33280
	ds_read_b128 v[164:167], v142 offset:33296
	ds_read_b128 v[168:171], v142 offset:49920
	ds_read_b128 v[172:175], v142 offset:49936
	s_waitcnt lgkmcnt(6)
	v_cvt_pk_bf16_f32 v144, v144, v145
	v_cvt_pk_bf16_f32 v145, v146, v147
	v_cvt_pk_bf16_f32 v146, v148, v149
	v_cvt_pk_bf16_f32 v147, v150, v151
	s_add_u32 s46, s20, 0x53000
	s_addc_u32 s47, s21, 0
	global_store_dwordx4 v143, v[144:147], s[46:47] nt
	s_waitcnt lgkmcnt(4)
	v_cvt_pk_bf16_f32 v152, v152, v153
	v_cvt_pk_bf16_f32 v153, v154, v155
	v_cvt_pk_bf16_f32 v154, v156, v157
	v_cvt_pk_bf16_f32 v155, v158, v159
	s_add_u32 s46, s20, 0x67c00
	s_addc_u32 s47, s21, 0
	global_store_dwordx4 v143, v[152:155], s[46:47] nt
	s_waitcnt lgkmcnt(2)
	v_cvt_pk_bf16_f32 v160, v160, v161
	v_cvt_pk_bf16_f32 v161, v162, v163
	v_cvt_pk_bf16_f32 v162, v164, v165
	v_cvt_pk_bf16_f32 v163, v166, v167
	s_add_u32 s46, s20, 0x7c800
	s_addc_u32 s47, s21, 0
	global_store_dwordx4 v143, v[160:163], s[46:47] nt
	s_waitcnt lgkmcnt(0)
	v_cvt_pk_bf16_f32 v168, v168, v169
	v_cvt_pk_bf16_f32 v169, v170, v171
	v_cvt_pk_bf16_f32 v170, v172, v173
	v_cvt_pk_bf16_f32 v171, v174, v175
	s_add_u32 s46, s20, 0x91400
	s_addc_u32 s47, s21, 0
	global_store_dwordx4 v143, v[168:171], s[46:47] nt
	s_or_b32 s2, s4, 0x80
	s_mov_b32 s4, 0
	s_waitcnt lgkmcnt(0)
	s_barrier
; DI u32x2 pack4(f32x4 v) { u32x2 r = {cvtpk(v[0], v[1]), cvtpk(v[2], v[3])}; return r; }
; template <class Epi>
; DI void gemm256(const bf16_t* __restrict__ A, int lda, const bf16_t* __restrict__ Bt, int ldb, int K, char* lds, Epi epi) {
;     ...
;   for (int ai = 0; ai < 2; ++ai) {
;     __syncthreads();
; #pragma unroll
;     for (int bj = 0; bj < 2; ++bj)
; #pragma unroll
;       for (int m = 0; m < 4; ++m)
; #pragma unroll
;         for (int n = 0; n < 2; ++n)
; #pragma unroll
;           for (int j = 0; j < 4; ++j) ct[(wr * 64 + m * 16 + fq * 4 + j) * 260 + bj * 128 + wc * 32 + n * 16 + fr] = acc[ai][bj][m][n][j];
;     __syncthreads();
; #pragma unroll 2
;     for (int it = 0; it < 16; ++it) {
;       const int idx = it * NTHR + tid; const int row = idx >> 6, c4 = (idx & 63) * 4;
;       f32x4 v = *(const f32x4*)(ct + row * 260 + c4);
;       epi(ai * 128 + row, c4, v);
;     }
;   }
; DI void phase_inproj(KP p, int l, char* lds) {
;     ...
;       gemm256(hx + (size_t)m0 * 1024, 1024, wt + (size_t)n0 * 1024, 1024, 1024, lds, [&](int m, int n, f32x4 v) {
;         __builtin_nontemporal_store(pack4(v), (u32x2*)(P + (size_t)(m0 + m) * NIN + n0 + n));
;       });
	ds_write2_b32 v131, v2, v18 offset1:16
	ds_write2_b32 v114, v3, v19 offset0:4 offset1:20
	ds_write2_b32 v115, v4, v20 offset0:8 offset1:24
	ds_write2_b32 v116, v5, v21 offset0:12 offset1:28
	ds_write2_b32 v117, v6, v22 offset0:64 offset1:80
	ds_write2_b32 v82, v7, v23 offset0:68 offset1:84
	ds_write2_b32 v83, v8, v24 offset0:72 offset1:88
	ds_write2_b32 v84, v9, v25 offset0:76 offset1:92
	ds_write2_b32 v85, v10, v26 offset0:128 offset1:144
	ds_write2_b32 v74, v11, v27 offset0:132 offset1:148
	ds_write2_b32 v75, v12, v28 offset0:136 offset1:152
	ds_write2_b32 v76, v13, v29 offset0:140 offset1:156
	ds_write2_b32 v77, v14, v30 offset0:192 offset1:208
	ds_write2_b32 v70, v15, v31 offset0:196 offset1:212
	ds_write2_b32 v71, v16, v32 offset0:200 offset1:216
	ds_write2_b32 v68, v17, v33 offset0:204 offset1:220
	ds_write2_b32 v131, v34, v50 offset0:128 offset1:144
	ds_write2_b32 v114, v35, v51 offset0:132 offset1:148
	ds_write2_b32 v115, v36, v52 offset0:136 offset1:152
	ds_write2_b32 v116, v37, v53 offset0:140 offset1:156
	ds_write2_b32 v117, v38, v54 offset0:192 offset1:208
	ds_write2_b32 v82, v39, v55 offset0:196 offset1:212
	ds_write2_b32 v83, v40, v56 offset0:200 offset1:216
	ds_write2_b32 v84, v41, v57 offset0:204 offset1:220
	ds_write2_b32 v74, v42, v58 offset1:16
	ds_write2_b32 v75, v43, v59 offset0:4 offset1:20
	ds_write2_b32 v76, v44, v60 offset0:8 offset1:24
	ds_write2_b32 v69, v45, v61 offset0:12 offset1:28
	ds_write2_b32 v70, v46, v62 offset0:64 offset1:80
	ds_write2_b32 v71, v47, v63 offset0:68 offset1:84
	ds_write2_b32 v68, v48, v64 offset0:72 offset1:88
	ds_write2_b32 v72, v49, v65 offset0:76 offset1:92
	s_waitcnt lgkmcnt(0)
	s_barrier
	s_mul_i32 s20, s2, s11
	s_add_u32 s20, s18, s20
	s_addc_u32 s21, s19, 0
	ds_read_b128 v[144:147], v141 offset:0
	ds_read_b128 v[148:151], v141 offset:16
	ds_read_b128 v[152:155], v141 offset:16640
	ds_read_b128 v[156:159], v141 offset:16656
	ds_read_b128 v[160:163], v141 offset:33280
	ds_read_b128 v[164:167], v141 offset:33296
	ds_read_b128 v[168:171], v141 offset:49920
	ds_read_b128 v[172:175], v141 offset:49936
	s_waitcnt lgkmcnt(6)
	v_cvt_pk_bf16_f32 v144, v144, v145
	v_cvt_pk_bf16_f32 v145, v146, v147
	v_cvt_pk_bf16_f32 v146, v148, v149
	v_cvt_pk_bf16_f32 v147, v150, v151
	s_add_u32 s46, s20, 0x0
	s_addc_u32 s47, s21, 0
	global_store_dwordx4 v143, v[144:147], s[46:47] nt
	s_waitcnt lgkmcnt(4)
	v_cvt_pk_bf16_f32 v152, v152, v153
	v_cvt_pk_bf16_f32 v153, v154, v155
	v_cvt_pk_bf16_f32 v154, v156, v157
	v_cvt_pk_bf16_f32 v155, v158, v159
	s_add_u32 s46, s20, 0x14c00
	s_addc_u32 s47, s21, 0
	global_store_dwordx4 v143, v[152:155], s[46:47] nt
	s_waitcnt lgkmcnt(2)
	v_cvt_pk_bf16_f32 v160, v160, v161
	v_cvt_pk_bf16_f32 v161, v162, v163
	v_cvt_pk_bf16_f32 v162, v164, v165
	v_cvt_pk_bf16_f32 v163, v166, v167
	s_add_u32 s46, s20, 0x29800
	s_addc_u32 s47, s21, 0
	global_store_dwordx4 v143, v[160:163], s[46:47] nt
	s_waitcnt lgkmcnt(0)
	v_cvt_pk_bf16_f32 v168, v168, v169
	v_cvt_pk_bf16_f32 v169, v170, v171
	v_cvt_pk_bf16_f32 v170, v172, v173
	v_cvt_pk_bf16_f32 v171, v174, v175
	s_add_u32 s46, s20, 0x3e400
	s_addc_u32 s47, s21, 0
	global_store_dwordx4 v143, v[168:171], s[46:47] nt
	ds_read_b128 v[144:147], v142 offset:0
	ds_read_b128 v[148:151], v142 offset:16
	ds_read_b128 v[152:155], v142 offset:16640
	ds_read_b128 v[156:159], v142 offset:16656
	ds_read_b128 v[160:163], v142 offset:33280
	ds_read_b128 v[164:167], v142 offset:33296
	ds_read_b128 v[168:171], v142 offset:49920
	ds_read_b128 v[172:175], v142 offset:49936
	s_waitcnt lgkmcnt(6)
	v_cvt_pk_bf16_f32 v144, v144, v145
	v_cvt_pk_bf16_f32 v145, v146, v147
	v_cvt_pk_bf16_f32 v146, v148, v149
	v_cvt_pk_bf16_f32 v147, v150, v151
	s_add_u32 s46, s20, 0x53000
	s_addc_u32 s47, s21, 0
	global_store_dwordx4 v143, v[144:147], s[46:47] nt
	s_waitcnt lgkmcnt(4)
	v_cvt_pk_bf16_f32 v152, v152, v153
	v_cvt_pk_bf16_f32 v153, v154, v155
	v_cvt_pk_bf16_f32 v154, v156, v157
	v_cvt_pk_bf16_f32 v155, v158, v159
	s_add_u32 s46, s20, 0x67c00
	s_addc_u32 s47, s21, 0
	global_store_dwordx4 v143, v[152:155], s[46:47] nt
	s_waitcnt lgkmcnt(2)
	v_cvt_pk_bf16_f32 v160, v160, v161
	v_cvt_pk_bf16_f32 v161, v162, v163
	v_cvt_pk_bf16_f32 v162, v164, v165
	v_cvt_pk_bf16_f32 v163, v166, v167
	s_add_u32 s46, s20, 0x7c800
	s_addc_u32 s47, s21, 0
	global_store_dwordx4 v143, v[160:163], s[46:47] nt
	s_waitcnt lgkmcnt(0)
	v_cvt_pk_bf16_f32 v168, v168, v169
	v_cvt_pk_bf16_f32 v169, v170, v171
	v_cvt_pk_bf16_f32 v170, v172, v173
	v_cvt_pk_bf16_f32 v171, v174, v175
	s_add_u32 s46, s20, 0x91400
	s_addc_u32 s47, s21, 0
	global_store_dwordx4 v143, v[168:171], s[46:47] nt
	s_waitcnt lgkmcnt(0)
	s_barrier
	s_branch .LBB0_304

; DI u32x2 pack4(f32x4 v) { u32x2 r = {cvtpk(v[0], v[1]), cvtpk(v[2], v[3])}; return r; }
;     ...
; #pragma unroll 4
;   for (int it = 0; it < 16; ++it) {
;     const int idx = it * 256 + tid; const int row = idx >> 5, c4 = (idx & 31) * 4;
;     f32x4 v = *(const f32x4*)(ct + row * 132 + c4);
;     epi(row, c4, v);
;   }
; DI void phase_inproj(KP p, int l, char* lds) {
;     ...
;       gemm_tile(hx + (size_t)m0 * 1024, 1024, wt + (size_t)2560 * 1024, 1024, 1024, lds, [&](int m, int n, f32x4 v) {
;         if (2560 + n < NIN) __builtin_nontemporal_store(pack4(v), (u32x2*)(P + (size_t)(m0 + m) * NIN + 2560 + n));
;       });
.LBB0_337:
	s_and_saveexec_b64 s[18:19], s[40:41]
	s_cbranch_execz .LBB0_336
	ds_read_b128 v[4:7], v3
	v_add_u32_e32 v10, s34, v2
	v_mov_b64_e32 v[8:9], s[42:43]
	s_waitcnt lgkmcnt(0)
	v_cvt_pk_bf16_f32 v4, v4, v5
	v_cvt_pk_bf16_f32 v5, v6, v7
	v_mad_i64_i32 v[6:7], s[52:53], v10, s11, v[8:9]
	v_lshl_add_u64 v[6:7], v[6:7], 0, v[0:1]
	v_add_co_u32_e32 v6, vcc, 0x1000, v6
	s_nop 1
	v_addc_co_u32_e32 v7, vcc, 0, v7, vcc
	global_store_dwordx2 v[6:7], v[4:5], off offset:1024 nt
	ds_read_b128 v[4:7], v3 offset:4224
	s_waitcnt lgkmcnt(0)
	v_cvt_pk_bf16_f32 v4, v4, v5
	v_cvt_pk_bf16_f32 v5, v6, v7
	v_add_u32_e32 v6, 8, v10
	v_mad_i64_i32 v[6:7], s[52:53], v6, s11, v[8:9]
	v_lshl_add_u64 v[6:7], v[6:7], 0, v[0:1]
	v_add_co_u32_e32 v6, vcc, s6, v6
	s_nop 1
	v_addc_co_u32_e32 v7, vcc, 0, v7, vcc
	global_store_dwordx2 v[6:7], v[4:5], off offset:1024 nt
	ds_read_b128 v[4:7], v3 offset:8448
	s_waitcnt lgkmcnt(0)
	v_cvt_pk_bf16_f32 v4, v4, v5
	v_cvt_pk_bf16_f32 v5, v6, v7
	v_add_u32_e32 v6, 16, v10
	v_mad_i64_i32 v[6:7], s[52:53], v6, s11, v[8:9]
	v_lshl_add_u64 v[6:7], v[6:7], 0, v[0:1]
	v_add_co_u32_e32 v6, vcc, s6, v6
	s_nop 1
	v_addc_co_u32_e32 v7, vcc, 0, v7, vcc
	global_store_dwordx2 v[6:7], v[4:5], off offset:1024 nt
	ds_read_b128 v[4:7], v3 offset:12672
	s_waitcnt lgkmcnt(0)
	v_cvt_pk_bf16_f32 v4, v4, v5
	v_cvt_pk_bf16_f32 v5, v6, v7
	v_add_u32_e32 v6, 24, v10
	v_mad_i64_i32 v[6:7], s[52:53], v6, s11, v[8:9]
	v_lshl_add_u64 v[6:7], v[6:7], 0, v[0:1]
	v_add_co_u32_e32 v6, vcc, 0x1000, v6
	s_nop 1
	v_addc_co_u32_e32 v7, vcc, 0, v7, vcc
	global_store_dwordx2 v[6:7], v[4:5], off offset:1024 nt
	s_branch .LBB0_336

;     ...
;   float* ct = (float*)lds;
; #pragma unroll
;   for (int i = 0; i < 2; ++i)
; #pragma unroll
;     for (int j = 0; j < 2; ++j)
; #pragma unroll
;       for (int q = 0; q < 4; ++q) {
;         f32x4 v = {acc[i][j][4 * q], acc[i][j][4 * q + 1], acc[i][j][4 * q + 2], acc[i][j][4 * q + 3]};
;         *(f32x4*)(ct + (wr * 64 + i * 32 + l31) * 132 + wc * 64 + j * 32 + 8 * q + 4 * h) = v;
;       }
;   __syncthreads();
; #pragma unroll 4
;   for (int it = 0; it < 16; ++it) {
;     const int idx = it * 256 + tid; const int row = idx >> 5, c4 = (idx & 31) * 4;
;     f32x4 v = *(const f32x4*)(ct + row * 132 + c4);
;     epi(row, c4, v);
;   }
; DI void phase_outproj(KP p, int l, char* lds) {
;     ...
;       gemm_tile(Y + (size_t)m0 * 1024, 1024, wo + (size_t)n0 * 1024, 1024, 1024, lds, [&](int m, int n, f32x4 v) {
;         const size_t o = (size_t)m * 1024 + n0 + n;
;         f32x4 xv = *(const f32x4*)(src + o), g = *(const f32x4*)(gt + n0 + n);
;         f32x4 r = {xv[0] + g[0] * v[0], xv[1] + g[1] * v[1], xv[2] + g[2] * v[2], xv[3] + g[3] * v[3]};
;         *(f32x4*)(dst + o) = r; });
.LBB0_360:
	v_cndmask_b32_e64 v0, 0, 1, s[44:45]
	v_lshlrev_b32_e32 v66, 19, v0
	v_and_b32_e32 v0, 64, v76
	v_lshl_add_u32 v0, v0, 2, v77
	v_lshlrev_b32_e32 v67, 4, v78
	v_mul_u32_u24_e32 v68, 0x210, v79
	s_and_b32 s43, s43, 7
	v_add3_u32 v0, v0, v67, v68
	s_lshl_b32 s46, s43, 7
	s_ashr_i32 s43, s42, 31
	ds_write_b128 v0, v[50:53]
	ds_write_b128 v0, v[54:57] offset:32
	ds_write_b128 v0, v[58:61] offset:64
	ds_write_b128 v0, v[62:65] offset:96
	ds_write_b128 v0, v[34:37] offset:128
	ds_write_b128 v0, v[38:41] offset:160
	ds_write_b128 v0, v[42:45] offset:192
	ds_write_b128 v0, v[46:49] offset:224
	ds_write_b128 v0, v[18:21] offset:16896
	ds_write_b128 v0, v[22:25] offset:16928
	ds_write_b128 v0, v[26:29] offset:16960
	ds_write_b128 v0, v[30:33] offset:16992
	ds_write_b128 v0, v[2:5] offset:17024
	ds_write_b128 v0, v[6:9] offset:17056
	ds_write_b128 v0, v[10:13] offset:17088
	ds_write_b128 v0, v[14:17] offset:17120
	v_lshlrev_b32_e32 v0, 2, v76
	s_lshl_b32 s44, s51, 2
	v_and_b32_e32 v4, 0x7c, v0
	s_add_u32 s44, s18, s44
	s_addc_u32 s45, s19, 0
	v_lshlrev_b32_e32 v0, 2, v4
	v_lshl_add_u64 v[2:3], s[44:45], 0, v[0:1]
	v_mov_b32_e32 v0, 5
	v_lshrrev_b32_sdwa v20, v0, v76 dst_sel:DWORD dst_unused:UNUSED_PAD src0_sel:DWORD src1_sel:BYTE_0
	v_lshlrev_b32_e32 v0, 10, v20
	v_or3_b32 v0, v0, s46, v4
	s_lshl_b64 s[42:43], s[42:43], 20
	v_lshlrev_b32_e32 v18, 2, v0
	v_or_b32_e32 v16, s42, v66
	v_mov_b32_e32 v17, s43
	v_or_b32_e32 v0, 0x18000, v18
	v_lshl_add_u64 v[6:7], v[16:17], 0, v[0:1]
	v_or_b32_e32 v0, 0x10000, v18
	v_lshl_add_u64 v[10:11], v[16:17], 0, v[0:1]
	v_or_b32_e32 v0, 0x8000, v18
	v_mov_b32_e32 v19, v1
	s_movk_i32 s42, 0x210
	v_lshl_add_u64 v[14:15], v[16:17], 0, v[0:1]
	v_lshl_add_u64 v[18:19], v[16:17], 0, v[18:19]
	v_mad_u32_u24 v0, v20, s42, v74
	v_lshlrev_b32_e32 v20, 4, v75
	v_lshl_add_u64 v[4:5], s[40:41], 0, v[6:7]
	v_lshl_add_u64 v[6:7], s[4:5], 0, v[6:7]
	v_lshl_add_u64 v[8:9], s[40:41], 0, v[10:11]
	v_lshl_add_u64 v[10:11], s[4:5], 0, v[10:11]
	v_lshl_add_u64 v[12:13], s[40:41], 0, v[14:15]
	v_lshl_add_u64 v[14:15], s[4:5], 0, v[14:15]
	v_lshl_add_u64 v[16:17], s[40:41], 0, v[18:19]
	v_lshl_add_u64 v[18:19], s[4:5], 0, v[18:19]
	v_add3_u32 v0, v0, v20, 0
	s_mov_b64 s[42:43], 0
	s_waitcnt lgkmcnt(0)
	s_barrier
	global_load_dwordx4 v[232:235], v[2:3], off
	s_mov_b32 s47, 0
	s_mov_b32 s46, 0x0
	v_lshl_add_u64 v[34:35], v[18:19], 0, s[46:47]
	global_load_dwordx4 v[112:115], v[34:35], off
	s_mov_b32 s46, 0x0
	v_lshl_add_u64 v[34:35], v[14:15], 0, s[46:47]
	global_load_dwordx4 v[116:119], v[34:35], off
	s_mov_b32 s46, 0x0
	v_lshl_add_u64 v[34:35], v[10:11], 0, s[46:47]
	global_load_dwordx4 v[120:123], v[34:35], off
	s_mov_b32 s46, 0x0
	v_lshl_add_u64 v[34:35], v[6:7], 0, s[46:47]
	global_load_dwordx4 v[124:127], v[34:35], off
	s_mov_b32 s46, 0x20000
	v_lshl_add_u64 v[34:35], v[18:19], 0, s[46:47]
	global_load_dwordx4 v[128:131], v[34:35], off
	s_mov_b32 s46, 0x20000
	v_lshl_add_u64 v[34:35], v[14:15], 0, s[46:47]
	global_load_dwordx4 v[132:135], v[34:35], off
	s_mov_b32 s46, 0x20000
	v_lshl_add_u64 v[34:35], v[10:11], 0, s[46:47]
	global_load_dwordx4 v[136:139], v[34:35], off
	s_mov_b32 s46, 0x20000
	v_lshl_add_u64 v[34:35], v[6:7], 0, s[46:47]
	global_load_dwordx4 v[140:143], v[34:35], off
	s_mov_b32 s46, 0x40000
	v_lshl_add_u64 v[34:35], v[18:19], 0, s[46:47]
	global_load_dwordx4 v[144:147], v[34:35], off
	s_mov_b32 s46, 0x40000
	v_lshl_add_u64 v[34:35], v[14:15], 0, s[46:47]
	global_load_dwordx4 v[148:151], v[34:35], off
	s_mov_b32 s46, 0x40000
	v_lshl_add_u64 v[34:35], v[10:11], 0, s[46:47]
	global_load_dwordx4 v[152:155], v[34:35], off
	s_mov_b32 s46, 0x40000
	v_lshl_add_u64 v[34:35], v[6:7], 0, s[46:47]
	global_load_dwordx4 v[156:159], v[34:35], off
	s_mov_b32 s46, 0x60000
	v_lshl_add_u64 v[34:35], v[18:19], 0, s[46:47]
	global_load_dwordx4 v[216:219], v[34:35], off
	s_mov_b32 s46, 0x60000
	v_lshl_add_u64 v[34:35], v[14:15], 0, s[46:47]
	global_load_dwordx4 v[220:223], v[34:35], off
	s_mov_b32 s46, 0x60000
	v_lshl_add_u64 v[34:35], v[10:11], 0, s[46:47]
	global_load_dwordx4 v[224:227], v[34:35], off
	s_mov_b32 s46, 0x60000
	v_lshl_add_u64 v[34:35], v[6:7], 0, s[46:47]
	global_load_dwordx4 v[228:231], v[34:35], off
	ds_read_b128 v[236:239], v0 offset:0
	ds_read_b128 v[240:243], v0 offset:4224
	ds_read_b128 v[244:247], v0 offset:8448
	s_mov_b32 s46, 0x0
	v_lshl_add_u64 v[34:35], v[16:17], 0, s[46:47]
	ds_read_b128 v[248:251], v0 offset:12672
	s_waitcnt vmcnt(15) lgkmcnt(3)
	v_pk_fma_f32 v[238:239], v[238:239], v[234:235], v[114:115]
	v_pk_fma_f32 v[236:237], v[236:237], v[232:233], v[112:113]
	global_store_dwordx4 v[34:35], v[236:239], off
	s_mov_b32 s46, 0x0
	v_lshl_add_u64 v[34:35], v[12:13], 0, s[46:47]
	ds_read_b128 v[236:239], v0 offset:16896
	s_waitcnt vmcnt(15) lgkmcnt(3)
;     ...
; #pragma unroll 4
;   for (int it = 0; it < 16; ++it) {
;     const int idx = it * 256 + tid; const int row = idx >> 5, c4 = (idx & 31) * 4;
;     f32x4 v = *(const f32x4*)(ct + row * 132 + c4);
;     epi(row, c4, v);
;   }
; DI void phase_outproj(KP p, int l, char* lds) {
;     ...
;   for (int j = lb; j < nsm; j += nlb) {
;     {
;       const int item = 2 * j + hb; const int bb = 2 * xcd + (item >> 4), m128 = (item >> 3) & 1, nt = item & 7;
;       const int m0 = (bb * 18 + 16 + m128) * 128, n0 = nt * 128;
;       const float* src = p->ctx + ((size_t)bb * CL + m128 * 128) * 1024;
;       float* dst = ctx1 + ((size_t)bb * CL + m128 * 128) * 1024;
;       const float* gt = mod + (size_t)16 * 3072 + 2048;
;       gemm_tile(Y + (size_t)m0 * 1024, 1024, wo + (size_t)n0 * 1024, 1024, 1024, lds, [&](int m, int n, f32x4 v) {
;         const size_t o = (size_t)m * 1024 + n0 + n;
;         f32x4 xv = *(const f32x4*)(src + o), g = *(const f32x4*)(gt + n0 + n);
;         f32x4 r = {xv[0] + g[0] * v[0], xv[1] + g[1] * v[1], xv[2] + g[2] * v[2], xv[3] + g[3] * v[3]};
;         *(f32x4*)(dst + o) = r; });
	v_pk_fma_f32 v[242:243], v[242:243], v[234:235], v[118:119]
	v_pk_fma_f32 v[240:241], v[240:241], v[232:233], v[116:117]
	global_store_dwordx4 v[34:35], v[240:243], off
	s_mov_b32 s46, 0x0
	v_lshl_add_u64 v[34:35], v[8:9], 0, s[46:47]
	ds_read_b128 v[240:243], v0 offset:21120
	s_waitcnt vmcnt(15) lgkmcnt(3)
	v_pk_fma_f32 v[246:247], v[246:247], v[234:235], v[122:123]
	v_pk_fma_f32 v[244:245], v[244:245], v[232:233], v[120:121]
	global_store_dwordx4 v[34:35], v[244:247], off
	s_mov_b32 s46, 0x0
	v_lshl_add_u64 v[34:35], v[4:5], 0, s[46:47]
	ds_read_b128 v[244:247], v0 offset:25344
	s_waitcnt vmcnt(15) lgkmcnt(3)
	v_pk_fma_f32 v[250:251], v[250:251], v[234:235], v[126:127]
	v_pk_fma_f32 v[248:249], v[248:249], v[232:233], v[124:125]
	global_store_dwordx4 v[34:35], v[248:251], off
	s_mov_b32 s46, 0x20000
	v_lshl_add_u64 v[34:35], v[16:17], 0, s[46:47]
	ds_read_b128 v[248:251], v0 offset:29568
	s_waitcnt vmcnt(15) lgkmcnt(3)
	v_pk_fma_f32 v[238:239], v[238:239], v[234:235], v[130:131]
	v_pk_fma_f32 v[236:237], v[236:237], v[232:233], v[128:129]
	global_store_dwordx4 v[34:35], v[236:239], off
	s_mov_b32 s46, 0x20000
	v_lshl_add_u64 v[34:35], v[12:13], 0, s[46:47]
	ds_read_b128 v[236:239], v0 offset:33792
	s_waitcnt vmcnt(15) lgkmcnt(3)
	v_pk_fma_f32 v[242:243], v[242:243], v[234:235], v[134:135]
	v_pk_fma_f32 v[240:241], v[240:241], v[232:233], v[132:133]
	global_store_dwordx4 v[34:35], v[240:243], off
	s_mov_b32 s46, 0x20000
	v_lshl_add_u64 v[34:35], v[8:9], 0, s[46:47]
	ds_read_b128 v[240:243], v0 offset:38016
	s_waitcnt vmcnt(15) lgkmcnt(3)
	v_pk_fma_f32 v[246:247], v[246:247], v[234:235], v[138:139]
	v_pk_fma_f32 v[244:245], v[244:245], v[232:233], v[136:137]
	global_store_dwordx4 v[34:35], v[244:247], off
	s_mov_b32 s46, 0x20000
	v_lshl_add_u64 v[34:35], v[4:5], 0, s[46:47]
	ds_read_b128 v[244:247], v0 offset:42240
	s_waitcnt vmcnt(15) lgkmcnt(3)
	v_pk_fma_f32 v[250:251], v[250:251], v[234:235], v[142:143]
	v_pk_fma_f32 v[248:249], v[248:249], v[232:233], v[140:141]
	global_store_dwordx4 v[34:35], v[248:251], off
	s_mov_b32 s46, 0x40000
	v_lshl_add_u64 v[34:35], v[16:17], 0, s[46:47]
	ds_read_b128 v[248:251], v0 offset:46464
	s_waitcnt vmcnt(15) lgkmcnt(3)
	v_pk_fma_f32 v[238:239], v[238:239], v[234:235], v[146:147]
	v_pk_fma_f32 v[236:237], v[236:237], v[232:233], v[144:145]
	global_store_dwordx4 v[34:35], v[236:239], off
	s_mov_b32 s46, 0x40000
	v_lshl_add_u64 v[34:35], v[12:13], 0, s[46:47]
	ds_read_b128 v[236:239], v0 offset:50688
	s_waitcnt vmcnt(15) lgkmcnt(3)
	v_pk_fma_f32 v[242:243], v[242:243], v[234:235], v[150:151]
	v_pk_fma_f32 v[240:241], v[240:241], v[232:233], v[148:149]
	global_store_dwordx4 v[34:35], v[240:243], off
	s_mov_b32 s46, 0x40000
	v_lshl_add_u64 v[34:35], v[8:9], 0, s[46:47]
	ds_read_b128 v[240:243], v0 offset:54912
	s_waitcnt vmcnt(15) lgkmcnt(3)
	v_pk_fma_f32 v[246:247], v[246:247], v[234:235], v[154:155]
	v_pk_fma_f32 v[244:245], v[244:245], v[232:233], v[152:153]
	global_store_dwordx4 v[34:35], v[244:247], off
	s_mov_b32 s46, 0x40000
	v_lshl_add_u64 v[34:35], v[4:5], 0, s[46:47]
	ds_read_b128 v[244:247], v0 offset:59136
	s_waitcnt vmcnt(15) lgkmcnt(3)
	v_pk_fma_f32 v[250:251], v[250:251], v[234:235], v[158:159]
	v_pk_fma_f32 v[248:249], v[248:249], v[232:233], v[156:157]
	global_store_dwordx4 v[34:35], v[248:251], off
	s_mov_b32 s46, 0x60000
	v_lshl_add_u64 v[34:35], v[16:17], 0, s[46:47]
	ds_read_b128 v[248:251], v0 offset:63360
	s_waitcnt vmcnt(15) lgkmcnt(3)
	v_pk_fma_f32 v[238:239], v[238:239], v[234:235], v[218:219]
	v_pk_fma_f32 v[236:237], v[236:237], v[232:233], v[216:217]
	global_store_dwordx4 v[34:35], v[236:239], off
	s_mov_b32 s46, 0x60000
	v_lshl_add_u64 v[34:35], v[12:13], 0, s[46:47]
	s_waitcnt vmcnt(15) lgkmcnt(2)
	v_pk_fma_f32 v[242:243], v[242:243], v[234:235], v[222:223]
	v_pk_fma_f32 v[240:241], v[240:241], v[232:233], v[220:221]
	global_store_dwordx4 v[34:35], v[240:243], off
	s_mov_b32 s46, 0x60000
	v_lshl_add_u64 v[34:35], v[8:9], 0, s[46:47]
	s_waitcnt vmcnt(15) lgkmcnt(1)
	v_pk_fma_f32 v[246:247], v[246:247], v[234:235], v[226:227]
	v_pk_fma_f32 v[244:245], v[244:245], v[232:233], v[224:225]
	global_store_dwordx4 v[34:35], v[244:247], off
	s_mov_b32 s46, 0x60000
	v_lshl_add_u64 v[34:35], v[4:5], 0, s[46:47]
	s_waitcnt vmcnt(15) lgkmcnt(0)
	v_pk_fma_f32 v[250:251], v[250:251], v[234:235], v[230:231]
	v_pk_fma_f32 v[248:249], v[248:249], v[232:233], v[228:229]
	global_store_dwordx4 v[34:35], v[248:251], off
	v_add_u32_e32 v0, 0x10800, v0
	s_mov_b64 s[42:43], 0x80000
	v_readlane_b32 s42, v254, 45
	s_add_i32 s48, s48, s42
	v_readlane_b32 s42, v253, 4
	s_add_i32 s50, s50, s69
	s_add_i32 s49, s49, s42
	s_cmp_gt_u32 s50, 15
	s_waitcnt lgkmcnt(0)
	s_barrier
	s_cbranch_scc0 .LBB0_356

; DI unsigned cvtpk(float lo, float hi) { f32x2 v = {lo, hi}; bf16x2_t b = __builtin_convertvector(v, bf16x2_t); return __builtin_bit_cast(unsigned, b); }
; DI void xpose_cvt(const float* __restrict__ src, bf16_t* __restrict__ dst, int K, int N, int Npad, bool perm_kv, size_t gtid, size_t gstride) {
;   const size_t total = (size_t)Npad * (K >> 3);
; #pragma nounroll
;   for (size_t i = gtid; i < total; i += gstride) {
;     const int n = (int)(i % Npad), kb = (int)(i / Npad);
;     float v[8];
; #pragma unroll
;     for (int e = 0; e < 8; ++e) v[e] = (n < N) ? src[(size_t)(8 * kb + e) * N + n] : 0.f;
;     int row = n;
;     if (perm_kv) { const int hh = n >> 7, wv = n & 127; row = (wv < 64) ? (64 * hh + wv) : (256 + 64 * hh + (wv - 64)); }
;     u32x4 o = {cvtpk(v[0], v[1]), cvtpk(v[2], v[3]), cvtpk(v[4], v[5]), cvtpk(v[6], v[7])};
;     *(u32x4*)(dst + (size_t)row * K + 8 * kb) = o;
;   }
.LBB0_369:
	s_or_b64 exec, exec, s[34:35]
	v_lshlrev_b32_e32 v0, 11, v0
	v_lshl_add_u64 v[12:13], v[12:13], 0, s[62:63]
	s_mov_b64 s[34:35], 0x57fff
	s_waitcnt vmcnt(0)
	v_cvt_pk_bf16_f32 v14, v19, v20
	v_cvt_pk_bf16_f32 v15, v22, v21
	v_lshl_add_u64 v[20:21], s[18:19], 0, v[0:1]
	v_lshlrev_b32_e32 v0, 4, v18
	v_cmp_lt_u64_e32 vcc, s[34:35], v[12:13]
	v_cvt_pk_bf16_f32 v16, v24, v23
	v_cvt_pk_bf16_f32 v17, v26, v25
	v_lshl_add_u64 v[18:19], v[20:21], 0, v[0:1]
	s_or_b64 s[20:21], vcc, s[20:21]
	global_store_dwordx4 v[18:19], v[14:17], off
	s_andn2_b64 exec, exec, s[20:21]
	s_cbranch_execz .LBB0_386

; DI unsigned cvtpk(float lo, float hi) { f32x2 v = {lo, hi}; bf16x2_t b = __builtin_convertvector(v, bf16x2_t); return __builtin_bit_cast(unsigned, b); }
; DI void xpose_cvt(const float* __restrict__ src, bf16_t* __restrict__ dst, int K, int N, int Npad, bool perm_kv, size_t gtid, size_t gstride) {
;   const size_t total = (size_t)Npad * (K >> 3);
; #pragma nounroll
;   for (size_t i = gtid; i < total; i += gstride) {
;     const int n = (int)(i % Npad), kb = (int)(i / Npad);
;     float v[8];
; #pragma unroll
;     for (int e = 0; e < 8; ++e) v[e] = (n < N) ? src[(size_t)(8 * kb + e) * N + n] : 0.f;
;     int row = n;
;     if (perm_kv) { const int hh = n >> 7, wv = n & 127; row = (wv < 64) ? (64 * hh + wv) : (256 + 64 * hh + (wv - 64)); }
;     u32x4 o = {cvtpk(v[0], v[1]), cvtpk(v[2], v[3]), cvtpk(v[4], v[5]), cvtpk(v[6], v[7])};
;     *(u32x4*)(dst + (size_t)row * K + 8 * kb) = o;
;   }
.LBB0_388:
	s_mov_b32 s34, 0xaaab
	v_mul_u32_u24_sdwa v14, v12, s34 dst_sel:DWORD dst_unused:UNUSED_PAD src0_sel:WORD_0 src1_sel:DWORD
	v_mul_lo_u16_sdwa v15, v14, s8 dst_sel:DWORD dst_unused:UNUSED_PAD src0_sel:BYTE_3 src1_sel:DWORD
	v_mov_b32_e32 v0, 3
	v_sub_u16_e32 v21, v12, v15
	v_lshlrev_b16_sdwa v20, v0, v14 dst_sel:DWORD dst_unused:UNUSED_PAD src0_sel:DWORD src1_sel:BYTE_3
	v_lshlrev_b32_e32 v0, 2, v21
	s_movk_i32 s35, 0x600
	v_lshl_add_u64 v[14:15], s[20:21], 0, v[0:1]
	v_mad_u64_u32 v[14:15], s[34:35], v20, s35, v[14:15]
	v_add_co_u32_e32 v16, vcc, s6, v14
	s_waitcnt vmcnt(0)
	v_add_co_u32_e64 v18, s[50:51], s7, v14
	v_addc_co_u32_e32 v17, vcc, 0, v15, vcc
	global_load_dword v22, v[14:15], off
	global_load_dword v23, v[14:15], off offset:1536
	global_load_dword v24, v[14:15], off offset:3072
	v_addc_co_u32_e64 v19, s[50:51], 0, v15, s[50:51]
	global_load_dword v25, v[16:17], off offset:512
	global_load_dword v26, v[16:17], off offset:2048
	s_nop 0
	global_load_dword v16, v[16:17], off offset:3584
	s_nop 0
	global_load_dword v17, v[18:19], off offset:1024
	global_load_dword v27, v[18:19], off offset:2560
	v_mov_b64_e32 v[14:15], s[64:65]
	s_mov_b64 s[34:35], 0x23ff
	v_lshl_add_u64 v[12:13], v[12:13], 0, s[62:63]
	v_mad_u64_u32 v[14:15], s[50:51], v21, s8, v[14:15]
	v_cmp_lt_u64_e32 vcc, s[34:35], v[12:13]
	v_lshlrev_b32_e32 v0, 1, v20
	s_or_b64 s[74:75], vcc, s[74:75]
	v_lshl_add_u64 v[18:19], v[14:15], 0, v[0:1]
	s_waitcnt vmcnt(0)
	v_cvt_pk_bf16_f32 v14, v22, v23
	v_cvt_pk_bf16_f32 v15, v24, v25
	v_cvt_pk_bf16_f32 v16, v26, v16
	v_cvt_pk_bf16_f32 v17, v17, v27
	global_store_dwordx4 v[18:19], v[14:17], off
	s_andn2_b64 exec, exec, s[74:75]
	s_cbranch_execnz .LBB0_388

; DI unsigned cvtpk(float lo, float hi) { f32x2 v = {lo, hi}; bf16x2_t b = __builtin_convertvector(v, bf16x2_t); return __builtin_bit_cast(unsigned, b); }
; DI void xpose_cvt(const float* __restrict__ src, bf16_t* __restrict__ dst, int K, int N, int Npad, bool perm_kv, size_t gtid, size_t gstride) {
;   const size_t total = (size_t)Npad * (K >> 3);
; #pragma nounroll
;   for (size_t i = gtid; i < total; i += gstride) {
;     const int n = (int)(i % Npad), kb = (int)(i / Npad);
;     float v[8];
; #pragma unroll
;     for (int e = 0; e < 8; ++e) v[e] = (n < N) ? src[(size_t)(8 * kb + e) * N + n] : 0.f;
;     int row = n;
;     if (perm_kv) { const int hh = n >> 7, wv = n & 127; row = (wv < 64) ? (64 * hh + wv) : (256 + 64 * hh + (wv - 64)); }
;     u32x4 o = {cvtpk(v[0], v[1]), cvtpk(v[2], v[3]), cvtpk(v[4], v[5]), cvtpk(v[6], v[7])};
;     *(u32x4*)(dst + (size_t)row * K + 8 * kb) = o;
;   }
.LBB0_391:
	s_waitcnt vmcnt(0)
	v_lshrrev_b64 v[18:19], 9, v[16:17]
	v_lshlrev_b64 v[20:21], 14, v[18:19]
	v_lshl_add_u64 v[20:21], v[12:13], 0, v[20:21]
	v_add_co_u32_e32 v22, vcc, 0x1000, v20
	global_load_dword v0, v[20:21], off
	global_load_dword v26, v[20:21], off offset:2048
	v_addc_co_u32_e32 v23, vcc, 0, v21, vcc
	v_add_co_u32_e32 v24, vcc, 0x2000, v20
	global_load_dword v27, v[22:23], off
	global_load_dword v28, v[22:23], off offset:2048
	v_addc_co_u32_e32 v25, vcc, 0, v21, vcc
	v_add_co_u32_e32 v20, vcc, 0x3000, v20
	v_lshl_add_u64 v[16:17], v[16:17], 0, s[62:63]
	s_nop 0
	v_addc_co_u32_e32 v21, vcc, 0, v21, vcc
	global_load_dword v29, v[24:25], off
	s_nop 0
	global_load_dword v24, v[24:25], off offset:2048
	s_nop 0
	global_load_dword v25, v[20:21], off
	s_nop 0
	global_load_dword v21, v[20:21], off offset:2048
	v_cmp_lt_u64_e32 vcc, s[30:31], v[16:17]
	v_lshl_add_u64 v[22:23], v[18:19], 4, v[14:15]
	s_or_b64 s[64:65], vcc, s[64:65]
	s_waitcnt vmcnt(0)
	v_cvt_pk_bf16_f32 v18, v0, v26
	v_cvt_pk_bf16_f32 v19, v27, v28
	v_cvt_pk_bf16_f32 v20, v29, v24
	v_cvt_pk_bf16_f32 v21, v25, v21
	global_store_dwordx4 v[22:23], v[18:21], off
	s_andn2_b64 exec, exec, s[64:65]
	s_cbranch_execnz .LBB0_391
	s_or_b64 exec, exec, s[64:65]
	s_load_dwordx2 s[34:35], s[0:1], 0xa0
	v_lshlrev_b32_e32 v0, 2, v70
	v_lshl_add_u64 v[12:13], v[10:11], 0, s[50:51]
	s_mov_b64 s[50:51], 0
	v_mov_b64_e32 v[16:17], v[4:5]
	s_waitcnt lgkmcnt(0)
	s_add_u32 s20, s34, s20
	s_addc_u32 s21, s35, s21
	v_lshl_add_u64 v[14:15], s[20:21], 0, v[0:1]
.LBB0_393:
	v_lshrrev_b64 v[18:19], 8, v[16:17]
	v_lshlrev_b64 v[20:21], 13, v[18:19]
	v_lshl_add_u64 v[20:21], v[14:15], 0, v[20:21]
	global_load_dword v0, v[20:21], off
	global_load_dword v24, v[20:21], off offset:1024
	global_load_dword v25, v[20:21], off offset:2048
	global_load_dword v26, v[20:21], off offset:3072
	v_add_co_u32_e32 v20, vcc, 0x1000, v20
	v_lshl_add_u64 v[16:17], v[16:17], 0, s[62:63]
	s_nop 0
	v_addc_co_u32_e32 v21, vcc, 0, v21, vcc
	global_load_dword v27, v[20:21], off
	global_load_dword v28, v[20:21], off offset:1024
	global_load_dword v29, v[20:21], off offset:2048
	s_nop 0
	global_load_dword v21, v[20:21], off offset:3072
	v_cmp_lt_u64_e32 vcc, s[30:31], v[16:17]
	v_lshl_add_u64 v[22:23], v[18:19], 4, v[12:13]
	s_or_b64 s[50:51], vcc, s[50:51]
	s_waitcnt vmcnt(0)
	v_cvt_pk_bf16_f32 v18, v0, v24
	v_cvt_pk_bf16_f32 v19, v25, v26
	v_cvt_pk_bf16_f32 v20, v27, v28
	v_cvt_pk_bf16_f32 v21, v29, v21
	global_store_dwordx4 v[22:23], v[18:21], off
	s_andn2_b64 exec, exec, s[50:51]
	s_cbranch_execnz .LBB0_393
	s_or_b64 exec, exec, s[50:51]

; DI unsigned cvtpk(float lo, float hi) { f32x2 v = {lo, hi}; bf16x2_t b = __builtin_convertvector(v, bf16x2_t); return __builtin_bit_cast(unsigned, b); }
; DI void xpose_cvt(const float* __restrict__ src, bf16_t* __restrict__ dst, int K, int N, int Npad, bool perm_kv, size_t gtid, size_t gstride) {
;   const size_t total = (size_t)Npad * (K >> 3);
; #pragma nounroll
;   for (size_t i = gtid; i < total; i += gstride) {
;     const int n = (int)(i % Npad), kb = (int)(i / Npad);
;     float v[8];
; #pragma unroll
;     for (int e = 0; e < 8; ++e) v[e] = (n < N) ? src[(size_t)(8 * kb + e) * N + n] : 0.f;
;     int row = n;
;     if (perm_kv) { const int hh = n >> 7, wv = n & 127; row = (wv < 64) ? (64 * hh + wv) : (256 + 64 * hh + (wv - 64)); }
;     u32x4 o = {cvtpk(v[0], v[1]), cvtpk(v[2], v[3]), cvtpk(v[4], v[5]), cvtpk(v[6], v[7])};
;     *(u32x4*)(dst + (size_t)row * K + 8 * kb) = o;
;   }
; DI void phase0(KP p, char* lds) {
;     ...
;   for (int l = 0; l < 2; ++l) {
;     xpose_cvt(p->w_in + (size_t)l * 1024 * NIN, (bf16_t*)(ws + WS_WIN) + (size_t)l * NINP * 1024, 1024, NIN, NINP, false, gtid, gstride);
;     xpose_cvt(p->mla_w_uq + (size_t)l * 192 * 384, (bf16_t*)(ws + WS_WUQ) + (size_t)l * 384 * 192, 192, 384, 384, false, gtid, gstride);
;     xpose_cvt(p->mla_w_ukv + (size_t)l * 128 * 512, (bf16_t*)(ws + WS_WUKV) + (size_t)l * 512 * 128, 128, 512, 512, true, gtid, gstride);
;     xpose_cvt(p->fnet_w + (size_t)l * 256 * 256, (bf16_t*)(ws + WS_WF) + (size_t)l * 256 * 256, 256, 256, 256, false, gtid, gstride);
;     xpose_cvt(p->w_out + (size_t)l * 1024 * 1024, (bf16_t*)(ws + WS_WOUT) + (size_t)l * 1024 * 1024, 1024, 1024, 1024, false, gtid, gstride);
;   }
.LBB0_397:
	v_and_b32_e32 v24, 0x3ff, v12
	v_lshrrev_b64 v[14:15], 10, v[12:13]
	v_lshlrev_b32_e32 v0, 2, v24
	v_lshlrev_b64 v[16:17], 15, v[14:15]
	s_waitcnt vmcnt(0)
	v_lshl_add_u64 v[18:19], s[20:21], 0, v[0:1]
	v_lshl_add_u64 v[16:17], v[18:19], 0, v[16:17]
	v_add_co_u32_e32 v18, vcc, 0x1000, v16
	global_load_dword v25, v[16:17], off
	s_nop 0
	v_addc_co_u32_e32 v19, vcc, 0, v17, vcc
	v_add_co_u32_e32 v20, vcc, s59, v16
	v_lshl_add_u64 v[12:13], v[12:13], 0, s[62:63]
	s_nop 0
	v_addc_co_u32_e32 v21, vcc, 0, v17, vcc
	v_add_co_u32_e32 v22, vcc, s13, v16
	global_load_dword v26, v[18:19], off
	global_load_dword v27, v[20:21], off offset:-4096
	s_nop 0
	global_load_dword v20, v[20:21], off
	v_addc_co_u32_e32 v23, vcc, 0, v17, vcc
	v_add_co_u32_e32 v16, vcc, s27, v16
	s_mov_b64 s[34:35], 0x1ffff
	s_nop 0
	v_addc_co_u32_e32 v17, vcc, 0, v17, vcc
	global_load_dword v21, v[22:23], off offset:-4096
	s_nop 0
	global_load_dword v22, v[22:23], off
	s_nop 0
	global_load_dword v23, v[16:17], off offset:-4096
	global_load_dword v28, v[16:17], off
	v_lshlrev_b32_e32 v0, 11, v24
	v_cmp_lt_u64_e32 vcc, s[34:35], v[12:13]
	v_lshl_add_u64 v[16:17], s[50:51], 0, v[0:1]
	s_or_b64 s[64:65], vcc, s[64:65]
	v_lshl_add_u64 v[18:19], v[14:15], 4, v[16:17]
	s_waitcnt vmcnt(0)
	v_cvt_pk_bf16_f32 v14, v25, v26
	v_cvt_pk_bf16_f32 v15, v27, v20
	v_cvt_pk_bf16_f32 v16, v21, v22
	v_cvt_pk_bf16_f32 v17, v23, v28
	global_store_dwordx4 v[18:19], v[14:17], off
	s_andn2_b64 exec, exec, s[64:65]
	s_cbranch_execnz .LBB0_397
	s_branch .LBB0_366

; DI unsigned cvtpk(float lo, float hi) { f32x2 v = {lo, hi}; bf16x2_t b = __builtin_convertvector(v, bf16x2_t); return __builtin_bit_cast(unsigned, b); }
; DI void phase0(KP p, char* lds) {
;     ...
;   {
;     const float* src = p->cm_w_s; bf16_t* dst = (bf16_t*)(ws + WS_WS);
;     for (size_t i = gtid; i < (size_t)2 * 4 * 128 * 128 / 8; i += gstride) {
;       f32x4 a = *(const f32x4*)(src + i * 8), b = *(const f32x4*)(src + i * 8 + 4);
;       u32x4 o = {cvtpk(a[0], a[1]), cvtpk(a[2], a[3]), cvtpk(b[0], b[1]), cvtpk(b[2], b[3])};
;       *(u32x4*)(dst + i * 8) = o;
;     }
;   }
.LBB0_400:
	global_load_dwordx4 v[12:15], v[8:9], off offset:-16
	global_load_dwordx4 v[16:19], v[8:9], off
	v_lshl_add_u64 v[10:11], v[10:11], 0, s[62:63]
	v_cmp_lt_u64_e64 s[42:43], s[44:45], v[10:11]
	v_lshl_add_u64 v[8:9], v[8:9], 0, s[40:41]
	s_or_b64 s[18:19], s[42:43], s[18:19]
	s_waitcnt vmcnt(0)
	v_cvt_pk_bf16_f32 v12, v12, v13
	v_cvt_pk_bf16_f32 v13, v14, v15
	v_cvt_pk_bf16_f32 v14, v16, v17
	v_cvt_pk_bf16_f32 v15, v18, v19
	global_store_dwordx4 v[6:7], v[12:15], off
	v_lshl_add_u64 v[6:7], v[6:7], 0, s[34:35]
	s_andn2_b64 exec, exec, s[18:19]
	s_cbranch_execnz .LBB0_400

; DI unsigned cvtpk(float lo, float hi) { f32x2 v = {lo, hi}; bf16x2_t b = __builtin_convertvector(v, bf16x2_t); return __builtin_bit_cast(unsigned, b); }
; DI void phase0(KP p, char* lds) {
;     ...
;     bf16_t* dl = (bf16_t*)(ws + WS_DLAT);
; #pragma nounroll
;     for (size_t i = gtid; i < (size_t)2048 * 256; i += gstride) {
;       const int sp = (int)(i >> 8), k8 = (int)(i & 255) * 8;
;       float v[8];
; #pragma unroll
;       for (int e = 0; e < 8; ++e) { const int k = k8 + e, s = (k <= 1024) ? k : k - 1024; const int ph = (sp * s) & 2047; const float a = (float)ph * (1.f / 1024.f); v[e] = (k <= 1024) ? cospif(a) : -sinpif(a); }
;       u32x4 o = {cvtpk(v[0], v[1]), cvtpk(v[2], v[3]), cvtpk(v[4], v[5]), cvtpk(v[6], v[7])};
;       *(u32x4*)(dl + (size_t)sp * 2048 + k8) = o;
;     }
.LBB0_403:
	s_or_b64 exec, exec, s[18:19]
	v_lshrrev_b64 v[18:19], 8, v[6:7]
	v_cvt_pk_bf16_f32 v10, v10, v12
	v_cvt_pk_bf16_f32 v11, v13, v14
	v_cvt_pk_bf16_f32 v12, v15, v16
	v_lshlrev_b64 v[14:15], 12, v[18:19]
	v_lshl_add_u64 v[6:7], v[6:7], 0, s[62:63]
	s_mov_b64 s[18:19], 0x7ffff
	v_lshl_add_u64 v[14:15], s[46:47], 0, v[14:15]
	v_lshlrev_b32_e32 v0, 1, v0
	v_cmp_lt_u64_e64 s[42:43], s[18:19], v[6:7]
	v_readlane_b32 s2, v254, 48
	v_cvt_pk_bf16_f32 v13, v17, v21
	v_lshl_add_u64 v[14:15], v[14:15], 0, v[0:1]
	s_or_b64 s[48:49], s[42:43], s[48:49]
	v_add_u32_e32 v9, s2, v9
	global_store_dwordx4 v[14:15], v[10:13], off
	s_andn2_b64 exec, exec, s[48:49]
	s_cbranch_execz .LBB0_436

; DI unsigned cvtpk(float lo, float hi) { f32x2 v = {lo, hi}; bf16x2_t b = __builtin_convertvector(v, bf16x2_t); return __builtin_bit_cast(unsigned, b); }
; DI void phase0(KP p, char* lds) {
;     ...
;     bf16_t* dc = (bf16_t*)(ws + WS_DCTX);
;     for (size_t i = gtid; i < (size_t)256 * 64; i += gstride) {
;       const int sp = (int)(i >> 6), k8 = (int)(i & 63) * 8;
;       float v[8];
; #pragma unroll
;       for (int e = 0; e < 8; ++e) { const int k = k8 + e, s = k & 255; const int ph = (sp * s) & 255; const float a = (float)ph * (1.f / 128.f); v[e] = (k < 256) ? cospif(a) : -sinpif(a); }
;       u32x4 o = {cvtpk(v[0], v[1]), cvtpk(v[2], v[3]), cvtpk(v[4], v[5]), cvtpk(v[6], v[7])};
;       *(u32x4*)(dc + (size_t)sp * 512 + k8) = o;
;     }
.LBB0_438:
	s_or_b64 exec, exec, s[18:19]
	v_lshrrev_b64 v[18:19], 6, v[6:7]
	v_cvt_pk_bf16_f32 v10, v9, v11
	v_cvt_pk_bf16_f32 v11, v12, v13
	v_cvt_pk_bf16_f32 v12, v14, v15
	v_lshlrev_b64 v[14:15], 10, v[18:19]
	v_lshl_add_u64 v[6:7], v[6:7], 0, s[62:63]
	v_lshl_add_u64 v[14:15], s[46:47], 0, v[14:15]
	v_lshlrev_b32_e32 v0, 1, v0
	v_cmp_lt_u64_e32 vcc, s[34:35], v[6:7]
	v_readlane_b32 s2, v254, 48
	v_cvt_pk_bf16_f32 v13, v16, v20
	v_lshl_add_u64 v[14:15], v[14:15], 0, v[0:1]
	s_or_b64 s[48:49], vcc, s[48:49]
	v_add_u32_e32 v8, s2, v8
	global_store_dwordx4 v[14:15], v[10:13], off
	s_andn2_b64 exec, exec, s[48:49]
	s_cbranch_execz .LBB0_471

; DI bf16_t f2bf(float f) { return (bf16_t)(cvtpk(f, 0.f) & 0xffffu); }
; DI void phase0(KP p, char* lds) {
;     ...
;     bf16_t* cm = (bf16_t*)(ws + WS_CM);
;     for (size_t i = gtid; i < (size_t)128 * 64; i += gstride) {
;       const int n = (int)(i >> 6), c = (int)(i & 63);
;       const int ph = (c * (n & 63)) & 63; const float a = (float)ph * (1.f / 32.f);
;       cm[i] = f2bf((n < 64) ? cospif(a) : sinpif(a));
;     }
.LBB0_478:
	v_lshrrev_b32_e32 v0, 6, v16
	v_lshrrev_b32_e32 v28, 6, v14
	v_lshrrev_b32_e32 v29, 6, v12
	v_lshrrev_b32_e32 v30, 6, v10
	v_mul_lo_u32 v30, v30, v10
	v_mul_lo_u32 v29, v29, v12
	v_mul_lo_u32 v28, v28, v14
	v_mul_lo_u32 v0, v0, v16
	v_and_b32_e32 v0, 63, v0
	v_and_b32_e32 v28, 63, v28
	v_and_b32_e32 v29, 63, v29
	v_and_b32_e32 v30, 63, v30
	v_cvt_f32_ubyte0_e32 v31, v30
	v_cvt_f32_ubyte0_e32 v30, v29
	v_cvt_f32_ubyte0_e32 v29, v28
	v_cvt_f32_ubyte0_e32 v28, v0
	v_pk_mul_f32 v[28:29], v[28:29], s[14:15] op_sel_hi:[1,0]
	v_pk_mul_f32 v[30:31], v[30:31], s[14:15] op_sel_hi:[1,0]
	v_lshl_add_u64 v[20:21], v[20:21], 0, -4
	v_pk_mul_f32 v[36:37], v[30:31], 0.5 op_sel_hi:[1,0]
	v_pk_mul_f32 v[38:39], v[28:29], 0.5 op_sel_hi:[1,0]
	v_cmp_eq_u64_e32 vcc, 0, v[20:21]
	v_fract_f32_e32 v40, v38
	v_fract_f32_e32 v41, v39
	v_fract_f32_e32 v42, v36
	v_fract_f32_e32 v43, v37
	s_or_b64 s[48:49], vcc, s[48:49]
	v_pk_add_f32 v[40:41], v[40:41], v[40:41]
	v_pk_add_f32 v[42:43], v[42:43], v[42:43]
	v_cmp_neq_f32_e32 vcc, s68, v37
	v_cmp_neq_f32_e64 s[40:41], s68, v38
	v_cmp_neq_f32_e64 s[42:43], s68, v39
	v_cmp_neq_f32_e64 s[44:45], s68, v36
	v_cndmask_b32_e32 v38, 0, v43, vcc
	v_cndmask_b32_e64 v36, 0, v40, s[40:41]
	v_cndmask_b32_e64 v0, 0, v42, s[44:45]
	v_cndmask_b32_e64 v37, 0, v41, s[42:43]
	v_cmp_lt_f32_e32 vcc, 1.0, v30
	v_cmp_lt_f32_e64 s[40:41], 1.0, v31
	v_cmp_lt_f32_e64 s[42:43], 1.0, v28
	v_cmp_lt_f32_e64 s[44:45], 1.0, v29
	v_cndmask_b32_e64 v39, v31, v38, s[40:41]
	v_cndmask_b32_e64 v36, v28, v36, s[42:43]
	v_cndmask_b32_e64 v37, v29, v37, s[44:45]
	v_cndmask_b32_e32 v38, v30, v0, vcc
	v_pk_add_f32 v[40:41], v[38:39], v[38:39]
	v_pk_add_f32 v[42:43], v[36:37], v[36:37]
	v_rndne_f32_e32 v41, v41
	v_rndne_f32_e32 v43, v43
	v_rndne_f32_e32 v42, v42
	v_rndne_f32_e32 v40, v40
	s_mov_b32 s2, 0xbf1f24be
	s_mov_b32 s18, 0x3e642e9d
	v_pk_fma_f32 v[38:39], v[40:41], -0.5, v[38:39] op_sel_hi:[1,0,1]
	v_pk_fma_f32 v[36:37], v[42:43], -0.5, v[36:37] op_sel_hi:[1,0,1]
	v_mov_b64_e32 v[32:33], s[2:3]
	v_mov_b64_e32 v[34:35], s[18:19]
	v_cvt_i32_f32_e32 v0, v40
	v_cvt_i32_f32_e32 v52, v41
	v_cvt_i32_f32_e32 v53, v42
	v_cvt_i32_f32_e32 v54, v43
	v_pk_mul_f32 v[40:41], v[36:37], v[36:37]
	v_pk_mul_f32 v[42:43], v[38:39], v[38:39]
	v_pk_mul_f32 v[48:49], v[36:37], v[40:41]
	v_pk_fma_f32 v[44:45], v[42:43], s[74:75], v[32:33] op_sel_hi:[1,0,0]
	v_pk_fma_f32 v[32:33], v[40:41], s[74:75], v[32:33] op_sel_hi:[1,0,0]
	v_pk_fma_f32 v[50:51], v[42:43], s[28:29], v[34:35] op_sel_hi:[1,0,0]
	v_pk_fma_f32 v[34:35], v[40:41], s[28:29], v[34:35] op_sel_hi:[1,0,0]
	v_pk_fma_f32 v[32:33], v[40:41], v[32:33], s[46:47] op_sel_hi:[1,1,0]
	v_pk_fma_f32 v[34:35], v[40:41], v[34:35], s[88:89] op_sel_hi:[1,1,0]
	v_pk_fma_f32 v[44:45], v[42:43], v[44:45], s[46:47] op_sel_hi:[1,1,0]
	v_pk_fma_f32 v[50:51], v[42:43], v[50:51], s[88:89] op_sel_hi:[1,1,0]
	v_pk_fma_f32 v[32:33], v[40:41], v[32:33], s[86:87] op_sel_hi:[1,1,0]
	v_pk_fma_f32 v[34:35], v[40:41], v[34:35], s[90:91] op_sel_hi:[1,1,0]
	v_pk_mul_f32 v[46:47], v[38:39], v[42:43]
	v_pk_fma_f32 v[44:45], v[42:43], v[44:45], s[86:87] op_sel_hi:[1,1,0]
	v_pk_fma_f32 v[50:51], v[42:43], v[50:51], s[90:91] op_sel_hi:[1,1,0]
	v_and_b32_e32 v55, 1, v54
	v_and_b32_e32 v56, 1, v53
	v_pk_mul_f32 v[32:33], v[48:49], v[32:33]
	v_pk_fma_f32 v[34:35], v[40:41], v[34:35], s[4:5] op_sel_hi:[1,1,0]
	v_and_b32_e32 v57, 1, v52
	v_and_b32_e32 v58, 1, v0
	v_lshlrev_b32_e32 v61, 30, v53
	v_and_b32_e32 v53, 2, v53
	v_pk_mul_f32 v[44:45], v[46:47], v[44:45]
	v_pk_fma_f32 v[46:47], v[42:43], v[50:51], s[4:5] op_sel_hi:[1,1,0]
	v_pk_fma_f32 v[32:33], v[36:37], s[76:77], v[32:33] op_sel_hi:[1,0,1]
	v_pk_fma_f32 v[34:35], v[40:41], v[34:35], 1.0 op_sel_hi:[1,1,0]
	v_cmp_eq_u32_e64 s[42:43], 0, v56
	v_cmp_eq_u32_e64 s[44:45], 0, v55
	v_lshlrev_b32_e32 v59, 30, v0
	v_lshlrev_b32_e32 v60, 30, v52
	v_lshlrev_b32_e32 v62, 30, v54
	v_and_b32_e32 v54, 2, v54
	v_and_b32_e32 v0, 2, v0
	v_and_b32_e32 v52, 2, v52
	v_and_b32_e32 v49, 0x80000000, v61
	v_pk_fma_f32 v[38:39], v[38:39], s[76:77], v[44:45] op_sel_hi:[1,0,1]
	v_pk_fma_f32 v[36:37], v[42:43], v[46:47], 1.0 op_sel_hi:[1,1,0]
	v_cmp_eq_u32_e32 vcc, 0, v58
	v_cmp_eq_u32_e64 s[40:41], 0, v57
	v_cndmask_b32_e64 v40, v35, v33, s[44:45]
	v_cndmask_b32_e64 v41, v34, v32, s[42:43]
	v_cndmask_b32_e64 v33, -v33, v35, s[44:45]
	v_cndmask_b32_e64 v32, -v32, v34, s[42:43]
	v_cmp_eq_u32_e64 s[44:45], 0, v53
	v_and_b32_e32 v48, 0x80000000, v62
	v_and_b32_e32 v50, 0x80000000, v60
	v_and_b32_e32 v51, 0x80000000, v59
	v_cndmask_b32_e64 v42, v37, v39, s[40:41]
	v_cndmask_b32_e32 v43, v36, v38, vcc
	v_cndmask_b32_e64 v37, -v39, v37, s[40:41]
	v_cndmask_b32_e64 v36, -v38, v36, vcc
	v_cmp_eq_u32_e32 vcc, 0, v52
	v_cmp_eq_u32_e64 s[40:41], 0, v0
	v_cmp_eq_u32_e64 s[42:43], 0, v54
	v_cndmask_b32_e64 v0, -v32, v32, s[44:45]
	v_xor_b32_e32 v32, v49, v41
	v_cmp_gt_u64_e64 s[44:45], s[34:35], v[16:17]
	v_cndmask_b32_e64 v33, -v33, v33, s[42:43]
	v_xor_b32_e32 v34, v48, v40
	v_cmp_gt_u64_e64 s[42:43], s[34:35], v[14:15]
	v_cndmask_b32_e64 v35, -v36, v36, s[40:41]
	v_xor_b32_e32 v36, v51, v43
	v_cmp_gt_u64_e64 s[40:41], s[34:35], v[12:13]
	v_cndmask_b32_e64 v37, -v37, v37, vcc
	v_xor_b32_e32 v38, v50, v42
	v_cmp_gt_u64_e32 vcc, s[34:35], v[10:11]
	v_cndmask_b32_e64 v0, v32, v0, s[44:45]
	v_cmp_lg_f32_e64 s[44:45], s68, v28
	v_cndmask_b32_e32 v37, v38, v37, vcc
	v_cmp_lg_f32_e32 vcc, s68, v31
	v_cndmask_b32_e64 v31, v36, v35, s[40:41]
	v_cmp_lg_f32_e64 s[40:41], s68, v30
	v_cndmask_b32_e64 v30, v34, v33, s[42:43]
	v_cmp_lg_f32_e64 s[42:43], s68, v29
	v_cndmask_b32_e64 v0, v208, v0, s[44:45]
	v_cndmask_b32_e64 v29, v208, v31, s[40:41]
	v_cndmask_b32_e64 v28, v208, v30, s[42:43]
	v_cndmask_b32_e32 v30, v208, v37, vcc
	v_cvt_pk_bf16_f32 v0, v0, s0
	v_lshl_add_u64 v[22:23], v[18:19], 0, s[50:51]
	v_lshl_add_u64 v[24:25], v[18:19], 0, s[52:53]
	v_lshl_add_u64 v[26:27], v[18:19], 0, s[54:55]
	v_lshl_add_u64 v[10:11], v[10:11], 0, s[72:73]
	v_lshl_add_u64 v[12:13], v[12:13], 0, s[64:65]
	v_lshl_add_u64 v[14:15], v[14:15], 0, s[56:57]
	v_lshl_add_u64 v[16:17], v[16:17], 0, s[52:53]
	v_cvt_pk_bf16_f32 v30, v30, s0
	v_cvt_pk_bf16_f32 v29, v29, s0
	v_cvt_pk_bf16_f32 v28, v28, s0
	global_store_short v[18:19], v0, off
	global_store_short v[22:23], v28, off
	global_store_short v[24:25], v29, off
	global_store_short v[26:27], v30, off
	v_lshl_add_u64 v[18:19], v[18:19], 0, s[20:21]
	s_andn2_b64 exec, exec, s[48:49]
	s_cbranch_execnz .LBB0_478
	s_or_b64 exec, exec, s[48:49]
	v_mad_u64_u32 v[10:11], s[18:19], v8, s62, v[4:5]
	v_mul_lo_u32 v0, v8, s63
	v_mul_lo_u32 v12, v9, s62
	v_cmp_ne_u64_e32 vcc, v[6:7], v[8:9]
	v_readlane_b32 s48, v255, 26
	v_readlane_b32 s4, v255, 28
	v_add3_u32 v11, v12, v11, v0
	s_orn2_b64 s[18:19], vcc, exec
	s_mov_b64 s[28:29], 0x80
	s_mov_b64 s[86:87], 0x18c5200
	s_mov_b64 s[88:89], 0x18d5200
	s_mov_b64 s[90:91], 0x18e5200
	v_readlane_b32 s49, v255, 27
	v_readlane_b32 s5, v255, 29

; DI bf16_t f2bf(float f) { return (bf16_t)(cvtpk(f, 0.f) & 0xffffu); }
; DI void phase0(KP p, char* lds) {
;     ...
;     bf16_t* cm = (bf16_t*)(ws + WS_CM);
;     for (size_t i = gtid; i < (size_t)128 * 64; i += gstride) {
;       const int n = (int)(i >> 6), c = (int)(i & 63);
;       const int ph = (c * (n & 63)) & 63; const float a = (float)ph * (1.f / 32.f);
;       cm[i] = f2bf((n < 64) ? cospif(a) : sinpif(a));
;     }
.LBB0_482:
	s_or_b64 exec, exec, s[20:21]
	v_cmp_lg_f32_e32 vcc, s68, v0
	v_lshl_add_u64 v[10:11], v[10:11], 0, s[62:63]
	s_nop 0
	v_cndmask_b32_e32 v0, v208, v15, vcc
	v_cvt_pk_bf16_f32 v0, v0, s0
	v_cmp_lt_u64_e32 vcc, s[30:31], v[10:11]
	global_store_short v[6:7], v0, off
	s_or_b64 s[18:19], vcc, s[18:19]
	v_lshl_add_u64 v[6:7], v[6:7], 0, s[50:51]
	s_andn2_b64 exec, exec, s[18:19]
	s_cbranch_execz .LBB0_487

; DI void phase0(KP p, char* lds) {
;     ...
;     float* rg = (float*)(ws + WS_ROPG);
;     for (size_t i = gtid; i < 64 * 16; i += gstride) {
;       const int pos = (int)(i >> 4), j = (int)(i & 15);
;       const float inv = powf(10000.f, -(float)j / 16.f); float sn, cs; sincosf((float)pos * inv, &sn, &cs);
;       rg[2 * i] = cs; rg[2 * i + 1] = sn;
;     }
.LBB0_489:
	s_or_b64 exec, exec, s[18:19]
	v_mul_f32_e32 v14, v0, v0
	v_fmamk_f32 v15, v14, 0xb94c1982, v252
	v_fmaak_f32 v15, v14, v15, 0xbe2aaa9d
	v_mul_f32_e32 v15, v14, v15
	v_fmac_f32_e32 v0, v0, v15
	v_fmamk_f32 v15, v14, 0x37d75334, v205
	v_fmaak_f32 v15, v14, v15, 0x3d2aabf7
	v_fmaak_f32 v15, v14, v15, 0xbf000004
	v_fma_f32 v14, v14, v15, 1.0
	v_lshlrev_b32_e32 v15, 30, v13
	v_and_b32_e32 v13, 1, v13
	v_cmp_eq_u32_e32 vcc, 0, v13
	v_xor_b32_e32 v12, v12, v11
	v_and_b32_e32 v16, 0x80000000, v15
	v_cndmask_b32_e32 v13, v14, v0, vcc
	v_xor_b32_e32 v0, 0x80000000, v0
	v_xor_b32_e32 v12, v12, v13
	v_cndmask_b32_e32 v0, v0, v14, vcc
	s_movk_i32 s2, 0x1f8
	v_xor_b32_e32 v13, v12, v16
	v_bitop3_b32 v0, v0, v15, s10 bitop3:0x78
	v_cmp_class_f32_e64 vcc, v11, s2
	v_lshl_add_u64 v[8:9], v[8:9], 0, s[62:63]
	s_mov_b64 s[18:19], 0x3ff
	v_cndmask_b32_e32 v12, v208, v0, vcc
	v_cndmask_b32_e32 v13, v208, v13, vcc
	v_add_co_u32_e32 v14, vcc, -4, v6
	s_nop 1
	v_addc_co_u32_e32 v15, vcc, -1, v7, vcc
	v_cmp_lt_u64_e32 vcc, s[18:19], v[8:9]
	v_readlane_b32 s18, v255, 7
	v_readlane_b32 s19, v255, 8
	s_or_b64 s[46:47], vcc, s[46:47]
	global_store_dwordx2 v[14:15], v[12:13], off
	v_lshl_add_u64 v[6:7], v[6:7], 0, s[18:19]
	s_andn2_b64 exec, exec, s[46:47]
	s_cbranch_execz .LBB0_494

; DI void phase0(KP p, char* lds) {
;     ...
;     if (blockIdx.x == 0 && tid < 4) {
;       const int l = tid >> 1, isb = tid & 1; const int d = isb ? 64 : 96;
;       const float* gq = (isb ? p->gqa_qn : p->mla_qn) + l * d; const float* gk = (isb ? p->gqa_kn : p->mla_kn) + l * d;
;       float mq = 0.f, mk = 0.f;
;       for (int i = 0; i < d; ++i) { mq = fmaxf(mq, fabsf(gq[i])); mk = fmaxf(mk, fabsf(gk[i])); }
;       ((float*)(ws + WS_SBND))[l * 2 + isb] = sqrtf((float)d) * mq * mk * 1.4426950408889634f;
;     }
.LBB0_496:
	global_load_dword v13, v[6:7], off
	global_load_dword v14, v[8:9], off
	v_add_u32_e32 v12, -1, v12
	v_max_f32_e32 v0, v0, v0
	v_max_f32_e32 v11, v11, v11
	v_cmp_eq_u32_e32 vcc, 0, v12
	v_lshl_add_u64 v[8:9], v[8:9], 0, 4
	v_lshl_add_u64 v[6:7], v[6:7], 0, 4
	s_or_b64 s[18:19], vcc, s[18:19]
	s_waitcnt vmcnt(0)
	v_max_f32_e64 v13, |v13|, |v13|
	v_max_f32_e64 v14, |v14|, |v14|
	v_max_f32_e32 v0, v0, v13
	v_max_f32_e32 v11, v11, v14
	s_andn2_b64 exec, exec, s[18:19]
	s_cbranch_execnz .LBB0_496
	s_or_b64 exec, exec, s[18:19]
	v_cvt_f32_ubyte0_e32 v6, v10
	s_mov_b32 s2, 0xf800000
	v_mul_f32_e32 v7, 0x4f800000, v6
	v_cmp_gt_f32_e32 vcc, s2, v6
	s_nop 1
	v_cndmask_b32_e32 v6, v6, v7, vcc
	v_sqrt_f32_e32 v7, v6
	s_nop 0
	v_add_u32_e32 v8, -1, v7
	v_fma_f32 v10, -v8, v7, v6
	v_add_u32_e32 v9, 1, v7
	v_cmp_ge_f32_e64 s[40:41], 0, v10
	s_nop 1
	v_cndmask_b32_e64 v8, v7, v8, s[40:41]
	v_fma_f32 v7, -v9, v7, v6
	v_cmp_lt_f32_e64 s[40:41], 0, v7
	s_nop 1
	v_cndmask_b32_e64 v7, v8, v9, s[40:41]
	v_mul_f32_e32 v8, 0x37800000, v7
	v_cndmask_b32_e32 v7, v7, v8, vcc
	v_mov_b32_e32 v8, 0x260
	v_cmp_class_f32_e32 vcc, v6, v8
	s_nop 1
	v_cndmask_b32_e32 v6, v7, v6, vcc
	v_mul_f32_e32 v0, v6, v0
	v_lshl_add_u64 v[6:7], v[2:3], 2, s[36:37]
	v_mul_f32_e32 v0, v11, v0
	v_add_co_u32_e32 v6, vcc, 0x69000, v6
	v_mul_f32_e32 v0, 0x3fb8aa3b, v0
	s_nop 0
	v_addc_co_u32_e32 v7, vcc, 0, v7, vcc
	global_store_dword v[6:7], v0, off

; DI void phase0(KP p, char* lds) {
;     ...
;     float* rm = (float*)(ws + WS_ROPM);
;     for (size_t i = gtid; i < 64 * 8; i += gstride) {
;       const int pos = (int)(i >> 3), j = (int)(i & 7);
;       const float inv = powf(10000.f, -(float)j / 8.f); float sn, cs; sincosf((float)pos * inv, &sn, &cs);
;       rm[2 * i] = cs; rm[2 * i + 1] = sn;
;     }
.LBB0_500:
	s_or_b64 exec, exec, s[18:19]
	v_mul_f32_e32 v10, v0, v0
	v_fmamk_f32 v11, v10, 0xb94c1982, v252
	v_fmaak_f32 v11, v10, v11, 0xbe2aaa9d
	v_mul_f32_e32 v11, v10, v11
	v_fmac_f32_e32 v0, v0, v11
	v_fmamk_f32 v11, v10, 0x37d75334, v205
	v_fmaak_f32 v11, v10, v11, 0x3d2aabf7
	v_fmaak_f32 v11, v10, v11, 0xbf000004
	v_fma_f32 v10, v10, v11, 1.0
	v_lshlrev_b32_e32 v11, 30, v9
	v_and_b32_e32 v9, 1, v9
	v_cmp_eq_u32_e64 s[40:41], 0, v9
	v_xor_b32_e32 v8, v8, v3
	v_and_b32_e32 v12, 0x80000000, v11
	v_cndmask_b32_e64 v9, v10, v0, s[40:41]
	v_xor_b32_e32 v0, 0x80000000, v0
	v_xor_b32_e32 v8, v8, v9
	v_cndmask_b32_e64 v0, v0, v10, s[40:41]
	s_movk_i32 s2, 0x1f8
	v_xor_b32_e32 v9, v8, v12
	v_bitop3_b32 v0, v0, v11, s10 bitop3:0x78
	v_cmp_class_f32_e64 s[40:41], v3, s2
	s_and_b64 s[18:19], exec, vcc
	v_lshl_add_u64 v[4:5], v[4:5], 3, s[48:49]
	v_cndmask_b32_e64 v8, v208, v0, s[40:41]
	v_cndmask_b32_e64 v9, v208, v9, s[40:41]
	s_or_b64 s[50:51], s[18:19], s[50:51]
	global_store_dwordx2 v[4:5], v[8:9], off
	v_mov_b64_e32 v[4:5], v[6:7]
	s_andn2_b64 exec, exec, s[50:51]
	s_cbranch_execz .LBB0_505

; DI void phase0(KP p, char* lds) {
;     ...
;     for (int e = tq; e < 17 * 32; e += 256) {
;       const int i = e >> 5, c2 = e & 31;
;       float s = 0.f;
; #pragma unroll
;       for (int g = 0; g < 8; ++g) s += sl[(g * 17 + i) * 32 + c2];
;       const int nn = (it % 96) * 32 + c2;
;       mod[((size_t)l * 17 + i) * 3072 + nn] = s + p->b_mod[l * 3072 + nn];
;     }
;     __syncthreads();
;   }
.LBB0_512:
	global_load_dword v7, v[2:3], off
	ds_read_b32 v8, v0
	ds_read_b32 v9, v0 offset:2176
	ds_read_b32 v10, v0 offset:4352
	ds_read_b32 v11, v0 offset:6528
	ds_read_b32 v12, v0 offset:8704
	ds_read_b32 v13, v0 offset:10880
	ds_read_b32 v14, v0 offset:13056
	ds_read_b32 v15, v0 offset:15232
	s_waitcnt lgkmcnt(0)
	v_add_f32_e32 v8, 0, v8
	s_waitcnt lgkmcnt(6)
	v_add_f32_e32 v8, v8, v9
	s_waitcnt lgkmcnt(5)
	v_add_f32_e32 v8, v8, v10
	s_waitcnt lgkmcnt(4)
	v_add_f32_e32 v8, v8, v11
	s_waitcnt lgkmcnt(3)
	v_add_f32_e32 v8, v8, v12
	s_waitcnt lgkmcnt(2)
	v_add_f32_e32 v8, v8, v13
	s_waitcnt lgkmcnt(1)
	v_add_f32_e32 v8, v8, v14
	v_add_u32_e32 v6, 0x100, v6
	s_movk_i32 s2, 0x11f
	s_waitcnt lgkmcnt(0)
	v_add_f32_e32 v8, v8, v15
	s_mov_b64 s[18:19], 0x18000
	v_cmp_lt_u32_e32 vcc, s2, v6
	v_add_u32_e32 v0, 0x400, v0
	s_or_b64 s[4:5], vcc, s[4:5]
	s_waitcnt vmcnt(0)
	v_add_f32_e32 v7, v8, v7
	global_store_dword v[4:5], v7, off
	v_lshl_add_u64 v[4:5], v[4:5], 0, s[18:19]
	s_andn2_b64 exec, exec, s[4:5]
	s_cbranch_execnz .LBB0_512
	s_or_b64 exec, exec, s[4:5]
	v_readlane_b32 s2, v253, 8
	s_waitcnt lgkmcnt(0)
	s_barrier
	v_add_u32_e32 v71, s2, v71
	s_movk_i32 s2, 0xbf
	v_cmp_lt_i32_e32 vcc, s2, v71
	s_or_b64 s[50:51], vcc, s[50:51]
	s_andn2_b64 exec, exec, s[50:51]
	s_cbranch_execnz .LBB0_507
